# back-to-back s_setprio 0/1 pairs inside GEMM MFMA bursts removed (56 pairs)
# baseline (speedup 1.0000x reference)
; template <class Epi, class Sched, bool ALIGN_EPI = false, bool SP2 = false>
; __device__ __forceinline__ void gemm_phase(PG8_LAS unsigned char* lds, const Gemm g, const Sched& S, const Epi& E) {
;     ...
;         const bool has_next = S.next(ui + 1, nxt);
;         const char* nA = has_next ? (const char*)g.A + (size_t)nxt.pm * tstep : cA; const char* nB = has_next ? (const char*)g.Bt + (size_t)nxt.pn * tstep : cB;
;         for (int t = 0; t < nt; t += 2) {
;             const bool last = (t == nt - 2);
;             const char* a1 = cA + (size_t)(t + 1) * kstep;
;             const char* a2 = last ? nA : cA + (size_t)(t + 2) * kstep; const char* b2 = last ? nB : cB + (size_t)(t + 2) * kstep;
;             const char* a3 = a2 + kstep; const char* b3 = b2 + kstep;
.LBB0_15:
	s_ashr_i32 s25, s24, 31
	s_lshl_b64 s[26:27], s[24:25], 20
	s_add_u32 s26, s40, s26
	s_addc_u32 s27, s41, s27
	s_and_b64 s[28:29], s[4:5], exec
	s_cselect_b32 s25, s27, s35
	s_cselect_b32 s65, s26, s34
	s_ashr_i32 s23, s22, 31
	s_lshl_b64 s[28:29], s[22:23], 20
	s_add_u32 s28, s42, s28
	s_addc_u32 s29, s43, s29
	s_and_b64 s[38:39], s[4:5], exec
	s_cselect_b32 s23, s29, s37
	s_cselect_b32 s66, s28, s36
	s_add_u32 s34, s34, 0x80080
	s_addc_u32 s35, s35, 0
	s_add_u32 s67, s36, 0x100

; template <class Epi, class Sched, bool ALIGN_EPI = false, bool SP2 = false>
; __device__ __forceinline__ void gemm_phase(PG8_LAS unsigned char* lds, const Gemm g, const Sched& S, const Epi& E) {
;     ...
;         const char* nA = has_next ? (const char*)g.A + (size_t)nxt.pm * tstep : cA; const char* nB = has_next ? (const char*)g.Bt + (size_t)nxt.pn * tstep : cB;
;         for (int t = 0; t < nt; t += 2) {
;             const bool last = (t == nt - 2);
;             const char* a1 = cA + (size_t)(t + 1) * kstep;
;             const char* a2 = last ? nA : cA + (size_t)(t + 2) * kstep; const char* b2 = last ? nB : cB + (size_t)(t + 2) * kstep;
;             const char* a3 = a2 + kstep; const char* b3 = b2 + kstep;
	s_addc_u32 s68, s37, 0
	s_mov_b32 s69, -2


; #define PG8_STAGE(bufoff, gbase, voff) do { _Pragma("unroll") for (int _i = 0; _i < 2; ++_i) \
;         __builtin_amdgcn_global_load_lds((const unsigned*)((const char*)(gbase) + (voff)[_i]), (PG8_LAS unsigned*)(lds + (bufoff) + ldsw + _i * 8192), 16, 0, 0); } while (0)
; #define PG8_LDA(dst, b, h) do { _Pragma("unroll") for (int m = 0; m < 4; ++m) _Pragma("unroll") for (int k = 0; k < 2; ++k) dst[m][k] = *(const PG8_LAS bf16x8*)(lds + PG8_SA(b, h) + aoff + m * 2048 + k * 1024); } while (0)
; #define PG8_LDB(dst, b, h) do { _Pragma("unroll") for (int n = 0; n < 2; ++n) _Pragma("unroll") for (int k = 0; k < 2; ++k) dst[n][k] = *(const PG8_LAS bf16x8*)(lds + PG8_SB(b, h) + boff + n * 2048 + k * 1024); } while (0)
; #define PG8_MMA(ai, bj, At, Bt) do { __builtin_amdgcn_s_setprio(1); _Pragma("unroll") for (int m = 0; m < 4; ++m) _Pragma("unroll") for (int n = 0; n < 2; ++n) _Pragma("unroll") for (int k = 0; k < 2; ++k) \
;         acc[ai][bj][m][n] = __builtin_amdgcn_mfma_f32_16x16x32_bf16(Bt[n][k], At[m][k], acc[ai][bj][m][n], 0, 0, 0); __builtin_amdgcn_s_setprio(0); } while (0)
; #define PG8_WAIT_V(n) asm volatile("s_waitcnt vmcnt(" #n ")" ::: "memory")
; #define PG8_WAIT_L(n) asm volatile("s_waitcnt lgkmcnt(" #n ")" ::: "memory")
; #define PG8_BAR __builtin_amdgcn_s_barrier()
; #define PG8_SCHED __builtin_amdgcn_sched_barrier(0)
; template <class Epi, class Sched, bool ALIGN_EPI = false, bool SP2 = false>
; __device__ __forceinline__ void gemm_phase(PG8_LAS unsigned char* lds, const Gemm g, const Sched& S, const Epi& E) {
;     ...
;             PG8_LDB(B0, 0, 0); PG8_LDB(B1, 0, 1); PG8_SCHED; PG8_LDA(At, 0, 0); PG8_STAGE(PG8_SA(1, 1), a1 + hstep, voffA);
;             PG8_WAIT_V(8); PG8_WAIT_L(0); PG8_BAR; PG8_MMA(0, 0, At, B0); PG8_MMA(0, 1, At, B1); PG8_BAR; PG8_SCHED;
;             PG8_LDA(At, 0, 1); PG8_STAGE(PG8_SB(0, 0), b2, voffB); PG8_STAGE(PG8_SB(0, 1), b2 + hstep, voffB); PG8_STAGE(PG8_SA(0, 0), a2, voffA);
;             PG8_WAIT_V(8); PG8_WAIT_L(0); PG8_BAR; PG8_MMA(1, 0, At, B0); PG8_MMA(1, 1, At, B1); PG8_BAR; PG8_SCHED;
	ds_read_b128 v[154:157], v150
	ds_read_b128 v[158:161], v150 offset:1024
	ds_read_b128 v[162:165], v150 offset:2048
	ds_read_b128 v[166:169], v150 offset:3072
	ds_read_b128 v[170:173], v151
	ds_read_b128 v[174:177], v151 offset:1024
	ds_read_b128 v[178:181], v151 offset:2048
	ds_read_b128 v[182:185], v151 offset:3072
	s_add_u32 s36, s34, 0xfff80080
	s_addc_u32 s37, s35, -1
	s_cmp_eq_u32 s69, 28
	s_cselect_b32 s39, s25, s37
	s_cselect_b32 s38, s65, s36
	s_cselect_b32 s37, s23, s68
	s_cselect_b32 s36, s66, s67
	v_lshl_add_u64 v[146:147], s[34:35], 0, v[136:137]
	s_add_i32 m0, s31, 0xc000
	ds_read_b128 v[186:189], v152
	ds_read_b128 v[190:193], v152 offset:1024
	ds_read_b128 v[194:197], v152 offset:2048
	ds_read_b128 v[198:201], v152 offset:3072
	ds_read_b128 v[202:205], v152 offset:4096
	ds_read_b128 v[210:213], v152 offset:5120
	ds_read_b128 v[214:217], v152 offset:6144
	ds_read_b128 v[218:221], v152 offset:7168
	global_load_lds_dwordx4 v[146:147], off
	v_lshl_add_u64 v[146:147], s[34:35], 0, v[138:139]
	s_add_i32 m0, s31, 0xe000
	s_nop 0
	global_load_lds_dwordx4 v[146:147], off
	s_waitcnt vmcnt(8)
	s_waitcnt lgkmcnt(0)
	s_barrier
	s_setprio 1
	s_waitcnt lgkmcnt(0)
	v_mfma_f32_16x16x32_bf16 v[124:127], v[154:157], v[186:189], 0
	v_mfma_f32_16x16x32_bf16 v[120:123], v[162:165], v[186:189], 0
	v_mfma_f32_16x16x32_bf16 v[116:119], v[154:157], v[194:197], 0
	v_mfma_f32_16x16x32_bf16 v[112:115], v[162:165], v[194:197], 0
	v_mfma_f32_16x16x32_bf16 v[100:103], v[154:157], v[202:205], 0
	v_mfma_f32_16x16x32_bf16 v[96:99], v[162:165], v[202:205], 0
	v_mfma_f32_16x16x32_bf16 v[80:83], v[154:157], v[214:217], 0
	v_mfma_f32_16x16x32_bf16 v[76:79], v[162:165], v[214:217], 0
	v_mfma_f32_16x16x32_bf16 v[124:127], v[158:161], v[190:193], v[124:127]
	v_mfma_f32_16x16x32_bf16 v[120:123], v[166:169], v[190:193], v[120:123]
	v_mfma_f32_16x16x32_bf16 v[116:119], v[158:161], v[198:201], v[116:119]
	v_mfma_f32_16x16x32_bf16 v[112:115], v[166:169], v[198:201], v[112:115]
	v_mfma_f32_16x16x32_bf16 v[100:103], v[158:161], v[210:213], v[100:103]
	v_mfma_f32_16x16x32_bf16 v[96:99], v[166:169], v[210:213], v[96:99]
	v_mfma_f32_16x16x32_bf16 v[80:83], v[158:161], v[218:221], v[80:83]
	v_mfma_f32_16x16x32_bf16 v[76:79], v[166:169], v[218:221], v[76:79]
	v_mfma_f32_16x16x32_bf16 v[108:111], v[170:173], v[186:189], 0
	v_mfma_f32_16x16x32_bf16 v[104:107], v[178:181], v[186:189], 0
	v_mfma_f32_16x16x32_bf16 v[92:95], v[170:173], v[194:197], 0
	v_mfma_f32_16x16x32_bf16 v[88:91], v[178:181], v[194:197], 0
	v_mfma_f32_16x16x32_bf16 v[84:87], v[170:173], v[202:205], 0
	v_mfma_f32_16x16x32_bf16 v[72:75], v[178:181], v[202:205], 0
	v_mfma_f32_16x16x32_bf16 v[68:71], v[170:173], v[214:217], 0
	v_mfma_f32_16x16x32_bf16 v[64:67], v[178:181], v[214:217], 0
	v_mfma_f32_16x16x32_bf16 v[108:111], v[174:177], v[190:193], v[108:111]
	v_mfma_f32_16x16x32_bf16 v[104:107], v[182:185], v[190:193], v[104:107]
	v_mfma_f32_16x16x32_bf16 v[92:95], v[174:177], v[198:201], v[92:95]
	v_mfma_f32_16x16x32_bf16 v[88:91], v[182:185], v[198:201], v[88:91]
	v_mfma_f32_16x16x32_bf16 v[84:87], v[174:177], v[210:213], v[84:87]
	v_mfma_f32_16x16x32_bf16 v[72:75], v[182:185], v[210:213], v[72:75]
	v_mfma_f32_16x16x32_bf16 v[68:71], v[174:177], v[218:221], v[68:71]
	v_mfma_f32_16x16x32_bf16 v[64:67], v[182:185], v[218:221], v[64:67]
	s_setprio 0
	s_barrier
	s_add_i32 s70, s58, s44
	v_lshl_add_u64 v[146:147], s[36:37], 0, v[132:133]
	s_mov_b32 m0, s70
	ds_read_b128 v[186:189], v152 offset:16384
	ds_read_b128 v[190:193], v152 offset:17408
	ds_read_b128 v[194:197], v152 offset:18432
	ds_read_b128 v[198:201], v152 offset:19456
	ds_read_b128 v[202:205], v152 offset:20480
	ds_read_b128 v[210:213], v152 offset:21504
	ds_read_b128 v[214:217], v152 offset:22528
	ds_read_b128 v[218:221], v152 offset:23552
	global_load_lds_dwordx4 v[146:147], off
	s_add_i32 m0, s70, 0x2000
	s_add_u32 s70, s36, 0x80000
	v_lshl_add_u64 v[206:207], s[36:37], 0, v[128:129]
	s_addc_u32 s71, s37, 0
	s_add_i32 s72, s59, s44
	global_load_lds_dwordx4 v[206:207], off
	v_lshl_add_u64 v[222:223], s[70:71], 0, v[132:133]
	s_mov_b32 m0, s72
	v_lshl_add_u64 v[224:225], s[38:39], 0, v[130:131]
	global_load_lds_dwordx4 v[222:223], off
	v_lshl_add_u64 v[222:223], s[70:71], 0, v[128:129]
	s_add_i32 m0, s72, 0x2000
	s_nop 0
	global_load_lds_dwordx4 v[222:223], off
	v_lshl_add_u64 v[222:223], s[38:39], 0, v[134:135]
	s_mov_b32 m0, s31
	s_nop 0
	global_load_lds_dwordx4 v[222:223], off
	s_mov_b32 m0, s47
	s_nop 0
	global_load_lds_dwordx4 v[224:225], off
	s_waitcnt vmcnt(8)
	s_waitcnt lgkmcnt(0)
	s_barrier
	s_setprio 1
	s_waitcnt lgkmcnt(0)
	v_mfma_f32_16x16x32_bf16 v[60:63], v[154:157], v[186:189], 0
	v_mfma_f32_16x16x32_bf16 v[56:59], v[162:165], v[186:189], 0
	v_mfma_f32_16x16x32_bf16 v[52:55], v[154:157], v[194:197], 0
	v_mfma_f32_16x16x32_bf16 v[44:47], v[162:165], v[194:197], 0
	v_mfma_f32_16x16x32_bf16 v[36:39], v[154:157], v[202:205], 0
	v_mfma_f32_16x16x32_bf16 v[28:31], v[162:165], v[202:205], 0
	v_mfma_f32_16x16x32_bf16 v[20:23], v[154:157], v[214:217], 0
	v_mfma_f32_16x16x32_bf16 v[12:15], v[162:165], v[214:217], 0
	v_mfma_f32_16x16x32_bf16 v[60:63], v[158:161], v[190:193], v[60:63]
	v_mfma_f32_16x16x32_bf16 v[56:59], v[166:169], v[190:193], v[56:59]
	v_mfma_f32_16x16x32_bf16 v[52:55], v[158:161], v[198:201], v[52:55]
	v_mfma_f32_16x16x32_bf16 v[44:47], v[166:169], v[198:201], v[44:47]
	v_mfma_f32_16x16x32_bf16 v[36:39], v[158:161], v[210:213], v[36:39]
	v_mfma_f32_16x16x32_bf16 v[28:31], v[166:169], v[210:213], v[28:31]
	v_mfma_f32_16x16x32_bf16 v[20:23], v[158:161], v[218:221], v[20:23]
	v_mfma_f32_16x16x32_bf16 v[12:15], v[166:169], v[218:221], v[12:15]
	v_mfma_f32_16x16x32_bf16 v[48:51], v[170:173], v[186:189], 0
	v_mfma_f32_16x16x32_bf16 v[40:43], v[178:181], v[186:189], 0
	v_mfma_f32_16x16x32_bf16 v[32:35], v[170:173], v[194:197], 0
	v_mfma_f32_16x16x32_bf16 v[24:27], v[178:181], v[194:197], 0
	v_mfma_f32_16x16x32_bf16 v[16:19], v[170:173], v[202:205], 0
	v_mfma_f32_16x16x32_bf16 v[8:11], v[178:181], v[202:205], 0
	v_mfma_f32_16x16x32_bf16 v[4:7], v[170:173], v[214:217], 0
	v_mfma_f32_16x16x32_bf16 v[0:3], v[178:181], v[214:217], 0
	v_mfma_f32_16x16x32_bf16 v[48:51], v[174:177], v[190:193], v[48:51]
	v_mfma_f32_16x16x32_bf16 v[40:43], v[182:185], v[190:193], v[40:43]
	v_mfma_f32_16x16x32_bf16 v[32:35], v[174:177], v[198:201], v[32:35]
	v_mfma_f32_16x16x32_bf16 v[24:27], v[182:185], v[198:201], v[24:27]
	v_mfma_f32_16x16x32_bf16 v[16:19], v[174:177], v[210:213], v[16:19]
	v_mfma_f32_16x16x32_bf16 v[8:11], v[182:185], v[210:213], v[8:11]
	v_mfma_f32_16x16x32_bf16 v[4:7], v[174:177], v[218:221], v[4:7]
	v_mfma_f32_16x16x32_bf16 v[0:3], v[182:185], v[218:221], v[0:3]
	s_setprio 0
	s_barrier
; #define PG8_STAGE(bufoff, gbase, voff) do { _Pragma("unroll") for (int _i = 0; _i < 2; ++_i) \
;         __builtin_amdgcn_global_load_lds((const unsigned*)((const char*)(gbase) + (voff)[_i]), (PG8_LAS unsigned*)(lds + (bufoff) + ldsw + _i * 8192), 16, 0, 0); } while (0)
; #define PG8_LDA(dst, b, h) do { _Pragma("unroll") for (int m = 0; m < 4; ++m) _Pragma("unroll") for (int k = 0; k < 2; ++k) dst[m][k] = *(const PG8_LAS bf16x8*)(lds + PG8_SA(b, h) + aoff + m * 2048 + k * 1024); } while (0)
; #define PG8_LDB(dst, b, h) do { _Pragma("unroll") for (int n = 0; n < 2; ++n) _Pragma("unroll") for (int k = 0; k < 2; ++k) dst[n][k] = *(const PG8_LAS bf16x8*)(lds + PG8_SB(b, h) + boff + n * 2048 + k * 1024); } while (0)
; #define PG8_MMA(ai, bj, At, Bt) do { __builtin_amdgcn_s_setprio(1); _Pragma("unroll") for (int m = 0; m < 4; ++m) _Pragma("unroll") for (int n = 0; n < 2; ++n) _Pragma("unroll") for (int k = 0; k < 2; ++k) \
;         acc[ai][bj][m][n] = __builtin_amdgcn_mfma_f32_16x16x32_bf16(Bt[n][k], At[m][k], acc[ai][bj][m][n], 0, 0, 0); __builtin_amdgcn_s_setprio(0); } while (0)
; #define PG8_WAIT_V(n) asm volatile("s_waitcnt vmcnt(" #n ")" ::: "memory")
; #define PG8_WAIT_L(n) asm volatile("s_waitcnt lgkmcnt(" #n ")" ::: "memory")
; #define PG8_BAR __builtin_amdgcn_s_barrier()
; #define PG8_SCHED __builtin_amdgcn_sched_barrier(0)
; template <class Epi, class Sched, bool ALIGN_EPI = false, bool SP2 = false>
; __device__ __forceinline__ void gemm_phase(PG8_LAS unsigned char* lds, const Gemm g, const Sched& S, const Epi& E) {
;     ...
;             PG8_LDB(B0, 1, 0); PG8_LDB(B1, 1, 1); PG8_SCHED; PG8_LDA(At, 1, 0); PG8_STAGE(PG8_SA(0, 1), a2 + hstep, voffA);
;             PG8_WAIT_V(8); PG8_WAIT_L(0); PG8_BAR; PG8_MMA(0, 0, At, B0); PG8_MMA(0, 1, At, B1); PG8_BAR; PG8_SCHED;
;             PG8_LDA(At, 1, 1); PG8_STAGE(PG8_SB(1, 0), b3, voffB); PG8_STAGE(PG8_SB(1, 1), b3 + hstep, voffB); PG8_STAGE(PG8_SA(1, 0), a3, voffA);
	s_add_i32 s70, 0, 0x18000
	v_add_u32_e32 v144, s70, v148
	s_add_i32 s71, 0, 0x1c000
	ds_read_b128 v[154:157], v144
	ds_read_b128 v[158:161], v144 offset:1024
	ds_read_b128 v[162:165], v144 offset:2048
	ds_read_b128 v[166:169], v144 offset:3072
	v_add_u32_e32 v144, s71, v148
	ds_read_b128 v[170:173], v144
	ds_read_b128 v[174:177], v144 offset:1024
	ds_read_b128 v[178:181], v144 offset:2048
	ds_read_b128 v[182:185], v144 offset:3072
	s_add_u32 s38, s38, 0x80000
	s_addc_u32 s39, s39, 0
	s_mov_b32 m0, s48
	v_lshl_add_u64 v[226:227], s[38:39], 0, v[134:135]
	ds_read_b128 v[186:189], v152 offset:32768
	ds_read_b128 v[190:193], v152 offset:33792
	ds_read_b128 v[194:197], v152 offset:34816
	ds_read_b128 v[198:201], v152 offset:35840
	ds_read_b128 v[202:205], v152 offset:36864
	ds_read_b128 v[210:213], v152 offset:37888
	ds_read_b128 v[214:217], v152 offset:38912
	ds_read_b128 v[218:221], v152 offset:39936
	global_load_lds_dwordx4 v[226:227], off
	v_lshl_add_u64 v[226:227], s[38:39], 0, v[130:131]
	s_mov_b32 m0, s49
	s_nop 0
	global_load_lds_dwordx4 v[226:227], off
	s_waitcnt vmcnt(8)
	s_waitcnt lgkmcnt(0)
	s_barrier
	s_setprio 1
	s_waitcnt lgkmcnt(0)
	v_mfma_f32_16x16x32_bf16 v[124:127], v[154:157], v[186:189], v[124:127]
	v_mfma_f32_16x16x32_bf16 v[120:123], v[162:165], v[186:189], v[120:123]
	v_mfma_f32_16x16x32_bf16 v[116:119], v[154:157], v[194:197], v[116:119]
	v_mfma_f32_16x16x32_bf16 v[112:115], v[162:165], v[194:197], v[112:115]
	v_mfma_f32_16x16x32_bf16 v[100:103], v[154:157], v[202:205], v[100:103]
	v_mfma_f32_16x16x32_bf16 v[96:99], v[162:165], v[202:205], v[96:99]
	v_mfma_f32_16x16x32_bf16 v[80:83], v[154:157], v[214:217], v[80:83]
	v_mfma_f32_16x16x32_bf16 v[76:79], v[162:165], v[214:217], v[76:79]
	v_mfma_f32_16x16x32_bf16 v[124:127], v[158:161], v[190:193], v[124:127]
	v_mfma_f32_16x16x32_bf16 v[120:123], v[166:169], v[190:193], v[120:123]
	v_mfma_f32_16x16x32_bf16 v[116:119], v[158:161], v[198:201], v[116:119]
	v_mfma_f32_16x16x32_bf16 v[112:115], v[166:169], v[198:201], v[112:115]
	v_mfma_f32_16x16x32_bf16 v[100:103], v[158:161], v[210:213], v[100:103]
	v_mfma_f32_16x16x32_bf16 v[96:99], v[166:169], v[210:213], v[96:99]
	v_mfma_f32_16x16x32_bf16 v[80:83], v[158:161], v[218:221], v[80:83]
	v_mfma_f32_16x16x32_bf16 v[76:79], v[166:169], v[218:221], v[76:79]
	v_mfma_f32_16x16x32_bf16 v[108:111], v[170:173], v[186:189], v[108:111]
	v_mfma_f32_16x16x32_bf16 v[104:107], v[178:181], v[186:189], v[104:107]
	v_mfma_f32_16x16x32_bf16 v[92:95], v[170:173], v[194:197], v[92:95]
	v_mfma_f32_16x16x32_bf16 v[88:91], v[178:181], v[194:197], v[88:91]
	v_mfma_f32_16x16x32_bf16 v[84:87], v[170:173], v[202:205], v[84:87]
	v_mfma_f32_16x16x32_bf16 v[72:75], v[178:181], v[202:205], v[72:75]
	v_mfma_f32_16x16x32_bf16 v[68:71], v[170:173], v[214:217], v[68:71]
	v_mfma_f32_16x16x32_bf16 v[64:67], v[178:181], v[214:217], v[64:67]
	v_mfma_f32_16x16x32_bf16 v[108:111], v[174:177], v[190:193], v[108:111]
	v_mfma_f32_16x16x32_bf16 v[104:107], v[182:185], v[190:193], v[104:107]
	v_mfma_f32_16x16x32_bf16 v[92:95], v[174:177], v[198:201], v[92:95]
	v_mfma_f32_16x16x32_bf16 v[88:91], v[182:185], v[198:201], v[88:91]
	v_mfma_f32_16x16x32_bf16 v[84:87], v[174:177], v[210:213], v[84:87]
	v_mfma_f32_16x16x32_bf16 v[72:75], v[182:185], v[210:213], v[72:75]
	v_mfma_f32_16x16x32_bf16 v[68:71], v[174:177], v[218:221], v[68:71]
	v_mfma_f32_16x16x32_bf16 v[64:67], v[182:185], v[218:221], v[64:67]
	s_setprio 0
	s_barrier
	s_add_i32 s38, s70, s44
	v_lshl_add_u64 v[146:147], v[146:147], 0, s[10:11]
	s_mov_b32 m0, s38
	ds_read_b128 v[186:189], v152 offset:49152
	ds_read_b128 v[190:193], v152 offset:50176
	ds_read_b128 v[194:197], v152 offset:51200
	ds_read_b128 v[198:201], v152 offset:52224
	ds_read_b128 v[202:205], v152 offset:53248
	ds_read_b128 v[210:213], v152 offset:54272
	ds_read_b128 v[214:217], v152 offset:55296
	ds_read_b128 v[218:221], v152 offset:56320
	global_load_lds_dwordx4 v[146:147], off
	s_add_i32 m0, s38, 0x2000
	s_add_u32 s36, s36, 0x80080
	v_lshl_add_u64 v[146:147], v[206:207], 0, s[10:11]
	s_addc_u32 s37, s37, 0
	s_add_i32 s38, s71, s44
	global_load_lds_dwordx4 v[146:147], off
	v_lshl_add_u64 v[146:147], s[36:37], 0, v[132:133]
	s_mov_b32 m0, s38
	s_nop 0
	global_load_lds_dwordx4 v[146:147], off
	v_lshl_add_u64 v[146:147], s[36:37], 0, v[128:129]
	s_add_i32 m0, s38, 0x2000
	s_nop 0
	global_load_lds_dwordx4 v[146:147], off
	v_lshl_add_u64 v[146:147], v[222:223], 0, s[10:11]
	s_mov_b32 m0, s55
	s_nop 0
	global_load_lds_dwordx4 v[146:147], off
	v_lshl_add_u64 v[146:147], v[224:225], 0, s[10:11]
	s_mov_b32 m0, s56
	s_nop 0
	global_load_lds_dwordx4 v[146:147], off
	s_waitcnt vmcnt(8)
	s_waitcnt lgkmcnt(0)
	s_barrier
; #define PG8_STAGE(bufoff, gbase, voff) do { _Pragma("unroll") for (int _i = 0; _i < 2; ++_i) \
;         __builtin_amdgcn_global_load_lds((const unsigned*)((const char*)(gbase) + (voff)[_i]), (PG8_LAS unsigned*)(lds + (bufoff) + ldsw + _i * 8192), 16, 0, 0); } while (0)
; #define PG8_LDA(dst, b, h) do { _Pragma("unroll") for (int m = 0; m < 4; ++m) _Pragma("unroll") for (int k = 0; k < 2; ++k) dst[m][k] = *(const PG8_LAS bf16x8*)(lds + PG8_SA(b, h) + aoff + m * 2048 + k * 1024); } while (0)
; #define PG8_LDB(dst, b, h) do { _Pragma("unroll") for (int n = 0; n < 2; ++n) _Pragma("unroll") for (int k = 0; k < 2; ++k) dst[n][k] = *(const PG8_LAS bf16x8*)(lds + PG8_SB(b, h) + boff + n * 2048 + k * 1024); } while (0)
; #define PG8_MMA(ai, bj, At, Bt) do { __builtin_amdgcn_s_setprio(1); _Pragma("unroll") for (int m = 0; m < 4; ++m) _Pragma("unroll") for (int n = 0; n < 2; ++n) _Pragma("unroll") for (int k = 0; k < 2; ++k) \
;         acc[ai][bj][m][n] = __builtin_amdgcn_mfma_f32_16x16x32_bf16(Bt[n][k], At[m][k], acc[ai][bj][m][n], 0, 0, 0); __builtin_amdgcn_s_setprio(0); } while (0)
; #define PG8_WAIT_V(n) asm volatile("s_waitcnt vmcnt(" #n ")" ::: "memory")
; template <class Epi, class Sched, bool ALIGN_EPI = false, bool SP2 = false>
; __device__ __forceinline__ void gemm_phase(PG8_LAS unsigned char* lds, const Gemm g, const Sched& S, const Epi& E) {
;     ...
;             PG8_LDB(B0, 0, 0); PG8_LDB(B1, 0, 1); PG8_SCHED; PG8_LDA(At, 0, 0); PG8_STAGE(PG8_SA(1, 1), a1 + hstep, voffA);
;             PG8_WAIT_V(8); PG8_WAIT_L(0); PG8_BAR; PG8_MMA(0, 0, At, B0); PG8_MMA(0, 1, At, B1); PG8_BAR; PG8_SCHED;
;             PG8_LDA(At, 0, 1); PG8_STAGE(PG8_SB(0, 0), b2, voffB); PG8_STAGE(PG8_SB(0, 1), b2 + hstep, voffB); PG8_STAGE(PG8_SA(0, 0), a2, voffA);
;             PG8_WAIT_V(8); PG8_WAIT_L(0); PG8_BAR; PG8_MMA(1, 0, At, B0); PG8_MMA(1, 1, At, B1); PG8_BAR; PG8_SCHED;
;             PG8_LDB(B0, 1, 0); PG8_LDB(B1, 1, 1); PG8_SCHED; PG8_LDA(At, 1, 0); PG8_STAGE(PG8_SA(0, 1), a2 + hstep, voffA);
;             PG8_WAIT_V(8); PG8_WAIT_L(0); PG8_BAR; PG8_MMA(0, 0, At, B0); PG8_MMA(0, 1, At, B1); PG8_BAR; PG8_SCHED;
;             PG8_LDA(At, 1, 1); PG8_STAGE(PG8_SB(1, 0), b3, voffB); PG8_STAGE(PG8_SB(1, 1), b3 + hstep, voffB); PG8_STAGE(PG8_SA(1, 0), a3, voffA);
;             PG8_WAIT_V(8); PG8_WAIT_L(0); PG8_BAR; PG8_MMA(1, 0, At, B0); PG8_MMA(1, 1, At, B1); PG8_BAR; PG8_SCHED;
	s_setprio 1
	s_waitcnt lgkmcnt(0)
	v_mfma_f32_16x16x32_bf16 v[60:63], v[154:157], v[186:189], v[60:63]
	v_mfma_f32_16x16x32_bf16 v[56:59], v[162:165], v[186:189], v[56:59]
	v_mfma_f32_16x16x32_bf16 v[52:55], v[154:157], v[194:197], v[52:55]
	v_mfma_f32_16x16x32_bf16 v[44:47], v[162:165], v[194:197], v[44:47]
	v_mfma_f32_16x16x32_bf16 v[36:39], v[154:157], v[202:205], v[36:39]
	v_mfma_f32_16x16x32_bf16 v[28:31], v[162:165], v[202:205], v[28:31]
	v_mfma_f32_16x16x32_bf16 v[20:23], v[154:157], v[214:217], v[20:23]
	v_mfma_f32_16x16x32_bf16 v[12:15], v[162:165], v[214:217], v[12:15]
	v_mfma_f32_16x16x32_bf16 v[60:63], v[158:161], v[190:193], v[60:63]
	v_mfma_f32_16x16x32_bf16 v[56:59], v[166:169], v[190:193], v[56:59]
	v_mfma_f32_16x16x32_bf16 v[52:55], v[158:161], v[198:201], v[52:55]
	v_mfma_f32_16x16x32_bf16 v[44:47], v[166:169], v[198:201], v[44:47]
	v_mfma_f32_16x16x32_bf16 v[36:39], v[158:161], v[210:213], v[36:39]
	v_mfma_f32_16x16x32_bf16 v[28:31], v[166:169], v[210:213], v[28:31]
	v_mfma_f32_16x16x32_bf16 v[20:23], v[158:161], v[218:221], v[20:23]
	v_mfma_f32_16x16x32_bf16 v[12:15], v[166:169], v[218:221], v[12:15]
	v_mfma_f32_16x16x32_bf16 v[48:51], v[170:173], v[186:189], v[48:51]
	v_mfma_f32_16x16x32_bf16 v[40:43], v[178:181], v[186:189], v[40:43]
	v_mfma_f32_16x16x32_bf16 v[32:35], v[170:173], v[194:197], v[32:35]
	v_mfma_f32_16x16x32_bf16 v[24:27], v[178:181], v[194:197], v[24:27]
	v_mfma_f32_16x16x32_bf16 v[16:19], v[170:173], v[202:205], v[16:19]
	v_mfma_f32_16x16x32_bf16 v[8:11], v[178:181], v[202:205], v[8:11]
	v_mfma_f32_16x16x32_bf16 v[4:7], v[170:173], v[214:217], v[4:7]
	v_mfma_f32_16x16x32_bf16 v[0:3], v[178:181], v[214:217], v[0:3]
	v_mfma_f32_16x16x32_bf16 v[48:51], v[174:177], v[190:193], v[48:51]
	v_mfma_f32_16x16x32_bf16 v[40:43], v[182:185], v[190:193], v[40:43]
	v_mfma_f32_16x16x32_bf16 v[32:35], v[174:177], v[198:201], v[32:35]
	v_mfma_f32_16x16x32_bf16 v[24:27], v[182:185], v[198:201], v[24:27]
	v_mfma_f32_16x16x32_bf16 v[16:19], v[174:177], v[210:213], v[16:19]
	v_mfma_f32_16x16x32_bf16 v[8:11], v[182:185], v[210:213], v[8:11]
	v_mfma_f32_16x16x32_bf16 v[4:7], v[174:177], v[218:221], v[4:7]
	v_mfma_f32_16x16x32_bf16 v[0:3], v[182:185], v[218:221], v[0:3]
	s_setprio 0
	s_barrier
	s_add_i32 s69, s69, 2
	s_add_u32 s34, s34, 0x100
	s_addc_u32 s35, s35, 0
	s_add_u32 s67, s67, 0x100
	s_addc_u32 s68, s68, 0
	s_cmp_gt_u32 s69, 29
.LBB0_16:
	ds_read_b128 v[154:157], v150
	ds_read_b128 v[158:161], v150 offset:1024
	ds_read_b128 v[162:165], v150 offset:2048
	ds_read_b128 v[166:169], v150 offset:3072
	ds_read_b128 v[170:173], v151
	ds_read_b128 v[174:177], v151 offset:1024
	ds_read_b128 v[178:181], v151 offset:2048
	ds_read_b128 v[182:185], v151 offset:3072
	s_add_u32 s36, s34, 0xfff80080
	s_addc_u32 s37, s35, -1
	s_cmp_eq_u32 s69, 28
	s_cselect_b32 s39, s25, s37
	s_cselect_b32 s38, s65, s36
	s_cselect_b32 s37, s23, s68
	s_cselect_b32 s36, s66, s67
	v_lshl_add_u64 v[146:147], s[34:35], 0, v[136:137]
	s_add_i32 m0, s31, 0xc000
	ds_read_b128 v[186:189], v152
	ds_read_b128 v[190:193], v152 offset:1024
	ds_read_b128 v[194:197], v152 offset:2048
	ds_read_b128 v[198:201], v152 offset:3072
	ds_read_b128 v[202:205], v152 offset:4096
	ds_read_b128 v[210:213], v152 offset:5120
	ds_read_b128 v[214:217], v152 offset:6144
	ds_read_b128 v[218:221], v152 offset:7168
	global_load_lds_dwordx4 v[146:147], off
	v_lshl_add_u64 v[146:147], s[34:35], 0, v[138:139]
	s_add_i32 m0, s31, 0xe000
	s_nop 0
	global_load_lds_dwordx4 v[146:147], off
	s_waitcnt vmcnt(8)
	s_waitcnt lgkmcnt(0)
	s_barrier
	s_setprio 1
	s_waitcnt lgkmcnt(0)
	v_mfma_f32_16x16x32_bf16 v[124:127], v[154:157], v[186:189], v[124:127]
	v_mfma_f32_16x16x32_bf16 v[120:123], v[162:165], v[186:189], v[120:123]
	v_mfma_f32_16x16x32_bf16 v[116:119], v[154:157], v[194:197], v[116:119]
	v_mfma_f32_16x16x32_bf16 v[112:115], v[162:165], v[194:197], v[112:115]
	v_mfma_f32_16x16x32_bf16 v[100:103], v[154:157], v[202:205], v[100:103]
	v_mfma_f32_16x16x32_bf16 v[96:99], v[162:165], v[202:205], v[96:99]
	v_mfma_f32_16x16x32_bf16 v[80:83], v[154:157], v[214:217], v[80:83]
	v_mfma_f32_16x16x32_bf16 v[76:79], v[162:165], v[214:217], v[76:79]
	v_mfma_f32_16x16x32_bf16 v[124:127], v[158:161], v[190:193], v[124:127]
	v_mfma_f32_16x16x32_bf16 v[120:123], v[166:169], v[190:193], v[120:123]
	v_mfma_f32_16x16x32_bf16 v[116:119], v[158:161], v[198:201], v[116:119]
	v_mfma_f32_16x16x32_bf16 v[112:115], v[166:169], v[198:201], v[112:115]
	v_mfma_f32_16x16x32_bf16 v[100:103], v[158:161], v[210:213], v[100:103]
	v_mfma_f32_16x16x32_bf16 v[96:99], v[166:169], v[210:213], v[96:99]
	v_mfma_f32_16x16x32_bf16 v[80:83], v[158:161], v[218:221], v[80:83]
	v_mfma_f32_16x16x32_bf16 v[76:79], v[166:169], v[218:221], v[76:79]
	v_mfma_f32_16x16x32_bf16 v[108:111], v[170:173], v[186:189], v[108:111]
	v_mfma_f32_16x16x32_bf16 v[104:107], v[178:181], v[186:189], v[104:107]
	v_mfma_f32_16x16x32_bf16 v[92:95], v[170:173], v[194:197], v[92:95]
	v_mfma_f32_16x16x32_bf16 v[88:91], v[178:181], v[194:197], v[88:91]
	v_mfma_f32_16x16x32_bf16 v[84:87], v[170:173], v[202:205], v[84:87]
	v_mfma_f32_16x16x32_bf16 v[72:75], v[178:181], v[202:205], v[72:75]
	v_mfma_f32_16x16x32_bf16 v[68:71], v[170:173], v[214:217], v[68:71]
	v_mfma_f32_16x16x32_bf16 v[64:67], v[178:181], v[214:217], v[64:67]
	v_mfma_f32_16x16x32_bf16 v[108:111], v[174:177], v[190:193], v[108:111]
	v_mfma_f32_16x16x32_bf16 v[104:107], v[182:185], v[190:193], v[104:107]
	v_mfma_f32_16x16x32_bf16 v[92:95], v[174:177], v[198:201], v[92:95]
	v_mfma_f32_16x16x32_bf16 v[88:91], v[182:185], v[198:201], v[88:91]
	v_mfma_f32_16x16x32_bf16 v[84:87], v[174:177], v[210:213], v[84:87]
	v_mfma_f32_16x16x32_bf16 v[72:75], v[182:185], v[210:213], v[72:75]
	v_mfma_f32_16x16x32_bf16 v[68:71], v[174:177], v[218:221], v[68:71]
	v_mfma_f32_16x16x32_bf16 v[64:67], v[182:185], v[218:221], v[64:67]
	s_setprio 0
	s_barrier
; #define PG8_STAGE(bufoff, gbase, voff) do { _Pragma("unroll") for (int _i = 0; _i < 2; ++_i) \
;         __builtin_amdgcn_global_load_lds((const unsigned*)((const char*)(gbase) + (voff)[_i]), (PG8_LAS unsigned*)(lds + (bufoff) + ldsw + _i * 8192), 16, 0, 0); } while (0)
; #define PG8_LDA(dst, b, h) do { _Pragma("unroll") for (int m = 0; m < 4; ++m) _Pragma("unroll") for (int k = 0; k < 2; ++k) dst[m][k] = *(const PG8_LAS bf16x8*)(lds + PG8_SA(b, h) + aoff + m * 2048 + k * 1024); } while (0)
; #define PG8_LDB(dst, b, h) do { _Pragma("unroll") for (int n = 0; n < 2; ++n) _Pragma("unroll") for (int k = 0; k < 2; ++k) dst[n][k] = *(const PG8_LAS bf16x8*)(lds + PG8_SB(b, h) + boff + n * 2048 + k * 1024); } while (0)
; #define PG8_MMA(ai, bj, At, Bt) do { __builtin_amdgcn_s_setprio(1); _Pragma("unroll") for (int m = 0; m < 4; ++m) _Pragma("unroll") for (int n = 0; n < 2; ++n) _Pragma("unroll") for (int k = 0; k < 2; ++k) \
;         acc[ai][bj][m][n] = __builtin_amdgcn_mfma_f32_16x16x32_bf16(Bt[n][k], At[m][k], acc[ai][bj][m][n], 0, 0, 0); __builtin_amdgcn_s_setprio(0); } while (0)
; #define PG8_WAIT_V(n) asm volatile("s_waitcnt vmcnt(" #n ")" ::: "memory")
; #define PG8_WAIT_L(n) asm volatile("s_waitcnt lgkmcnt(" #n ")" ::: "memory")
; #define PG8_BAR __builtin_amdgcn_s_barrier()
; #define PG8_SCHED __builtin_amdgcn_sched_barrier(0)
; template <class Epi, class Sched, bool ALIGN_EPI = false, bool SP2 = false>
; __device__ __forceinline__ void gemm_phase(PG8_LAS unsigned char* lds, const Gemm g, const Sched& S, const Epi& E) {
;     ...
;             PG8_LDA(At, 0, 1); PG8_STAGE(PG8_SB(0, 0), b2, voffB); PG8_STAGE(PG8_SB(0, 1), b2 + hstep, voffB); PG8_STAGE(PG8_SA(0, 0), a2, voffA);
;             PG8_WAIT_V(8); PG8_WAIT_L(0); PG8_BAR; PG8_MMA(1, 0, At, B0); PG8_MMA(1, 1, At, B1); PG8_BAR; PG8_SCHED;
;             PG8_LDB(B0, 1, 0); PG8_LDB(B1, 1, 1); PG8_SCHED; PG8_LDA(At, 1, 0); PG8_STAGE(PG8_SA(0, 1), a2 + hstep, voffA);
;             PG8_WAIT_V(8); PG8_WAIT_L(0); PG8_BAR; PG8_MMA(0, 0, At, B0); PG8_MMA(0, 1, At, B1); PG8_BAR; PG8_SCHED;
	s_add_i32 s70, s58, s44
	v_lshl_add_u64 v[146:147], s[36:37], 0, v[132:133]
	s_mov_b32 m0, s70
	ds_read_b128 v[186:189], v152 offset:16384
	ds_read_b128 v[190:193], v152 offset:17408
	ds_read_b128 v[194:197], v152 offset:18432
	ds_read_b128 v[198:201], v152 offset:19456
	ds_read_b128 v[202:205], v152 offset:20480
	ds_read_b128 v[210:213], v152 offset:21504
	ds_read_b128 v[214:217], v152 offset:22528
	ds_read_b128 v[218:221], v152 offset:23552
	global_load_lds_dwordx4 v[146:147], off
	s_add_i32 m0, s70, 0x2000
	s_add_u32 s70, s36, 0x80000
	v_lshl_add_u64 v[206:207], s[36:37], 0, v[128:129]
	s_addc_u32 s71, s37, 0
	s_add_i32 s72, s59, s44
	global_load_lds_dwordx4 v[206:207], off
	v_lshl_add_u64 v[222:223], s[70:71], 0, v[132:133]
	s_mov_b32 m0, s72
	v_lshl_add_u64 v[224:225], s[38:39], 0, v[130:131]
	global_load_lds_dwordx4 v[222:223], off
	v_lshl_add_u64 v[222:223], s[70:71], 0, v[128:129]
	s_add_i32 m0, s72, 0x2000
	s_nop 0
	global_load_lds_dwordx4 v[222:223], off
	v_lshl_add_u64 v[222:223], s[38:39], 0, v[134:135]
	s_mov_b32 m0, s31
	s_nop 0
	global_load_lds_dwordx4 v[222:223], off
	s_mov_b32 m0, s47
	s_nop 0
	global_load_lds_dwordx4 v[224:225], off
	s_waitcnt vmcnt(8)
	s_waitcnt lgkmcnt(0)
	s_barrier
	s_setprio 1
	s_waitcnt lgkmcnt(0)
	v_mfma_f32_16x16x32_bf16 v[60:63], v[154:157], v[186:189], v[60:63]
	v_mfma_f32_16x16x32_bf16 v[56:59], v[162:165], v[186:189], v[56:59]
	v_mfma_f32_16x16x32_bf16 v[52:55], v[154:157], v[194:197], v[52:55]
	v_mfma_f32_16x16x32_bf16 v[44:47], v[162:165], v[194:197], v[44:47]
	v_mfma_f32_16x16x32_bf16 v[36:39], v[154:157], v[202:205], v[36:39]
	v_mfma_f32_16x16x32_bf16 v[28:31], v[162:165], v[202:205], v[28:31]
	v_mfma_f32_16x16x32_bf16 v[20:23], v[154:157], v[214:217], v[20:23]
	v_mfma_f32_16x16x32_bf16 v[12:15], v[162:165], v[214:217], v[12:15]
	v_mfma_f32_16x16x32_bf16 v[60:63], v[158:161], v[190:193], v[60:63]
	v_mfma_f32_16x16x32_bf16 v[56:59], v[166:169], v[190:193], v[56:59]
	v_mfma_f32_16x16x32_bf16 v[52:55], v[158:161], v[198:201], v[52:55]
	v_mfma_f32_16x16x32_bf16 v[44:47], v[166:169], v[198:201], v[44:47]
	v_mfma_f32_16x16x32_bf16 v[36:39], v[158:161], v[210:213], v[36:39]
	v_mfma_f32_16x16x32_bf16 v[28:31], v[166:169], v[210:213], v[28:31]
	v_mfma_f32_16x16x32_bf16 v[20:23], v[158:161], v[218:221], v[20:23]
	v_mfma_f32_16x16x32_bf16 v[12:15], v[166:169], v[218:221], v[12:15]
	v_mfma_f32_16x16x32_bf16 v[48:51], v[170:173], v[186:189], v[48:51]
	v_mfma_f32_16x16x32_bf16 v[40:43], v[178:181], v[186:189], v[40:43]
	v_mfma_f32_16x16x32_bf16 v[32:35], v[170:173], v[194:197], v[32:35]
	v_mfma_f32_16x16x32_bf16 v[24:27], v[178:181], v[194:197], v[24:27]
	v_mfma_f32_16x16x32_bf16 v[16:19], v[170:173], v[202:205], v[16:19]
	v_mfma_f32_16x16x32_bf16 v[8:11], v[178:181], v[202:205], v[8:11]
	v_mfma_f32_16x16x32_bf16 v[4:7], v[170:173], v[214:217], v[4:7]
	v_mfma_f32_16x16x32_bf16 v[0:3], v[178:181], v[214:217], v[0:3]
	v_mfma_f32_16x16x32_bf16 v[48:51], v[174:177], v[190:193], v[48:51]
	v_mfma_f32_16x16x32_bf16 v[40:43], v[182:185], v[190:193], v[40:43]
	v_mfma_f32_16x16x32_bf16 v[32:35], v[174:177], v[198:201], v[32:35]
	v_mfma_f32_16x16x32_bf16 v[24:27], v[182:185], v[198:201], v[24:27]
	v_mfma_f32_16x16x32_bf16 v[16:19], v[174:177], v[210:213], v[16:19]
	v_mfma_f32_16x16x32_bf16 v[8:11], v[182:185], v[210:213], v[8:11]
	v_mfma_f32_16x16x32_bf16 v[4:7], v[174:177], v[218:221], v[4:7]
	v_mfma_f32_16x16x32_bf16 v[0:3], v[182:185], v[218:221], v[0:3]
	s_setprio 0
	s_barrier
	s_add_i32 s70, 0, 0x18000
	v_add_u32_e32 v144, s70, v148
	s_add_i32 s71, 0, 0x1c000
	ds_read_b128 v[154:157], v144
	ds_read_b128 v[158:161], v144 offset:1024
	ds_read_b128 v[162:165], v144 offset:2048
	ds_read_b128 v[166:169], v144 offset:3072
	v_add_u32_e32 v144, s71, v148
	ds_read_b128 v[170:173], v144
	ds_read_b128 v[174:177], v144 offset:1024
	ds_read_b128 v[178:181], v144 offset:2048
	ds_read_b128 v[182:185], v144 offset:3072
	s_add_u32 s38, s38, 0x80000
	s_addc_u32 s39, s39, 0
	s_mov_b32 m0, s48
	v_lshl_add_u64 v[226:227], s[38:39], 0, v[134:135]
	ds_read_b128 v[186:189], v152 offset:32768
	ds_read_b128 v[190:193], v152 offset:33792
	ds_read_b128 v[194:197], v152 offset:34816
	ds_read_b128 v[198:201], v152 offset:35840
	ds_read_b128 v[202:205], v152 offset:36864
	ds_read_b128 v[210:213], v152 offset:37888
	ds_read_b128 v[214:217], v152 offset:38912
	ds_read_b128 v[218:221], v152 offset:39936
	global_load_lds_dwordx4 v[226:227], off
	v_lshl_add_u64 v[226:227], s[38:39], 0, v[130:131]
	s_mov_b32 m0, s49
	s_nop 0
	global_load_lds_dwordx4 v[226:227], off
	s_waitcnt vmcnt(8)
	s_waitcnt lgkmcnt(0)
	s_barrier
; #define PG8_STAGE(bufoff, gbase, voff) do { _Pragma("unroll") for (int _i = 0; _i < 2; ++_i) \
;         __builtin_amdgcn_global_load_lds((const unsigned*)((const char*)(gbase) + (voff)[_i]), (PG8_LAS unsigned*)(lds + (bufoff) + ldsw + _i * 8192), 16, 0, 0); } while (0)
; #define PG8_BAR __builtin_amdgcn_s_barrier()
; template <class Epi, class Sched, bool ALIGN_EPI = false, bool SP2 = false>
; __device__ __forceinline__ void gemm_phase(PG8_LAS unsigned char* lds, const Gemm g, const Sched& S, const Epi& E) {
;     ...
;             PG8_LDB(B0, 1, 0); PG8_LDB(B1, 1, 1); PG8_SCHED; PG8_LDA(At, 1, 0); PG8_STAGE(PG8_SA(0, 1), a2 + hstep, voffA);
;             PG8_WAIT_V(8); PG8_WAIT_L(0); PG8_BAR; PG8_MMA(0, 0, At, B0); PG8_MMA(0, 1, At, B1); PG8_BAR; PG8_SCHED;
;             PG8_LDA(At, 1, 1); PG8_STAGE(PG8_SB(1, 0), b3, voffB); PG8_STAGE(PG8_SB(1, 1), b3 + hstep, voffB); PG8_STAGE(PG8_SA(1, 0), a3, voffA);
;             PG8_WAIT_V(8); PG8_WAIT_L(0); PG8_BAR; PG8_MMA(1, 0, At, B0); PG8_MMA(1, 1, At, B1); PG8_BAR; PG8_SCHED;
;             } else {
;             PG8_LDB(B0, 0, 0); PG8_SCHED; PG8_LDA(At, 0, 0); PG8_STAGE(PG8_SA(1, 1), a1 + hstep, voffA);
;             PG8_WAIT_L(8); PG8_BAR; PG8_WAIT_L(0); PG8_MMA(0, 0, At, B0); PG8_BAR; PG8_SCHED;
;             PG8_LDB(B1, 0, 1); PG8_STAGE(PG8_SB(0, 0), b2, voffB);
;             PG8_BAR; PG8_WAIT_L(0); PG8_MMA(0, 1, At, B1); PG8_BAR;
;             PG8_LDA(At, 0, 1); PG8_STAGE(PG8_SA(0, 0), a2, voffA);
;             PG8_BAR; PG8_WAIT_L(0); PG8_MMA(1, 0, At, B0); PG8_BAR; PG8_SCHED;
;             PG8_STAGE(PG8_SB(0, 1), b2 + hstep, voffB);
;             PG8_WAIT_V(6); PG8_BAR; PG8_MMA(1, 1, At, B1); PG8_BAR;
;             PG8_LDB(B0, 1, 0); PG8_SCHED; PG8_LDA(At, 1, 0); PG8_STAGE(PG8_SA(0, 1), a2 + hstep, voffA);
;             PG8_WAIT_L(8); PG8_BAR; PG8_WAIT_L(0); PG8_MMA(0, 0, At, B0); PG8_BAR; PG8_SCHED;
;             PG8_LDB(B1, 1, 1); PG8_STAGE(PG8_SB(1, 0), b3, voffB);
;             PG8_BAR; PG8_WAIT_L(0); PG8_MMA(0, 1, At, B1); PG8_BAR;
;             PG8_LDA(At, 1, 1); PG8_STAGE(PG8_SA(1, 0), a3, voffA);
;             PG8_BAR; PG8_WAIT_L(0); PG8_MMA(1, 0, At, B0); PG8_BAR; PG8_SCHED;
;             PG8_STAGE(PG8_SB(1, 1), b3 + hstep, voffB);
;             PG8_WAIT_V(6); PG8_BAR; PG8_MMA(1, 1, At, B1); PG8_BAR;
;             }
;         }
;         if constexpr (ALIGN_EPI) { if (wr == 0) PG8_BAR; }
	s_setprio 1
	s_waitcnt lgkmcnt(0)
	v_mfma_f32_16x16x32_bf16 v[124:127], v[154:157], v[186:189], v[124:127]
	v_mfma_f32_16x16x32_bf16 v[120:123], v[162:165], v[186:189], v[120:123]
	v_mfma_f32_16x16x32_bf16 v[116:119], v[154:157], v[194:197], v[116:119]
	v_mfma_f32_16x16x32_bf16 v[112:115], v[162:165], v[194:197], v[112:115]
	v_mfma_f32_16x16x32_bf16 v[100:103], v[154:157], v[202:205], v[100:103]
	v_mfma_f32_16x16x32_bf16 v[96:99], v[162:165], v[202:205], v[96:99]
	v_mfma_f32_16x16x32_bf16 v[80:83], v[154:157], v[214:217], v[80:83]
	v_mfma_f32_16x16x32_bf16 v[76:79], v[162:165], v[214:217], v[76:79]
	v_mfma_f32_16x16x32_bf16 v[124:127], v[158:161], v[190:193], v[124:127]
	v_mfma_f32_16x16x32_bf16 v[120:123], v[166:169], v[190:193], v[120:123]
	v_mfma_f32_16x16x32_bf16 v[116:119], v[158:161], v[198:201], v[116:119]
	v_mfma_f32_16x16x32_bf16 v[112:115], v[166:169], v[198:201], v[112:115]
	v_mfma_f32_16x16x32_bf16 v[100:103], v[158:161], v[210:213], v[100:103]
	v_mfma_f32_16x16x32_bf16 v[96:99], v[166:169], v[210:213], v[96:99]
	v_mfma_f32_16x16x32_bf16 v[80:83], v[158:161], v[218:221], v[80:83]
	v_mfma_f32_16x16x32_bf16 v[76:79], v[166:169], v[218:221], v[76:79]
	v_mfma_f32_16x16x32_bf16 v[108:111], v[170:173], v[186:189], v[108:111]
	v_mfma_f32_16x16x32_bf16 v[104:107], v[178:181], v[186:189], v[104:107]
	v_mfma_f32_16x16x32_bf16 v[92:95], v[170:173], v[194:197], v[92:95]
	v_mfma_f32_16x16x32_bf16 v[88:91], v[178:181], v[194:197], v[88:91]
	v_mfma_f32_16x16x32_bf16 v[84:87], v[170:173], v[202:205], v[84:87]
	v_mfma_f32_16x16x32_bf16 v[72:75], v[178:181], v[202:205], v[72:75]
	v_mfma_f32_16x16x32_bf16 v[68:71], v[170:173], v[214:217], v[68:71]
	v_mfma_f32_16x16x32_bf16 v[64:67], v[178:181], v[214:217], v[64:67]
	v_mfma_f32_16x16x32_bf16 v[108:111], v[174:177], v[190:193], v[108:111]
	v_mfma_f32_16x16x32_bf16 v[104:107], v[182:185], v[190:193], v[104:107]
	v_mfma_f32_16x16x32_bf16 v[92:95], v[174:177], v[198:201], v[92:95]
	v_mfma_f32_16x16x32_bf16 v[88:91], v[182:185], v[198:201], v[88:91]
	v_mfma_f32_16x16x32_bf16 v[84:87], v[174:177], v[210:213], v[84:87]
	v_mfma_f32_16x16x32_bf16 v[72:75], v[182:185], v[210:213], v[72:75]
	v_mfma_f32_16x16x32_bf16 v[68:71], v[174:177], v[218:221], v[68:71]
	v_mfma_f32_16x16x32_bf16 v[64:67], v[182:185], v[218:221], v[64:67]
	s_setprio 0
	s_barrier
	s_add_i32 s38, s70, s44
	v_lshl_add_u64 v[146:147], v[146:147], 0, s[10:11]
	s_mov_b32 m0, s38
	ds_read_b128 v[186:189], v152 offset:49152
	ds_read_b128 v[190:193], v152 offset:50176
	ds_read_b128 v[194:197], v152 offset:51200
	ds_read_b128 v[198:201], v152 offset:52224
	ds_read_b128 v[202:205], v152 offset:53248
	ds_read_b128 v[210:213], v152 offset:54272
	ds_read_b128 v[214:217], v152 offset:55296
	ds_read_b128 v[218:221], v152 offset:56320
	global_load_lds_dwordx4 v[146:147], off
	s_add_i32 m0, s38, 0x2000
	s_add_u32 s36, s36, 0x80080
	v_lshl_add_u64 v[146:147], v[206:207], 0, s[10:11]
	s_addc_u32 s37, s37, 0
	s_add_i32 s38, s71, s44
	global_load_lds_dwordx4 v[146:147], off
	v_lshl_add_u64 v[146:147], s[36:37], 0, v[132:133]
	s_mov_b32 m0, s38
	s_nop 0
	global_load_lds_dwordx4 v[146:147], off
	v_lshl_add_u64 v[146:147], s[36:37], 0, v[128:129]
	s_add_i32 m0, s38, 0x2000
	s_nop 0
	global_load_lds_dwordx4 v[146:147], off
	v_lshl_add_u64 v[146:147], v[222:223], 0, s[10:11]
	s_mov_b32 m0, s55
	s_nop 0
	global_load_lds_dwordx4 v[146:147], off
	v_lshl_add_u64 v[146:147], v[224:225], 0, s[10:11]
	s_mov_b32 m0, s56
	s_nop 0
	global_load_lds_dwordx4 v[146:147], off
	s_waitcnt vmcnt(8)
	s_waitcnt lgkmcnt(0)
	s_barrier
	s_setprio 1
	s_waitcnt lgkmcnt(0)
	v_mfma_f32_16x16x32_bf16 v[60:63], v[154:157], v[186:189], v[60:63]
	v_mfma_f32_16x16x32_bf16 v[56:59], v[162:165], v[186:189], v[56:59]
	v_mfma_f32_16x16x32_bf16 v[52:55], v[154:157], v[194:197], v[52:55]
	v_mfma_f32_16x16x32_bf16 v[44:47], v[162:165], v[194:197], v[44:47]
	v_mfma_f32_16x16x32_bf16 v[36:39], v[154:157], v[202:205], v[36:39]
	v_mfma_f32_16x16x32_bf16 v[28:31], v[162:165], v[202:205], v[28:31]
	v_mfma_f32_16x16x32_bf16 v[20:23], v[154:157], v[214:217], v[20:23]
	v_mfma_f32_16x16x32_bf16 v[12:15], v[162:165], v[214:217], v[12:15]
	v_mfma_f32_16x16x32_bf16 v[60:63], v[158:161], v[190:193], v[60:63]
	v_mfma_f32_16x16x32_bf16 v[56:59], v[166:169], v[190:193], v[56:59]
	v_mfma_f32_16x16x32_bf16 v[52:55], v[158:161], v[198:201], v[52:55]
	v_mfma_f32_16x16x32_bf16 v[44:47], v[166:169], v[198:201], v[44:47]
	v_mfma_f32_16x16x32_bf16 v[36:39], v[158:161], v[210:213], v[36:39]
	v_mfma_f32_16x16x32_bf16 v[28:31], v[166:169], v[210:213], v[28:31]
	v_mfma_f32_16x16x32_bf16 v[20:23], v[158:161], v[218:221], v[20:23]
	v_mfma_f32_16x16x32_bf16 v[12:15], v[166:169], v[218:221], v[12:15]
	v_mfma_f32_16x16x32_bf16 v[48:51], v[170:173], v[186:189], v[48:51]
	v_mfma_f32_16x16x32_bf16 v[40:43], v[178:181], v[186:189], v[40:43]
	v_mfma_f32_16x16x32_bf16 v[32:35], v[170:173], v[194:197], v[32:35]
	v_mfma_f32_16x16x32_bf16 v[24:27], v[178:181], v[194:197], v[24:27]
	v_mfma_f32_16x16x32_bf16 v[16:19], v[170:173], v[202:205], v[16:19]
	v_mfma_f32_16x16x32_bf16 v[8:11], v[178:181], v[202:205], v[8:11]
	v_mfma_f32_16x16x32_bf16 v[4:7], v[170:173], v[214:217], v[4:7]
	v_mfma_f32_16x16x32_bf16 v[0:3], v[178:181], v[214:217], v[0:3]
	v_mfma_f32_16x16x32_bf16 v[48:51], v[174:177], v[190:193], v[48:51]
	v_mfma_f32_16x16x32_bf16 v[40:43], v[182:185], v[190:193], v[40:43]
	v_mfma_f32_16x16x32_bf16 v[32:35], v[174:177], v[198:201], v[32:35]
	v_mfma_f32_16x16x32_bf16 v[24:27], v[182:185], v[198:201], v[24:27]
	v_mfma_f32_16x16x32_bf16 v[16:19], v[174:177], v[210:213], v[16:19]
	v_mfma_f32_16x16x32_bf16 v[8:11], v[182:185], v[210:213], v[8:11]
	v_mfma_f32_16x16x32_bf16 v[4:7], v[174:177], v[218:221], v[4:7]
	v_mfma_f32_16x16x32_bf16 v[0:3], v[182:185], v[218:221], v[0:3]
	s_setprio 0
	s_barrier
	s_add_i32 s69, s69, 2
	s_add_u32 s34, s34, 0x100
	s_addc_u32 s35, s35, 0
	s_add_u32 s67, s67, 0x100
	s_addc_u32 s68, s68, 0
	s_cmp_gt_u32 s69, 29
	s_cbranch_scc0 .LBB0_16
	s_and_b64 vcc, exec, s[12:13]
	s_cbranch_vccz .LBB0_19
	s_barrier

; template <class Epi, class Sched, bool ALIGN_EPI = false, bool SP2 = false>
; __device__ __forceinline__ void gemm_phase(PG8_LAS unsigned char* lds, const Gemm g, const Sched& S, const Epi& E) {
;     ...
;         const bool has_next = S.next(ui + 1, nxt);
;         const char* nA = has_next ? (const char*)g.A + (size_t)nxt.pm * tstep : cA; const char* nB = has_next ? (const char*)g.Bt + (size_t)nxt.pn * tstep : cB;
;         for (int t = 0; t < nt; t += 2) {
;             const bool last = (t == nt - 2);
;             const char* a1 = cA + (size_t)(t + 1) * kstep;
;             const char* a2 = last ? nA : cA + (size_t)(t + 2) * kstep; const char* b2 = last ? nB : cB + (size_t)(t + 2) * kstep;
;             const char* a3 = a2 + kstep; const char* b3 = b2 + kstep;
.LBB0_520:
	s_ashr_i32 s19, s18, 31
	s_lshl_b64 s[20:21], s[18:19], 20
	s_add_u32 s20, s35, s20
	s_addc_u32 s21, s36, s21
	s_and_b64 s[22:23], s[40:41], exec
	s_cselect_b32 s19, s21, s27
	s_cselect_b32 s58, s20, s26
	s_ashr_i32 s17, s16, 31
	s_lshl_b64 s[22:23], s[16:17], 20
	s_add_u32 s22, s37, s22
	s_addc_u32 s23, s38, s23
	s_and_b64 s[30:31], s[40:41], exec
	s_cselect_b32 s17, s23, s29
	s_cselect_b32 s59, s22, s28
	s_add_u32 s26, s26, 0x80080
	s_addc_u32 s27, s27, 0
	s_add_u32 s60, s28, 0x100

; template <class Epi, class Sched, bool ALIGN_EPI = false, bool SP2 = false>
; __device__ __forceinline__ void gemm_phase(PG8_LAS unsigned char* lds, const Gemm g, const Sched& S, const Epi& E) {
;     ...
;         const char* nA = has_next ? (const char*)g.A + (size_t)nxt.pm * tstep : cA; const char* nB = has_next ? (const char*)g.Bt + (size_t)nxt.pn * tstep : cB;
;         for (int t = 0; t < nt; t += 2) {
;             const bool last = (t == nt - 2);
;             const char* a1 = cA + (size_t)(t + 1) * kstep;
;             const char* a2 = last ? nA : cA + (size_t)(t + 2) * kstep; const char* b2 = last ? nB : cB + (size_t)(t + 2) * kstep;
;             const char* a3 = a2 + kstep; const char* b3 = b2 + kstep;
	s_addc_u32 s61, s29, 0
	s_mov_b32 s62, -2


; #define PG8_STAGE(bufoff, gbase, voff) do { _Pragma("unroll") for (int _i = 0; _i < 2; ++_i) \
;         __builtin_amdgcn_global_load_lds((const unsigned*)((const char*)(gbase) + (voff)[_i]), (PG8_LAS unsigned*)(lds + (bufoff) + ldsw + _i * 8192), 16, 0, 0); } while (0)
; #define PG8_LDA(dst, b, h) do { _Pragma("unroll") for (int m = 0; m < 4; ++m) _Pragma("unroll") for (int k = 0; k < 2; ++k) dst[m][k] = *(const PG8_LAS bf16x8*)(lds + PG8_SA(b, h) + aoff + m * 2048 + k * 1024); } while (0)
; #define PG8_LDB(dst, b, h) do { _Pragma("unroll") for (int n = 0; n < 2; ++n) _Pragma("unroll") for (int k = 0; k < 2; ++k) dst[n][k] = *(const PG8_LAS bf16x8*)(lds + PG8_SB(b, h) + boff + n * 2048 + k * 1024); } while (0)
; #define PG8_MMA(ai, bj, At, Bt) do { __builtin_amdgcn_s_setprio(1); _Pragma("unroll") for (int m = 0; m < 4; ++m) _Pragma("unroll") for (int n = 0; n < 2; ++n) _Pragma("unroll") for (int k = 0; k < 2; ++k) \
;         acc[ai][bj][m][n] = __builtin_amdgcn_mfma_f32_16x16x32_bf16(Bt[n][k], At[m][k], acc[ai][bj][m][n], 0, 0, 0); __builtin_amdgcn_s_setprio(0); } while (0)
; #define PG8_WAIT_V(n) asm volatile("s_waitcnt vmcnt(" #n ")" ::: "memory")
; #define PG8_WAIT_L(n) asm volatile("s_waitcnt lgkmcnt(" #n ")" ::: "memory")
; #define PG8_BAR __builtin_amdgcn_s_barrier()
; #define PG8_SCHED __builtin_amdgcn_sched_barrier(0)
; template <class Epi, class Sched, bool ALIGN_EPI = false, bool SP2 = false>
; __device__ __forceinline__ void gemm_phase(PG8_LAS unsigned char* lds, const Gemm g, const Sched& S, const Epi& E) {
;     ...
;             PG8_LDB(B0, 0, 0); PG8_LDB(B1, 0, 1); PG8_SCHED; PG8_LDA(At, 0, 0); PG8_STAGE(PG8_SA(1, 1), a1 + hstep, voffA);
;             PG8_WAIT_V(8); PG8_WAIT_L(0); PG8_BAR; PG8_MMA(0, 0, At, B0); PG8_MMA(0, 1, At, B1); PG8_BAR; PG8_SCHED;
;             PG8_LDA(At, 0, 1); PG8_STAGE(PG8_SB(0, 0), b2, voffB); PG8_STAGE(PG8_SB(0, 1), b2 + hstep, voffB); PG8_STAGE(PG8_SA(0, 0), a2, voffA);
	s_add_u32 s28, s26, 0xfff80080
	s_addc_u32 s29, s27, -1
	s_add_i32 s68, 0, 0x10000
	s_cmp_eq_u32 s62, 28
	s_cselect_b32 s31, s19, s29
	s_cselect_b32 s30, s58, s28
	v_add_u32_e32 v130, s68, v156
	s_cselect_b32 s29, s17, s61
	s_cselect_b32 s28, s59, s60
	s_add_i32 s74, 0, 0x14000
	ds_read_b128 v[160:163], v130
	ds_read_b128 v[164:167], v130 offset:1024
	ds_read_b128 v[168:171], v130 offset:2048
	ds_read_b128 v[172:175], v130 offset:3072
	v_add_u32_e32 v130, s74, v156
	ds_read_b128 v[176:179], v130
	ds_read_b128 v[180:183], v130 offset:1024
	ds_read_b128 v[184:187], v130 offset:2048
	ds_read_b128 v[188:191], v130 offset:3072
	v_lshl_add_u64 v[130:131], s[26:27], 0, v[148:149]
	s_add_i32 m0, s42, 0xc000
	ds_read_b128 v[192:195], v158
	ds_read_b128 v[196:199], v158 offset:1024
	ds_read_b128 v[200:203], v158 offset:2048
	ds_read_b128 v[204:207], v158 offset:3072
	ds_read_b128 v[218:221], v158 offset:4096
	ds_read_b128 v[222:225], v158 offset:5120
	ds_read_b128 v[226:229], v158 offset:6144
	ds_read_b128 v[230:233], v158 offset:7168
	global_load_lds_dwordx4 v[130:131], off
	v_lshl_add_u64 v[130:131], s[26:27], 0, v[150:151]
	s_add_i32 m0, s42, 0xe000
	s_nop 0
	global_load_lds_dwordx4 v[130:131], off
	s_waitcnt vmcnt(8)
	s_waitcnt lgkmcnt(0)
	s_barrier
	s_setprio 1
	s_waitcnt lgkmcnt(0)
	v_mfma_f32_16x16x32_bf16 v[124:127], v[160:163], v[192:195], 0
	v_mfma_f32_16x16x32_bf16 v[120:123], v[168:171], v[192:195], 0
	v_mfma_f32_16x16x32_bf16 v[116:119], v[160:163], v[200:203], 0
	v_mfma_f32_16x16x32_bf16 v[112:115], v[168:171], v[200:203], 0
	v_mfma_f32_16x16x32_bf16 v[100:103], v[160:163], v[218:221], 0
	v_mfma_f32_16x16x32_bf16 v[96:99], v[168:171], v[218:221], 0
	v_mfma_f32_16x16x32_bf16 v[80:83], v[160:163], v[226:229], 0
	v_mfma_f32_16x16x32_bf16 v[76:79], v[168:171], v[226:229], 0
	v_mfma_f32_16x16x32_bf16 v[124:127], v[164:167], v[196:199], v[124:127]
	v_mfma_f32_16x16x32_bf16 v[120:123], v[172:175], v[196:199], v[120:123]
	v_mfma_f32_16x16x32_bf16 v[116:119], v[164:167], v[204:207], v[116:119]
	v_mfma_f32_16x16x32_bf16 v[112:115], v[172:175], v[204:207], v[112:115]
	v_mfma_f32_16x16x32_bf16 v[100:103], v[164:167], v[222:225], v[100:103]
	v_mfma_f32_16x16x32_bf16 v[96:99], v[172:175], v[222:225], v[96:99]
	v_mfma_f32_16x16x32_bf16 v[80:83], v[164:167], v[230:233], v[80:83]
	v_mfma_f32_16x16x32_bf16 v[76:79], v[172:175], v[230:233], v[76:79]
	v_mfma_f32_16x16x32_bf16 v[108:111], v[176:179], v[192:195], 0
	v_mfma_f32_16x16x32_bf16 v[104:107], v[184:187], v[192:195], 0
	v_mfma_f32_16x16x32_bf16 v[92:95], v[176:179], v[200:203], 0
	v_mfma_f32_16x16x32_bf16 v[88:91], v[184:187], v[200:203], 0
	v_mfma_f32_16x16x32_bf16 v[84:87], v[176:179], v[218:221], 0
	v_mfma_f32_16x16x32_bf16 v[72:75], v[184:187], v[218:221], 0
	v_mfma_f32_16x16x32_bf16 v[68:71], v[176:179], v[226:229], 0
	v_mfma_f32_16x16x32_bf16 v[64:67], v[184:187], v[226:229], 0
	v_mfma_f32_16x16x32_bf16 v[108:111], v[180:183], v[196:199], v[108:111]
	v_mfma_f32_16x16x32_bf16 v[104:107], v[188:191], v[196:199], v[104:107]
	v_mfma_f32_16x16x32_bf16 v[92:95], v[180:183], v[204:207], v[92:95]
	v_mfma_f32_16x16x32_bf16 v[88:91], v[188:191], v[204:207], v[88:91]
	v_mfma_f32_16x16x32_bf16 v[84:87], v[180:183], v[222:225], v[84:87]
	v_mfma_f32_16x16x32_bf16 v[72:75], v[188:191], v[222:225], v[72:75]
	v_mfma_f32_16x16x32_bf16 v[68:71], v[180:183], v[230:233], v[68:71]
	v_mfma_f32_16x16x32_bf16 v[64:67], v[188:191], v[230:233], v[64:67]
	s_setprio 0
	s_barrier
	s_add_i32 s68, s68, s39
	v_lshl_add_u64 v[130:131], s[28:29], 0, v[128:129]
	s_mov_b32 m0, s68
	ds_read_b128 v[192:195], v158 offset:16384
	ds_read_b128 v[196:199], v158 offset:17408
	ds_read_b128 v[200:203], v158 offset:18432
	ds_read_b128 v[204:207], v158 offset:19456
	ds_read_b128 v[218:221], v158 offset:20480
	ds_read_b128 v[222:225], v158 offset:21504
	ds_read_b128 v[226:229], v158 offset:22528
	ds_read_b128 v[230:233], v158 offset:23552
	global_load_lds_dwordx4 v[130:131], off
	s_add_i32 m0, s68, 0x2000
	s_add_u32 s68, s28, 0x80000
	v_lshl_add_u64 v[132:133], s[28:29], 0, v[142:143]
	s_addc_u32 s69, s29, 0
	s_add_i32 s74, s74, s39
	global_load_lds_dwordx4 v[132:133], off
	v_lshl_add_u64 v[154:155], s[68:69], 0, v[128:129]
	s_mov_b32 m0, s74
	v_lshl_add_u64 v[234:235], s[30:31], 0, v[144:145]
	global_load_lds_dwordx4 v[154:155], off
	v_lshl_add_u64 v[154:155], s[68:69], 0, v[142:143]
	s_add_i32 m0, s74, 0x2000
	s_nop 0
	global_load_lds_dwordx4 v[154:155], off
	v_lshl_add_u64 v[154:155], s[30:31], 0, v[146:147]
	s_mov_b32 m0, s42
	s_nop 0
	global_load_lds_dwordx4 v[154:155], off
	s_mov_b32 m0, s43
	s_nop 0
	global_load_lds_dwordx4 v[234:235], off
	s_waitcnt vmcnt(8)
	s_waitcnt lgkmcnt(0)
	s_barrier
; #define PG8_STAGE(bufoff, gbase, voff) do { _Pragma("unroll") for (int _i = 0; _i < 2; ++_i) \
;         __builtin_amdgcn_global_load_lds((const unsigned*)((const char*)(gbase) + (voff)[_i]), (PG8_LAS unsigned*)(lds + (bufoff) + ldsw + _i * 8192), 16, 0, 0); } while (0)
; #define PG8_LDA(dst, b, h) do { _Pragma("unroll") for (int m = 0; m < 4; ++m) _Pragma("unroll") for (int k = 0; k < 2; ++k) dst[m][k] = *(const PG8_LAS bf16x8*)(lds + PG8_SA(b, h) + aoff + m * 2048 + k * 1024); } while (0)
; #define PG8_LDB(dst, b, h) do { _Pragma("unroll") for (int n = 0; n < 2; ++n) _Pragma("unroll") for (int k = 0; k < 2; ++k) dst[n][k] = *(const PG8_LAS bf16x8*)(lds + PG8_SB(b, h) + boff + n * 2048 + k * 1024); } while (0)
; #define PG8_MMA(ai, bj, At, Bt) do { __builtin_amdgcn_s_setprio(1); _Pragma("unroll") for (int m = 0; m < 4; ++m) _Pragma("unroll") for (int n = 0; n < 2; ++n) _Pragma("unroll") for (int k = 0; k < 2; ++k) \
;         acc[ai][bj][m][n] = __builtin_amdgcn_mfma_f32_16x16x32_bf16(Bt[n][k], At[m][k], acc[ai][bj][m][n], 0, 0, 0); __builtin_amdgcn_s_setprio(0); } while (0)
; #define PG8_WAIT_V(n) asm volatile("s_waitcnt vmcnt(" #n ")" ::: "memory")
; #define PG8_WAIT_L(n) asm volatile("s_waitcnt lgkmcnt(" #n ")" ::: "memory")
; #define PG8_BAR __builtin_amdgcn_s_barrier()
; #define PG8_SCHED __builtin_amdgcn_sched_barrier(0)
; template <class Epi, class Sched, bool ALIGN_EPI = false, bool SP2 = false>
; __device__ __forceinline__ void gemm_phase(PG8_LAS unsigned char* lds, const Gemm g, const Sched& S, const Epi& E) {
;     ...
;             PG8_WAIT_V(8); PG8_WAIT_L(0); PG8_BAR; PG8_MMA(1, 0, At, B0); PG8_MMA(1, 1, At, B1); PG8_BAR; PG8_SCHED;
;             PG8_LDB(B0, 1, 0); PG8_LDB(B1, 1, 1); PG8_SCHED; PG8_LDA(At, 1, 0); PG8_STAGE(PG8_SA(0, 1), a2 + hstep, voffA);
;             PG8_WAIT_V(8); PG8_WAIT_L(0); PG8_BAR; PG8_MMA(0, 0, At, B0); PG8_MMA(0, 1, At, B1); PG8_BAR; PG8_SCHED;
	s_setprio 1
	s_waitcnt lgkmcnt(0)
	v_mfma_f32_16x16x32_bf16 v[60:63], v[160:163], v[192:195], 0
	v_mfma_f32_16x16x32_bf16 v[56:59], v[168:171], v[192:195], 0
	v_mfma_f32_16x16x32_bf16 v[52:55], v[160:163], v[200:203], 0
	v_mfma_f32_16x16x32_bf16 v[44:47], v[168:171], v[200:203], 0
	v_mfma_f32_16x16x32_bf16 v[36:39], v[160:163], v[218:221], 0
	v_mfma_f32_16x16x32_bf16 v[28:31], v[168:171], v[218:221], 0
	v_mfma_f32_16x16x32_bf16 v[20:23], v[160:163], v[226:229], 0
	v_mfma_f32_16x16x32_bf16 v[12:15], v[168:171], v[226:229], 0
	v_mfma_f32_16x16x32_bf16 v[60:63], v[164:167], v[196:199], v[60:63]
	v_mfma_f32_16x16x32_bf16 v[56:59], v[172:175], v[196:199], v[56:59]
	v_mfma_f32_16x16x32_bf16 v[52:55], v[164:167], v[204:207], v[52:55]
	v_mfma_f32_16x16x32_bf16 v[44:47], v[172:175], v[204:207], v[44:47]
	v_mfma_f32_16x16x32_bf16 v[36:39], v[164:167], v[222:225], v[36:39]
	v_mfma_f32_16x16x32_bf16 v[28:31], v[172:175], v[222:225], v[28:31]
	v_mfma_f32_16x16x32_bf16 v[20:23], v[164:167], v[230:233], v[20:23]
	v_mfma_f32_16x16x32_bf16 v[12:15], v[172:175], v[230:233], v[12:15]
	v_mfma_f32_16x16x32_bf16 v[48:51], v[176:179], v[192:195], 0
	v_mfma_f32_16x16x32_bf16 v[40:43], v[184:187], v[192:195], 0
	v_mfma_f32_16x16x32_bf16 v[32:35], v[176:179], v[200:203], 0
	v_mfma_f32_16x16x32_bf16 v[24:27], v[184:187], v[200:203], 0
	v_mfma_f32_16x16x32_bf16 v[16:19], v[176:179], v[218:221], 0
	v_mfma_f32_16x16x32_bf16 v[8:11], v[184:187], v[218:221], 0
	v_mfma_f32_16x16x32_bf16 v[4:7], v[176:179], v[226:229], 0
	v_mfma_f32_16x16x32_bf16 v[0:3], v[184:187], v[226:229], 0
	v_mfma_f32_16x16x32_bf16 v[48:51], v[180:183], v[196:199], v[48:51]
	v_mfma_f32_16x16x32_bf16 v[40:43], v[188:191], v[196:199], v[40:43]
	v_mfma_f32_16x16x32_bf16 v[32:35], v[180:183], v[204:207], v[32:35]
	v_mfma_f32_16x16x32_bf16 v[24:27], v[188:191], v[204:207], v[24:27]
	v_mfma_f32_16x16x32_bf16 v[16:19], v[180:183], v[222:225], v[16:19]
	v_mfma_f32_16x16x32_bf16 v[8:11], v[188:191], v[222:225], v[8:11]
	v_mfma_f32_16x16x32_bf16 v[4:7], v[180:183], v[230:233], v[4:7]
	v_mfma_f32_16x16x32_bf16 v[0:3], v[188:191], v[230:233], v[0:3]
	s_setprio 0
	s_barrier
	s_add_i32 s68, 0, 0x18000
	v_add_u32_e32 v134, s68, v156
	s_add_i32 s69, 0, 0x1c000
	ds_read_b128 v[160:163], v134
	ds_read_b128 v[164:167], v134 offset:1024
	ds_read_b128 v[168:171], v134 offset:2048
	ds_read_b128 v[172:175], v134 offset:3072
	v_add_u32_e32 v134, s69, v156
	ds_read_b128 v[176:179], v134
	ds_read_b128 v[180:183], v134 offset:1024
	ds_read_b128 v[184:187], v134 offset:2048
	ds_read_b128 v[188:191], v134 offset:3072
	s_add_u32 s30, s30, 0x80000
	s_addc_u32 s31, s31, 0
	s_mov_b32 m0, s44
	v_lshl_add_u64 v[236:237], s[30:31], 0, v[146:147]
	ds_read_b128 v[192:195], v158 offset:32768
	ds_read_b128 v[196:199], v158 offset:33792
	ds_read_b128 v[200:203], v158 offset:34816
	ds_read_b128 v[204:207], v158 offset:35840
	ds_read_b128 v[218:221], v158 offset:36864
	ds_read_b128 v[222:225], v158 offset:37888
	ds_read_b128 v[226:229], v158 offset:38912
	ds_read_b128 v[230:233], v158 offset:39936
	global_load_lds_dwordx4 v[236:237], off
	v_lshl_add_u64 v[236:237], s[30:31], 0, v[144:145]
	s_mov_b32 m0, s45
	s_nop 0
	global_load_lds_dwordx4 v[236:237], off
	s_waitcnt vmcnt(8)
	s_waitcnt lgkmcnt(0)
	s_barrier
	s_setprio 1
	s_waitcnt lgkmcnt(0)
	v_mfma_f32_16x16x32_bf16 v[124:127], v[160:163], v[192:195], v[124:127]
	v_mfma_f32_16x16x32_bf16 v[120:123], v[168:171], v[192:195], v[120:123]
	v_mfma_f32_16x16x32_bf16 v[116:119], v[160:163], v[200:203], v[116:119]
	v_mfma_f32_16x16x32_bf16 v[112:115], v[168:171], v[200:203], v[112:115]
	v_mfma_f32_16x16x32_bf16 v[100:103], v[160:163], v[218:221], v[100:103]
	v_mfma_f32_16x16x32_bf16 v[96:99], v[168:171], v[218:221], v[96:99]
	v_mfma_f32_16x16x32_bf16 v[80:83], v[160:163], v[226:229], v[80:83]
	v_mfma_f32_16x16x32_bf16 v[76:79], v[168:171], v[226:229], v[76:79]
	v_mfma_f32_16x16x32_bf16 v[124:127], v[164:167], v[196:199], v[124:127]
	v_mfma_f32_16x16x32_bf16 v[120:123], v[172:175], v[196:199], v[120:123]
	v_mfma_f32_16x16x32_bf16 v[116:119], v[164:167], v[204:207], v[116:119]
	v_mfma_f32_16x16x32_bf16 v[112:115], v[172:175], v[204:207], v[112:115]
	v_mfma_f32_16x16x32_bf16 v[100:103], v[164:167], v[222:225], v[100:103]
	v_mfma_f32_16x16x32_bf16 v[96:99], v[172:175], v[222:225], v[96:99]
	v_mfma_f32_16x16x32_bf16 v[80:83], v[164:167], v[230:233], v[80:83]
	v_mfma_f32_16x16x32_bf16 v[76:79], v[172:175], v[230:233], v[76:79]
	v_mfma_f32_16x16x32_bf16 v[108:111], v[176:179], v[192:195], v[108:111]
	v_mfma_f32_16x16x32_bf16 v[104:107], v[184:187], v[192:195], v[104:107]
	v_mfma_f32_16x16x32_bf16 v[92:95], v[176:179], v[200:203], v[92:95]
	v_mfma_f32_16x16x32_bf16 v[88:91], v[184:187], v[200:203], v[88:91]
	v_mfma_f32_16x16x32_bf16 v[84:87], v[176:179], v[218:221], v[84:87]
	v_mfma_f32_16x16x32_bf16 v[72:75], v[184:187], v[218:221], v[72:75]
	v_mfma_f32_16x16x32_bf16 v[68:71], v[176:179], v[226:229], v[68:71]
	v_mfma_f32_16x16x32_bf16 v[64:67], v[184:187], v[226:229], v[64:67]
	v_mfma_f32_16x16x32_bf16 v[108:111], v[180:183], v[196:199], v[108:111]
	v_mfma_f32_16x16x32_bf16 v[104:107], v[188:191], v[196:199], v[104:107]
	v_mfma_f32_16x16x32_bf16 v[92:95], v[180:183], v[204:207], v[92:95]
	v_mfma_f32_16x16x32_bf16 v[88:91], v[188:191], v[204:207], v[88:91]
	v_mfma_f32_16x16x32_bf16 v[84:87], v[180:183], v[222:225], v[84:87]
	v_mfma_f32_16x16x32_bf16 v[72:75], v[188:191], v[222:225], v[72:75]
	v_mfma_f32_16x16x32_bf16 v[68:71], v[180:183], v[230:233], v[68:71]
	v_mfma_f32_16x16x32_bf16 v[64:67], v[188:191], v[230:233], v[64:67]
	s_setprio 0
	s_barrier
; #define PG8_STAGE(bufoff, gbase, voff) do { _Pragma("unroll") for (int _i = 0; _i < 2; ++_i) \
;         __builtin_amdgcn_global_load_lds((const unsigned*)((const char*)(gbase) + (voff)[_i]), (PG8_LAS unsigned*)(lds + (bufoff) + ldsw + _i * 8192), 16, 0, 0); } while (0)
; #define PG8_LDA(dst, b, h) do { _Pragma("unroll") for (int m = 0; m < 4; ++m) _Pragma("unroll") for (int k = 0; k < 2; ++k) dst[m][k] = *(const PG8_LAS bf16x8*)(lds + PG8_SA(b, h) + aoff + m * 2048 + k * 1024); } while (0)
; #define PG8_LDB(dst, b, h) do { _Pragma("unroll") for (int n = 0; n < 2; ++n) _Pragma("unroll") for (int k = 0; k < 2; ++k) dst[n][k] = *(const PG8_LAS bf16x8*)(lds + PG8_SB(b, h) + boff + n * 2048 + k * 1024); } while (0)
; #define PG8_MMA(ai, bj, At, Bt) do { __builtin_amdgcn_s_setprio(1); _Pragma("unroll") for (int m = 0; m < 4; ++m) _Pragma("unroll") for (int n = 0; n < 2; ++n) _Pragma("unroll") for (int k = 0; k < 2; ++k) \
;         acc[ai][bj][m][n] = __builtin_amdgcn_mfma_f32_16x16x32_bf16(Bt[n][k], At[m][k], acc[ai][bj][m][n], 0, 0, 0); __builtin_amdgcn_s_setprio(0); } while (0)
; #define PG8_WAIT_V(n) asm volatile("s_waitcnt vmcnt(" #n ")" ::: "memory")
; template <class Epi, class Sched, bool ALIGN_EPI = false, bool SP2 = false>
; __device__ __forceinline__ void gemm_phase(PG8_LAS unsigned char* lds, const Gemm g, const Sched& S, const Epi& E) {
;     ...
;             PG8_LDB(B0, 0, 0); PG8_LDB(B1, 0, 1); PG8_SCHED; PG8_LDA(At, 0, 0); PG8_STAGE(PG8_SA(1, 1), a1 + hstep, voffA);
;             PG8_WAIT_V(8); PG8_WAIT_L(0); PG8_BAR; PG8_MMA(0, 0, At, B0); PG8_MMA(0, 1, At, B1); PG8_BAR; PG8_SCHED;
;             PG8_LDA(At, 0, 1); PG8_STAGE(PG8_SB(0, 0), b2, voffB); PG8_STAGE(PG8_SB(0, 1), b2 + hstep, voffB); PG8_STAGE(PG8_SA(0, 0), a2, voffA);
;             PG8_WAIT_V(8); PG8_WAIT_L(0); PG8_BAR; PG8_MMA(1, 0, At, B0); PG8_MMA(1, 1, At, B1); PG8_BAR; PG8_SCHED;
;             PG8_LDB(B0, 1, 0); PG8_LDB(B1, 1, 1); PG8_SCHED; PG8_LDA(At, 1, 0); PG8_STAGE(PG8_SA(0, 1), a2 + hstep, voffA);
;             PG8_WAIT_V(8); PG8_WAIT_L(0); PG8_BAR; PG8_MMA(0, 0, At, B0); PG8_MMA(0, 1, At, B1); PG8_BAR; PG8_SCHED;
;             PG8_LDA(At, 1, 1); PG8_STAGE(PG8_SB(1, 0), b3, voffB); PG8_STAGE(PG8_SB(1, 1), b3 + hstep, voffB); PG8_STAGE(PG8_SA(1, 0), a3, voffA);
;             PG8_WAIT_V(8); PG8_WAIT_L(0); PG8_BAR; PG8_MMA(1, 0, At, B0); PG8_MMA(1, 1, At, B1); PG8_BAR; PG8_SCHED;
	s_add_i32 s30, s68, s39
	v_lshl_add_u64 v[130:131], v[130:131], 0, s[78:79]
	s_mov_b32 m0, s30
	ds_read_b128 v[192:195], v158 offset:49152
	ds_read_b128 v[196:199], v158 offset:50176
	ds_read_b128 v[200:203], v158 offset:51200
	ds_read_b128 v[204:207], v158 offset:52224
	ds_read_b128 v[218:221], v158 offset:53248
	ds_read_b128 v[222:225], v158 offset:54272
	ds_read_b128 v[226:229], v158 offset:55296
	ds_read_b128 v[230:233], v158 offset:56320
	global_load_lds_dwordx4 v[130:131], off
	s_add_i32 m0, s30, 0x2000
	s_add_u32 s28, s28, 0x80080
	v_lshl_add_u64 v[130:131], v[132:133], 0, s[78:79]
	s_addc_u32 s29, s29, 0
	s_add_i32 s30, s69, s39
	global_load_lds_dwordx4 v[130:131], off
	v_lshl_add_u64 v[130:131], s[28:29], 0, v[128:129]
	s_mov_b32 m0, s30
	s_nop 0
	global_load_lds_dwordx4 v[130:131], off
	v_lshl_add_u64 v[130:131], s[28:29], 0, v[142:143]
	s_add_i32 m0, s30, 0x2000
	s_nop 0
	global_load_lds_dwordx4 v[130:131], off
	v_lshl_add_u64 v[130:131], v[154:155], 0, s[78:79]
	s_mov_b32 m0, s55
	s_nop 0
	global_load_lds_dwordx4 v[130:131], off
	v_lshl_add_u64 v[130:131], v[234:235], 0, s[78:79]
	s_mov_b32 m0, s56
	s_nop 0
	global_load_lds_dwordx4 v[130:131], off
	s_waitcnt vmcnt(8)
	s_waitcnt lgkmcnt(0)
	s_barrier
	s_setprio 1
	s_waitcnt lgkmcnt(0)
	v_mfma_f32_16x16x32_bf16 v[60:63], v[160:163], v[192:195], v[60:63]
	v_mfma_f32_16x16x32_bf16 v[56:59], v[168:171], v[192:195], v[56:59]
	v_mfma_f32_16x16x32_bf16 v[52:55], v[160:163], v[200:203], v[52:55]
	v_mfma_f32_16x16x32_bf16 v[44:47], v[168:171], v[200:203], v[44:47]
	v_mfma_f32_16x16x32_bf16 v[36:39], v[160:163], v[218:221], v[36:39]
	v_mfma_f32_16x16x32_bf16 v[28:31], v[168:171], v[218:221], v[28:31]
	v_mfma_f32_16x16x32_bf16 v[20:23], v[160:163], v[226:229], v[20:23]
	v_mfma_f32_16x16x32_bf16 v[12:15], v[168:171], v[226:229], v[12:15]
	v_mfma_f32_16x16x32_bf16 v[60:63], v[164:167], v[196:199], v[60:63]
	v_mfma_f32_16x16x32_bf16 v[56:59], v[172:175], v[196:199], v[56:59]
	v_mfma_f32_16x16x32_bf16 v[52:55], v[164:167], v[204:207], v[52:55]
	v_mfma_f32_16x16x32_bf16 v[44:47], v[172:175], v[204:207], v[44:47]
	v_mfma_f32_16x16x32_bf16 v[36:39], v[164:167], v[222:225], v[36:39]
	v_mfma_f32_16x16x32_bf16 v[28:31], v[172:175], v[222:225], v[28:31]
	v_mfma_f32_16x16x32_bf16 v[20:23], v[164:167], v[230:233], v[20:23]
	v_mfma_f32_16x16x32_bf16 v[12:15], v[172:175], v[230:233], v[12:15]
	v_mfma_f32_16x16x32_bf16 v[48:51], v[176:179], v[192:195], v[48:51]
	v_mfma_f32_16x16x32_bf16 v[40:43], v[184:187], v[192:195], v[40:43]
	v_mfma_f32_16x16x32_bf16 v[32:35], v[176:179], v[200:203], v[32:35]
	v_mfma_f32_16x16x32_bf16 v[24:27], v[184:187], v[200:203], v[24:27]
	v_mfma_f32_16x16x32_bf16 v[16:19], v[176:179], v[218:221], v[16:19]
	v_mfma_f32_16x16x32_bf16 v[8:11], v[184:187], v[218:221], v[8:11]
	v_mfma_f32_16x16x32_bf16 v[4:7], v[176:179], v[226:229], v[4:7]
	v_mfma_f32_16x16x32_bf16 v[0:3], v[184:187], v[226:229], v[0:3]
	v_mfma_f32_16x16x32_bf16 v[48:51], v[180:183], v[196:199], v[48:51]
	v_mfma_f32_16x16x32_bf16 v[40:43], v[188:191], v[196:199], v[40:43]
	v_mfma_f32_16x16x32_bf16 v[32:35], v[180:183], v[204:207], v[32:35]
	v_mfma_f32_16x16x32_bf16 v[24:27], v[188:191], v[204:207], v[24:27]
	v_mfma_f32_16x16x32_bf16 v[16:19], v[180:183], v[222:225], v[16:19]
	v_mfma_f32_16x16x32_bf16 v[8:11], v[188:191], v[222:225], v[8:11]
	v_mfma_f32_16x16x32_bf16 v[4:7], v[180:183], v[230:233], v[4:7]
	v_mfma_f32_16x16x32_bf16 v[0:3], v[188:191], v[230:233], v[0:3]
	s_setprio 0
	s_barrier
	s_add_i32 s62, s62, 2
	s_add_u32 s26, s26, 0x100
	s_addc_u32 s27, s27, 0
	s_add_u32 s60, s60, 0x100
	s_addc_u32 s61, s61, 0
	s_cmp_gt_u32 s62, 29
.LBB0_521:
	s_add_u32 s28, s26, 0xfff80080
	s_addc_u32 s29, s27, -1
	s_add_i32 s68, 0, 0x10000
	s_cmp_eq_u32 s62, 28
	s_cselect_b32 s31, s19, s29
	s_cselect_b32 s30, s58, s28
	v_add_u32_e32 v130, s68, v156
	s_cselect_b32 s29, s17, s61
	s_cselect_b32 s28, s59, s60
	s_add_i32 s74, 0, 0x14000
	ds_read_b128 v[160:163], v130
	ds_read_b128 v[164:167], v130 offset:1024
	ds_read_b128 v[168:171], v130 offset:2048
	ds_read_b128 v[172:175], v130 offset:3072
	v_add_u32_e32 v130, s74, v156
	ds_read_b128 v[176:179], v130
	ds_read_b128 v[180:183], v130 offset:1024
	ds_read_b128 v[184:187], v130 offset:2048
	ds_read_b128 v[188:191], v130 offset:3072
	v_lshl_add_u64 v[130:131], s[26:27], 0, v[148:149]
	s_add_i32 m0, s42, 0xc000
	ds_read_b128 v[192:195], v158
	ds_read_b128 v[196:199], v158 offset:1024
	ds_read_b128 v[200:203], v158 offset:2048
	ds_read_b128 v[204:207], v158 offset:3072
	ds_read_b128 v[218:221], v158 offset:4096
	ds_read_b128 v[222:225], v158 offset:5120
	ds_read_b128 v[226:229], v158 offset:6144
	ds_read_b128 v[230:233], v158 offset:7168
	global_load_lds_dwordx4 v[130:131], off
	v_lshl_add_u64 v[130:131], s[26:27], 0, v[150:151]
	s_add_i32 m0, s42, 0xe000
	s_nop 0
	global_load_lds_dwordx4 v[130:131], off
	s_waitcnt vmcnt(8)
	s_waitcnt lgkmcnt(0)
	s_barrier
; #define PG8_STAGE(bufoff, gbase, voff) do { _Pragma("unroll") for (int _i = 0; _i < 2; ++_i) \
;         __builtin_amdgcn_global_load_lds((const unsigned*)((const char*)(gbase) + (voff)[_i]), (PG8_LAS unsigned*)(lds + (bufoff) + ldsw + _i * 8192), 16, 0, 0); } while (0)
; #define PG8_LDA(dst, b, h) do { _Pragma("unroll") for (int m = 0; m < 4; ++m) _Pragma("unroll") for (int k = 0; k < 2; ++k) dst[m][k] = *(const PG8_LAS bf16x8*)(lds + PG8_SA(b, h) + aoff + m * 2048 + k * 1024); } while (0)
; #define PG8_LDB(dst, b, h) do { _Pragma("unroll") for (int n = 0; n < 2; ++n) _Pragma("unroll") for (int k = 0; k < 2; ++k) dst[n][k] = *(const PG8_LAS bf16x8*)(lds + PG8_SB(b, h) + boff + n * 2048 + k * 1024); } while (0)
; #define PG8_MMA(ai, bj, At, Bt) do { __builtin_amdgcn_s_setprio(1); _Pragma("unroll") for (int m = 0; m < 4; ++m) _Pragma("unroll") for (int n = 0; n < 2; ++n) _Pragma("unroll") for (int k = 0; k < 2; ++k) \
;         acc[ai][bj][m][n] = __builtin_amdgcn_mfma_f32_16x16x32_bf16(Bt[n][k], At[m][k], acc[ai][bj][m][n], 0, 0, 0); __builtin_amdgcn_s_setprio(0); } while (0)
; #define PG8_WAIT_V(n) asm volatile("s_waitcnt vmcnt(" #n ")" ::: "memory")
; #define PG8_WAIT_L(n) asm volatile("s_waitcnt lgkmcnt(" #n ")" ::: "memory")
; #define PG8_BAR __builtin_amdgcn_s_barrier()
; #define PG8_SCHED __builtin_amdgcn_sched_barrier(0)
; template <class Epi, class Sched, bool ALIGN_EPI = false, bool SP2 = false>
; __device__ __forceinline__ void gemm_phase(PG8_LAS unsigned char* lds, const Gemm g, const Sched& S, const Epi& E) {
;     ...
;             PG8_LDB(B0, 0, 0); PG8_LDB(B1, 0, 1); PG8_SCHED; PG8_LDA(At, 0, 0); PG8_STAGE(PG8_SA(1, 1), a1 + hstep, voffA);
;             PG8_WAIT_V(8); PG8_WAIT_L(0); PG8_BAR; PG8_MMA(0, 0, At, B0); PG8_MMA(0, 1, At, B1); PG8_BAR; PG8_SCHED;
;             PG8_LDA(At, 0, 1); PG8_STAGE(PG8_SB(0, 0), b2, voffB); PG8_STAGE(PG8_SB(0, 1), b2 + hstep, voffB); PG8_STAGE(PG8_SA(0, 0), a2, voffA);
;             PG8_WAIT_V(8); PG8_WAIT_L(0); PG8_BAR; PG8_MMA(1, 0, At, B0); PG8_MMA(1, 1, At, B1); PG8_BAR; PG8_SCHED;
	s_setprio 1
	s_waitcnt lgkmcnt(0)
	v_mfma_f32_16x16x32_bf16 v[124:127], v[160:163], v[192:195], v[124:127]
	v_mfma_f32_16x16x32_bf16 v[120:123], v[168:171], v[192:195], v[120:123]
	v_mfma_f32_16x16x32_bf16 v[116:119], v[160:163], v[200:203], v[116:119]
	v_mfma_f32_16x16x32_bf16 v[112:115], v[168:171], v[200:203], v[112:115]
	v_mfma_f32_16x16x32_bf16 v[100:103], v[160:163], v[218:221], v[100:103]
	v_mfma_f32_16x16x32_bf16 v[96:99], v[168:171], v[218:221], v[96:99]
	v_mfma_f32_16x16x32_bf16 v[80:83], v[160:163], v[226:229], v[80:83]
	v_mfma_f32_16x16x32_bf16 v[76:79], v[168:171], v[226:229], v[76:79]
	v_mfma_f32_16x16x32_bf16 v[124:127], v[164:167], v[196:199], v[124:127]
	v_mfma_f32_16x16x32_bf16 v[120:123], v[172:175], v[196:199], v[120:123]
	v_mfma_f32_16x16x32_bf16 v[116:119], v[164:167], v[204:207], v[116:119]
	v_mfma_f32_16x16x32_bf16 v[112:115], v[172:175], v[204:207], v[112:115]
	v_mfma_f32_16x16x32_bf16 v[100:103], v[164:167], v[222:225], v[100:103]
	v_mfma_f32_16x16x32_bf16 v[96:99], v[172:175], v[222:225], v[96:99]
	v_mfma_f32_16x16x32_bf16 v[80:83], v[164:167], v[230:233], v[80:83]
	v_mfma_f32_16x16x32_bf16 v[76:79], v[172:175], v[230:233], v[76:79]
	v_mfma_f32_16x16x32_bf16 v[108:111], v[176:179], v[192:195], v[108:111]
	v_mfma_f32_16x16x32_bf16 v[104:107], v[184:187], v[192:195], v[104:107]
	v_mfma_f32_16x16x32_bf16 v[92:95], v[176:179], v[200:203], v[92:95]
	v_mfma_f32_16x16x32_bf16 v[88:91], v[184:187], v[200:203], v[88:91]
	v_mfma_f32_16x16x32_bf16 v[84:87], v[176:179], v[218:221], v[84:87]
	v_mfma_f32_16x16x32_bf16 v[72:75], v[184:187], v[218:221], v[72:75]
	v_mfma_f32_16x16x32_bf16 v[68:71], v[176:179], v[226:229], v[68:71]
	v_mfma_f32_16x16x32_bf16 v[64:67], v[184:187], v[226:229], v[64:67]
	v_mfma_f32_16x16x32_bf16 v[108:111], v[180:183], v[196:199], v[108:111]
	v_mfma_f32_16x16x32_bf16 v[104:107], v[188:191], v[196:199], v[104:107]
	v_mfma_f32_16x16x32_bf16 v[92:95], v[180:183], v[204:207], v[92:95]
	v_mfma_f32_16x16x32_bf16 v[88:91], v[188:191], v[204:207], v[88:91]
	v_mfma_f32_16x16x32_bf16 v[84:87], v[180:183], v[222:225], v[84:87]
	v_mfma_f32_16x16x32_bf16 v[72:75], v[188:191], v[222:225], v[72:75]
	v_mfma_f32_16x16x32_bf16 v[68:71], v[180:183], v[230:233], v[68:71]
	v_mfma_f32_16x16x32_bf16 v[64:67], v[188:191], v[230:233], v[64:67]
	s_setprio 0
	s_barrier
	s_add_i32 s68, s68, s39
	v_lshl_add_u64 v[130:131], s[28:29], 0, v[128:129]
	s_mov_b32 m0, s68
	ds_read_b128 v[192:195], v158 offset:16384
	ds_read_b128 v[196:199], v158 offset:17408
	ds_read_b128 v[200:203], v158 offset:18432
	ds_read_b128 v[204:207], v158 offset:19456
	ds_read_b128 v[218:221], v158 offset:20480
	ds_read_b128 v[222:225], v158 offset:21504
	ds_read_b128 v[226:229], v158 offset:22528
	ds_read_b128 v[230:233], v158 offset:23552
	global_load_lds_dwordx4 v[130:131], off
	s_add_i32 m0, s68, 0x2000
	s_add_u32 s68, s28, 0x80000
	v_lshl_add_u64 v[132:133], s[28:29], 0, v[142:143]
	s_addc_u32 s69, s29, 0
	s_add_i32 s74, s74, s39
	global_load_lds_dwordx4 v[132:133], off
	v_lshl_add_u64 v[154:155], s[68:69], 0, v[128:129]
	s_mov_b32 m0, s74
	v_lshl_add_u64 v[234:235], s[30:31], 0, v[144:145]
	global_load_lds_dwordx4 v[154:155], off
	v_lshl_add_u64 v[154:155], s[68:69], 0, v[142:143]
	s_add_i32 m0, s74, 0x2000
	s_nop 0
	global_load_lds_dwordx4 v[154:155], off
	v_lshl_add_u64 v[154:155], s[30:31], 0, v[146:147]
	s_mov_b32 m0, s42
	s_nop 0
	global_load_lds_dwordx4 v[154:155], off
	s_mov_b32 m0, s43
	s_nop 0
	global_load_lds_dwordx4 v[234:235], off
	s_waitcnt vmcnt(8)
	s_waitcnt lgkmcnt(0)
	s_barrier
	s_setprio 1
	s_waitcnt lgkmcnt(0)
	v_mfma_f32_16x16x32_bf16 v[60:63], v[160:163], v[192:195], v[60:63]
	v_mfma_f32_16x16x32_bf16 v[56:59], v[168:171], v[192:195], v[56:59]
	v_mfma_f32_16x16x32_bf16 v[52:55], v[160:163], v[200:203], v[52:55]
	v_mfma_f32_16x16x32_bf16 v[44:47], v[168:171], v[200:203], v[44:47]
	v_mfma_f32_16x16x32_bf16 v[36:39], v[160:163], v[218:221], v[36:39]
	v_mfma_f32_16x16x32_bf16 v[28:31], v[168:171], v[218:221], v[28:31]
	v_mfma_f32_16x16x32_bf16 v[20:23], v[160:163], v[226:229], v[20:23]
	v_mfma_f32_16x16x32_bf16 v[12:15], v[168:171], v[226:229], v[12:15]
	v_mfma_f32_16x16x32_bf16 v[60:63], v[164:167], v[196:199], v[60:63]
	v_mfma_f32_16x16x32_bf16 v[56:59], v[172:175], v[196:199], v[56:59]
	v_mfma_f32_16x16x32_bf16 v[52:55], v[164:167], v[204:207], v[52:55]
	v_mfma_f32_16x16x32_bf16 v[44:47], v[172:175], v[204:207], v[44:47]
	v_mfma_f32_16x16x32_bf16 v[36:39], v[164:167], v[222:225], v[36:39]
	v_mfma_f32_16x16x32_bf16 v[28:31], v[172:175], v[222:225], v[28:31]
	v_mfma_f32_16x16x32_bf16 v[20:23], v[164:167], v[230:233], v[20:23]
	v_mfma_f32_16x16x32_bf16 v[12:15], v[172:175], v[230:233], v[12:15]
	v_mfma_f32_16x16x32_bf16 v[48:51], v[176:179], v[192:195], v[48:51]
	v_mfma_f32_16x16x32_bf16 v[40:43], v[184:187], v[192:195], v[40:43]
	v_mfma_f32_16x16x32_bf16 v[32:35], v[176:179], v[200:203], v[32:35]
	v_mfma_f32_16x16x32_bf16 v[24:27], v[184:187], v[200:203], v[24:27]
	v_mfma_f32_16x16x32_bf16 v[16:19], v[176:179], v[218:221], v[16:19]
	v_mfma_f32_16x16x32_bf16 v[8:11], v[184:187], v[218:221], v[8:11]
	v_mfma_f32_16x16x32_bf16 v[4:7], v[176:179], v[226:229], v[4:7]
	v_mfma_f32_16x16x32_bf16 v[0:3], v[184:187], v[226:229], v[0:3]
	v_mfma_f32_16x16x32_bf16 v[48:51], v[180:183], v[196:199], v[48:51]
	v_mfma_f32_16x16x32_bf16 v[40:43], v[188:191], v[196:199], v[40:43]
	v_mfma_f32_16x16x32_bf16 v[32:35], v[180:183], v[204:207], v[32:35]
	v_mfma_f32_16x16x32_bf16 v[24:27], v[188:191], v[204:207], v[24:27]
	v_mfma_f32_16x16x32_bf16 v[16:19], v[180:183], v[222:225], v[16:19]
	v_mfma_f32_16x16x32_bf16 v[8:11], v[188:191], v[222:225], v[8:11]
	v_mfma_f32_16x16x32_bf16 v[4:7], v[180:183], v[230:233], v[4:7]
	v_mfma_f32_16x16x32_bf16 v[0:3], v[188:191], v[230:233], v[0:3]
	s_setprio 0
	s_barrier
; #define PG8_STAGE(bufoff, gbase, voff) do { _Pragma("unroll") for (int _i = 0; _i < 2; ++_i) \
;         __builtin_amdgcn_global_load_lds((const unsigned*)((const char*)(gbase) + (voff)[_i]), (PG8_LAS unsigned*)(lds + (bufoff) + ldsw + _i * 8192), 16, 0, 0); } while (0)
; #define PG8_LDA(dst, b, h) do { _Pragma("unroll") for (int m = 0; m < 4; ++m) _Pragma("unroll") for (int k = 0; k < 2; ++k) dst[m][k] = *(const PG8_LAS bf16x8*)(lds + PG8_SA(b, h) + aoff + m * 2048 + k * 1024); } while (0)
; #define PG8_LDB(dst, b, h) do { _Pragma("unroll") for (int n = 0; n < 2; ++n) _Pragma("unroll") for (int k = 0; k < 2; ++k) dst[n][k] = *(const PG8_LAS bf16x8*)(lds + PG8_SB(b, h) + boff + n * 2048 + k * 1024); } while (0)
; #define PG8_MMA(ai, bj, At, Bt) do { __builtin_amdgcn_s_setprio(1); _Pragma("unroll") for (int m = 0; m < 4; ++m) _Pragma("unroll") for (int n = 0; n < 2; ++n) _Pragma("unroll") for (int k = 0; k < 2; ++k) \
;         acc[ai][bj][m][n] = __builtin_amdgcn_mfma_f32_16x16x32_bf16(Bt[n][k], At[m][k], acc[ai][bj][m][n], 0, 0, 0); __builtin_amdgcn_s_setprio(0); } while (0)
; #define PG8_WAIT_V(n) asm volatile("s_waitcnt vmcnt(" #n ")" ::: "memory")
; #define PG8_WAIT_L(n) asm volatile("s_waitcnt lgkmcnt(" #n ")" ::: "memory")
; #define PG8_BAR __builtin_amdgcn_s_barrier()
; #define PG8_SCHED __builtin_amdgcn_sched_barrier(0)
; template <class Epi, class Sched, bool ALIGN_EPI = false, bool SP2 = false>
; __device__ __forceinline__ void gemm_phase(PG8_LAS unsigned char* lds, const Gemm g, const Sched& S, const Epi& E) {
;     ...
;             PG8_LDB(B0, 1, 0); PG8_LDB(B1, 1, 1); PG8_SCHED; PG8_LDA(At, 1, 0); PG8_STAGE(PG8_SA(0, 1), a2 + hstep, voffA);
;             PG8_WAIT_V(8); PG8_WAIT_L(0); PG8_BAR; PG8_MMA(0, 0, At, B0); PG8_MMA(0, 1, At, B1); PG8_BAR; PG8_SCHED;
	s_add_i32 s68, 0, 0x18000
	v_add_u32_e32 v134, s68, v156
	s_add_i32 s69, 0, 0x1c000
	ds_read_b128 v[160:163], v134
	ds_read_b128 v[164:167], v134 offset:1024
	ds_read_b128 v[168:171], v134 offset:2048
	ds_read_b128 v[172:175], v134 offset:3072
	v_add_u32_e32 v134, s69, v156
	ds_read_b128 v[176:179], v134
	ds_read_b128 v[180:183], v134 offset:1024
	ds_read_b128 v[184:187], v134 offset:2048
	ds_read_b128 v[188:191], v134 offset:3072
	s_add_u32 s30, s30, 0x80000
	s_addc_u32 s31, s31, 0
	s_mov_b32 m0, s44
	v_lshl_add_u64 v[236:237], s[30:31], 0, v[146:147]
	ds_read_b128 v[192:195], v158 offset:32768
	ds_read_b128 v[196:199], v158 offset:33792
	ds_read_b128 v[200:203], v158 offset:34816
	ds_read_b128 v[204:207], v158 offset:35840
	ds_read_b128 v[218:221], v158 offset:36864
	ds_read_b128 v[222:225], v158 offset:37888
	ds_read_b128 v[226:229], v158 offset:38912
	ds_read_b128 v[230:233], v158 offset:39936
	global_load_lds_dwordx4 v[236:237], off
	v_lshl_add_u64 v[236:237], s[30:31], 0, v[144:145]
	s_mov_b32 m0, s45
	s_nop 0
	global_load_lds_dwordx4 v[236:237], off
	s_waitcnt vmcnt(8)
	s_waitcnt lgkmcnt(0)
	s_barrier
	s_setprio 1
	s_waitcnt lgkmcnt(0)
	v_mfma_f32_16x16x32_bf16 v[124:127], v[160:163], v[192:195], v[124:127]
	v_mfma_f32_16x16x32_bf16 v[120:123], v[168:171], v[192:195], v[120:123]
	v_mfma_f32_16x16x32_bf16 v[116:119], v[160:163], v[200:203], v[116:119]
	v_mfma_f32_16x16x32_bf16 v[112:115], v[168:171], v[200:203], v[112:115]
	v_mfma_f32_16x16x32_bf16 v[100:103], v[160:163], v[218:221], v[100:103]
	v_mfma_f32_16x16x32_bf16 v[96:99], v[168:171], v[218:221], v[96:99]
	v_mfma_f32_16x16x32_bf16 v[80:83], v[160:163], v[226:229], v[80:83]
	v_mfma_f32_16x16x32_bf16 v[76:79], v[168:171], v[226:229], v[76:79]
	v_mfma_f32_16x16x32_bf16 v[124:127], v[164:167], v[196:199], v[124:127]
	v_mfma_f32_16x16x32_bf16 v[120:123], v[172:175], v[196:199], v[120:123]
	v_mfma_f32_16x16x32_bf16 v[116:119], v[164:167], v[204:207], v[116:119]
	v_mfma_f32_16x16x32_bf16 v[112:115], v[172:175], v[204:207], v[112:115]
	v_mfma_f32_16x16x32_bf16 v[100:103], v[164:167], v[222:225], v[100:103]
	v_mfma_f32_16x16x32_bf16 v[96:99], v[172:175], v[222:225], v[96:99]
	v_mfma_f32_16x16x32_bf16 v[80:83], v[164:167], v[230:233], v[80:83]
	v_mfma_f32_16x16x32_bf16 v[76:79], v[172:175], v[230:233], v[76:79]
	v_mfma_f32_16x16x32_bf16 v[108:111], v[176:179], v[192:195], v[108:111]
	v_mfma_f32_16x16x32_bf16 v[104:107], v[184:187], v[192:195], v[104:107]
	v_mfma_f32_16x16x32_bf16 v[92:95], v[176:179], v[200:203], v[92:95]
	v_mfma_f32_16x16x32_bf16 v[88:91], v[184:187], v[200:203], v[88:91]
	v_mfma_f32_16x16x32_bf16 v[84:87], v[176:179], v[218:221], v[84:87]
	v_mfma_f32_16x16x32_bf16 v[72:75], v[184:187], v[218:221], v[72:75]
	v_mfma_f32_16x16x32_bf16 v[68:71], v[176:179], v[226:229], v[68:71]
	v_mfma_f32_16x16x32_bf16 v[64:67], v[184:187], v[226:229], v[64:67]
	v_mfma_f32_16x16x32_bf16 v[108:111], v[180:183], v[196:199], v[108:111]
	v_mfma_f32_16x16x32_bf16 v[104:107], v[188:191], v[196:199], v[104:107]
	v_mfma_f32_16x16x32_bf16 v[92:95], v[180:183], v[204:207], v[92:95]
	v_mfma_f32_16x16x32_bf16 v[88:91], v[188:191], v[204:207], v[88:91]
	v_mfma_f32_16x16x32_bf16 v[84:87], v[180:183], v[222:225], v[84:87]
	v_mfma_f32_16x16x32_bf16 v[72:75], v[188:191], v[222:225], v[72:75]
	v_mfma_f32_16x16x32_bf16 v[68:71], v[180:183], v[230:233], v[68:71]
	v_mfma_f32_16x16x32_bf16 v[64:67], v[188:191], v[230:233], v[64:67]
	s_setprio 0
	s_barrier
; #define PG8_STAGE(bufoff, gbase, voff) do { _Pragma("unroll") for (int _i = 0; _i < 2; ++_i) \
;         __builtin_amdgcn_global_load_lds((const unsigned*)((const char*)(gbase) + (voff)[_i]), (PG8_LAS unsigned*)(lds + (bufoff) + ldsw + _i * 8192), 16, 0, 0); } while (0)
; #define PG8_LDA(dst, b, h) do { _Pragma("unroll") for (int m = 0; m < 4; ++m) _Pragma("unroll") for (int k = 0; k < 2; ++k) dst[m][k] = *(const PG8_LAS bf16x8*)(lds + PG8_SA(b, h) + aoff + m * 2048 + k * 1024); } while (0)
; #define PG8_WAIT_V(n) asm volatile("s_waitcnt vmcnt(" #n ")" ::: "memory")
; template <class Epi, class Sched, bool ALIGN_EPI = false, bool SP2 = false>
; __device__ __forceinline__ void gemm_phase(PG8_LAS unsigned char* lds, const Gemm g, const Sched& S, const Epi& E) {
;     ...
;             PG8_LDA(At, 1, 1); PG8_STAGE(PG8_SB(1, 0), b3, voffB); PG8_STAGE(PG8_SB(1, 1), b3 + hstep, voffB); PG8_STAGE(PG8_SA(1, 0), a3, voffA);
;             PG8_WAIT_V(8); PG8_WAIT_L(0); PG8_BAR; PG8_MMA(1, 0, At, B0); PG8_MMA(1, 1, At, B1); PG8_BAR; PG8_SCHED;
;             } else {
;             PG8_LDB(B0, 0, 0); PG8_SCHED; PG8_LDA(At, 0, 0); PG8_STAGE(PG8_SA(1, 1), a1 + hstep, voffA);
;             PG8_WAIT_L(8); PG8_BAR; PG8_WAIT_L(0); PG8_MMA(0, 0, At, B0); PG8_BAR; PG8_SCHED;
;             PG8_LDB(B1, 0, 1); PG8_STAGE(PG8_SB(0, 0), b2, voffB);
;             PG8_BAR; PG8_WAIT_L(0); PG8_MMA(0, 1, At, B1); PG8_BAR;
;             PG8_LDA(At, 0, 1); PG8_STAGE(PG8_SA(0, 0), a2, voffA);
;             PG8_BAR; PG8_WAIT_L(0); PG8_MMA(1, 0, At, B0); PG8_BAR; PG8_SCHED;
;             PG8_STAGE(PG8_SB(0, 1), b2 + hstep, voffB);
;             PG8_WAIT_V(6); PG8_BAR; PG8_MMA(1, 1, At, B1); PG8_BAR;
;             PG8_LDB(B0, 1, 0); PG8_SCHED; PG8_LDA(At, 1, 0); PG8_STAGE(PG8_SA(0, 1), a2 + hstep, voffA);
;             PG8_WAIT_L(8); PG8_BAR; PG8_WAIT_L(0); PG8_MMA(0, 0, At, B0); PG8_BAR; PG8_SCHED;
;             PG8_LDB(B1, 1, 1); PG8_STAGE(PG8_SB(1, 0), b3, voffB);
;             PG8_BAR; PG8_WAIT_L(0); PG8_MMA(0, 1, At, B1); PG8_BAR;
;             PG8_LDA(At, 1, 1); PG8_STAGE(PG8_SA(1, 0), a3, voffA);
;             PG8_BAR; PG8_WAIT_L(0); PG8_MMA(1, 0, At, B0); PG8_BAR; PG8_SCHED;
;             PG8_STAGE(PG8_SB(1, 1), b3 + hstep, voffB);
;             PG8_WAIT_V(6); PG8_BAR; PG8_MMA(1, 1, At, B1); PG8_BAR;
;             }
;         }
;         if constexpr (ALIGN_EPI) { if (wr == 0) PG8_BAR; }
	s_add_i32 s30, s68, s39
	v_lshl_add_u64 v[130:131], v[130:131], 0, s[78:79]
	s_mov_b32 m0, s30
	ds_read_b128 v[192:195], v158 offset:49152
	ds_read_b128 v[196:199], v158 offset:50176
	ds_read_b128 v[200:203], v158 offset:51200
	ds_read_b128 v[204:207], v158 offset:52224
	ds_read_b128 v[218:221], v158 offset:53248
	ds_read_b128 v[222:225], v158 offset:54272
	ds_read_b128 v[226:229], v158 offset:55296
	ds_read_b128 v[230:233], v158 offset:56320
	global_load_lds_dwordx4 v[130:131], off
	s_add_i32 m0, s30, 0x2000
	s_add_u32 s28, s28, 0x80080
	v_lshl_add_u64 v[130:131], v[132:133], 0, s[78:79]
	s_addc_u32 s29, s29, 0
	s_add_i32 s30, s69, s39
	global_load_lds_dwordx4 v[130:131], off
	v_lshl_add_u64 v[130:131], s[28:29], 0, v[128:129]
	s_mov_b32 m0, s30
	s_nop 0
	global_load_lds_dwordx4 v[130:131], off
	v_lshl_add_u64 v[130:131], s[28:29], 0, v[142:143]
	s_add_i32 m0, s30, 0x2000
	s_nop 0
	global_load_lds_dwordx4 v[130:131], off
	v_lshl_add_u64 v[130:131], v[154:155], 0, s[78:79]
	s_mov_b32 m0, s55
	s_nop 0
	global_load_lds_dwordx4 v[130:131], off
	v_lshl_add_u64 v[130:131], v[234:235], 0, s[78:79]
	s_mov_b32 m0, s56
	s_nop 0
	global_load_lds_dwordx4 v[130:131], off
	s_waitcnt vmcnt(8)
	s_waitcnt lgkmcnt(0)
	s_barrier
	s_setprio 1
	s_waitcnt lgkmcnt(0)
	v_mfma_f32_16x16x32_bf16 v[60:63], v[160:163], v[192:195], v[60:63]
	v_mfma_f32_16x16x32_bf16 v[56:59], v[168:171], v[192:195], v[56:59]
	v_mfma_f32_16x16x32_bf16 v[52:55], v[160:163], v[200:203], v[52:55]
	v_mfma_f32_16x16x32_bf16 v[44:47], v[168:171], v[200:203], v[44:47]
	v_mfma_f32_16x16x32_bf16 v[36:39], v[160:163], v[218:221], v[36:39]
	v_mfma_f32_16x16x32_bf16 v[28:31], v[168:171], v[218:221], v[28:31]
	v_mfma_f32_16x16x32_bf16 v[20:23], v[160:163], v[226:229], v[20:23]
	v_mfma_f32_16x16x32_bf16 v[12:15], v[168:171], v[226:229], v[12:15]
	v_mfma_f32_16x16x32_bf16 v[60:63], v[164:167], v[196:199], v[60:63]
	v_mfma_f32_16x16x32_bf16 v[56:59], v[172:175], v[196:199], v[56:59]
	v_mfma_f32_16x16x32_bf16 v[52:55], v[164:167], v[204:207], v[52:55]
	v_mfma_f32_16x16x32_bf16 v[44:47], v[172:175], v[204:207], v[44:47]
	v_mfma_f32_16x16x32_bf16 v[36:39], v[164:167], v[222:225], v[36:39]
	v_mfma_f32_16x16x32_bf16 v[28:31], v[172:175], v[222:225], v[28:31]
	v_mfma_f32_16x16x32_bf16 v[20:23], v[164:167], v[230:233], v[20:23]
	v_mfma_f32_16x16x32_bf16 v[12:15], v[172:175], v[230:233], v[12:15]
	v_mfma_f32_16x16x32_bf16 v[48:51], v[176:179], v[192:195], v[48:51]
	v_mfma_f32_16x16x32_bf16 v[40:43], v[184:187], v[192:195], v[40:43]
	v_mfma_f32_16x16x32_bf16 v[32:35], v[176:179], v[200:203], v[32:35]
	v_mfma_f32_16x16x32_bf16 v[24:27], v[184:187], v[200:203], v[24:27]
	v_mfma_f32_16x16x32_bf16 v[16:19], v[176:179], v[218:221], v[16:19]
	v_mfma_f32_16x16x32_bf16 v[8:11], v[184:187], v[218:221], v[8:11]
	v_mfma_f32_16x16x32_bf16 v[4:7], v[176:179], v[226:229], v[4:7]
	v_mfma_f32_16x16x32_bf16 v[0:3], v[184:187], v[226:229], v[0:3]
	v_mfma_f32_16x16x32_bf16 v[48:51], v[180:183], v[196:199], v[48:51]
	v_mfma_f32_16x16x32_bf16 v[40:43], v[188:191], v[196:199], v[40:43]
	v_mfma_f32_16x16x32_bf16 v[32:35], v[180:183], v[204:207], v[32:35]
	v_mfma_f32_16x16x32_bf16 v[24:27], v[188:191], v[204:207], v[24:27]
	v_mfma_f32_16x16x32_bf16 v[16:19], v[180:183], v[222:225], v[16:19]
	v_mfma_f32_16x16x32_bf16 v[8:11], v[188:191], v[222:225], v[8:11]
	v_mfma_f32_16x16x32_bf16 v[4:7], v[180:183], v[230:233], v[4:7]
	v_mfma_f32_16x16x32_bf16 v[0:3], v[188:191], v[230:233], v[0:3]
	s_setprio 0
	s_barrier
	s_add_i32 s62, s62, 2
	s_add_u32 s26, s26, 0x100
	s_addc_u32 s27, s27, 0
	s_add_u32 s60, s60, 0x100
	s_addc_u32 s61, s61, 0
	s_cmp_gt_u32 s62, 29
	s_cbranch_scc0 .LBB0_521
	s_and_b64 vcc, exec, s[14:15]
	s_cbranch_vccz .LBB0_524
	s_barrier

; template <class Epi, class Sched, bool ALIGN_EPI = false, bool SP2 = false>
; __device__ __forceinline__ void gemm_phase(PG8_LAS unsigned char* lds, const Gemm g, const Sched& S, const Epi& E) {
;     ...
;         const bool has_next = S.next(ui + 1, nxt);
;         const char* nA = has_next ? (const char*)g.A + (size_t)nxt.pm * tstep : cA; const char* nB = has_next ? (const char*)g.Bt + (size_t)nxt.pn * tstep : cB;
;         for (int t = 0; t < nt; t += 2) {
;             const bool last = (t == nt - 2);
;             const char* a1 = cA + (size_t)(t + 1) * kstep;
;             const char* a2 = last ? nA : cA + (size_t)(t + 2) * kstep; const char* b2 = last ? nB : cB + (size_t)(t + 2) * kstep;
;             const char* a3 = a2 + kstep; const char* b3 = b2 + kstep;
.LBB0_817:
	s_ashr_i32 s31, s30, 31
	s_lshl_b64 s[26:27], s[30:31], 20
	s_add_u32 s34, s12, s26
	s_addc_u32 s35, s13, s27
	s_and_b64 s[26:27], s[42:43], exec
	s_cselect_b32 s21, s35, s25
	s_cselect_b32 s31, s34, s24
	s_ashr_i32 s29, s28, 31
	s_lshl_b64 s[26:27], s[28:29], 20
	s_add_u32 s26, s39, s26
	s_addc_u32 s27, s54, s27
	s_and_b64 s[68:69], s[42:43], exec
	s_cselect_b32 s29, s27, s81
	s_cselect_b32 s37, s26, s80
	s_add_u32 s68, s80, 0x100

; template <class Epi, class Sched, bool ALIGN_EPI = false, bool SP2 = false>
; __device__ __forceinline__ void gemm_phase(PG8_LAS unsigned char* lds, const Gemm g, const Sched& S, const Epi& E) {
;     ...
;         const char* nA = has_next ? (const char*)g.A + (size_t)nxt.pm * tstep : cA; const char* nB = has_next ? (const char*)g.Bt + (size_t)nxt.pn * tstep : cB;
;         for (int t = 0; t < nt; t += 2) {
;             const bool last = (t == nt - 2);
;             const char* a1 = cA + (size_t)(t + 1) * kstep;
;             const char* a2 = last ? nA : cA + (size_t)(t + 2) * kstep; const char* b2 = last ? nB : cB + (size_t)(t + 2) * kstep;
;             const char* a3 = a2 + kstep; const char* b3 = b2 + kstep;
	s_addc_u32 s69, s81, 0
	s_mov_b32 s74, -2
	s_waitcnt lgkmcnt(0)


; #define PG8_STAGE(bufoff, gbase, voff) do { _Pragma("unroll") for (int _i = 0; _i < 2; ++_i) \
;         __builtin_amdgcn_global_load_lds((const unsigned*)((const char*)(gbase) + (voff)[_i]), (PG8_LAS unsigned*)(lds + (bufoff) + ldsw + _i * 8192), 16, 0, 0); } while (0)
; #define PG8_LDA(dst, b, h) do { _Pragma("unroll") for (int m = 0; m < 4; ++m) _Pragma("unroll") for (int k = 0; k < 2; ++k) dst[m][k] = *(const PG8_LAS bf16x8*)(lds + PG8_SA(b, h) + aoff + m * 2048 + k * 1024); } while (0)
; #define PG8_LDB(dst, b, h) do { _Pragma("unroll") for (int n = 0; n < 2; ++n) _Pragma("unroll") for (int k = 0; k < 2; ++k) dst[n][k] = *(const PG8_LAS bf16x8*)(lds + PG8_SB(b, h) + boff + n * 2048 + k * 1024); } while (0)
; #define PG8_MMA(ai, bj, At, Bt) do { __builtin_amdgcn_s_setprio(1); _Pragma("unroll") for (int m = 0; m < 4; ++m) _Pragma("unroll") for (int n = 0; n < 2; ++n) _Pragma("unroll") for (int k = 0; k < 2; ++k) \
;         acc[ai][bj][m][n] = __builtin_amdgcn_mfma_f32_16x16x32_bf16(Bt[n][k], At[m][k], acc[ai][bj][m][n], 0, 0, 0); __builtin_amdgcn_s_setprio(0); } while (0)
; #define PG8_WAIT_V(n) asm volatile("s_waitcnt vmcnt(" #n ")" ::: "memory")
; #define PG8_WAIT_L(n) asm volatile("s_waitcnt lgkmcnt(" #n ")" ::: "memory")
; #define PG8_BAR __builtin_amdgcn_s_barrier()
; #define PG8_SCHED __builtin_amdgcn_sched_barrier(0)
; template <class Epi, class Sched, bool ALIGN_EPI = false, bool SP2 = false>
; __device__ __forceinline__ void gemm_phase(PG8_LAS unsigned char* lds, const Gemm g, const Sched& S, const Epi& E) {
;     ...
;             PG8_LDB(B0, 0, 0); PG8_LDB(B1, 0, 1); PG8_SCHED; PG8_LDA(At, 0, 0); PG8_STAGE(PG8_SA(1, 1), a1 + hstep, voffA);
;             PG8_WAIT_V(8); PG8_WAIT_L(0); PG8_BAR; PG8_MMA(0, 0, At, B0); PG8_MMA(0, 1, At, B1); PG8_BAR; PG8_SCHED;
;             PG8_LDA(At, 0, 1); PG8_STAGE(PG8_SB(0, 0), b2, voffB); PG8_STAGE(PG8_SB(0, 1), b2 + hstep, voffB); PG8_STAGE(PG8_SA(0, 0), a2, voffA);
	s_add_u32 s80, s24, 0x100
	s_addc_u32 s81, s25, 0
	s_add_i32 s76, 0, 0x10000
	s_cmp_eq_u32 s74, 28
	s_cselect_b32 s97, s21, s81
	s_cselect_b32 s96, s31, s80
	v_add_u32_e32 v130, s76, v191
	s_cselect_b32 vcc_hi, s29, s69
	s_cselect_b32 vcc_lo, s37, s68
	s_add_i32 s77, 0, 0x14000
	ds_read_b128 v[148:151], v130
	ds_read_b128 v[152:155], v130 offset:1024
	ds_read_b128 v[156:159], v130 offset:2048
	ds_read_b128 v[160:163], v130 offset:3072
	v_add_u32_e32 v130, s77, v191
	ds_read_b128 v[164:167], v130
	ds_read_b128 v[168:171], v130 offset:1024
	ds_read_b128 v[172:175], v130 offset:2048
	ds_read_b128 v[176:179], v130 offset:3072
	v_lshl_add_u64 v[130:131], s[24:25], 0, v[144:145]
	s_add_i32 m0, s23, 0xc000
	ds_read_b128 v[180:183], v193
	ds_read_b128 v[184:187], v193 offset:1024
	ds_read_b128 v[194:197], v193 offset:2048
	ds_read_b128 v[198:201], v193 offset:3072
	ds_read_b128 v[202:205], v193 offset:4096
	ds_read_b128 v[218:221], v193 offset:5120
	ds_read_b128 v[222:225], v193 offset:6144
	ds_read_b128 v[226:229], v193 offset:7168
	global_load_lds_dwordx4 v[130:131], off
	v_lshl_add_u64 v[130:131], s[24:25], 0, v[146:147]
	s_add_i32 m0, s23, 0xe000
	s_nop 0
	global_load_lds_dwordx4 v[130:131], off
	s_waitcnt vmcnt(8)
	s_waitcnt lgkmcnt(0)
	s_barrier
	s_setprio 1
	s_waitcnt lgkmcnt(0)
	v_mfma_f32_16x16x32_bf16 v[124:127], v[148:151], v[180:183], 0
	v_mfma_f32_16x16x32_bf16 v[120:123], v[156:159], v[180:183], 0
	v_mfma_f32_16x16x32_bf16 v[108:111], v[148:151], v[194:197], 0
	v_mfma_f32_16x16x32_bf16 v[104:107], v[156:159], v[194:197], 0
	v_mfma_f32_16x16x32_bf16 v[92:95], v[148:151], v[202:205], 0
	v_mfma_f32_16x16x32_bf16 v[88:91], v[156:159], v[202:205], 0
	v_mfma_f32_16x16x32_bf16 v[76:79], v[148:151], v[222:225], 0
	v_mfma_f32_16x16x32_bf16 v[72:75], v[156:159], v[222:225], 0
	v_mfma_f32_16x16x32_bf16 v[124:127], v[152:155], v[184:187], v[124:127]
	v_mfma_f32_16x16x32_bf16 v[120:123], v[160:163], v[184:187], v[120:123]
	v_mfma_f32_16x16x32_bf16 v[108:111], v[152:155], v[198:201], v[108:111]
	v_mfma_f32_16x16x32_bf16 v[104:107], v[160:163], v[198:201], v[104:107]
	v_mfma_f32_16x16x32_bf16 v[92:95], v[152:155], v[218:221], v[92:95]
	v_mfma_f32_16x16x32_bf16 v[88:91], v[160:163], v[218:221], v[88:91]
	v_mfma_f32_16x16x32_bf16 v[76:79], v[152:155], v[226:229], v[76:79]
	v_mfma_f32_16x16x32_bf16 v[72:75], v[160:163], v[226:229], v[72:75]
	v_mfma_f32_16x16x32_bf16 v[116:119], v[164:167], v[180:183], 0
	v_mfma_f32_16x16x32_bf16 v[112:115], v[172:175], v[180:183], 0
	v_mfma_f32_16x16x32_bf16 v[100:103], v[164:167], v[194:197], 0
	v_mfma_f32_16x16x32_bf16 v[96:99], v[172:175], v[194:197], 0
	v_mfma_f32_16x16x32_bf16 v[84:87], v[164:167], v[202:205], 0
	v_mfma_f32_16x16x32_bf16 v[80:83], v[172:175], v[202:205], 0
	v_mfma_f32_16x16x32_bf16 v[68:71], v[164:167], v[222:225], 0
	v_mfma_f32_16x16x32_bf16 v[64:67], v[172:175], v[222:225], 0
	v_mfma_f32_16x16x32_bf16 v[116:119], v[168:171], v[184:187], v[116:119]
	v_mfma_f32_16x16x32_bf16 v[112:115], v[176:179], v[184:187], v[112:115]
	v_mfma_f32_16x16x32_bf16 v[100:103], v[168:171], v[198:201], v[100:103]
	v_mfma_f32_16x16x32_bf16 v[96:99], v[176:179], v[198:201], v[96:99]
	v_mfma_f32_16x16x32_bf16 v[84:87], v[168:171], v[218:221], v[84:87]
	v_mfma_f32_16x16x32_bf16 v[80:83], v[176:179], v[218:221], v[80:83]
	v_mfma_f32_16x16x32_bf16 v[68:71], v[168:171], v[226:229], v[68:71]
	v_mfma_f32_16x16x32_bf16 v[64:67], v[176:179], v[226:229], v[64:67]
	s_setprio 0
	s_barrier
	s_add_i32 s24, s76, s55
	v_lshl_add_u64 v[130:131], vcc, 0, v[128:129]
	s_mov_b32 m0, s24
	ds_read_b128 v[180:183], v193 offset:16384
	ds_read_b128 v[184:187], v193 offset:17408
	ds_read_b128 v[194:197], v193 offset:18432
	ds_read_b128 v[198:201], v193 offset:19456
	ds_read_b128 v[202:205], v193 offset:20480
	ds_read_b128 v[218:221], v193 offset:21504
	ds_read_b128 v[222:225], v193 offset:22528
	ds_read_b128 v[226:229], v193 offset:23552
	global_load_lds_dwordx4 v[130:131], off
	s_add_i32 m0, s24, 0x2000
	s_add_u32 s24, vcc_lo, 0x80000
	v_lshl_add_u64 v[132:133], vcc, 0, v[142:143]
	s_addc_u32 s25, vcc_hi, 0
	s_add_i32 s76, s77, s55
	global_load_lds_dwordx4 v[132:133], off
	v_lshl_add_u64 v[188:189], s[24:25], 0, v[128:129]
	s_mov_b32 m0, s76
	v_lshl_add_u64 v[206:207], s[96:97], 0, v[142:143]
	global_load_lds_dwordx4 v[188:189], off
	v_lshl_add_u64 v[188:189], s[24:25], 0, v[142:143]
	s_add_i32 m0, s76, 0x2000
	s_nop 0
	global_load_lds_dwordx4 v[188:189], off
	v_lshl_add_u64 v[188:189], s[96:97], 0, v[128:129]
	s_mov_b32 m0, s23
	s_nop 0
	global_load_lds_dwordx4 v[188:189], off
	s_mov_b32 m0, s56
	s_nop 0
	global_load_lds_dwordx4 v[206:207], off
	s_waitcnt vmcnt(8)
	s_waitcnt lgkmcnt(0)
	s_barrier
; #define PG8_STAGE(bufoff, gbase, voff) do { _Pragma("unroll") for (int _i = 0; _i < 2; ++_i) \
;         __builtin_amdgcn_global_load_lds((const unsigned*)((const char*)(gbase) + (voff)[_i]), (PG8_LAS unsigned*)(lds + (bufoff) + ldsw + _i * 8192), 16, 0, 0); } while (0)
; #define PG8_LDA(dst, b, h) do { _Pragma("unroll") for (int m = 0; m < 4; ++m) _Pragma("unroll") for (int k = 0; k < 2; ++k) dst[m][k] = *(const PG8_LAS bf16x8*)(lds + PG8_SA(b, h) + aoff + m * 2048 + k * 1024); } while (0)
; #define PG8_LDB(dst, b, h) do { _Pragma("unroll") for (int n = 0; n < 2; ++n) _Pragma("unroll") for (int k = 0; k < 2; ++k) dst[n][k] = *(const PG8_LAS bf16x8*)(lds + PG8_SB(b, h) + boff + n * 2048 + k * 1024); } while (0)
; #define PG8_MMA(ai, bj, At, Bt) do { __builtin_amdgcn_s_setprio(1); _Pragma("unroll") for (int m = 0; m < 4; ++m) _Pragma("unroll") for (int n = 0; n < 2; ++n) _Pragma("unroll") for (int k = 0; k < 2; ++k) \
;         acc[ai][bj][m][n] = __builtin_amdgcn_mfma_f32_16x16x32_bf16(Bt[n][k], At[m][k], acc[ai][bj][m][n], 0, 0, 0); __builtin_amdgcn_s_setprio(0); } while (0)
; #define PG8_WAIT_V(n) asm volatile("s_waitcnt vmcnt(" #n ")" ::: "memory")
; #define PG8_WAIT_L(n) asm volatile("s_waitcnt lgkmcnt(" #n ")" ::: "memory")
; #define PG8_BAR __builtin_amdgcn_s_barrier()
; #define PG8_SCHED __builtin_amdgcn_sched_barrier(0)
; template <class Epi, class Sched, bool ALIGN_EPI = false, bool SP2 = false>
; __device__ __forceinline__ void gemm_phase(PG8_LAS unsigned char* lds, const Gemm g, const Sched& S, const Epi& E) {
;     ...
;             PG8_WAIT_V(8); PG8_WAIT_L(0); PG8_BAR; PG8_MMA(1, 0, At, B0); PG8_MMA(1, 1, At, B1); PG8_BAR; PG8_SCHED;
;             PG8_LDB(B0, 1, 0); PG8_LDB(B1, 1, 1); PG8_SCHED; PG8_LDA(At, 1, 0); PG8_STAGE(PG8_SA(0, 1), a2 + hstep, voffA);
;             PG8_WAIT_V(8); PG8_WAIT_L(0); PG8_BAR; PG8_MMA(0, 0, At, B0); PG8_MMA(0, 1, At, B1); PG8_BAR; PG8_SCHED;
	s_setprio 1
	s_waitcnt lgkmcnt(0)
	v_mfma_f32_16x16x32_bf16 v[60:63], v[148:151], v[180:183], 0
	v_mfma_f32_16x16x32_bf16 v[56:59], v[156:159], v[180:183], 0
	v_mfma_f32_16x16x32_bf16 v[44:47], v[148:151], v[194:197], 0
	v_mfma_f32_16x16x32_bf16 v[40:43], v[156:159], v[194:197], 0
	v_mfma_f32_16x16x32_bf16 v[28:31], v[148:151], v[202:205], 0
	v_mfma_f32_16x16x32_bf16 v[24:27], v[156:159], v[202:205], 0
	v_mfma_f32_16x16x32_bf16 v[12:15], v[148:151], v[222:225], 0
	v_mfma_f32_16x16x32_bf16 v[8:11], v[156:159], v[222:225], 0
	v_mfma_f32_16x16x32_bf16 v[60:63], v[152:155], v[184:187], v[60:63]
	v_mfma_f32_16x16x32_bf16 v[56:59], v[160:163], v[184:187], v[56:59]
	v_mfma_f32_16x16x32_bf16 v[44:47], v[152:155], v[198:201], v[44:47]
	v_mfma_f32_16x16x32_bf16 v[40:43], v[160:163], v[198:201], v[40:43]
	v_mfma_f32_16x16x32_bf16 v[28:31], v[152:155], v[218:221], v[28:31]
	v_mfma_f32_16x16x32_bf16 v[24:27], v[160:163], v[218:221], v[24:27]
	v_mfma_f32_16x16x32_bf16 v[12:15], v[152:155], v[226:229], v[12:15]
	v_mfma_f32_16x16x32_bf16 v[8:11], v[160:163], v[226:229], v[8:11]
	v_mfma_f32_16x16x32_bf16 v[52:55], v[164:167], v[180:183], 0
	v_mfma_f32_16x16x32_bf16 v[48:51], v[172:175], v[180:183], 0
	v_mfma_f32_16x16x32_bf16 v[36:39], v[164:167], v[194:197], 0
	v_mfma_f32_16x16x32_bf16 v[32:35], v[172:175], v[194:197], 0
	v_mfma_f32_16x16x32_bf16 v[20:23], v[164:167], v[202:205], 0
	v_mfma_f32_16x16x32_bf16 v[16:19], v[172:175], v[202:205], 0
	v_mfma_f32_16x16x32_bf16 v[4:7], v[164:167], v[222:225], 0
	v_mfma_f32_16x16x32_bf16 v[0:3], v[172:175], v[222:225], 0
	v_mfma_f32_16x16x32_bf16 v[52:55], v[168:171], v[184:187], v[52:55]
	v_mfma_f32_16x16x32_bf16 v[48:51], v[176:179], v[184:187], v[48:51]
	v_mfma_f32_16x16x32_bf16 v[36:39], v[168:171], v[198:201], v[36:39]
	v_mfma_f32_16x16x32_bf16 v[32:35], v[176:179], v[198:201], v[32:35]
	v_mfma_f32_16x16x32_bf16 v[20:23], v[168:171], v[218:221], v[20:23]
	v_mfma_f32_16x16x32_bf16 v[16:19], v[176:179], v[218:221], v[16:19]
	v_mfma_f32_16x16x32_bf16 v[4:7], v[168:171], v[226:229], v[4:7]
	v_mfma_f32_16x16x32_bf16 v[0:3], v[176:179], v[226:229], v[0:3]
	s_setprio 0
	s_barrier
	s_add_i32 s76, 0, 0x18000
	v_add_u32_e32 v134, s76, v191
	s_add_i32 s77, 0, 0x1c000
	ds_read_b128 v[148:151], v134
	ds_read_b128 v[152:155], v134 offset:1024
	ds_read_b128 v[156:159], v134 offset:2048
	ds_read_b128 v[160:163], v134 offset:3072
	v_add_u32_e32 v134, s77, v191
	ds_read_b128 v[164:167], v134
	ds_read_b128 v[168:171], v134 offset:1024
	ds_read_b128 v[172:175], v134 offset:2048
	ds_read_b128 v[176:179], v134 offset:3072
	s_add_u32 s24, s96, 0x80000
	s_addc_u32 s25, s97, 0
	s_mov_b32 m0, s57
	v_lshl_add_u64 v[230:231], s[24:25], 0, v[128:129]
	ds_read_b128 v[180:183], v193 offset:32768
	ds_read_b128 v[184:187], v193 offset:33792
	ds_read_b128 v[194:197], v193 offset:34816
	ds_read_b128 v[198:201], v193 offset:35840
	ds_read_b128 v[202:205], v193 offset:36864
	ds_read_b128 v[218:221], v193 offset:37888
	ds_read_b128 v[222:225], v193 offset:38912
	ds_read_b128 v[226:229], v193 offset:39936
	global_load_lds_dwordx4 v[230:231], off
	v_lshl_add_u64 v[230:231], s[24:25], 0, v[142:143]
	s_mov_b32 m0, s58
	s_nop 0
	global_load_lds_dwordx4 v[230:231], off
	s_waitcnt vmcnt(8)
	s_waitcnt lgkmcnt(0)
	s_barrier
	s_setprio 1
	s_waitcnt lgkmcnt(0)
	v_mfma_f32_16x16x32_bf16 v[124:127], v[148:151], v[180:183], v[124:127]
	v_mfma_f32_16x16x32_bf16 v[120:123], v[156:159], v[180:183], v[120:123]
	v_mfma_f32_16x16x32_bf16 v[108:111], v[148:151], v[194:197], v[108:111]
	v_mfma_f32_16x16x32_bf16 v[104:107], v[156:159], v[194:197], v[104:107]
	v_mfma_f32_16x16x32_bf16 v[92:95], v[148:151], v[202:205], v[92:95]
	v_mfma_f32_16x16x32_bf16 v[88:91], v[156:159], v[202:205], v[88:91]
	v_mfma_f32_16x16x32_bf16 v[76:79], v[148:151], v[222:225], v[76:79]
	v_mfma_f32_16x16x32_bf16 v[72:75], v[156:159], v[222:225], v[72:75]
	v_mfma_f32_16x16x32_bf16 v[124:127], v[152:155], v[184:187], v[124:127]
	v_mfma_f32_16x16x32_bf16 v[120:123], v[160:163], v[184:187], v[120:123]
	v_mfma_f32_16x16x32_bf16 v[108:111], v[152:155], v[198:201], v[108:111]
	v_mfma_f32_16x16x32_bf16 v[104:107], v[160:163], v[198:201], v[104:107]
	v_mfma_f32_16x16x32_bf16 v[92:95], v[152:155], v[218:221], v[92:95]
	v_mfma_f32_16x16x32_bf16 v[88:91], v[160:163], v[218:221], v[88:91]
	v_mfma_f32_16x16x32_bf16 v[76:79], v[152:155], v[226:229], v[76:79]
	v_mfma_f32_16x16x32_bf16 v[72:75], v[160:163], v[226:229], v[72:75]
	v_mfma_f32_16x16x32_bf16 v[116:119], v[164:167], v[180:183], v[116:119]
	v_mfma_f32_16x16x32_bf16 v[112:115], v[172:175], v[180:183], v[112:115]
	v_mfma_f32_16x16x32_bf16 v[100:103], v[164:167], v[194:197], v[100:103]
	v_mfma_f32_16x16x32_bf16 v[96:99], v[172:175], v[194:197], v[96:99]
	v_mfma_f32_16x16x32_bf16 v[84:87], v[164:167], v[202:205], v[84:87]
	v_mfma_f32_16x16x32_bf16 v[80:83], v[172:175], v[202:205], v[80:83]
	v_mfma_f32_16x16x32_bf16 v[68:71], v[164:167], v[222:225], v[68:71]
	v_mfma_f32_16x16x32_bf16 v[64:67], v[172:175], v[222:225], v[64:67]
	v_mfma_f32_16x16x32_bf16 v[116:119], v[168:171], v[184:187], v[116:119]
	v_mfma_f32_16x16x32_bf16 v[112:115], v[176:179], v[184:187], v[112:115]
	v_mfma_f32_16x16x32_bf16 v[100:103], v[168:171], v[198:201], v[100:103]
	v_mfma_f32_16x16x32_bf16 v[96:99], v[176:179], v[198:201], v[96:99]
	v_mfma_f32_16x16x32_bf16 v[84:87], v[168:171], v[218:221], v[84:87]
	v_mfma_f32_16x16x32_bf16 v[80:83], v[176:179], v[218:221], v[80:83]
	v_mfma_f32_16x16x32_bf16 v[68:71], v[168:171], v[226:229], v[68:71]
	v_mfma_f32_16x16x32_bf16 v[64:67], v[176:179], v[226:229], v[64:67]
	s_setprio 0
	s_barrier
; #define PG8_STAGE(bufoff, gbase, voff) do { _Pragma("unroll") for (int _i = 0; _i < 2; ++_i) \
;         __builtin_amdgcn_global_load_lds((const unsigned*)((const char*)(gbase) + (voff)[_i]), (PG8_LAS unsigned*)(lds + (bufoff) + ldsw + _i * 8192), 16, 0, 0); } while (0)
; #define PG8_LDA(dst, b, h) do { _Pragma("unroll") for (int m = 0; m < 4; ++m) _Pragma("unroll") for (int k = 0; k < 2; ++k) dst[m][k] = *(const PG8_LAS bf16x8*)(lds + PG8_SA(b, h) + aoff + m * 2048 + k * 1024); } while (0)
; #define PG8_LDB(dst, b, h) do { _Pragma("unroll") for (int n = 0; n < 2; ++n) _Pragma("unroll") for (int k = 0; k < 2; ++k) dst[n][k] = *(const PG8_LAS bf16x8*)(lds + PG8_SB(b, h) + boff + n * 2048 + k * 1024); } while (0)
; #define PG8_MMA(ai, bj, At, Bt) do { __builtin_amdgcn_s_setprio(1); _Pragma("unroll") for (int m = 0; m < 4; ++m) _Pragma("unroll") for (int n = 0; n < 2; ++n) _Pragma("unroll") for (int k = 0; k < 2; ++k) \
;         acc[ai][bj][m][n] = __builtin_amdgcn_mfma_f32_16x16x32_bf16(Bt[n][k], At[m][k], acc[ai][bj][m][n], 0, 0, 0); __builtin_amdgcn_s_setprio(0); } while (0)
; #define PG8_WAIT_V(n) asm volatile("s_waitcnt vmcnt(" #n ")" ::: "memory")
; template <class Epi, class Sched, bool ALIGN_EPI = false, bool SP2 = false>
; __device__ __forceinline__ void gemm_phase(PG8_LAS unsigned char* lds, const Gemm g, const Sched& S, const Epi& E) {
;     ...
;             PG8_LDB(B0, 0, 0); PG8_LDB(B1, 0, 1); PG8_SCHED; PG8_LDA(At, 0, 0); PG8_STAGE(PG8_SA(1, 1), a1 + hstep, voffA);
;             PG8_WAIT_V(8); PG8_WAIT_L(0); PG8_BAR; PG8_MMA(0, 0, At, B0); PG8_MMA(0, 1, At, B1); PG8_BAR; PG8_SCHED;
;             PG8_LDA(At, 0, 1); PG8_STAGE(PG8_SB(0, 0), b2, voffB); PG8_STAGE(PG8_SB(0, 1), b2 + hstep, voffB); PG8_STAGE(PG8_SA(0, 0), a2, voffA);
;             PG8_WAIT_V(8); PG8_WAIT_L(0); PG8_BAR; PG8_MMA(1, 0, At, B0); PG8_MMA(1, 1, At, B1); PG8_BAR; PG8_SCHED;
;             PG8_LDB(B0, 1, 0); PG8_LDB(B1, 1, 1); PG8_SCHED; PG8_LDA(At, 1, 0); PG8_STAGE(PG8_SA(0, 1), a2 + hstep, voffA);
;             PG8_WAIT_V(8); PG8_WAIT_L(0); PG8_BAR; PG8_MMA(0, 0, At, B0); PG8_MMA(0, 1, At, B1); PG8_BAR; PG8_SCHED;
;             PG8_LDA(At, 1, 1); PG8_STAGE(PG8_SB(1, 0), b3, voffB); PG8_STAGE(PG8_SB(1, 1), b3 + hstep, voffB); PG8_STAGE(PG8_SA(1, 0), a3, voffA);
;             PG8_WAIT_V(8); PG8_WAIT_L(0); PG8_BAR; PG8_MMA(1, 0, At, B0); PG8_MMA(1, 1, At, B1); PG8_BAR; PG8_SCHED;
	s_add_i32 s24, s76, s55
	v_lshl_add_u64 v[130:131], v[130:131], 0, s[78:79]
	s_mov_b32 m0, s24
	ds_read_b128 v[180:183], v193 offset:49152
	ds_read_b128 v[184:187], v193 offset:50176
	ds_read_b128 v[194:197], v193 offset:51200
	ds_read_b128 v[198:201], v193 offset:52224
	ds_read_b128 v[202:205], v193 offset:53248
	ds_read_b128 v[218:221], v193 offset:54272
	ds_read_b128 v[222:225], v193 offset:55296
	ds_read_b128 v[226:229], v193 offset:56320
	global_load_lds_dwordx4 v[130:131], off
	s_add_i32 m0, s24, 0x2000
	s_add_u32 s24, vcc_lo, 0x80080
	v_lshl_add_u64 v[130:131], v[132:133], 0, s[78:79]
	s_addc_u32 s25, vcc_hi, 0
	s_add_i32 s76, s77, s55
	global_load_lds_dwordx4 v[130:131], off
	v_lshl_add_u64 v[130:131], s[24:25], 0, v[128:129]
	s_mov_b32 m0, s76
	s_nop 0
	global_load_lds_dwordx4 v[130:131], off
	v_lshl_add_u64 v[130:131], s[24:25], 0, v[142:143]
	s_add_i32 m0, s76, 0x2000
	s_nop 0
	global_load_lds_dwordx4 v[130:131], off
	v_lshl_add_u64 v[130:131], v[188:189], 0, s[78:79]
	s_mov_b32 m0, s60
	s_nop 0
	global_load_lds_dwordx4 v[130:131], off
	v_lshl_add_u64 v[130:131], v[206:207], 0, s[78:79]
	s_mov_b32 m0, s61
	s_nop 0
	global_load_lds_dwordx4 v[130:131], off
	s_waitcnt vmcnt(8)
	s_waitcnt lgkmcnt(0)
	s_barrier
	s_setprio 1
	s_waitcnt lgkmcnt(0)
	v_mfma_f32_16x16x32_bf16 v[60:63], v[148:151], v[180:183], v[60:63]
	v_mfma_f32_16x16x32_bf16 v[56:59], v[156:159], v[180:183], v[56:59]
	v_mfma_f32_16x16x32_bf16 v[44:47], v[148:151], v[194:197], v[44:47]
	v_mfma_f32_16x16x32_bf16 v[40:43], v[156:159], v[194:197], v[40:43]
	v_mfma_f32_16x16x32_bf16 v[28:31], v[148:151], v[202:205], v[28:31]
	v_mfma_f32_16x16x32_bf16 v[24:27], v[156:159], v[202:205], v[24:27]
	v_mfma_f32_16x16x32_bf16 v[12:15], v[148:151], v[222:225], v[12:15]
	v_mfma_f32_16x16x32_bf16 v[8:11], v[156:159], v[222:225], v[8:11]
	v_mfma_f32_16x16x32_bf16 v[60:63], v[152:155], v[184:187], v[60:63]
	v_mfma_f32_16x16x32_bf16 v[56:59], v[160:163], v[184:187], v[56:59]
	v_mfma_f32_16x16x32_bf16 v[44:47], v[152:155], v[198:201], v[44:47]
	v_mfma_f32_16x16x32_bf16 v[40:43], v[160:163], v[198:201], v[40:43]
	v_mfma_f32_16x16x32_bf16 v[28:31], v[152:155], v[218:221], v[28:31]
	v_mfma_f32_16x16x32_bf16 v[24:27], v[160:163], v[218:221], v[24:27]
	v_mfma_f32_16x16x32_bf16 v[12:15], v[152:155], v[226:229], v[12:15]
	v_mfma_f32_16x16x32_bf16 v[8:11], v[160:163], v[226:229], v[8:11]
	v_mfma_f32_16x16x32_bf16 v[52:55], v[164:167], v[180:183], v[52:55]
	v_mfma_f32_16x16x32_bf16 v[48:51], v[172:175], v[180:183], v[48:51]
	v_mfma_f32_16x16x32_bf16 v[36:39], v[164:167], v[194:197], v[36:39]
	v_mfma_f32_16x16x32_bf16 v[32:35], v[172:175], v[194:197], v[32:35]
	v_mfma_f32_16x16x32_bf16 v[20:23], v[164:167], v[202:205], v[20:23]
	v_mfma_f32_16x16x32_bf16 v[16:19], v[172:175], v[202:205], v[16:19]
	v_mfma_f32_16x16x32_bf16 v[4:7], v[164:167], v[222:225], v[4:7]
	v_mfma_f32_16x16x32_bf16 v[0:3], v[172:175], v[222:225], v[0:3]
	v_mfma_f32_16x16x32_bf16 v[52:55], v[168:171], v[184:187], v[52:55]
	v_mfma_f32_16x16x32_bf16 v[48:51], v[176:179], v[184:187], v[48:51]
	v_mfma_f32_16x16x32_bf16 v[36:39], v[168:171], v[198:201], v[36:39]
	v_mfma_f32_16x16x32_bf16 v[32:35], v[176:179], v[198:201], v[32:35]
	v_mfma_f32_16x16x32_bf16 v[20:23], v[168:171], v[218:221], v[20:23]
	v_mfma_f32_16x16x32_bf16 v[16:19], v[176:179], v[218:221], v[16:19]
	v_mfma_f32_16x16x32_bf16 v[4:7], v[168:171], v[226:229], v[4:7]
	v_mfma_f32_16x16x32_bf16 v[0:3], v[176:179], v[226:229], v[0:3]
	s_setprio 0
	s_barrier
	s_add_i32 s74, s74, 2
	s_add_u32 s68, s68, 0x100
	s_addc_u32 s69, s69, 0
	s_cmp_gt_u32 s74, 29
	s_mov_b64 s[24:25], s[80:81]
.LBB0_818:
	s_add_u32 s80, s24, 0x100
	s_addc_u32 s81, s25, 0
	s_add_i32 s76, 0, 0x10000
	s_cmp_eq_u32 s74, 28
	s_cselect_b32 s97, s21, s81
	s_cselect_b32 s96, s31, s80
	v_add_u32_e32 v130, s76, v191
	s_cselect_b32 vcc_hi, s29, s69
	s_cselect_b32 vcc_lo, s37, s68
	s_add_i32 s77, 0, 0x14000
	ds_read_b128 v[148:151], v130
	ds_read_b128 v[152:155], v130 offset:1024
	ds_read_b128 v[156:159], v130 offset:2048
	ds_read_b128 v[160:163], v130 offset:3072
	v_add_u32_e32 v130, s77, v191
	ds_read_b128 v[164:167], v130
	ds_read_b128 v[168:171], v130 offset:1024
	ds_read_b128 v[172:175], v130 offset:2048
	ds_read_b128 v[176:179], v130 offset:3072
	v_lshl_add_u64 v[130:131], s[24:25], 0, v[144:145]
	s_add_i32 m0, s23, 0xc000
	ds_read_b128 v[180:183], v193
	ds_read_b128 v[184:187], v193 offset:1024
	ds_read_b128 v[194:197], v193 offset:2048
	ds_read_b128 v[198:201], v193 offset:3072
	ds_read_b128 v[202:205], v193 offset:4096
	ds_read_b128 v[218:221], v193 offset:5120
	ds_read_b128 v[222:225], v193 offset:6144
	ds_read_b128 v[226:229], v193 offset:7168
	global_load_lds_dwordx4 v[130:131], off
	v_lshl_add_u64 v[130:131], s[24:25], 0, v[146:147]
	s_add_i32 m0, s23, 0xe000
	s_nop 0
	global_load_lds_dwordx4 v[130:131], off
	s_waitcnt vmcnt(8)
	s_waitcnt lgkmcnt(0)
	s_barrier
; #define PG8_STAGE(bufoff, gbase, voff) do { _Pragma("unroll") for (int _i = 0; _i < 2; ++_i) \
;         __builtin_amdgcn_global_load_lds((const unsigned*)((const char*)(gbase) + (voff)[_i]), (PG8_LAS unsigned*)(lds + (bufoff) + ldsw + _i * 8192), 16, 0, 0); } while (0)
; #define PG8_LDA(dst, b, h) do { _Pragma("unroll") for (int m = 0; m < 4; ++m) _Pragma("unroll") for (int k = 0; k < 2; ++k) dst[m][k] = *(const PG8_LAS bf16x8*)(lds + PG8_SA(b, h) + aoff + m * 2048 + k * 1024); } while (0)
; #define PG8_LDB(dst, b, h) do { _Pragma("unroll") for (int n = 0; n < 2; ++n) _Pragma("unroll") for (int k = 0; k < 2; ++k) dst[n][k] = *(const PG8_LAS bf16x8*)(lds + PG8_SB(b, h) + boff + n * 2048 + k * 1024); } while (0)
; #define PG8_MMA(ai, bj, At, Bt) do { __builtin_amdgcn_s_setprio(1); _Pragma("unroll") for (int m = 0; m < 4; ++m) _Pragma("unroll") for (int n = 0; n < 2; ++n) _Pragma("unroll") for (int k = 0; k < 2; ++k) \
;         acc[ai][bj][m][n] = __builtin_amdgcn_mfma_f32_16x16x32_bf16(Bt[n][k], At[m][k], acc[ai][bj][m][n], 0, 0, 0); __builtin_amdgcn_s_setprio(0); } while (0)
; #define PG8_WAIT_V(n) asm volatile("s_waitcnt vmcnt(" #n ")" ::: "memory")
; #define PG8_WAIT_L(n) asm volatile("s_waitcnt lgkmcnt(" #n ")" ::: "memory")
; #define PG8_BAR __builtin_amdgcn_s_barrier()
; #define PG8_SCHED __builtin_amdgcn_sched_barrier(0)
; template <class Epi, class Sched, bool ALIGN_EPI = false, bool SP2 = false>
; __device__ __forceinline__ void gemm_phase(PG8_LAS unsigned char* lds, const Gemm g, const Sched& S, const Epi& E) {
;     ...
;             PG8_LDB(B0, 0, 0); PG8_LDB(B1, 0, 1); PG8_SCHED; PG8_LDA(At, 0, 0); PG8_STAGE(PG8_SA(1, 1), a1 + hstep, voffA);
;             PG8_WAIT_V(8); PG8_WAIT_L(0); PG8_BAR; PG8_MMA(0, 0, At, B0); PG8_MMA(0, 1, At, B1); PG8_BAR; PG8_SCHED;
;             PG8_LDA(At, 0, 1); PG8_STAGE(PG8_SB(0, 0), b2, voffB); PG8_STAGE(PG8_SB(0, 1), b2 + hstep, voffB); PG8_STAGE(PG8_SA(0, 0), a2, voffA);
;             PG8_WAIT_V(8); PG8_WAIT_L(0); PG8_BAR; PG8_MMA(1, 0, At, B0); PG8_MMA(1, 1, At, B1); PG8_BAR; PG8_SCHED;
	s_setprio 1
	s_waitcnt lgkmcnt(0)
	v_mfma_f32_16x16x32_bf16 v[124:127], v[148:151], v[180:183], v[124:127]
	v_mfma_f32_16x16x32_bf16 v[120:123], v[156:159], v[180:183], v[120:123]
	v_mfma_f32_16x16x32_bf16 v[108:111], v[148:151], v[194:197], v[108:111]
	v_mfma_f32_16x16x32_bf16 v[104:107], v[156:159], v[194:197], v[104:107]
	v_mfma_f32_16x16x32_bf16 v[92:95], v[148:151], v[202:205], v[92:95]
	v_mfma_f32_16x16x32_bf16 v[88:91], v[156:159], v[202:205], v[88:91]
	v_mfma_f32_16x16x32_bf16 v[76:79], v[148:151], v[222:225], v[76:79]
	v_mfma_f32_16x16x32_bf16 v[72:75], v[156:159], v[222:225], v[72:75]
	v_mfma_f32_16x16x32_bf16 v[124:127], v[152:155], v[184:187], v[124:127]
	v_mfma_f32_16x16x32_bf16 v[120:123], v[160:163], v[184:187], v[120:123]
	v_mfma_f32_16x16x32_bf16 v[108:111], v[152:155], v[198:201], v[108:111]
	v_mfma_f32_16x16x32_bf16 v[104:107], v[160:163], v[198:201], v[104:107]
	v_mfma_f32_16x16x32_bf16 v[92:95], v[152:155], v[218:221], v[92:95]
	v_mfma_f32_16x16x32_bf16 v[88:91], v[160:163], v[218:221], v[88:91]
	v_mfma_f32_16x16x32_bf16 v[76:79], v[152:155], v[226:229], v[76:79]
	v_mfma_f32_16x16x32_bf16 v[72:75], v[160:163], v[226:229], v[72:75]
	v_mfma_f32_16x16x32_bf16 v[116:119], v[164:167], v[180:183], v[116:119]
	v_mfma_f32_16x16x32_bf16 v[112:115], v[172:175], v[180:183], v[112:115]
	v_mfma_f32_16x16x32_bf16 v[100:103], v[164:167], v[194:197], v[100:103]
	v_mfma_f32_16x16x32_bf16 v[96:99], v[172:175], v[194:197], v[96:99]
	v_mfma_f32_16x16x32_bf16 v[84:87], v[164:167], v[202:205], v[84:87]
	v_mfma_f32_16x16x32_bf16 v[80:83], v[172:175], v[202:205], v[80:83]
	v_mfma_f32_16x16x32_bf16 v[68:71], v[164:167], v[222:225], v[68:71]
	v_mfma_f32_16x16x32_bf16 v[64:67], v[172:175], v[222:225], v[64:67]
	v_mfma_f32_16x16x32_bf16 v[116:119], v[168:171], v[184:187], v[116:119]
	v_mfma_f32_16x16x32_bf16 v[112:115], v[176:179], v[184:187], v[112:115]
	v_mfma_f32_16x16x32_bf16 v[100:103], v[168:171], v[198:201], v[100:103]
	v_mfma_f32_16x16x32_bf16 v[96:99], v[176:179], v[198:201], v[96:99]
	v_mfma_f32_16x16x32_bf16 v[84:87], v[168:171], v[218:221], v[84:87]
	v_mfma_f32_16x16x32_bf16 v[80:83], v[176:179], v[218:221], v[80:83]
	v_mfma_f32_16x16x32_bf16 v[68:71], v[168:171], v[226:229], v[68:71]
	v_mfma_f32_16x16x32_bf16 v[64:67], v[176:179], v[226:229], v[64:67]
	s_setprio 0
	s_barrier
	s_add_i32 s24, s76, s55
	v_lshl_add_u64 v[130:131], vcc, 0, v[128:129]
	s_mov_b32 m0, s24
	ds_read_b128 v[180:183], v193 offset:16384
	ds_read_b128 v[184:187], v193 offset:17408
	ds_read_b128 v[194:197], v193 offset:18432
	ds_read_b128 v[198:201], v193 offset:19456
	ds_read_b128 v[202:205], v193 offset:20480
	ds_read_b128 v[218:221], v193 offset:21504
	ds_read_b128 v[222:225], v193 offset:22528
	ds_read_b128 v[226:229], v193 offset:23552
	global_load_lds_dwordx4 v[130:131], off
	s_add_i32 m0, s24, 0x2000
	s_add_u32 s24, vcc_lo, 0x80000
	v_lshl_add_u64 v[132:133], vcc, 0, v[142:143]
	s_addc_u32 s25, vcc_hi, 0
	s_add_i32 s76, s77, s55
	global_load_lds_dwordx4 v[132:133], off
	v_lshl_add_u64 v[188:189], s[24:25], 0, v[128:129]
	s_mov_b32 m0, s76
	v_lshl_add_u64 v[206:207], s[96:97], 0, v[142:143]
	global_load_lds_dwordx4 v[188:189], off
	v_lshl_add_u64 v[188:189], s[24:25], 0, v[142:143]
	s_add_i32 m0, s76, 0x2000
	s_nop 0
	global_load_lds_dwordx4 v[188:189], off
	v_lshl_add_u64 v[188:189], s[96:97], 0, v[128:129]
	s_mov_b32 m0, s23
	s_nop 0
	global_load_lds_dwordx4 v[188:189], off
	s_mov_b32 m0, s56
	s_nop 0
	global_load_lds_dwordx4 v[206:207], off
	s_waitcnt vmcnt(8)
	s_waitcnt lgkmcnt(0)
	s_barrier
	s_setprio 1
	s_waitcnt lgkmcnt(0)
	v_mfma_f32_16x16x32_bf16 v[60:63], v[148:151], v[180:183], v[60:63]
	v_mfma_f32_16x16x32_bf16 v[56:59], v[156:159], v[180:183], v[56:59]
	v_mfma_f32_16x16x32_bf16 v[44:47], v[148:151], v[194:197], v[44:47]
	v_mfma_f32_16x16x32_bf16 v[40:43], v[156:159], v[194:197], v[40:43]
	v_mfma_f32_16x16x32_bf16 v[28:31], v[148:151], v[202:205], v[28:31]
	v_mfma_f32_16x16x32_bf16 v[24:27], v[156:159], v[202:205], v[24:27]
	v_mfma_f32_16x16x32_bf16 v[12:15], v[148:151], v[222:225], v[12:15]
	v_mfma_f32_16x16x32_bf16 v[8:11], v[156:159], v[222:225], v[8:11]
	v_mfma_f32_16x16x32_bf16 v[60:63], v[152:155], v[184:187], v[60:63]
	v_mfma_f32_16x16x32_bf16 v[56:59], v[160:163], v[184:187], v[56:59]
	v_mfma_f32_16x16x32_bf16 v[44:47], v[152:155], v[198:201], v[44:47]
	v_mfma_f32_16x16x32_bf16 v[40:43], v[160:163], v[198:201], v[40:43]
	v_mfma_f32_16x16x32_bf16 v[28:31], v[152:155], v[218:221], v[28:31]
	v_mfma_f32_16x16x32_bf16 v[24:27], v[160:163], v[218:221], v[24:27]
	v_mfma_f32_16x16x32_bf16 v[12:15], v[152:155], v[226:229], v[12:15]
	v_mfma_f32_16x16x32_bf16 v[8:11], v[160:163], v[226:229], v[8:11]
	v_mfma_f32_16x16x32_bf16 v[52:55], v[164:167], v[180:183], v[52:55]
	v_mfma_f32_16x16x32_bf16 v[48:51], v[172:175], v[180:183], v[48:51]
	v_mfma_f32_16x16x32_bf16 v[36:39], v[164:167], v[194:197], v[36:39]
	v_mfma_f32_16x16x32_bf16 v[32:35], v[172:175], v[194:197], v[32:35]
	v_mfma_f32_16x16x32_bf16 v[20:23], v[164:167], v[202:205], v[20:23]
	v_mfma_f32_16x16x32_bf16 v[16:19], v[172:175], v[202:205], v[16:19]
	v_mfma_f32_16x16x32_bf16 v[4:7], v[164:167], v[222:225], v[4:7]
	v_mfma_f32_16x16x32_bf16 v[0:3], v[172:175], v[222:225], v[0:3]
	v_mfma_f32_16x16x32_bf16 v[52:55], v[168:171], v[184:187], v[52:55]
	v_mfma_f32_16x16x32_bf16 v[48:51], v[176:179], v[184:187], v[48:51]
	v_mfma_f32_16x16x32_bf16 v[36:39], v[168:171], v[198:201], v[36:39]
	v_mfma_f32_16x16x32_bf16 v[32:35], v[176:179], v[198:201], v[32:35]
	v_mfma_f32_16x16x32_bf16 v[20:23], v[168:171], v[218:221], v[20:23]
	v_mfma_f32_16x16x32_bf16 v[16:19], v[176:179], v[218:221], v[16:19]
	v_mfma_f32_16x16x32_bf16 v[4:7], v[168:171], v[226:229], v[4:7]
	v_mfma_f32_16x16x32_bf16 v[0:3], v[176:179], v[226:229], v[0:3]
	s_setprio 0
	s_barrier
; #define PG8_STAGE(bufoff, gbase, voff) do { _Pragma("unroll") for (int _i = 0; _i < 2; ++_i) \
;         __builtin_amdgcn_global_load_lds((const unsigned*)((const char*)(gbase) + (voff)[_i]), (PG8_LAS unsigned*)(lds + (bufoff) + ldsw + _i * 8192), 16, 0, 0); } while (0)
; #define PG8_LDA(dst, b, h) do { _Pragma("unroll") for (int m = 0; m < 4; ++m) _Pragma("unroll") for (int k = 0; k < 2; ++k) dst[m][k] = *(const PG8_LAS bf16x8*)(lds + PG8_SA(b, h) + aoff + m * 2048 + k * 1024); } while (0)
; #define PG8_LDB(dst, b, h) do { _Pragma("unroll") for (int n = 0; n < 2; ++n) _Pragma("unroll") for (int k = 0; k < 2; ++k) dst[n][k] = *(const PG8_LAS bf16x8*)(lds + PG8_SB(b, h) + boff + n * 2048 + k * 1024); } while (0)
; #define PG8_MMA(ai, bj, At, Bt) do { __builtin_amdgcn_s_setprio(1); _Pragma("unroll") for (int m = 0; m < 4; ++m) _Pragma("unroll") for (int n = 0; n < 2; ++n) _Pragma("unroll") for (int k = 0; k < 2; ++k) \
;         acc[ai][bj][m][n] = __builtin_amdgcn_mfma_f32_16x16x32_bf16(Bt[n][k], At[m][k], acc[ai][bj][m][n], 0, 0, 0); __builtin_amdgcn_s_setprio(0); } while (0)
; #define PG8_WAIT_V(n) asm volatile("s_waitcnt vmcnt(" #n ")" ::: "memory")
; #define PG8_WAIT_L(n) asm volatile("s_waitcnt lgkmcnt(" #n ")" ::: "memory")
; #define PG8_BAR __builtin_amdgcn_s_barrier()
; #define PG8_SCHED __builtin_amdgcn_sched_barrier(0)
; template <class Epi, class Sched, bool ALIGN_EPI = false, bool SP2 = false>
; __device__ __forceinline__ void gemm_phase(PG8_LAS unsigned char* lds, const Gemm g, const Sched& S, const Epi& E) {
;     ...
;             PG8_LDB(B0, 1, 0); PG8_LDB(B1, 1, 1); PG8_SCHED; PG8_LDA(At, 1, 0); PG8_STAGE(PG8_SA(0, 1), a2 + hstep, voffA);
;             PG8_WAIT_V(8); PG8_WAIT_L(0); PG8_BAR; PG8_MMA(0, 0, At, B0); PG8_MMA(0, 1, At, B1); PG8_BAR; PG8_SCHED;
	s_add_i32 s76, 0, 0x18000
	v_add_u32_e32 v134, s76, v191
	s_add_i32 s77, 0, 0x1c000
	ds_read_b128 v[148:151], v134
	ds_read_b128 v[152:155], v134 offset:1024
	ds_read_b128 v[156:159], v134 offset:2048
	ds_read_b128 v[160:163], v134 offset:3072
	v_add_u32_e32 v134, s77, v191
	ds_read_b128 v[164:167], v134
	ds_read_b128 v[168:171], v134 offset:1024
	ds_read_b128 v[172:175], v134 offset:2048
	ds_read_b128 v[176:179], v134 offset:3072
	s_add_u32 s24, s96, 0x80000
	s_addc_u32 s25, s97, 0
	s_mov_b32 m0, s57
	v_lshl_add_u64 v[230:231], s[24:25], 0, v[128:129]
	ds_read_b128 v[180:183], v193 offset:32768
	ds_read_b128 v[184:187], v193 offset:33792
	ds_read_b128 v[194:197], v193 offset:34816
	ds_read_b128 v[198:201], v193 offset:35840
	ds_read_b128 v[202:205], v193 offset:36864
	ds_read_b128 v[218:221], v193 offset:37888
	ds_read_b128 v[222:225], v193 offset:38912
	ds_read_b128 v[226:229], v193 offset:39936
	global_load_lds_dwordx4 v[230:231], off
	v_lshl_add_u64 v[230:231], s[24:25], 0, v[142:143]
	s_mov_b32 m0, s58
	s_nop 0
	global_load_lds_dwordx4 v[230:231], off
	s_waitcnt vmcnt(8)
	s_waitcnt lgkmcnt(0)
	s_barrier
	s_setprio 1
	s_waitcnt lgkmcnt(0)
	v_mfma_f32_16x16x32_bf16 v[124:127], v[148:151], v[180:183], v[124:127]
	v_mfma_f32_16x16x32_bf16 v[120:123], v[156:159], v[180:183], v[120:123]
	v_mfma_f32_16x16x32_bf16 v[108:111], v[148:151], v[194:197], v[108:111]
	v_mfma_f32_16x16x32_bf16 v[104:107], v[156:159], v[194:197], v[104:107]
	v_mfma_f32_16x16x32_bf16 v[92:95], v[148:151], v[202:205], v[92:95]
	v_mfma_f32_16x16x32_bf16 v[88:91], v[156:159], v[202:205], v[88:91]
	v_mfma_f32_16x16x32_bf16 v[76:79], v[148:151], v[222:225], v[76:79]
	v_mfma_f32_16x16x32_bf16 v[72:75], v[156:159], v[222:225], v[72:75]
	v_mfma_f32_16x16x32_bf16 v[124:127], v[152:155], v[184:187], v[124:127]
	v_mfma_f32_16x16x32_bf16 v[120:123], v[160:163], v[184:187], v[120:123]
	v_mfma_f32_16x16x32_bf16 v[108:111], v[152:155], v[198:201], v[108:111]
	v_mfma_f32_16x16x32_bf16 v[104:107], v[160:163], v[198:201], v[104:107]
	v_mfma_f32_16x16x32_bf16 v[92:95], v[152:155], v[218:221], v[92:95]
	v_mfma_f32_16x16x32_bf16 v[88:91], v[160:163], v[218:221], v[88:91]
	v_mfma_f32_16x16x32_bf16 v[76:79], v[152:155], v[226:229], v[76:79]
	v_mfma_f32_16x16x32_bf16 v[72:75], v[160:163], v[226:229], v[72:75]
	v_mfma_f32_16x16x32_bf16 v[116:119], v[164:167], v[180:183], v[116:119]
	v_mfma_f32_16x16x32_bf16 v[112:115], v[172:175], v[180:183], v[112:115]
	v_mfma_f32_16x16x32_bf16 v[100:103], v[164:167], v[194:197], v[100:103]
	v_mfma_f32_16x16x32_bf16 v[96:99], v[172:175], v[194:197], v[96:99]
	v_mfma_f32_16x16x32_bf16 v[84:87], v[164:167], v[202:205], v[84:87]
	v_mfma_f32_16x16x32_bf16 v[80:83], v[172:175], v[202:205], v[80:83]
	v_mfma_f32_16x16x32_bf16 v[68:71], v[164:167], v[222:225], v[68:71]
	v_mfma_f32_16x16x32_bf16 v[64:67], v[172:175], v[222:225], v[64:67]
	v_mfma_f32_16x16x32_bf16 v[116:119], v[168:171], v[184:187], v[116:119]
	v_mfma_f32_16x16x32_bf16 v[112:115], v[176:179], v[184:187], v[112:115]
	v_mfma_f32_16x16x32_bf16 v[100:103], v[168:171], v[198:201], v[100:103]
	v_mfma_f32_16x16x32_bf16 v[96:99], v[176:179], v[198:201], v[96:99]
	v_mfma_f32_16x16x32_bf16 v[84:87], v[168:171], v[218:221], v[84:87]
	v_mfma_f32_16x16x32_bf16 v[80:83], v[176:179], v[218:221], v[80:83]
	v_mfma_f32_16x16x32_bf16 v[68:71], v[168:171], v[226:229], v[68:71]
	v_mfma_f32_16x16x32_bf16 v[64:67], v[176:179], v[226:229], v[64:67]
	s_setprio 0
	s_barrier
; #define PG8_STAGE(bufoff, gbase, voff) do { _Pragma("unroll") for (int _i = 0; _i < 2; ++_i) \
;         __builtin_amdgcn_global_load_lds((const unsigned*)((const char*)(gbase) + (voff)[_i]), (PG8_LAS unsigned*)(lds + (bufoff) + ldsw + _i * 8192), 16, 0, 0); } while (0)
; #define PG8_LDA(dst, b, h) do { _Pragma("unroll") for (int m = 0; m < 4; ++m) _Pragma("unroll") for (int k = 0; k < 2; ++k) dst[m][k] = *(const PG8_LAS bf16x8*)(lds + PG8_SA(b, h) + aoff + m * 2048 + k * 1024); } while (0)
; #define PG8_WAIT_V(n) asm volatile("s_waitcnt vmcnt(" #n ")" ::: "memory")
; template <class Epi, class Sched, bool ALIGN_EPI = false, bool SP2 = false>
; __device__ __forceinline__ void gemm_phase(PG8_LAS unsigned char* lds, const Gemm g, const Sched& S, const Epi& E) {
;     ...
;             PG8_LDA(At, 1, 1); PG8_STAGE(PG8_SB(1, 0), b3, voffB); PG8_STAGE(PG8_SB(1, 1), b3 + hstep, voffB); PG8_STAGE(PG8_SA(1, 0), a3, voffA);
;             PG8_WAIT_V(8); PG8_WAIT_L(0); PG8_BAR; PG8_MMA(1, 0, At, B0); PG8_MMA(1, 1, At, B1); PG8_BAR; PG8_SCHED;
;             } else {
;             PG8_LDB(B0, 0, 0); PG8_SCHED; PG8_LDA(At, 0, 0); PG8_STAGE(PG8_SA(1, 1), a1 + hstep, voffA);
;             PG8_WAIT_L(8); PG8_BAR; PG8_WAIT_L(0); PG8_MMA(0, 0, At, B0); PG8_BAR; PG8_SCHED;
;             PG8_LDB(B1, 0, 1); PG8_STAGE(PG8_SB(0, 0), b2, voffB);
;             PG8_BAR; PG8_WAIT_L(0); PG8_MMA(0, 1, At, B1); PG8_BAR;
;             PG8_LDA(At, 0, 1); PG8_STAGE(PG8_SA(0, 0), a2, voffA);
;             PG8_BAR; PG8_WAIT_L(0); PG8_MMA(1, 0, At, B0); PG8_BAR; PG8_SCHED;
;             PG8_STAGE(PG8_SB(0, 1), b2 + hstep, voffB);
;             PG8_WAIT_V(6); PG8_BAR; PG8_MMA(1, 1, At, B1); PG8_BAR;
;             PG8_LDB(B0, 1, 0); PG8_SCHED; PG8_LDA(At, 1, 0); PG8_STAGE(PG8_SA(0, 1), a2 + hstep, voffA);
;             PG8_WAIT_L(8); PG8_BAR; PG8_WAIT_L(0); PG8_MMA(0, 0, At, B0); PG8_BAR; PG8_SCHED;
;             PG8_LDB(B1, 1, 1); PG8_STAGE(PG8_SB(1, 0), b3, voffB);
;             PG8_BAR; PG8_WAIT_L(0); PG8_MMA(0, 1, At, B1); PG8_BAR;
;             PG8_LDA(At, 1, 1); PG8_STAGE(PG8_SA(1, 0), a3, voffA);
;             PG8_BAR; PG8_WAIT_L(0); PG8_MMA(1, 0, At, B0); PG8_BAR; PG8_SCHED;
;             PG8_STAGE(PG8_SB(1, 1), b3 + hstep, voffB);
;             PG8_WAIT_V(6); PG8_BAR; PG8_MMA(1, 1, At, B1); PG8_BAR;
;             }
;         }
;         if constexpr (ALIGN_EPI) { if (wr == 0) PG8_BAR; }
	s_add_i32 s24, s76, s55
	v_lshl_add_u64 v[130:131], v[130:131], 0, s[78:79]
	s_mov_b32 m0, s24
	ds_read_b128 v[180:183], v193 offset:49152
	ds_read_b128 v[184:187], v193 offset:50176
	ds_read_b128 v[194:197], v193 offset:51200
	ds_read_b128 v[198:201], v193 offset:52224
	ds_read_b128 v[202:205], v193 offset:53248
	ds_read_b128 v[218:221], v193 offset:54272
	ds_read_b128 v[222:225], v193 offset:55296
	ds_read_b128 v[226:229], v193 offset:56320
	global_load_lds_dwordx4 v[130:131], off
	s_add_i32 m0, s24, 0x2000
	s_add_u32 s24, vcc_lo, 0x80080
	v_lshl_add_u64 v[130:131], v[132:133], 0, s[78:79]
	s_addc_u32 s25, vcc_hi, 0
	s_add_i32 s76, s77, s55
	global_load_lds_dwordx4 v[130:131], off
	v_lshl_add_u64 v[130:131], s[24:25], 0, v[128:129]
	s_mov_b32 m0, s76
	s_nop 0
	global_load_lds_dwordx4 v[130:131], off
	v_lshl_add_u64 v[130:131], s[24:25], 0, v[142:143]
	s_add_i32 m0, s76, 0x2000
	s_nop 0
	global_load_lds_dwordx4 v[130:131], off
	v_lshl_add_u64 v[130:131], v[188:189], 0, s[78:79]
	s_mov_b32 m0, s60
	s_nop 0
	global_load_lds_dwordx4 v[130:131], off
	v_lshl_add_u64 v[130:131], v[206:207], 0, s[78:79]
	s_mov_b32 m0, s61
	s_nop 0
	global_load_lds_dwordx4 v[130:131], off
	s_waitcnt vmcnt(8)
	s_waitcnt lgkmcnt(0)
	s_barrier
	s_setprio 1
	s_waitcnt lgkmcnt(0)
	v_mfma_f32_16x16x32_bf16 v[60:63], v[148:151], v[180:183], v[60:63]
	v_mfma_f32_16x16x32_bf16 v[56:59], v[156:159], v[180:183], v[56:59]
	v_mfma_f32_16x16x32_bf16 v[44:47], v[148:151], v[194:197], v[44:47]
	v_mfma_f32_16x16x32_bf16 v[40:43], v[156:159], v[194:197], v[40:43]
	v_mfma_f32_16x16x32_bf16 v[28:31], v[148:151], v[202:205], v[28:31]
	v_mfma_f32_16x16x32_bf16 v[24:27], v[156:159], v[202:205], v[24:27]
	v_mfma_f32_16x16x32_bf16 v[12:15], v[148:151], v[222:225], v[12:15]
	v_mfma_f32_16x16x32_bf16 v[8:11], v[156:159], v[222:225], v[8:11]
	v_mfma_f32_16x16x32_bf16 v[60:63], v[152:155], v[184:187], v[60:63]
	v_mfma_f32_16x16x32_bf16 v[56:59], v[160:163], v[184:187], v[56:59]
	v_mfma_f32_16x16x32_bf16 v[44:47], v[152:155], v[198:201], v[44:47]
	v_mfma_f32_16x16x32_bf16 v[40:43], v[160:163], v[198:201], v[40:43]
	v_mfma_f32_16x16x32_bf16 v[28:31], v[152:155], v[218:221], v[28:31]
	v_mfma_f32_16x16x32_bf16 v[24:27], v[160:163], v[218:221], v[24:27]
	v_mfma_f32_16x16x32_bf16 v[12:15], v[152:155], v[226:229], v[12:15]
	v_mfma_f32_16x16x32_bf16 v[8:11], v[160:163], v[226:229], v[8:11]
	v_mfma_f32_16x16x32_bf16 v[52:55], v[164:167], v[180:183], v[52:55]
	v_mfma_f32_16x16x32_bf16 v[48:51], v[172:175], v[180:183], v[48:51]
	v_mfma_f32_16x16x32_bf16 v[36:39], v[164:167], v[194:197], v[36:39]
	v_mfma_f32_16x16x32_bf16 v[32:35], v[172:175], v[194:197], v[32:35]
	v_mfma_f32_16x16x32_bf16 v[20:23], v[164:167], v[202:205], v[20:23]
	v_mfma_f32_16x16x32_bf16 v[16:19], v[172:175], v[202:205], v[16:19]
	v_mfma_f32_16x16x32_bf16 v[4:7], v[164:167], v[222:225], v[4:7]
	v_mfma_f32_16x16x32_bf16 v[0:3], v[172:175], v[222:225], v[0:3]
	v_mfma_f32_16x16x32_bf16 v[52:55], v[168:171], v[184:187], v[52:55]
	v_mfma_f32_16x16x32_bf16 v[48:51], v[176:179], v[184:187], v[48:51]
	v_mfma_f32_16x16x32_bf16 v[36:39], v[168:171], v[198:201], v[36:39]
	v_mfma_f32_16x16x32_bf16 v[32:35], v[176:179], v[198:201], v[32:35]
	v_mfma_f32_16x16x32_bf16 v[20:23], v[168:171], v[218:221], v[20:23]
	v_mfma_f32_16x16x32_bf16 v[16:19], v[176:179], v[218:221], v[16:19]
	v_mfma_f32_16x16x32_bf16 v[4:7], v[168:171], v[226:229], v[4:7]
	v_mfma_f32_16x16x32_bf16 v[0:3], v[176:179], v[226:229], v[0:3]
	s_setprio 0
	s_barrier
	s_add_i32 s74, s74, 2
	s_add_u32 s68, s68, 0x100
	s_addc_u32 s69, s69, 0
	s_cmp_gt_u32 s74, 29
	s_mov_b64 s[24:25], s[80:81]
	s_cbranch_scc0 .LBB0_818
	s_and_b64 vcc, exec, s[18:19]
	s_cbranch_vccz .LBB0_821
	s_barrier

; template <class Epi, class Sched, bool ALIGN_EPI = false, bool SP2 = false>
; __device__ __forceinline__ void gemm_phase(PG8_LAS unsigned char* lds, const Gemm g, const Sched& S, const Epi& E) {
;     ...
;         const bool has_next = S.next(ui + 1, nxt);
;         const char* nA = has_next ? (const char*)g.A + (size_t)nxt.pm * tstep : cA; const char* nB = has_next ? (const char*)g.Bt + (size_t)nxt.pn * tstep : cB;
;         for (int t = 0; t < nt; t += 2) {
;             const bool last = (t == nt - 2);
;             const char* a1 = cA + (size_t)(t + 1) * kstep;
;             const char* a2 = last ? nA : cA + (size_t)(t + 2) * kstep; const char* b2 = last ? nB : cB + (size_t)(t + 2) * kstep;
;             const char* a3 = a2 + kstep; const char* b3 = b2 + kstep;
.LBB0_954:
	s_ashr_i32 s23, s22, 31
	s_lshl_b64 s[24:25], s[22:23], 20
	s_add_u32 s24, s38, s24
	s_addc_u32 s25, s39, s25
	s_and_b64 s[26:27], s[40:41], exec
	s_cselect_b32 s23, s25, s31
	s_cselect_b32 s60, s24, s30
	s_ashr_i32 s21, s20, 31
	s_lshl_b64 s[26:27], s[20:21], 20
	s_add_u32 s26, s54, s26
	s_addc_u32 s27, s55, s27
	s_and_b64 s[42:43], s[40:41], exec
	s_cselect_b32 s21, s27, s35
	s_cselect_b32 s61, s26, s34
	s_add_u32 s30, s30, 0x80080
	s_addc_u32 s31, s31, 0
	s_add_u32 s62, s34, 0x100

; template <class Epi, class Sched, bool ALIGN_EPI = false, bool SP2 = false>
; __device__ __forceinline__ void gemm_phase(PG8_LAS unsigned char* lds, const Gemm g, const Sched& S, const Epi& E) {
;     ...
;         const char* nA = has_next ? (const char*)g.A + (size_t)nxt.pm * tstep : cA; const char* nB = has_next ? (const char*)g.Bt + (size_t)nxt.pn * tstep : cB;
;         for (int t = 0; t < nt; t += 2) {
;             const bool last = (t == nt - 2);
;             const char* a1 = cA + (size_t)(t + 1) * kstep;
;             const char* a2 = last ? nA : cA + (size_t)(t + 2) * kstep; const char* b2 = last ? nB : cB + (size_t)(t + 2) * kstep;
;             const char* a3 = a2 + kstep; const char* b3 = b2 + kstep;
	s_addc_u32 s68, s35, 0
	s_mov_b32 s69, -2


; #define PG8_STAGE(bufoff, gbase, voff) do { _Pragma("unroll") for (int _i = 0; _i < 2; ++_i) \
;         __builtin_amdgcn_global_load_lds((const unsigned*)((const char*)(gbase) + (voff)[_i]), (PG8_LAS unsigned*)(lds + (bufoff) + ldsw + _i * 8192), 16, 0, 0); } while (0)
; #define PG8_LDA(dst, b, h) do { _Pragma("unroll") for (int m = 0; m < 4; ++m) _Pragma("unroll") for (int k = 0; k < 2; ++k) dst[m][k] = *(const PG8_LAS bf16x8*)(lds + PG8_SA(b, h) + aoff + m * 2048 + k * 1024); } while (0)
; #define PG8_LDB(dst, b, h) do { _Pragma("unroll") for (int n = 0; n < 2; ++n) _Pragma("unroll") for (int k = 0; k < 2; ++k) dst[n][k] = *(const PG8_LAS bf16x8*)(lds + PG8_SB(b, h) + boff + n * 2048 + k * 1024); } while (0)
; #define PG8_MMA(ai, bj, At, Bt) do { __builtin_amdgcn_s_setprio(1); _Pragma("unroll") for (int m = 0; m < 4; ++m) _Pragma("unroll") for (int n = 0; n < 2; ++n) _Pragma("unroll") for (int k = 0; k < 2; ++k) \
;         acc[ai][bj][m][n] = __builtin_amdgcn_mfma_f32_16x16x32_bf16(Bt[n][k], At[m][k], acc[ai][bj][m][n], 0, 0, 0); __builtin_amdgcn_s_setprio(0); } while (0)
; #define PG8_WAIT_V(n) asm volatile("s_waitcnt vmcnt(" #n ")" ::: "memory")
; #define PG8_WAIT_L(n) asm volatile("s_waitcnt lgkmcnt(" #n ")" ::: "memory")
; #define PG8_BAR __builtin_amdgcn_s_barrier()
; #define PG8_SCHED __builtin_amdgcn_sched_barrier(0)
; template <class Epi, class Sched, bool ALIGN_EPI = false, bool SP2 = false>
; __device__ __forceinline__ void gemm_phase(PG8_LAS unsigned char* lds, const Gemm g, const Sched& S, const Epi& E) {
;     ...
;             PG8_LDB(B0, 0, 0); PG8_LDB(B1, 0, 1); PG8_SCHED; PG8_LDA(At, 0, 0); PG8_STAGE(PG8_SA(1, 1), a1 + hstep, voffA);
;             PG8_WAIT_V(8); PG8_WAIT_L(0); PG8_BAR; PG8_MMA(0, 0, At, B0); PG8_MMA(0, 1, At, B1); PG8_BAR; PG8_SCHED;
;             PG8_LDA(At, 0, 1); PG8_STAGE(PG8_SB(0, 0), b2, voffB); PG8_STAGE(PG8_SB(0, 1), b2 + hstep, voffB); PG8_STAGE(PG8_SA(0, 0), a2, voffA);
	s_add_u32 s34, s30, 0xfff80080
	s_addc_u32 s35, s31, -1
	s_add_i32 s76, 0, 0x10000
	s_cmp_eq_u32 s69, 28
	s_cselect_b32 s43, s23, s35
	s_cselect_b32 s42, s60, s34
	v_add_u32_e32 v130, s76, v159
	s_cselect_b32 s35, s21, s68
	s_cselect_b32 s34, s61, s62
	s_add_i32 vcc_lo, 0, 0x14000
	ds_read_b128 v[154:157], v130
	ds_read_b128 v[164:167], v130 offset:1024
	ds_read_b128 v[168:171], v130 offset:2048
	ds_read_b128 v[172:175], v130 offset:3072
	v_add_u32_e32 v130, vcc_lo, v159
	ds_read_b128 v[176:179], v130
	ds_read_b128 v[180:183], v130 offset:1024
	ds_read_b128 v[184:187], v130 offset:2048
	ds_read_b128 v[188:191], v130 offset:3072
	v_lshl_add_u64 v[130:131], s[30:31], 0, v[148:149]
	s_add_i32 m0, s56, 0xc000
	ds_read_b128 v[192:195], v163
	ds_read_b128 v[196:199], v163 offset:1024
	ds_read_b128 v[200:203], v163 offset:2048
	ds_read_b128 v[204:207], v163 offset:3072
	ds_read_b128 v[218:221], v163 offset:4096
	ds_read_b128 v[222:225], v163 offset:5120
	ds_read_b128 v[226:229], v163 offset:6144
	ds_read_b128 v[230:233], v163 offset:7168
	global_load_lds_dwordx4 v[130:131], off
	v_lshl_add_u64 v[130:131], s[30:31], 0, v[150:151]
	s_add_i32 m0, s56, 0xe000
	s_nop 0
	global_load_lds_dwordx4 v[130:131], off
	s_waitcnt vmcnt(8)
	s_waitcnt lgkmcnt(0)
	s_barrier
	s_setprio 1
	s_waitcnt lgkmcnt(0)
	v_mfma_f32_16x16x32_bf16 v[124:127], v[154:157], v[192:195], 0
	v_mfma_f32_16x16x32_bf16 v[120:123], v[168:171], v[192:195], 0
	v_mfma_f32_16x16x32_bf16 v[108:111], v[154:157], v[200:203], 0
	v_mfma_f32_16x16x32_bf16 v[104:107], v[168:171], v[200:203], 0
	v_mfma_f32_16x16x32_bf16 v[92:95], v[154:157], v[218:221], 0
	v_mfma_f32_16x16x32_bf16 v[88:91], v[168:171], v[218:221], 0
	v_mfma_f32_16x16x32_bf16 v[76:79], v[154:157], v[226:229], 0
	v_mfma_f32_16x16x32_bf16 v[72:75], v[168:171], v[226:229], 0
	v_mfma_f32_16x16x32_bf16 v[124:127], v[164:167], v[196:199], v[124:127]
	v_mfma_f32_16x16x32_bf16 v[120:123], v[172:175], v[196:199], v[120:123]
	v_mfma_f32_16x16x32_bf16 v[108:111], v[164:167], v[204:207], v[108:111]
	v_mfma_f32_16x16x32_bf16 v[104:107], v[172:175], v[204:207], v[104:107]
	v_mfma_f32_16x16x32_bf16 v[92:95], v[164:167], v[222:225], v[92:95]
	v_mfma_f32_16x16x32_bf16 v[88:91], v[172:175], v[222:225], v[88:91]
	v_mfma_f32_16x16x32_bf16 v[76:79], v[164:167], v[230:233], v[76:79]
	v_mfma_f32_16x16x32_bf16 v[72:75], v[172:175], v[230:233], v[72:75]
	v_mfma_f32_16x16x32_bf16 v[116:119], v[176:179], v[192:195], 0
	v_mfma_f32_16x16x32_bf16 v[112:115], v[184:187], v[192:195], 0
	v_mfma_f32_16x16x32_bf16 v[100:103], v[176:179], v[200:203], 0
	v_mfma_f32_16x16x32_bf16 v[96:99], v[184:187], v[200:203], 0
	v_mfma_f32_16x16x32_bf16 v[84:87], v[176:179], v[218:221], 0
	v_mfma_f32_16x16x32_bf16 v[80:83], v[184:187], v[218:221], 0
	v_mfma_f32_16x16x32_bf16 v[68:71], v[176:179], v[226:229], 0
	v_mfma_f32_16x16x32_bf16 v[64:67], v[184:187], v[226:229], 0
	v_mfma_f32_16x16x32_bf16 v[116:119], v[180:183], v[196:199], v[116:119]
	v_mfma_f32_16x16x32_bf16 v[112:115], v[188:191], v[196:199], v[112:115]
	v_mfma_f32_16x16x32_bf16 v[100:103], v[180:183], v[204:207], v[100:103]
	v_mfma_f32_16x16x32_bf16 v[96:99], v[188:191], v[204:207], v[96:99]
	v_mfma_f32_16x16x32_bf16 v[84:87], v[180:183], v[222:225], v[84:87]
	v_mfma_f32_16x16x32_bf16 v[80:83], v[188:191], v[222:225], v[80:83]
	v_mfma_f32_16x16x32_bf16 v[68:71], v[180:183], v[230:233], v[68:71]
	v_mfma_f32_16x16x32_bf16 v[64:67], v[188:191], v[230:233], v[64:67]
	s_setprio 0
	s_barrier
	s_add_i32 s76, s76, s74
	v_lshl_add_u64 v[130:131], s[34:35], 0, v[128:129]
	s_mov_b32 m0, s76
	ds_read_b128 v[192:195], v163 offset:16384
	ds_read_b128 v[196:199], v163 offset:17408
	ds_read_b128 v[200:203], v163 offset:18432
	ds_read_b128 v[204:207], v163 offset:19456
	ds_read_b128 v[218:221], v163 offset:20480
	ds_read_b128 v[222:225], v163 offset:21504
	ds_read_b128 v[226:229], v163 offset:22528
	ds_read_b128 v[230:233], v163 offset:23552
	global_load_lds_dwordx4 v[130:131], off
	s_add_i32 m0, s76, 0x2000
	s_add_u32 s76, s34, 0x80000
	v_lshl_add_u64 v[132:133], s[34:35], 0, v[142:143]
	s_addc_u32 s77, s35, 0
	s_add_i32 vcc_lo, vcc_lo, s74
	global_load_lds_dwordx4 v[132:133], off
	v_lshl_add_u64 v[234:235], s[76:77], 0, v[128:129]
	s_mov_b32 m0, vcc_lo
	v_lshl_add_u64 v[236:237], s[42:43], 0, v[144:145]
	global_load_lds_dwordx4 v[234:235], off
	v_lshl_add_u64 v[234:235], s[76:77], 0, v[142:143]
	s_add_i32 m0, vcc_lo, 0x2000
	s_nop 0
	global_load_lds_dwordx4 v[234:235], off
	v_lshl_add_u64 v[234:235], s[42:43], 0, v[146:147]
	s_mov_b32 m0, s56
	s_nop 0
	global_load_lds_dwordx4 v[234:235], off
	s_mov_b32 m0, s57
	s_nop 0
	global_load_lds_dwordx4 v[236:237], off
	s_waitcnt vmcnt(8)
	s_waitcnt lgkmcnt(0)
	s_barrier
; #define PG8_STAGE(bufoff, gbase, voff) do { _Pragma("unroll") for (int _i = 0; _i < 2; ++_i) \
;         __builtin_amdgcn_global_load_lds((const unsigned*)((const char*)(gbase) + (voff)[_i]), (PG8_LAS unsigned*)(lds + (bufoff) + ldsw + _i * 8192), 16, 0, 0); } while (0)
; #define PG8_LDA(dst, b, h) do { _Pragma("unroll") for (int m = 0; m < 4; ++m) _Pragma("unroll") for (int k = 0; k < 2; ++k) dst[m][k] = *(const PG8_LAS bf16x8*)(lds + PG8_SA(b, h) + aoff + m * 2048 + k * 1024); } while (0)
; #define PG8_LDB(dst, b, h) do { _Pragma("unroll") for (int n = 0; n < 2; ++n) _Pragma("unroll") for (int k = 0; k < 2; ++k) dst[n][k] = *(const PG8_LAS bf16x8*)(lds + PG8_SB(b, h) + boff + n * 2048 + k * 1024); } while (0)
; #define PG8_MMA(ai, bj, At, Bt) do { __builtin_amdgcn_s_setprio(1); _Pragma("unroll") for (int m = 0; m < 4; ++m) _Pragma("unroll") for (int n = 0; n < 2; ++n) _Pragma("unroll") for (int k = 0; k < 2; ++k) \
;         acc[ai][bj][m][n] = __builtin_amdgcn_mfma_f32_16x16x32_bf16(Bt[n][k], At[m][k], acc[ai][bj][m][n], 0, 0, 0); __builtin_amdgcn_s_setprio(0); } while (0)
; #define PG8_WAIT_V(n) asm volatile("s_waitcnt vmcnt(" #n ")" ::: "memory")
; template <class Epi, class Sched, bool ALIGN_EPI = false, bool SP2 = false>
; __device__ __forceinline__ void gemm_phase(PG8_LAS unsigned char* lds, const Gemm g, const Sched& S, const Epi& E) {
;     ...
;             PG8_LDB(B0, 0, 0); PG8_LDB(B1, 0, 1); PG8_SCHED; PG8_LDA(At, 0, 0); PG8_STAGE(PG8_SA(1, 1), a1 + hstep, voffA);
;             PG8_WAIT_V(8); PG8_WAIT_L(0); PG8_BAR; PG8_MMA(0, 0, At, B0); PG8_MMA(0, 1, At, B1); PG8_BAR; PG8_SCHED;
;             PG8_LDA(At, 0, 1); PG8_STAGE(PG8_SB(0, 0), b2, voffB); PG8_STAGE(PG8_SB(0, 1), b2 + hstep, voffB); PG8_STAGE(PG8_SA(0, 0), a2, voffA);
;             PG8_WAIT_V(8); PG8_WAIT_L(0); PG8_BAR; PG8_MMA(1, 0, At, B0); PG8_MMA(1, 1, At, B1); PG8_BAR; PG8_SCHED;
;             PG8_LDB(B0, 1, 0); PG8_LDB(B1, 1, 1); PG8_SCHED; PG8_LDA(At, 1, 0); PG8_STAGE(PG8_SA(0, 1), a2 + hstep, voffA);
;             PG8_WAIT_V(8); PG8_WAIT_L(0); PG8_BAR; PG8_MMA(0, 0, At, B0); PG8_MMA(0, 1, At, B1); PG8_BAR; PG8_SCHED;
;             PG8_LDA(At, 1, 1); PG8_STAGE(PG8_SB(1, 0), b3, voffB); PG8_STAGE(PG8_SB(1, 1), b3 + hstep, voffB); PG8_STAGE(PG8_SA(1, 0), a3, voffA);
;             PG8_WAIT_V(8); PG8_WAIT_L(0); PG8_BAR; PG8_MMA(1, 0, At, B0); PG8_MMA(1, 1, At, B1); PG8_BAR; PG8_SCHED;
	s_setprio 1
	s_waitcnt lgkmcnt(0)
	v_mfma_f32_16x16x32_bf16 v[60:63], v[154:157], v[192:195], 0
	v_mfma_f32_16x16x32_bf16 v[56:59], v[168:171], v[192:195], 0
	v_mfma_f32_16x16x32_bf16 v[44:47], v[154:157], v[200:203], 0
	v_mfma_f32_16x16x32_bf16 v[40:43], v[168:171], v[200:203], 0
	v_mfma_f32_16x16x32_bf16 v[28:31], v[154:157], v[218:221], 0
	v_mfma_f32_16x16x32_bf16 v[24:27], v[168:171], v[218:221], 0
	v_mfma_f32_16x16x32_bf16 v[12:15], v[154:157], v[226:229], 0
	v_mfma_f32_16x16x32_bf16 v[8:11], v[168:171], v[226:229], 0
	v_mfma_f32_16x16x32_bf16 v[60:63], v[164:167], v[196:199], v[60:63]
	v_mfma_f32_16x16x32_bf16 v[56:59], v[172:175], v[196:199], v[56:59]
	v_mfma_f32_16x16x32_bf16 v[44:47], v[164:167], v[204:207], v[44:47]
	v_mfma_f32_16x16x32_bf16 v[40:43], v[172:175], v[204:207], v[40:43]
	v_mfma_f32_16x16x32_bf16 v[28:31], v[164:167], v[222:225], v[28:31]
	v_mfma_f32_16x16x32_bf16 v[24:27], v[172:175], v[222:225], v[24:27]
	v_mfma_f32_16x16x32_bf16 v[12:15], v[164:167], v[230:233], v[12:15]
	v_mfma_f32_16x16x32_bf16 v[8:11], v[172:175], v[230:233], v[8:11]
	v_mfma_f32_16x16x32_bf16 v[52:55], v[176:179], v[192:195], 0
	v_mfma_f32_16x16x32_bf16 v[48:51], v[184:187], v[192:195], 0
	v_mfma_f32_16x16x32_bf16 v[36:39], v[176:179], v[200:203], 0
	v_mfma_f32_16x16x32_bf16 v[32:35], v[184:187], v[200:203], 0
	v_mfma_f32_16x16x32_bf16 v[20:23], v[176:179], v[218:221], 0
	v_mfma_f32_16x16x32_bf16 v[16:19], v[184:187], v[218:221], 0
	v_mfma_f32_16x16x32_bf16 v[4:7], v[176:179], v[226:229], 0
	v_mfma_f32_16x16x32_bf16 v[0:3], v[184:187], v[226:229], 0
	v_mfma_f32_16x16x32_bf16 v[52:55], v[180:183], v[196:199], v[52:55]
	v_mfma_f32_16x16x32_bf16 v[48:51], v[188:191], v[196:199], v[48:51]
	v_mfma_f32_16x16x32_bf16 v[36:39], v[180:183], v[204:207], v[36:39]
	v_mfma_f32_16x16x32_bf16 v[32:35], v[188:191], v[204:207], v[32:35]
	v_mfma_f32_16x16x32_bf16 v[20:23], v[180:183], v[222:225], v[20:23]
	v_mfma_f32_16x16x32_bf16 v[16:19], v[188:191], v[222:225], v[16:19]
	v_mfma_f32_16x16x32_bf16 v[4:7], v[180:183], v[230:233], v[4:7]
	v_mfma_f32_16x16x32_bf16 v[0:3], v[188:191], v[230:233], v[0:3]
	s_setprio 0
	s_barrier
	s_add_i32 s76, 0, 0x18000
	v_add_u32_e32 v134, s76, v159
	s_add_i32 s77, 0, 0x1c000
	ds_read_b128 v[154:157], v134
	ds_read_b128 v[164:167], v134 offset:1024
	ds_read_b128 v[168:171], v134 offset:2048
	ds_read_b128 v[172:175], v134 offset:3072
	v_add_u32_e32 v134, s77, v159
	ds_read_b128 v[176:179], v134
	ds_read_b128 v[180:183], v134 offset:1024
	ds_read_b128 v[184:187], v134 offset:2048
	ds_read_b128 v[188:191], v134 offset:3072
	s_add_u32 s42, s42, 0x80000
	s_addc_u32 s43, s43, 0
	s_mov_b32 m0, s58
	v_lshl_add_u64 v[238:239], s[42:43], 0, v[146:147]
	ds_read_b128 v[192:195], v163 offset:32768
	ds_read_b128 v[196:199], v163 offset:33792
	ds_read_b128 v[200:203], v163 offset:34816
	ds_read_b128 v[204:207], v163 offset:35840
	ds_read_b128 v[218:221], v163 offset:36864
	ds_read_b128 v[222:225], v163 offset:37888
	ds_read_b128 v[226:229], v163 offset:38912
	ds_read_b128 v[230:233], v163 offset:39936
	global_load_lds_dwordx4 v[238:239], off
	v_lshl_add_u64 v[238:239], s[42:43], 0, v[144:145]
	s_mov_b32 m0, s59
	s_nop 0
	global_load_lds_dwordx4 v[238:239], off
	s_waitcnt vmcnt(8)
	s_waitcnt lgkmcnt(0)
	s_barrier
	s_setprio 1
	s_waitcnt lgkmcnt(0)
	v_mfma_f32_16x16x32_bf16 v[124:127], v[154:157], v[192:195], v[124:127]
	v_mfma_f32_16x16x32_bf16 v[120:123], v[168:171], v[192:195], v[120:123]
	v_mfma_f32_16x16x32_bf16 v[108:111], v[154:157], v[200:203], v[108:111]
	v_mfma_f32_16x16x32_bf16 v[104:107], v[168:171], v[200:203], v[104:107]
	v_mfma_f32_16x16x32_bf16 v[92:95], v[154:157], v[218:221], v[92:95]
	v_mfma_f32_16x16x32_bf16 v[88:91], v[168:171], v[218:221], v[88:91]
	v_mfma_f32_16x16x32_bf16 v[76:79], v[154:157], v[226:229], v[76:79]
	v_mfma_f32_16x16x32_bf16 v[72:75], v[168:171], v[226:229], v[72:75]
	v_mfma_f32_16x16x32_bf16 v[124:127], v[164:167], v[196:199], v[124:127]
	v_mfma_f32_16x16x32_bf16 v[120:123], v[172:175], v[196:199], v[120:123]
	v_mfma_f32_16x16x32_bf16 v[108:111], v[164:167], v[204:207], v[108:111]
	v_mfma_f32_16x16x32_bf16 v[104:107], v[172:175], v[204:207], v[104:107]
	v_mfma_f32_16x16x32_bf16 v[92:95], v[164:167], v[222:225], v[92:95]
	v_mfma_f32_16x16x32_bf16 v[88:91], v[172:175], v[222:225], v[88:91]
	v_mfma_f32_16x16x32_bf16 v[76:79], v[164:167], v[230:233], v[76:79]
	v_mfma_f32_16x16x32_bf16 v[72:75], v[172:175], v[230:233], v[72:75]
	v_mfma_f32_16x16x32_bf16 v[116:119], v[176:179], v[192:195], v[116:119]
	v_mfma_f32_16x16x32_bf16 v[112:115], v[184:187], v[192:195], v[112:115]
	v_mfma_f32_16x16x32_bf16 v[100:103], v[176:179], v[200:203], v[100:103]
	v_mfma_f32_16x16x32_bf16 v[96:99], v[184:187], v[200:203], v[96:99]
	v_mfma_f32_16x16x32_bf16 v[84:87], v[176:179], v[218:221], v[84:87]
	v_mfma_f32_16x16x32_bf16 v[80:83], v[184:187], v[218:221], v[80:83]
	v_mfma_f32_16x16x32_bf16 v[68:71], v[176:179], v[226:229], v[68:71]
	v_mfma_f32_16x16x32_bf16 v[64:67], v[184:187], v[226:229], v[64:67]
	v_mfma_f32_16x16x32_bf16 v[116:119], v[180:183], v[196:199], v[116:119]
	v_mfma_f32_16x16x32_bf16 v[112:115], v[188:191], v[196:199], v[112:115]
	v_mfma_f32_16x16x32_bf16 v[100:103], v[180:183], v[204:207], v[100:103]
	v_mfma_f32_16x16x32_bf16 v[96:99], v[188:191], v[204:207], v[96:99]
	v_mfma_f32_16x16x32_bf16 v[84:87], v[180:183], v[222:225], v[84:87]
	v_mfma_f32_16x16x32_bf16 v[80:83], v[188:191], v[222:225], v[80:83]
	v_mfma_f32_16x16x32_bf16 v[68:71], v[180:183], v[230:233], v[68:71]
	v_mfma_f32_16x16x32_bf16 v[64:67], v[188:191], v[230:233], v[64:67]
	s_setprio 0
	s_barrier
; #define PG8_STAGE(bufoff, gbase, voff) do { _Pragma("unroll") for (int _i = 0; _i < 2; ++_i) \
;         __builtin_amdgcn_global_load_lds((const unsigned*)((const char*)(gbase) + (voff)[_i]), (PG8_LAS unsigned*)(lds + (bufoff) + ldsw + _i * 8192), 16, 0, 0); } while (0)
; #define PG8_LDA(dst, b, h) do { _Pragma("unroll") for (int m = 0; m < 4; ++m) _Pragma("unroll") for (int k = 0; k < 2; ++k) dst[m][k] = *(const PG8_LAS bf16x8*)(lds + PG8_SA(b, h) + aoff + m * 2048 + k * 1024); } while (0)
; template <class Epi, class Sched, bool ALIGN_EPI = false, bool SP2 = false>
; __device__ __forceinline__ void gemm_phase(PG8_LAS unsigned char* lds, const Gemm g, const Sched& S, const Epi& E) {
;     ...
;         const bool has_next = S.next(ui + 1, nxt);
;         const char* nA = has_next ? (const char*)g.A + (size_t)nxt.pm * tstep : cA; const char* nB = has_next ? (const char*)g.Bt + (size_t)nxt.pn * tstep : cB;
;         for (int t = 0; t < nt; t += 2) {
;             const bool last = (t == nt - 2);
;             const char* a1 = cA + (size_t)(t + 1) * kstep;
;             const char* a2 = last ? nA : cA + (size_t)(t + 2) * kstep; const char* b2 = last ? nB : cB + (size_t)(t + 2) * kstep;
;             const char* a3 = a2 + kstep; const char* b3 = b2 + kstep;
;             if (last && has_next) S.a_ready(nxt);
;             if constexpr (SP2) {
;             PG8_LDB(B0, 0, 0); PG8_LDB(B1, 0, 1); PG8_SCHED; PG8_LDA(At, 0, 0); PG8_STAGE(PG8_SA(1, 1), a1 + hstep, voffA);
;             PG8_WAIT_V(8); PG8_WAIT_L(0); PG8_BAR; PG8_MMA(0, 0, At, B0); PG8_MMA(0, 1, At, B1); PG8_BAR; PG8_SCHED;
;             PG8_LDA(At, 0, 1); PG8_STAGE(PG8_SB(0, 0), b2, voffB); PG8_STAGE(PG8_SB(0, 1), b2 + hstep, voffB); PG8_STAGE(PG8_SA(0, 0), a2, voffA);
;             PG8_WAIT_V(8); PG8_WAIT_L(0); PG8_BAR; PG8_MMA(1, 0, At, B0); PG8_MMA(1, 1, At, B1); PG8_BAR; PG8_SCHED;
;             PG8_LDB(B0, 1, 0); PG8_LDB(B1, 1, 1); PG8_SCHED; PG8_LDA(At, 1, 0); PG8_STAGE(PG8_SA(0, 1), a2 + hstep, voffA);
;             PG8_WAIT_V(8); PG8_WAIT_L(0); PG8_BAR; PG8_MMA(0, 0, At, B0); PG8_MMA(0, 1, At, B1); PG8_BAR; PG8_SCHED;
;             PG8_LDA(At, 1, 1); PG8_STAGE(PG8_SB(1, 0), b3, voffB); PG8_STAGE(PG8_SB(1, 1), b3 + hstep, voffB); PG8_STAGE(PG8_SA(1, 0), a3, voffA);
;             PG8_WAIT_V(8); PG8_WAIT_L(0); PG8_BAR; PG8_MMA(1, 0, At, B0); PG8_MMA(1, 1, At, B1); PG8_BAR; PG8_SCHED;
	s_add_i32 s42, s76, s74
	v_lshl_add_u64 v[130:131], v[130:131], 0, s[78:79]
	s_mov_b32 m0, s42
	ds_read_b128 v[192:195], v163 offset:49152
	ds_read_b128 v[196:199], v163 offset:50176
	ds_read_b128 v[200:203], v163 offset:51200
	ds_read_b128 v[204:207], v163 offset:52224
	ds_read_b128 v[218:221], v163 offset:53248
	ds_read_b128 v[222:225], v163 offset:54272
	ds_read_b128 v[226:229], v163 offset:55296
	ds_read_b128 v[230:233], v163 offset:56320
	global_load_lds_dwordx4 v[130:131], off
	s_add_i32 m0, s42, 0x2000
	s_add_u32 s34, s34, 0x80080
	v_lshl_add_u64 v[130:131], v[132:133], 0, s[78:79]
	s_addc_u32 s35, s35, 0
	s_add_i32 s42, s77, s74
	global_load_lds_dwordx4 v[130:131], off
	v_lshl_add_u64 v[130:131], s[34:35], 0, v[128:129]
	s_mov_b32 m0, s42
	s_nop 0
	global_load_lds_dwordx4 v[130:131], off
	v_lshl_add_u64 v[130:131], s[34:35], 0, v[142:143]
	s_add_i32 m0, s42, 0x2000
	s_nop 0
	global_load_lds_dwordx4 v[130:131], off
	v_lshl_add_u64 v[130:131], v[234:235], 0, s[78:79]
	s_mov_b32 m0, s48
	s_nop 0
	global_load_lds_dwordx4 v[130:131], off
	v_lshl_add_u64 v[130:131], v[236:237], 0, s[78:79]
	s_mov_b32 m0, s36
	s_nop 0
	global_load_lds_dwordx4 v[130:131], off
	s_waitcnt vmcnt(8)
	s_waitcnt lgkmcnt(0)
	s_barrier
	s_setprio 1
	s_waitcnt lgkmcnt(0)
	v_mfma_f32_16x16x32_bf16 v[60:63], v[154:157], v[192:195], v[60:63]
	v_mfma_f32_16x16x32_bf16 v[56:59], v[168:171], v[192:195], v[56:59]
	v_mfma_f32_16x16x32_bf16 v[44:47], v[154:157], v[200:203], v[44:47]
	v_mfma_f32_16x16x32_bf16 v[40:43], v[168:171], v[200:203], v[40:43]
	v_mfma_f32_16x16x32_bf16 v[28:31], v[154:157], v[218:221], v[28:31]
	v_mfma_f32_16x16x32_bf16 v[24:27], v[168:171], v[218:221], v[24:27]
	v_mfma_f32_16x16x32_bf16 v[12:15], v[154:157], v[226:229], v[12:15]
	v_mfma_f32_16x16x32_bf16 v[8:11], v[168:171], v[226:229], v[8:11]
	v_mfma_f32_16x16x32_bf16 v[60:63], v[164:167], v[196:199], v[60:63]
	v_mfma_f32_16x16x32_bf16 v[56:59], v[172:175], v[196:199], v[56:59]
	v_mfma_f32_16x16x32_bf16 v[44:47], v[164:167], v[204:207], v[44:47]
	v_mfma_f32_16x16x32_bf16 v[40:43], v[172:175], v[204:207], v[40:43]
	v_mfma_f32_16x16x32_bf16 v[28:31], v[164:167], v[222:225], v[28:31]
	v_mfma_f32_16x16x32_bf16 v[24:27], v[172:175], v[222:225], v[24:27]
	v_mfma_f32_16x16x32_bf16 v[12:15], v[164:167], v[230:233], v[12:15]
	v_mfma_f32_16x16x32_bf16 v[8:11], v[172:175], v[230:233], v[8:11]
	v_mfma_f32_16x16x32_bf16 v[52:55], v[176:179], v[192:195], v[52:55]
	v_mfma_f32_16x16x32_bf16 v[48:51], v[184:187], v[192:195], v[48:51]
	v_mfma_f32_16x16x32_bf16 v[36:39], v[176:179], v[200:203], v[36:39]
	v_mfma_f32_16x16x32_bf16 v[32:35], v[184:187], v[200:203], v[32:35]
	v_mfma_f32_16x16x32_bf16 v[20:23], v[176:179], v[218:221], v[20:23]
	v_mfma_f32_16x16x32_bf16 v[16:19], v[184:187], v[218:221], v[16:19]
	v_mfma_f32_16x16x32_bf16 v[4:7], v[176:179], v[226:229], v[4:7]
	v_mfma_f32_16x16x32_bf16 v[0:3], v[184:187], v[226:229], v[0:3]
	v_mfma_f32_16x16x32_bf16 v[52:55], v[180:183], v[196:199], v[52:55]
	v_mfma_f32_16x16x32_bf16 v[48:51], v[188:191], v[196:199], v[48:51]
	v_mfma_f32_16x16x32_bf16 v[36:39], v[180:183], v[204:207], v[36:39]
	v_mfma_f32_16x16x32_bf16 v[32:35], v[188:191], v[204:207], v[32:35]
	v_mfma_f32_16x16x32_bf16 v[20:23], v[180:183], v[222:225], v[20:23]
	v_mfma_f32_16x16x32_bf16 v[16:19], v[188:191], v[222:225], v[16:19]
	v_mfma_f32_16x16x32_bf16 v[4:7], v[180:183], v[230:233], v[4:7]
	v_mfma_f32_16x16x32_bf16 v[0:3], v[188:191], v[230:233], v[0:3]
	s_setprio 0
	s_barrier
	s_add_i32 s69, s69, 2
	s_add_u32 s30, s30, 0x100
	s_addc_u32 s31, s31, 0
	s_add_u32 s62, s62, 0x100
	s_addc_u32 s68, s68, 0
	s_cmp_gt_u32 s69, 29
.LBB0_955:
	s_add_u32 s34, s30, 0xfff80080
	s_addc_u32 s35, s31, -1
	s_add_i32 s76, 0, 0x10000
	s_cmp_eq_u32 s69, 28
	s_cselect_b32 s43, s23, s35
	s_cselect_b32 s42, s60, s34
	v_add_u32_e32 v130, s76, v159
	s_cselect_b32 s35, s21, s68
	s_cselect_b32 s34, s61, s62
	s_add_i32 vcc_lo, 0, 0x14000
	ds_read_b128 v[154:157], v130
	ds_read_b128 v[164:167], v130 offset:1024
	ds_read_b128 v[168:171], v130 offset:2048
	ds_read_b128 v[172:175], v130 offset:3072
	v_add_u32_e32 v130, vcc_lo, v159
	ds_read_b128 v[176:179], v130
	ds_read_b128 v[180:183], v130 offset:1024
	ds_read_b128 v[184:187], v130 offset:2048
	ds_read_b128 v[188:191], v130 offset:3072
	v_lshl_add_u64 v[130:131], s[30:31], 0, v[148:149]
	s_add_i32 m0, s56, 0xc000
	ds_read_b128 v[192:195], v163
	ds_read_b128 v[196:199], v163 offset:1024
	ds_read_b128 v[200:203], v163 offset:2048
	ds_read_b128 v[204:207], v163 offset:3072
	ds_read_b128 v[218:221], v163 offset:4096
	ds_read_b128 v[222:225], v163 offset:5120
	ds_read_b128 v[226:229], v163 offset:6144
	ds_read_b128 v[230:233], v163 offset:7168
	global_load_lds_dwordx4 v[130:131], off
	v_lshl_add_u64 v[130:131], s[30:31], 0, v[150:151]
	s_add_i32 m0, s56, 0xe000
	s_nop 0
	global_load_lds_dwordx4 v[130:131], off
	s_waitcnt vmcnt(8)
	s_waitcnt lgkmcnt(0)
	s_barrier
; #define PG8_STAGE(bufoff, gbase, voff) do { _Pragma("unroll") for (int _i = 0; _i < 2; ++_i) \
;         __builtin_amdgcn_global_load_lds((const unsigned*)((const char*)(gbase) + (voff)[_i]), (PG8_LAS unsigned*)(lds + (bufoff) + ldsw + _i * 8192), 16, 0, 0); } while (0)
; #define PG8_LDA(dst, b, h) do { _Pragma("unroll") for (int m = 0; m < 4; ++m) _Pragma("unroll") for (int k = 0; k < 2; ++k) dst[m][k] = *(const PG8_LAS bf16x8*)(lds + PG8_SA(b, h) + aoff + m * 2048 + k * 1024); } while (0)
; #define PG8_LDB(dst, b, h) do { _Pragma("unroll") for (int n = 0; n < 2; ++n) _Pragma("unroll") for (int k = 0; k < 2; ++k) dst[n][k] = *(const PG8_LAS bf16x8*)(lds + PG8_SB(b, h) + boff + n * 2048 + k * 1024); } while (0)
; #define PG8_MMA(ai, bj, At, Bt) do { __builtin_amdgcn_s_setprio(1); _Pragma("unroll") for (int m = 0; m < 4; ++m) _Pragma("unroll") for (int n = 0; n < 2; ++n) _Pragma("unroll") for (int k = 0; k < 2; ++k) \
;         acc[ai][bj][m][n] = __builtin_amdgcn_mfma_f32_16x16x32_bf16(Bt[n][k], At[m][k], acc[ai][bj][m][n], 0, 0, 0); __builtin_amdgcn_s_setprio(0); } while (0)
; #define PG8_WAIT_V(n) asm volatile("s_waitcnt vmcnt(" #n ")" ::: "memory")
; #define PG8_WAIT_L(n) asm volatile("s_waitcnt lgkmcnt(" #n ")" ::: "memory")
; #define PG8_BAR __builtin_amdgcn_s_barrier()
; #define PG8_SCHED __builtin_amdgcn_sched_barrier(0)
; template <class Epi, class Sched, bool ALIGN_EPI = false, bool SP2 = false>
; __device__ __forceinline__ void gemm_phase(PG8_LAS unsigned char* lds, const Gemm g, const Sched& S, const Epi& E) {
;     ...
;             PG8_LDB(B0, 0, 0); PG8_LDB(B1, 0, 1); PG8_SCHED; PG8_LDA(At, 0, 0); PG8_STAGE(PG8_SA(1, 1), a1 + hstep, voffA);
;             PG8_WAIT_V(8); PG8_WAIT_L(0); PG8_BAR; PG8_MMA(0, 0, At, B0); PG8_MMA(0, 1, At, B1); PG8_BAR; PG8_SCHED;
;             PG8_LDA(At, 0, 1); PG8_STAGE(PG8_SB(0, 0), b2, voffB); PG8_STAGE(PG8_SB(0, 1), b2 + hstep, voffB); PG8_STAGE(PG8_SA(0, 0), a2, voffA);
;             PG8_WAIT_V(8); PG8_WAIT_L(0); PG8_BAR; PG8_MMA(1, 0, At, B0); PG8_MMA(1, 1, At, B1); PG8_BAR; PG8_SCHED;
	s_setprio 1
	s_waitcnt lgkmcnt(0)
	v_mfma_f32_16x16x32_bf16 v[124:127], v[154:157], v[192:195], v[124:127]
	v_mfma_f32_16x16x32_bf16 v[120:123], v[168:171], v[192:195], v[120:123]
	v_mfma_f32_16x16x32_bf16 v[108:111], v[154:157], v[200:203], v[108:111]
	v_mfma_f32_16x16x32_bf16 v[104:107], v[168:171], v[200:203], v[104:107]
	v_mfma_f32_16x16x32_bf16 v[92:95], v[154:157], v[218:221], v[92:95]
	v_mfma_f32_16x16x32_bf16 v[88:91], v[168:171], v[218:221], v[88:91]
	v_mfma_f32_16x16x32_bf16 v[76:79], v[154:157], v[226:229], v[76:79]
	v_mfma_f32_16x16x32_bf16 v[72:75], v[168:171], v[226:229], v[72:75]
	v_mfma_f32_16x16x32_bf16 v[124:127], v[164:167], v[196:199], v[124:127]
	v_mfma_f32_16x16x32_bf16 v[120:123], v[172:175], v[196:199], v[120:123]
	v_mfma_f32_16x16x32_bf16 v[108:111], v[164:167], v[204:207], v[108:111]
	v_mfma_f32_16x16x32_bf16 v[104:107], v[172:175], v[204:207], v[104:107]
	v_mfma_f32_16x16x32_bf16 v[92:95], v[164:167], v[222:225], v[92:95]
	v_mfma_f32_16x16x32_bf16 v[88:91], v[172:175], v[222:225], v[88:91]
	v_mfma_f32_16x16x32_bf16 v[76:79], v[164:167], v[230:233], v[76:79]
	v_mfma_f32_16x16x32_bf16 v[72:75], v[172:175], v[230:233], v[72:75]
	v_mfma_f32_16x16x32_bf16 v[116:119], v[176:179], v[192:195], v[116:119]
	v_mfma_f32_16x16x32_bf16 v[112:115], v[184:187], v[192:195], v[112:115]
	v_mfma_f32_16x16x32_bf16 v[100:103], v[176:179], v[200:203], v[100:103]
	v_mfma_f32_16x16x32_bf16 v[96:99], v[184:187], v[200:203], v[96:99]
	v_mfma_f32_16x16x32_bf16 v[84:87], v[176:179], v[218:221], v[84:87]
	v_mfma_f32_16x16x32_bf16 v[80:83], v[184:187], v[218:221], v[80:83]
	v_mfma_f32_16x16x32_bf16 v[68:71], v[176:179], v[226:229], v[68:71]
	v_mfma_f32_16x16x32_bf16 v[64:67], v[184:187], v[226:229], v[64:67]
	v_mfma_f32_16x16x32_bf16 v[116:119], v[180:183], v[196:199], v[116:119]
	v_mfma_f32_16x16x32_bf16 v[112:115], v[188:191], v[196:199], v[112:115]
	v_mfma_f32_16x16x32_bf16 v[100:103], v[180:183], v[204:207], v[100:103]
	v_mfma_f32_16x16x32_bf16 v[96:99], v[188:191], v[204:207], v[96:99]
	v_mfma_f32_16x16x32_bf16 v[84:87], v[180:183], v[222:225], v[84:87]
	v_mfma_f32_16x16x32_bf16 v[80:83], v[188:191], v[222:225], v[80:83]
	v_mfma_f32_16x16x32_bf16 v[68:71], v[180:183], v[230:233], v[68:71]
	v_mfma_f32_16x16x32_bf16 v[64:67], v[188:191], v[230:233], v[64:67]
	s_setprio 0
	s_barrier
	s_add_i32 s76, s76, s74
	v_lshl_add_u64 v[130:131], s[34:35], 0, v[128:129]
	s_mov_b32 m0, s76
	ds_read_b128 v[192:195], v163 offset:16384
	ds_read_b128 v[196:199], v163 offset:17408
	ds_read_b128 v[200:203], v163 offset:18432
	ds_read_b128 v[204:207], v163 offset:19456
	ds_read_b128 v[218:221], v163 offset:20480
	ds_read_b128 v[222:225], v163 offset:21504
	ds_read_b128 v[226:229], v163 offset:22528
	ds_read_b128 v[230:233], v163 offset:23552
	global_load_lds_dwordx4 v[130:131], off
	s_add_i32 m0, s76, 0x2000
	s_add_u32 s76, s34, 0x80000
	v_lshl_add_u64 v[132:133], s[34:35], 0, v[142:143]
	s_addc_u32 s77, s35, 0
	s_add_i32 vcc_lo, vcc_lo, s74
	global_load_lds_dwordx4 v[132:133], off
	v_lshl_add_u64 v[234:235], s[76:77], 0, v[128:129]
	s_mov_b32 m0, vcc_lo
	v_lshl_add_u64 v[236:237], s[42:43], 0, v[144:145]
	global_load_lds_dwordx4 v[234:235], off
	v_lshl_add_u64 v[234:235], s[76:77], 0, v[142:143]
	s_add_i32 m0, vcc_lo, 0x2000
	s_nop 0
	global_load_lds_dwordx4 v[234:235], off
	v_lshl_add_u64 v[234:235], s[42:43], 0, v[146:147]
	s_mov_b32 m0, s56
	s_nop 0
	global_load_lds_dwordx4 v[234:235], off
	s_mov_b32 m0, s57
	s_nop 0
	global_load_lds_dwordx4 v[236:237], off
	s_waitcnt vmcnt(8)
	s_waitcnt lgkmcnt(0)
	s_barrier
	s_setprio 1
	s_waitcnt lgkmcnt(0)
	v_mfma_f32_16x16x32_bf16 v[60:63], v[154:157], v[192:195], v[60:63]
	v_mfma_f32_16x16x32_bf16 v[56:59], v[168:171], v[192:195], v[56:59]
	v_mfma_f32_16x16x32_bf16 v[44:47], v[154:157], v[200:203], v[44:47]
	v_mfma_f32_16x16x32_bf16 v[40:43], v[168:171], v[200:203], v[40:43]
	v_mfma_f32_16x16x32_bf16 v[28:31], v[154:157], v[218:221], v[28:31]
	v_mfma_f32_16x16x32_bf16 v[24:27], v[168:171], v[218:221], v[24:27]
	v_mfma_f32_16x16x32_bf16 v[12:15], v[154:157], v[226:229], v[12:15]
	v_mfma_f32_16x16x32_bf16 v[8:11], v[168:171], v[226:229], v[8:11]
	v_mfma_f32_16x16x32_bf16 v[60:63], v[164:167], v[196:199], v[60:63]
	v_mfma_f32_16x16x32_bf16 v[56:59], v[172:175], v[196:199], v[56:59]
	v_mfma_f32_16x16x32_bf16 v[44:47], v[164:167], v[204:207], v[44:47]
	v_mfma_f32_16x16x32_bf16 v[40:43], v[172:175], v[204:207], v[40:43]
	v_mfma_f32_16x16x32_bf16 v[28:31], v[164:167], v[222:225], v[28:31]
	v_mfma_f32_16x16x32_bf16 v[24:27], v[172:175], v[222:225], v[24:27]
	v_mfma_f32_16x16x32_bf16 v[12:15], v[164:167], v[230:233], v[12:15]
	v_mfma_f32_16x16x32_bf16 v[8:11], v[172:175], v[230:233], v[8:11]
	v_mfma_f32_16x16x32_bf16 v[52:55], v[176:179], v[192:195], v[52:55]
	v_mfma_f32_16x16x32_bf16 v[48:51], v[184:187], v[192:195], v[48:51]
	v_mfma_f32_16x16x32_bf16 v[36:39], v[176:179], v[200:203], v[36:39]
	v_mfma_f32_16x16x32_bf16 v[32:35], v[184:187], v[200:203], v[32:35]
	v_mfma_f32_16x16x32_bf16 v[20:23], v[176:179], v[218:221], v[20:23]
	v_mfma_f32_16x16x32_bf16 v[16:19], v[184:187], v[218:221], v[16:19]
	v_mfma_f32_16x16x32_bf16 v[4:7], v[176:179], v[226:229], v[4:7]
	v_mfma_f32_16x16x32_bf16 v[0:3], v[184:187], v[226:229], v[0:3]
	v_mfma_f32_16x16x32_bf16 v[52:55], v[180:183], v[196:199], v[52:55]
	v_mfma_f32_16x16x32_bf16 v[48:51], v[188:191], v[196:199], v[48:51]
	v_mfma_f32_16x16x32_bf16 v[36:39], v[180:183], v[204:207], v[36:39]
	v_mfma_f32_16x16x32_bf16 v[32:35], v[188:191], v[204:207], v[32:35]
	v_mfma_f32_16x16x32_bf16 v[20:23], v[180:183], v[222:225], v[20:23]
	v_mfma_f32_16x16x32_bf16 v[16:19], v[188:191], v[222:225], v[16:19]
	v_mfma_f32_16x16x32_bf16 v[4:7], v[180:183], v[230:233], v[4:7]
	v_mfma_f32_16x16x32_bf16 v[0:3], v[188:191], v[230:233], v[0:3]
	s_setprio 0
	s_barrier
; #define PG8_STAGE(bufoff, gbase, voff) do { _Pragma("unroll") for (int _i = 0; _i < 2; ++_i) \
;         __builtin_amdgcn_global_load_lds((const unsigned*)((const char*)(gbase) + (voff)[_i]), (PG8_LAS unsigned*)(lds + (bufoff) + ldsw + _i * 8192), 16, 0, 0); } while (0)
; #define PG8_LDA(dst, b, h) do { _Pragma("unroll") for (int m = 0; m < 4; ++m) _Pragma("unroll") for (int k = 0; k < 2; ++k) dst[m][k] = *(const PG8_LAS bf16x8*)(lds + PG8_SA(b, h) + aoff + m * 2048 + k * 1024); } while (0)
; #define PG8_LDB(dst, b, h) do { _Pragma("unroll") for (int n = 0; n < 2; ++n) _Pragma("unroll") for (int k = 0; k < 2; ++k) dst[n][k] = *(const PG8_LAS bf16x8*)(lds + PG8_SB(b, h) + boff + n * 2048 + k * 1024); } while (0)
; #define PG8_MMA(ai, bj, At, Bt) do { __builtin_amdgcn_s_setprio(1); _Pragma("unroll") for (int m = 0; m < 4; ++m) _Pragma("unroll") for (int n = 0; n < 2; ++n) _Pragma("unroll") for (int k = 0; k < 2; ++k) \
;         acc[ai][bj][m][n] = __builtin_amdgcn_mfma_f32_16x16x32_bf16(Bt[n][k], At[m][k], acc[ai][bj][m][n], 0, 0, 0); __builtin_amdgcn_s_setprio(0); } while (0)
; #define PG8_WAIT_V(n) asm volatile("s_waitcnt vmcnt(" #n ")" ::: "memory")
; #define PG8_WAIT_L(n) asm volatile("s_waitcnt lgkmcnt(" #n ")" ::: "memory")
; #define PG8_BAR __builtin_amdgcn_s_barrier()
; #define PG8_SCHED __builtin_amdgcn_sched_barrier(0)
; template <class Epi, class Sched, bool ALIGN_EPI = false, bool SP2 = false>
; __device__ __forceinline__ void gemm_phase(PG8_LAS unsigned char* lds, const Gemm g, const Sched& S, const Epi& E) {
;     ...
;             PG8_LDB(B0, 1, 0); PG8_LDB(B1, 1, 1); PG8_SCHED; PG8_LDA(At, 1, 0); PG8_STAGE(PG8_SA(0, 1), a2 + hstep, voffA);
;             PG8_WAIT_V(8); PG8_WAIT_L(0); PG8_BAR; PG8_MMA(0, 0, At, B0); PG8_MMA(0, 1, At, B1); PG8_BAR; PG8_SCHED;
	s_add_i32 s76, 0, 0x18000
	v_add_u32_e32 v134, s76, v159
	s_add_i32 s77, 0, 0x1c000
	ds_read_b128 v[154:157], v134
	ds_read_b128 v[164:167], v134 offset:1024
	ds_read_b128 v[168:171], v134 offset:2048
	ds_read_b128 v[172:175], v134 offset:3072
	v_add_u32_e32 v134, s77, v159
	ds_read_b128 v[176:179], v134
	ds_read_b128 v[180:183], v134 offset:1024
	ds_read_b128 v[184:187], v134 offset:2048
	ds_read_b128 v[188:191], v134 offset:3072
	s_add_u32 s42, s42, 0x80000
	s_addc_u32 s43, s43, 0
	s_mov_b32 m0, s58
	v_lshl_add_u64 v[238:239], s[42:43], 0, v[146:147]
	ds_read_b128 v[192:195], v163 offset:32768
	ds_read_b128 v[196:199], v163 offset:33792
	ds_read_b128 v[200:203], v163 offset:34816
	ds_read_b128 v[204:207], v163 offset:35840
	ds_read_b128 v[218:221], v163 offset:36864
	ds_read_b128 v[222:225], v163 offset:37888
	ds_read_b128 v[226:229], v163 offset:38912
	ds_read_b128 v[230:233], v163 offset:39936
	global_load_lds_dwordx4 v[238:239], off
	v_lshl_add_u64 v[238:239], s[42:43], 0, v[144:145]
	s_mov_b32 m0, s59
	s_nop 0
	global_load_lds_dwordx4 v[238:239], off
	s_waitcnt vmcnt(8)
	s_waitcnt lgkmcnt(0)
	s_barrier
	s_setprio 1
	s_waitcnt lgkmcnt(0)
	v_mfma_f32_16x16x32_bf16 v[124:127], v[154:157], v[192:195], v[124:127]
	v_mfma_f32_16x16x32_bf16 v[120:123], v[168:171], v[192:195], v[120:123]
	v_mfma_f32_16x16x32_bf16 v[108:111], v[154:157], v[200:203], v[108:111]
	v_mfma_f32_16x16x32_bf16 v[104:107], v[168:171], v[200:203], v[104:107]
	v_mfma_f32_16x16x32_bf16 v[92:95], v[154:157], v[218:221], v[92:95]
	v_mfma_f32_16x16x32_bf16 v[88:91], v[168:171], v[218:221], v[88:91]
	v_mfma_f32_16x16x32_bf16 v[76:79], v[154:157], v[226:229], v[76:79]
	v_mfma_f32_16x16x32_bf16 v[72:75], v[168:171], v[226:229], v[72:75]
	v_mfma_f32_16x16x32_bf16 v[124:127], v[164:167], v[196:199], v[124:127]
	v_mfma_f32_16x16x32_bf16 v[120:123], v[172:175], v[196:199], v[120:123]
	v_mfma_f32_16x16x32_bf16 v[108:111], v[164:167], v[204:207], v[108:111]
	v_mfma_f32_16x16x32_bf16 v[104:107], v[172:175], v[204:207], v[104:107]
	v_mfma_f32_16x16x32_bf16 v[92:95], v[164:167], v[222:225], v[92:95]
	v_mfma_f32_16x16x32_bf16 v[88:91], v[172:175], v[222:225], v[88:91]
	v_mfma_f32_16x16x32_bf16 v[76:79], v[164:167], v[230:233], v[76:79]
	v_mfma_f32_16x16x32_bf16 v[72:75], v[172:175], v[230:233], v[72:75]
	v_mfma_f32_16x16x32_bf16 v[116:119], v[176:179], v[192:195], v[116:119]
	v_mfma_f32_16x16x32_bf16 v[112:115], v[184:187], v[192:195], v[112:115]
	v_mfma_f32_16x16x32_bf16 v[100:103], v[176:179], v[200:203], v[100:103]
	v_mfma_f32_16x16x32_bf16 v[96:99], v[184:187], v[200:203], v[96:99]
	v_mfma_f32_16x16x32_bf16 v[84:87], v[176:179], v[218:221], v[84:87]
	v_mfma_f32_16x16x32_bf16 v[80:83], v[184:187], v[218:221], v[80:83]
	v_mfma_f32_16x16x32_bf16 v[68:71], v[176:179], v[226:229], v[68:71]
	v_mfma_f32_16x16x32_bf16 v[64:67], v[184:187], v[226:229], v[64:67]
	v_mfma_f32_16x16x32_bf16 v[116:119], v[180:183], v[196:199], v[116:119]
	v_mfma_f32_16x16x32_bf16 v[112:115], v[188:191], v[196:199], v[112:115]
	v_mfma_f32_16x16x32_bf16 v[100:103], v[180:183], v[204:207], v[100:103]
	v_mfma_f32_16x16x32_bf16 v[96:99], v[188:191], v[204:207], v[96:99]
	v_mfma_f32_16x16x32_bf16 v[84:87], v[180:183], v[222:225], v[84:87]
	v_mfma_f32_16x16x32_bf16 v[80:83], v[188:191], v[222:225], v[80:83]
	v_mfma_f32_16x16x32_bf16 v[68:71], v[180:183], v[230:233], v[68:71]
	v_mfma_f32_16x16x32_bf16 v[64:67], v[188:191], v[230:233], v[64:67]
	s_setprio 0
	s_barrier
; #define PG8_STAGE(bufoff, gbase, voff) do { _Pragma("unroll") for (int _i = 0; _i < 2; ++_i) \
;         __builtin_amdgcn_global_load_lds((const unsigned*)((const char*)(gbase) + (voff)[_i]), (PG8_LAS unsigned*)(lds + (bufoff) + ldsw + _i * 8192), 16, 0, 0); } while (0)
; #define PG8_LDA(dst, b, h) do { _Pragma("unroll") for (int m = 0; m < 4; ++m) _Pragma("unroll") for (int k = 0; k < 2; ++k) dst[m][k] = *(const PG8_LAS bf16x8*)(lds + PG8_SA(b, h) + aoff + m * 2048 + k * 1024); } while (0)
; #define PG8_MMA(ai, bj, At, Bt) do { __builtin_amdgcn_s_setprio(1); _Pragma("unroll") for (int m = 0; m < 4; ++m) _Pragma("unroll") for (int n = 0; n < 2; ++n) _Pragma("unroll") for (int k = 0; k < 2; ++k) \
;         acc[ai][bj][m][n] = __builtin_amdgcn_mfma_f32_16x16x32_bf16(Bt[n][k], At[m][k], acc[ai][bj][m][n], 0, 0, 0); __builtin_amdgcn_s_setprio(0); } while (0)
; #define PG8_WAIT_V(n) asm volatile("s_waitcnt vmcnt(" #n ")" ::: "memory")
; #define PG8_WAIT_L(n) asm volatile("s_waitcnt lgkmcnt(" #n ")" ::: "memory")
; #define PG8_BAR __builtin_amdgcn_s_barrier()
; #define PG8_SCHED __builtin_amdgcn_sched_barrier(0)
; template <class Epi, class Sched, bool ALIGN_EPI = false, bool SP2 = false>
; __device__ __forceinline__ void gemm_phase(PG8_LAS unsigned char* lds, const Gemm g, const Sched& S, const Epi& E) {
;     ...
;             PG8_LDA(At, 1, 1); PG8_STAGE(PG8_SB(1, 0), b3, voffB); PG8_STAGE(PG8_SB(1, 1), b3 + hstep, voffB); PG8_STAGE(PG8_SA(1, 0), a3, voffA);
;             PG8_WAIT_V(8); PG8_WAIT_L(0); PG8_BAR; PG8_MMA(1, 0, At, B0); PG8_MMA(1, 1, At, B1); PG8_BAR; PG8_SCHED;
;     ...
;         if constexpr (ALIGN_EPI) { if (wr == 0) PG8_BAR; }
	s_add_i32 s42, s76, s74
	v_lshl_add_u64 v[130:131], v[130:131], 0, s[78:79]
	s_mov_b32 m0, s42
	ds_read_b128 v[192:195], v163 offset:49152
	ds_read_b128 v[196:199], v163 offset:50176
	ds_read_b128 v[200:203], v163 offset:51200
	ds_read_b128 v[204:207], v163 offset:52224
	ds_read_b128 v[218:221], v163 offset:53248
	ds_read_b128 v[222:225], v163 offset:54272
	ds_read_b128 v[226:229], v163 offset:55296
	ds_read_b128 v[230:233], v163 offset:56320
	global_load_lds_dwordx4 v[130:131], off
	s_add_i32 m0, s42, 0x2000
	s_add_u32 s34, s34, 0x80080
	v_lshl_add_u64 v[130:131], v[132:133], 0, s[78:79]
	s_addc_u32 s35, s35, 0
	s_add_i32 s42, s77, s74
	global_load_lds_dwordx4 v[130:131], off
	v_lshl_add_u64 v[130:131], s[34:35], 0, v[128:129]
	s_mov_b32 m0, s42
	s_nop 0
	global_load_lds_dwordx4 v[130:131], off
	v_lshl_add_u64 v[130:131], s[34:35], 0, v[142:143]
	s_add_i32 m0, s42, 0x2000
	s_nop 0
	global_load_lds_dwordx4 v[130:131], off
	v_lshl_add_u64 v[130:131], v[234:235], 0, s[78:79]
	s_mov_b32 m0, s48
	s_nop 0
	global_load_lds_dwordx4 v[130:131], off
	v_lshl_add_u64 v[130:131], v[236:237], 0, s[78:79]
	s_mov_b32 m0, s36
	s_nop 0
	global_load_lds_dwordx4 v[130:131], off
	s_waitcnt vmcnt(8)
	s_waitcnt lgkmcnt(0)
	s_barrier
	s_setprio 1
	s_waitcnt lgkmcnt(0)
	v_mfma_f32_16x16x32_bf16 v[60:63], v[154:157], v[192:195], v[60:63]
	v_mfma_f32_16x16x32_bf16 v[56:59], v[168:171], v[192:195], v[56:59]
	v_mfma_f32_16x16x32_bf16 v[44:47], v[154:157], v[200:203], v[44:47]
	v_mfma_f32_16x16x32_bf16 v[40:43], v[168:171], v[200:203], v[40:43]
	v_mfma_f32_16x16x32_bf16 v[28:31], v[154:157], v[218:221], v[28:31]
	v_mfma_f32_16x16x32_bf16 v[24:27], v[168:171], v[218:221], v[24:27]
	v_mfma_f32_16x16x32_bf16 v[12:15], v[154:157], v[226:229], v[12:15]
	v_mfma_f32_16x16x32_bf16 v[8:11], v[168:171], v[226:229], v[8:11]
	v_mfma_f32_16x16x32_bf16 v[60:63], v[164:167], v[196:199], v[60:63]
	v_mfma_f32_16x16x32_bf16 v[56:59], v[172:175], v[196:199], v[56:59]
	v_mfma_f32_16x16x32_bf16 v[44:47], v[164:167], v[204:207], v[44:47]
	v_mfma_f32_16x16x32_bf16 v[40:43], v[172:175], v[204:207], v[40:43]
	v_mfma_f32_16x16x32_bf16 v[28:31], v[164:167], v[222:225], v[28:31]
	v_mfma_f32_16x16x32_bf16 v[24:27], v[172:175], v[222:225], v[24:27]
	v_mfma_f32_16x16x32_bf16 v[12:15], v[164:167], v[230:233], v[12:15]
	v_mfma_f32_16x16x32_bf16 v[8:11], v[172:175], v[230:233], v[8:11]
	v_mfma_f32_16x16x32_bf16 v[52:55], v[176:179], v[192:195], v[52:55]
	v_mfma_f32_16x16x32_bf16 v[48:51], v[184:187], v[192:195], v[48:51]
	v_mfma_f32_16x16x32_bf16 v[36:39], v[176:179], v[200:203], v[36:39]
	v_mfma_f32_16x16x32_bf16 v[32:35], v[184:187], v[200:203], v[32:35]
	v_mfma_f32_16x16x32_bf16 v[20:23], v[176:179], v[218:221], v[20:23]
	v_mfma_f32_16x16x32_bf16 v[16:19], v[184:187], v[218:221], v[16:19]
	v_mfma_f32_16x16x32_bf16 v[4:7], v[176:179], v[226:229], v[4:7]
	v_mfma_f32_16x16x32_bf16 v[0:3], v[184:187], v[226:229], v[0:3]
	v_mfma_f32_16x16x32_bf16 v[52:55], v[180:183], v[196:199], v[52:55]
	v_mfma_f32_16x16x32_bf16 v[48:51], v[188:191], v[196:199], v[48:51]
	v_mfma_f32_16x16x32_bf16 v[36:39], v[180:183], v[204:207], v[36:39]
	v_mfma_f32_16x16x32_bf16 v[32:35], v[188:191], v[204:207], v[32:35]
	v_mfma_f32_16x16x32_bf16 v[20:23], v[180:183], v[222:225], v[20:23]
	v_mfma_f32_16x16x32_bf16 v[16:19], v[188:191], v[222:225], v[16:19]
	v_mfma_f32_16x16x32_bf16 v[4:7], v[180:183], v[230:233], v[4:7]
	v_mfma_f32_16x16x32_bf16 v[0:3], v[188:191], v[230:233], v[0:3]
	s_setprio 0
	s_barrier
	s_add_i32 s69, s69, 2
	s_add_u32 s30, s30, 0x100
	s_addc_u32 s31, s31, 0
	s_add_u32 s62, s62, 0x100
	s_addc_u32 s68, s68, 0
	s_cmp_gt_u32 s69, 29
	s_cbranch_scc0 .LBB0_955
	s_and_b64 vcc, exec, s[18:19]
	s_cbranch_vccz .LBB0_958
	s_barrier

; template <class Epi, class Sched, bool ALIGN_EPI = false, bool SP2 = false>
; __device__ __forceinline__ void gemm_phase(PG8_LAS unsigned char* lds, const Gemm g, const Sched& S, const Epi& E) {
;     ...
;         const char* nA = has_next ? (const char*)g.A + (size_t)nxt.pm * tstep : cA; const char* nB = has_next ? (const char*)g.Bt + (size_t)nxt.pn * tstep : cB;
;         for (int t = 0; t < nt; t += 2) {
;             const bool last = (t == nt - 2);
;             const char* a1 = cA + (size_t)(t + 1) * kstep;
;             const char* a2 = last ? nA : cA + (size_t)(t + 2) * kstep; const char* b2 = last ? nB : cB + (size_t)(t + 2) * kstep;
.LBB0_1026:
	s_add_u32 s44, s26, 0x100

; template <class Epi, class Sched, bool ALIGN_EPI = false, bool SP2 = false>
; __device__ __forceinline__ void gemm_phase(PG8_LAS unsigned char* lds, const Gemm g, const Sched& S, const Epi& E) {
;     ...
;         for (int t = 0; t < nt; t += 2) {
;             const bool last = (t == nt - 2);
	s_addc_u32 s45, s27, 0
	s_mov_b32 s74, -2
	s_waitcnt lgkmcnt(0)


; #define PG8_STAGE(bufoff, gbase, voff) do { _Pragma("unroll") for (int _i = 0; _i < 2; ++_i) \
;         __builtin_amdgcn_global_load_lds((const unsigned*)((const char*)(gbase) + (voff)[_i]), (PG8_LAS unsigned*)(lds + (bufoff) + ldsw + _i * 8192), 16, 0, 0); } while (0)
; #define PG8_LDA(dst, b, h) do { _Pragma("unroll") for (int m = 0; m < 4; ++m) _Pragma("unroll") for (int k = 0; k < 2; ++k) dst[m][k] = *(const PG8_LAS bf16x8*)(lds + PG8_SA(b, h) + aoff + m * 2048 + k * 1024); } while (0)
; #define PG8_LDB(dst, b, h) do { _Pragma("unroll") for (int n = 0; n < 2; ++n) _Pragma("unroll") for (int k = 0; k < 2; ++k) dst[n][k] = *(const PG8_LAS bf16x8*)(lds + PG8_SB(b, h) + boff + n * 2048 + k * 1024); } while (0)
; #define PG8_WAIT_V(n) asm volatile("s_waitcnt vmcnt(" #n ")" ::: "memory")
; #define PG8_WAIT_L(n) asm volatile("s_waitcnt lgkmcnt(" #n ")" ::: "memory")
; #define PG8_BAR __builtin_amdgcn_s_barrier()
; #define PG8_SCHED __builtin_amdgcn_sched_barrier(0)
; template <class Epi, class Sched, bool ALIGN_EPI = false, bool SP2 = false>
; __device__ __forceinline__ void gemm_phase(PG8_LAS unsigned char* lds, const Gemm g, const Sched& S, const Epi& E) {
;     ...
;         const bool has_next = S.next(ui + 1, nxt);
;         const char* nA = has_next ? (const char*)g.A + (size_t)nxt.pm * tstep : cA; const char* nB = has_next ? (const char*)g.Bt + (size_t)nxt.pn * tstep : cB;
;         for (int t = 0; t < nt; t += 2) {
;             const bool last = (t == nt - 2);
;             const char* a1 = cA + (size_t)(t + 1) * kstep;
;             const char* a2 = last ? nA : cA + (size_t)(t + 2) * kstep; const char* b2 = last ? nB : cB + (size_t)(t + 2) * kstep;
;             const char* a3 = a2 + kstep; const char* b3 = b2 + kstep;
;             if (last && has_next) S.a_ready(nxt);
;             if constexpr (SP2) {
;             PG8_LDB(B0, 0, 0); PG8_LDB(B1, 0, 1); PG8_SCHED; PG8_LDA(At, 0, 0); PG8_STAGE(PG8_SA(1, 1), a1 + hstep, voffA);
;             PG8_WAIT_V(8); PG8_WAIT_L(0); PG8_BAR; PG8_MMA(0, 0, At, B0); PG8_MMA(0, 1, At, B1); PG8_BAR; PG8_SCHED;
;             PG8_LDA(At, 0, 1); PG8_STAGE(PG8_SB(0, 0), b2, voffB); PG8_STAGE(PG8_SB(0, 1), b2 + hstep, voffB); PG8_STAGE(PG8_SA(0, 0), a2, voffA);
;             PG8_WAIT_V(8); PG8_WAIT_L(0); PG8_BAR; PG8_MMA(1, 0, At, B0); PG8_MMA(1, 1, At, B1); PG8_BAR; PG8_SCHED;
	s_add_u32 s26, s24, 0x100
	s_addc_u32 s27, s25, 0
	s_add_i32 s77, 0, 0x10000
	s_cmpk_eq_i32 s74, 0x54
	s_cselect_b32 s31, s21, s27
	s_cselect_b32 s30, s20, s26
	v_add_u32_e32 v130, s77, v191
	s_cselect_b32 s29, s23, s45
	s_cselect_b32 s28, s22, s44
	s_add_i32 vcc_lo, 0, 0x14000
	ds_read_b128 v[148:151], v130
	ds_read_b128 v[152:155], v130 offset:1024
	ds_read_b128 v[156:159], v130 offset:2048
	ds_read_b128 v[160:163], v130 offset:3072
	v_add_u32_e32 v130, vcc_lo, v191
	ds_read_b128 v[164:167], v130
	ds_read_b128 v[168:171], v130 offset:1024
	ds_read_b128 v[172:175], v130 offset:2048
	ds_read_b128 v[176:179], v130 offset:3072
	v_lshl_add_u64 v[130:131], s[24:25], 0, v[144:145]
	s_add_i32 m0, s55, 0xc000
	ds_read_b128 v[180:183], v193
	ds_read_b128 v[184:187], v193 offset:1024
	ds_read_b128 v[194:197], v193 offset:2048
	ds_read_b128 v[198:201], v193 offset:3072
	ds_read_b128 v[202:205], v193 offset:4096
	ds_read_b128 v[218:221], v193 offset:5120
	ds_read_b128 v[222:225], v193 offset:6144
	ds_read_b128 v[226:229], v193 offset:7168
	global_load_lds_dwordx4 v[130:131], off
	v_lshl_add_u64 v[130:131], s[24:25], 0, v[146:147]
	s_add_i32 m0, s55, 0xe000
	s_nop 0
	global_load_lds_dwordx4 v[130:131], off
	s_waitcnt vmcnt(8)
	s_waitcnt lgkmcnt(0)
	s_barrier
	s_setprio 1
	s_waitcnt lgkmcnt(0)
	v_mfma_f32_16x16x32_bf16 v[124:127], v[148:151], v[180:183], 0
	v_mfma_f32_16x16x32_bf16 v[120:123], v[156:159], v[180:183], 0
	v_mfma_f32_16x16x32_bf16 v[108:111], v[148:151], v[194:197], 0
	v_mfma_f32_16x16x32_bf16 v[104:107], v[156:159], v[194:197], 0
	v_mfma_f32_16x16x32_bf16 v[92:95], v[148:151], v[202:205], 0
	v_mfma_f32_16x16x32_bf16 v[88:91], v[156:159], v[202:205], 0
	v_mfma_f32_16x16x32_bf16 v[76:79], v[148:151], v[222:225], 0
	v_mfma_f32_16x16x32_bf16 v[72:75], v[156:159], v[222:225], 0
	v_mfma_f32_16x16x32_bf16 v[124:127], v[152:155], v[184:187], v[124:127]
	v_mfma_f32_16x16x32_bf16 v[120:123], v[160:163], v[184:187], v[120:123]
	v_mfma_f32_16x16x32_bf16 v[108:111], v[152:155], v[198:201], v[108:111]
	v_mfma_f32_16x16x32_bf16 v[104:107], v[160:163], v[198:201], v[104:107]
	v_mfma_f32_16x16x32_bf16 v[92:95], v[152:155], v[218:221], v[92:95]
	v_mfma_f32_16x16x32_bf16 v[88:91], v[160:163], v[218:221], v[88:91]
	v_mfma_f32_16x16x32_bf16 v[76:79], v[152:155], v[226:229], v[76:79]
	v_mfma_f32_16x16x32_bf16 v[72:75], v[160:163], v[226:229], v[72:75]
	v_mfma_f32_16x16x32_bf16 v[116:119], v[164:167], v[180:183], 0
	v_mfma_f32_16x16x32_bf16 v[112:115], v[172:175], v[180:183], 0
	v_mfma_f32_16x16x32_bf16 v[100:103], v[164:167], v[194:197], 0
	v_mfma_f32_16x16x32_bf16 v[96:99], v[172:175], v[194:197], 0
	v_mfma_f32_16x16x32_bf16 v[84:87], v[164:167], v[202:205], 0
	v_mfma_f32_16x16x32_bf16 v[80:83], v[172:175], v[202:205], 0
	v_mfma_f32_16x16x32_bf16 v[68:71], v[164:167], v[222:225], 0
	v_mfma_f32_16x16x32_bf16 v[64:67], v[172:175], v[222:225], 0
	v_mfma_f32_16x16x32_bf16 v[116:119], v[168:171], v[184:187], v[116:119]
	v_mfma_f32_16x16x32_bf16 v[112:115], v[176:179], v[184:187], v[112:115]
	v_mfma_f32_16x16x32_bf16 v[100:103], v[168:171], v[198:201], v[100:103]
	v_mfma_f32_16x16x32_bf16 v[96:99], v[176:179], v[198:201], v[96:99]
	v_mfma_f32_16x16x32_bf16 v[84:87], v[168:171], v[218:221], v[84:87]
	v_mfma_f32_16x16x32_bf16 v[80:83], v[176:179], v[218:221], v[80:83]
	v_mfma_f32_16x16x32_bf16 v[68:71], v[168:171], v[226:229], v[68:71]
	v_mfma_f32_16x16x32_bf16 v[64:67], v[176:179], v[226:229], v[64:67]
	s_setprio 0
	s_barrier
	s_add_i32 s24, s77, s54
	v_lshl_add_u64 v[130:131], s[28:29], 0, v[128:129]
	s_mov_b32 m0, s24
	ds_read_b128 v[180:183], v193 offset:16384
	ds_read_b128 v[184:187], v193 offset:17408
	ds_read_b128 v[194:197], v193 offset:18432
	ds_read_b128 v[198:201], v193 offset:19456
	ds_read_b128 v[202:205], v193 offset:20480
	ds_read_b128 v[218:221], v193 offset:21504
	ds_read_b128 v[222:225], v193 offset:22528
	ds_read_b128 v[226:229], v193 offset:23552
	global_load_lds_dwordx4 v[130:131], off
	s_add_i32 m0, s24, 0x2000
	s_add_u32 s24, s28, 0x160000
	v_lshl_add_u64 v[132:133], s[28:29], 0, v[142:143]
	s_addc_u32 s25, s29, 0
	s_add_i32 s77, vcc_lo, s54
	global_load_lds_dwordx4 v[132:133], off
	v_lshl_add_u64 v[188:189], s[24:25], 0, v[128:129]
	s_mov_b32 m0, s77
	v_lshl_add_u64 v[206:207], s[30:31], 0, v[142:143]
	global_load_lds_dwordx4 v[188:189], off
	v_lshl_add_u64 v[188:189], s[24:25], 0, v[142:143]
	s_add_i32 m0, s77, 0x2000
	s_nop 0
	global_load_lds_dwordx4 v[188:189], off
	v_lshl_add_u64 v[188:189], s[30:31], 0, v[128:129]
	s_mov_b32 m0, s55
	s_nop 0
	global_load_lds_dwordx4 v[188:189], off
	s_mov_b32 m0, s56
	s_nop 0
	global_load_lds_dwordx4 v[206:207], off
	s_waitcnt vmcnt(8)
	s_waitcnt lgkmcnt(0)
	s_barrier
; #define PG8_STAGE(bufoff, gbase, voff) do { _Pragma("unroll") for (int _i = 0; _i < 2; ++_i) \
;         __builtin_amdgcn_global_load_lds((const unsigned*)((const char*)(gbase) + (voff)[_i]), (PG8_LAS unsigned*)(lds + (bufoff) + ldsw + _i * 8192), 16, 0, 0); } while (0)
; #define PG8_LDA(dst, b, h) do { _Pragma("unroll") for (int m = 0; m < 4; ++m) _Pragma("unroll") for (int k = 0; k < 2; ++k) dst[m][k] = *(const PG8_LAS bf16x8*)(lds + PG8_SA(b, h) + aoff + m * 2048 + k * 1024); } while (0)
; #define PG8_LDB(dst, b, h) do { _Pragma("unroll") for (int n = 0; n < 2; ++n) _Pragma("unroll") for (int k = 0; k < 2; ++k) dst[n][k] = *(const PG8_LAS bf16x8*)(lds + PG8_SB(b, h) + boff + n * 2048 + k * 1024); } while (0)
; #define PG8_MMA(ai, bj, At, Bt) do { __builtin_amdgcn_s_setprio(1); _Pragma("unroll") for (int m = 0; m < 4; ++m) _Pragma("unroll") for (int n = 0; n < 2; ++n) _Pragma("unroll") for (int k = 0; k < 2; ++k) \
;         acc[ai][bj][m][n] = __builtin_amdgcn_mfma_f32_16x16x32_bf16(Bt[n][k], At[m][k], acc[ai][bj][m][n], 0, 0, 0); __builtin_amdgcn_s_setprio(0); } while (0)
; #define PG8_WAIT_V(n) asm volatile("s_waitcnt vmcnt(" #n ")" ::: "memory")
; #define PG8_WAIT_L(n) asm volatile("s_waitcnt lgkmcnt(" #n ")" ::: "memory")
; #define PG8_BAR __builtin_amdgcn_s_barrier()
; #define PG8_SCHED __builtin_amdgcn_sched_barrier(0)
; template <class Epi, class Sched, bool ALIGN_EPI = false, bool SP2 = false>
; __device__ __forceinline__ void gemm_phase(PG8_LAS unsigned char* lds, const Gemm g, const Sched& S, const Epi& E) {
;     ...
;             PG8_WAIT_V(8); PG8_WAIT_L(0); PG8_BAR; PG8_MMA(1, 0, At, B0); PG8_MMA(1, 1, At, B1); PG8_BAR; PG8_SCHED;
;             PG8_LDB(B0, 1, 0); PG8_LDB(B1, 1, 1); PG8_SCHED; PG8_LDA(At, 1, 0); PG8_STAGE(PG8_SA(0, 1), a2 + hstep, voffA);
;             PG8_WAIT_V(8); PG8_WAIT_L(0); PG8_BAR; PG8_MMA(0, 0, At, B0); PG8_MMA(0, 1, At, B1); PG8_BAR; PG8_SCHED;
	s_setprio 1
	s_waitcnt lgkmcnt(0)
	v_mfma_f32_16x16x32_bf16 v[60:63], v[148:151], v[180:183], 0
	v_mfma_f32_16x16x32_bf16 v[56:59], v[156:159], v[180:183], 0
	v_mfma_f32_16x16x32_bf16 v[44:47], v[148:151], v[194:197], 0
	v_mfma_f32_16x16x32_bf16 v[40:43], v[156:159], v[194:197], 0
	v_mfma_f32_16x16x32_bf16 v[28:31], v[148:151], v[202:205], 0
	v_mfma_f32_16x16x32_bf16 v[24:27], v[156:159], v[202:205], 0
	v_mfma_f32_16x16x32_bf16 v[12:15], v[148:151], v[222:225], 0
	v_mfma_f32_16x16x32_bf16 v[8:11], v[156:159], v[222:225], 0
	v_mfma_f32_16x16x32_bf16 v[60:63], v[152:155], v[184:187], v[60:63]
	v_mfma_f32_16x16x32_bf16 v[56:59], v[160:163], v[184:187], v[56:59]
	v_mfma_f32_16x16x32_bf16 v[44:47], v[152:155], v[198:201], v[44:47]
	v_mfma_f32_16x16x32_bf16 v[40:43], v[160:163], v[198:201], v[40:43]
	v_mfma_f32_16x16x32_bf16 v[28:31], v[152:155], v[218:221], v[28:31]
	v_mfma_f32_16x16x32_bf16 v[24:27], v[160:163], v[218:221], v[24:27]
	v_mfma_f32_16x16x32_bf16 v[12:15], v[152:155], v[226:229], v[12:15]
	v_mfma_f32_16x16x32_bf16 v[8:11], v[160:163], v[226:229], v[8:11]
	v_mfma_f32_16x16x32_bf16 v[52:55], v[164:167], v[180:183], 0
	v_mfma_f32_16x16x32_bf16 v[48:51], v[172:175], v[180:183], 0
	v_mfma_f32_16x16x32_bf16 v[36:39], v[164:167], v[194:197], 0
	v_mfma_f32_16x16x32_bf16 v[32:35], v[172:175], v[194:197], 0
	v_mfma_f32_16x16x32_bf16 v[20:23], v[164:167], v[202:205], 0
	v_mfma_f32_16x16x32_bf16 v[16:19], v[172:175], v[202:205], 0
	v_mfma_f32_16x16x32_bf16 v[4:7], v[164:167], v[222:225], 0
	v_mfma_f32_16x16x32_bf16 v[0:3], v[172:175], v[222:225], 0
	v_mfma_f32_16x16x32_bf16 v[52:55], v[168:171], v[184:187], v[52:55]
	v_mfma_f32_16x16x32_bf16 v[48:51], v[176:179], v[184:187], v[48:51]
	v_mfma_f32_16x16x32_bf16 v[36:39], v[168:171], v[198:201], v[36:39]
	v_mfma_f32_16x16x32_bf16 v[32:35], v[176:179], v[198:201], v[32:35]
	v_mfma_f32_16x16x32_bf16 v[20:23], v[168:171], v[218:221], v[20:23]
	v_mfma_f32_16x16x32_bf16 v[16:19], v[176:179], v[218:221], v[16:19]
	v_mfma_f32_16x16x32_bf16 v[4:7], v[168:171], v[226:229], v[4:7]
	v_mfma_f32_16x16x32_bf16 v[0:3], v[176:179], v[226:229], v[0:3]
	s_setprio 0
	s_barrier
	s_add_i32 s77, 0, 0x18000
	v_add_u32_e32 v134, s77, v191
	s_add_i32 vcc_lo, 0, 0x1c000
	ds_read_b128 v[148:151], v134
	ds_read_b128 v[152:155], v134 offset:1024
	ds_read_b128 v[156:159], v134 offset:2048
	ds_read_b128 v[160:163], v134 offset:3072
	v_add_u32_e32 v134, vcc_lo, v191
	ds_read_b128 v[164:167], v134
	ds_read_b128 v[168:171], v134 offset:1024
	ds_read_b128 v[172:175], v134 offset:2048
	ds_read_b128 v[176:179], v134 offset:3072
	s_add_u32 s24, s30, 0x160000
	s_addc_u32 s25, s31, 0
	s_mov_b32 m0, s57
	v_lshl_add_u64 v[230:231], s[24:25], 0, v[128:129]
	ds_read_b128 v[180:183], v193 offset:32768
	ds_read_b128 v[184:187], v193 offset:33792
	ds_read_b128 v[194:197], v193 offset:34816
	ds_read_b128 v[198:201], v193 offset:35840
	ds_read_b128 v[202:205], v193 offset:36864
	ds_read_b128 v[218:221], v193 offset:37888
	ds_read_b128 v[222:225], v193 offset:38912
	ds_read_b128 v[226:229], v193 offset:39936
	global_load_lds_dwordx4 v[230:231], off
	v_lshl_add_u64 v[230:231], s[24:25], 0, v[142:143]
	s_mov_b32 m0, s58
	s_nop 0
	global_load_lds_dwordx4 v[230:231], off
	s_waitcnt vmcnt(8)
	s_waitcnt lgkmcnt(0)
	s_barrier
	s_setprio 1
	s_waitcnt lgkmcnt(0)
	v_mfma_f32_16x16x32_bf16 v[124:127], v[148:151], v[180:183], v[124:127]
	v_mfma_f32_16x16x32_bf16 v[120:123], v[156:159], v[180:183], v[120:123]
	v_mfma_f32_16x16x32_bf16 v[108:111], v[148:151], v[194:197], v[108:111]
	v_mfma_f32_16x16x32_bf16 v[104:107], v[156:159], v[194:197], v[104:107]
	v_mfma_f32_16x16x32_bf16 v[92:95], v[148:151], v[202:205], v[92:95]
	v_mfma_f32_16x16x32_bf16 v[88:91], v[156:159], v[202:205], v[88:91]
	v_mfma_f32_16x16x32_bf16 v[76:79], v[148:151], v[222:225], v[76:79]
	v_mfma_f32_16x16x32_bf16 v[72:75], v[156:159], v[222:225], v[72:75]
	v_mfma_f32_16x16x32_bf16 v[124:127], v[152:155], v[184:187], v[124:127]
	v_mfma_f32_16x16x32_bf16 v[120:123], v[160:163], v[184:187], v[120:123]
	v_mfma_f32_16x16x32_bf16 v[108:111], v[152:155], v[198:201], v[108:111]
	v_mfma_f32_16x16x32_bf16 v[104:107], v[160:163], v[198:201], v[104:107]
	v_mfma_f32_16x16x32_bf16 v[92:95], v[152:155], v[218:221], v[92:95]
	v_mfma_f32_16x16x32_bf16 v[88:91], v[160:163], v[218:221], v[88:91]
	v_mfma_f32_16x16x32_bf16 v[76:79], v[152:155], v[226:229], v[76:79]
	v_mfma_f32_16x16x32_bf16 v[72:75], v[160:163], v[226:229], v[72:75]
	v_mfma_f32_16x16x32_bf16 v[116:119], v[164:167], v[180:183], v[116:119]
	v_mfma_f32_16x16x32_bf16 v[112:115], v[172:175], v[180:183], v[112:115]
	v_mfma_f32_16x16x32_bf16 v[100:103], v[164:167], v[194:197], v[100:103]
	v_mfma_f32_16x16x32_bf16 v[96:99], v[172:175], v[194:197], v[96:99]
	v_mfma_f32_16x16x32_bf16 v[84:87], v[164:167], v[202:205], v[84:87]
	v_mfma_f32_16x16x32_bf16 v[80:83], v[172:175], v[202:205], v[80:83]
	v_mfma_f32_16x16x32_bf16 v[68:71], v[164:167], v[222:225], v[68:71]
	v_mfma_f32_16x16x32_bf16 v[64:67], v[172:175], v[222:225], v[64:67]
	v_mfma_f32_16x16x32_bf16 v[116:119], v[168:171], v[184:187], v[116:119]
	v_mfma_f32_16x16x32_bf16 v[112:115], v[176:179], v[184:187], v[112:115]
	v_mfma_f32_16x16x32_bf16 v[100:103], v[168:171], v[198:201], v[100:103]
	v_mfma_f32_16x16x32_bf16 v[96:99], v[176:179], v[198:201], v[96:99]
	v_mfma_f32_16x16x32_bf16 v[84:87], v[168:171], v[218:221], v[84:87]
	v_mfma_f32_16x16x32_bf16 v[80:83], v[176:179], v[218:221], v[80:83]
	v_mfma_f32_16x16x32_bf16 v[68:71], v[168:171], v[226:229], v[68:71]
	v_mfma_f32_16x16x32_bf16 v[64:67], v[176:179], v[226:229], v[64:67]
	s_setprio 0
	s_barrier
; #define PG8_STAGE(bufoff, gbase, voff) do { _Pragma("unroll") for (int _i = 0; _i < 2; ++_i) \
;         __builtin_amdgcn_global_load_lds((const unsigned*)((const char*)(gbase) + (voff)[_i]), (PG8_LAS unsigned*)(lds + (bufoff) + ldsw + _i * 8192), 16, 0, 0); } while (0)
; #define PG8_LDA(dst, b, h) do { _Pragma("unroll") for (int m = 0; m < 4; ++m) _Pragma("unroll") for (int k = 0; k < 2; ++k) dst[m][k] = *(const PG8_LAS bf16x8*)(lds + PG8_SA(b, h) + aoff + m * 2048 + k * 1024); } while (0)
; template <class Epi, class Sched, bool ALIGN_EPI = false, bool SP2 = false>
; __device__ __forceinline__ void gemm_phase(PG8_LAS unsigned char* lds, const Gemm g, const Sched& S, const Epi& E) {
;     ...
;         const bool has_next = S.next(ui + 1, nxt);
;         const char* nA = has_next ? (const char*)g.A + (size_t)nxt.pm * tstep : cA; const char* nB = has_next ? (const char*)g.Bt + (size_t)nxt.pn * tstep : cB;
;         for (int t = 0; t < nt; t += 2) {
;             const bool last = (t == nt - 2);
;             const char* a1 = cA + (size_t)(t + 1) * kstep;
;             const char* a2 = last ? nA : cA + (size_t)(t + 2) * kstep; const char* b2 = last ? nB : cB + (size_t)(t + 2) * kstep;
;             const char* a3 = a2 + kstep; const char* b3 = b2 + kstep;
;             if (last && has_next) S.a_ready(nxt);
;             if constexpr (SP2) {
;             PG8_LDB(B0, 0, 0); PG8_LDB(B1, 0, 1); PG8_SCHED; PG8_LDA(At, 0, 0); PG8_STAGE(PG8_SA(1, 1), a1 + hstep, voffA);
;             PG8_WAIT_V(8); PG8_WAIT_L(0); PG8_BAR; PG8_MMA(0, 0, At, B0); PG8_MMA(0, 1, At, B1); PG8_BAR; PG8_SCHED;
;             PG8_LDA(At, 0, 1); PG8_STAGE(PG8_SB(0, 0), b2, voffB); PG8_STAGE(PG8_SB(0, 1), b2 + hstep, voffB); PG8_STAGE(PG8_SA(0, 0), a2, voffA);
;             PG8_WAIT_V(8); PG8_WAIT_L(0); PG8_BAR; PG8_MMA(1, 0, At, B0); PG8_MMA(1, 1, At, B1); PG8_BAR; PG8_SCHED;
;             PG8_LDB(B0, 1, 0); PG8_LDB(B1, 1, 1); PG8_SCHED; PG8_LDA(At, 1, 0); PG8_STAGE(PG8_SA(0, 1), a2 + hstep, voffA);
;             PG8_WAIT_V(8); PG8_WAIT_L(0); PG8_BAR; PG8_MMA(0, 0, At, B0); PG8_MMA(0, 1, At, B1); PG8_BAR; PG8_SCHED;
;             PG8_LDA(At, 1, 1); PG8_STAGE(PG8_SB(1, 0), b3, voffB); PG8_STAGE(PG8_SB(1, 1), b3 + hstep, voffB); PG8_STAGE(PG8_SA(1, 0), a3, voffA);
;             PG8_WAIT_V(8); PG8_WAIT_L(0); PG8_BAR; PG8_MMA(1, 0, At, B0); PG8_MMA(1, 1, At, B1); PG8_BAR; PG8_SCHED;
	s_add_i32 s24, s77, s54
	v_lshl_add_u64 v[130:131], v[130:131], 0, s[78:79]
	s_mov_b32 m0, s24
	ds_read_b128 v[180:183], v193 offset:49152
	ds_read_b128 v[184:187], v193 offset:50176
	ds_read_b128 v[194:197], v193 offset:51200
	ds_read_b128 v[198:201], v193 offset:52224
	ds_read_b128 v[202:205], v193 offset:53248
	ds_read_b128 v[218:221], v193 offset:54272
	ds_read_b128 v[222:225], v193 offset:55296
	ds_read_b128 v[226:229], v193 offset:56320
	global_load_lds_dwordx4 v[130:131], off
	s_add_i32 m0, s24, 0x2000
	s_add_u32 s24, s28, 0x160080
	v_lshl_add_u64 v[130:131], v[132:133], 0, s[78:79]
	s_addc_u32 s25, s29, 0
	s_add_i32 s28, vcc_lo, s54
	global_load_lds_dwordx4 v[130:131], off
	v_lshl_add_u64 v[130:131], s[24:25], 0, v[128:129]
	s_mov_b32 m0, s28
	s_nop 0
	global_load_lds_dwordx4 v[130:131], off
	v_lshl_add_u64 v[130:131], s[24:25], 0, v[142:143]
	s_add_i32 m0, s28, 0x2000
	s_nop 0
	global_load_lds_dwordx4 v[130:131], off
	v_lshl_add_u64 v[130:131], v[188:189], 0, s[78:79]
	s_mov_b32 m0, s60
	s_nop 0
	global_load_lds_dwordx4 v[130:131], off
	v_lshl_add_u64 v[130:131], v[206:207], 0, s[78:79]
	s_mov_b32 m0, s61
	s_nop 0
	global_load_lds_dwordx4 v[130:131], off
	s_waitcnt vmcnt(8)
	s_waitcnt lgkmcnt(0)
	s_barrier
	s_setprio 1
	s_waitcnt lgkmcnt(0)
	v_mfma_f32_16x16x32_bf16 v[60:63], v[148:151], v[180:183], v[60:63]
	v_mfma_f32_16x16x32_bf16 v[56:59], v[156:159], v[180:183], v[56:59]
	v_mfma_f32_16x16x32_bf16 v[44:47], v[148:151], v[194:197], v[44:47]
	v_mfma_f32_16x16x32_bf16 v[40:43], v[156:159], v[194:197], v[40:43]
	v_mfma_f32_16x16x32_bf16 v[28:31], v[148:151], v[202:205], v[28:31]
	v_mfma_f32_16x16x32_bf16 v[24:27], v[156:159], v[202:205], v[24:27]
	v_mfma_f32_16x16x32_bf16 v[12:15], v[148:151], v[222:225], v[12:15]
	v_mfma_f32_16x16x32_bf16 v[8:11], v[156:159], v[222:225], v[8:11]
	v_mfma_f32_16x16x32_bf16 v[60:63], v[152:155], v[184:187], v[60:63]
	v_mfma_f32_16x16x32_bf16 v[56:59], v[160:163], v[184:187], v[56:59]
	v_mfma_f32_16x16x32_bf16 v[44:47], v[152:155], v[198:201], v[44:47]
	v_mfma_f32_16x16x32_bf16 v[40:43], v[160:163], v[198:201], v[40:43]
	v_mfma_f32_16x16x32_bf16 v[28:31], v[152:155], v[218:221], v[28:31]
	v_mfma_f32_16x16x32_bf16 v[24:27], v[160:163], v[218:221], v[24:27]
	v_mfma_f32_16x16x32_bf16 v[12:15], v[152:155], v[226:229], v[12:15]
	v_mfma_f32_16x16x32_bf16 v[8:11], v[160:163], v[226:229], v[8:11]
	v_mfma_f32_16x16x32_bf16 v[52:55], v[164:167], v[180:183], v[52:55]
	v_mfma_f32_16x16x32_bf16 v[48:51], v[172:175], v[180:183], v[48:51]
	v_mfma_f32_16x16x32_bf16 v[36:39], v[164:167], v[194:197], v[36:39]
	v_mfma_f32_16x16x32_bf16 v[32:35], v[172:175], v[194:197], v[32:35]
	v_mfma_f32_16x16x32_bf16 v[20:23], v[164:167], v[202:205], v[20:23]
	v_mfma_f32_16x16x32_bf16 v[16:19], v[172:175], v[202:205], v[16:19]
	v_mfma_f32_16x16x32_bf16 v[4:7], v[164:167], v[222:225], v[4:7]
	v_mfma_f32_16x16x32_bf16 v[0:3], v[172:175], v[222:225], v[0:3]
	v_mfma_f32_16x16x32_bf16 v[52:55], v[168:171], v[184:187], v[52:55]
	v_mfma_f32_16x16x32_bf16 v[48:51], v[176:179], v[184:187], v[48:51]
	v_mfma_f32_16x16x32_bf16 v[36:39], v[168:171], v[198:201], v[36:39]
	v_mfma_f32_16x16x32_bf16 v[32:35], v[176:179], v[198:201], v[32:35]
	v_mfma_f32_16x16x32_bf16 v[20:23], v[168:171], v[218:221], v[20:23]
	v_mfma_f32_16x16x32_bf16 v[16:19], v[176:179], v[218:221], v[16:19]
	v_mfma_f32_16x16x32_bf16 v[4:7], v[168:171], v[226:229], v[4:7]
	v_mfma_f32_16x16x32_bf16 v[0:3], v[176:179], v[226:229], v[0:3]
	s_setprio 0
	s_barrier
	s_add_i32 s74, s74, 2
	s_add_u32 s44, s44, 0x100
	s_addc_u32 s45, s45, 0
	s_cmpk_gt_u32 s74, 0x55
	s_mov_b64 s[24:25], s[26:27]
.LBB0_1027:
	s_add_u32 s26, s24, 0x100
	s_addc_u32 s27, s25, 0
	s_add_i32 s77, 0, 0x10000
	s_cmpk_eq_i32 s74, 0x54
	s_cselect_b32 s31, s21, s27
	s_cselect_b32 s30, s20, s26
	v_add_u32_e32 v130, s77, v191
	s_cselect_b32 s29, s23, s45
	s_cselect_b32 s28, s22, s44
	s_add_i32 vcc_lo, 0, 0x14000
	ds_read_b128 v[148:151], v130
	ds_read_b128 v[152:155], v130 offset:1024
	ds_read_b128 v[156:159], v130 offset:2048
	ds_read_b128 v[160:163], v130 offset:3072
	v_add_u32_e32 v130, vcc_lo, v191
	ds_read_b128 v[164:167], v130
	ds_read_b128 v[168:171], v130 offset:1024
	ds_read_b128 v[172:175], v130 offset:2048
	ds_read_b128 v[176:179], v130 offset:3072
	v_lshl_add_u64 v[130:131], s[24:25], 0, v[144:145]
	s_add_i32 m0, s55, 0xc000
	ds_read_b128 v[180:183], v193
	ds_read_b128 v[184:187], v193 offset:1024
	ds_read_b128 v[194:197], v193 offset:2048
	ds_read_b128 v[198:201], v193 offset:3072
	ds_read_b128 v[202:205], v193 offset:4096
	ds_read_b128 v[218:221], v193 offset:5120
	ds_read_b128 v[222:225], v193 offset:6144
	ds_read_b128 v[226:229], v193 offset:7168
	global_load_lds_dwordx4 v[130:131], off
	v_lshl_add_u64 v[130:131], s[24:25], 0, v[146:147]
	s_add_i32 m0, s55, 0xe000
	s_nop 0
	global_load_lds_dwordx4 v[130:131], off
	s_waitcnt vmcnt(8)
	s_waitcnt lgkmcnt(0)
	s_barrier
; #define PG8_STAGE(bufoff, gbase, voff) do { _Pragma("unroll") for (int _i = 0; _i < 2; ++_i) \
;         __builtin_amdgcn_global_load_lds((const unsigned*)((const char*)(gbase) + (voff)[_i]), (PG8_LAS unsigned*)(lds + (bufoff) + ldsw + _i * 8192), 16, 0, 0); } while (0)
; #define PG8_LDA(dst, b, h) do { _Pragma("unroll") for (int m = 0; m < 4; ++m) _Pragma("unroll") for (int k = 0; k < 2; ++k) dst[m][k] = *(const PG8_LAS bf16x8*)(lds + PG8_SA(b, h) + aoff + m * 2048 + k * 1024); } while (0)
; #define PG8_LDB(dst, b, h) do { _Pragma("unroll") for (int n = 0; n < 2; ++n) _Pragma("unroll") for (int k = 0; k < 2; ++k) dst[n][k] = *(const PG8_LAS bf16x8*)(lds + PG8_SB(b, h) + boff + n * 2048 + k * 1024); } while (0)
; #define PG8_MMA(ai, bj, At, Bt) do { __builtin_amdgcn_s_setprio(1); _Pragma("unroll") for (int m = 0; m < 4; ++m) _Pragma("unroll") for (int n = 0; n < 2; ++n) _Pragma("unroll") for (int k = 0; k < 2; ++k) \
;         acc[ai][bj][m][n] = __builtin_amdgcn_mfma_f32_16x16x32_bf16(Bt[n][k], At[m][k], acc[ai][bj][m][n], 0, 0, 0); __builtin_amdgcn_s_setprio(0); } while (0)
; #define PG8_WAIT_V(n) asm volatile("s_waitcnt vmcnt(" #n ")" ::: "memory")
; #define PG8_WAIT_L(n) asm volatile("s_waitcnt lgkmcnt(" #n ")" ::: "memory")
; #define PG8_BAR __builtin_amdgcn_s_barrier()
; #define PG8_SCHED __builtin_amdgcn_sched_barrier(0)
; template <class Epi, class Sched, bool ALIGN_EPI = false, bool SP2 = false>
; __device__ __forceinline__ void gemm_phase(PG8_LAS unsigned char* lds, const Gemm g, const Sched& S, const Epi& E) {
;     ...
;             PG8_LDB(B0, 0, 0); PG8_LDB(B1, 0, 1); PG8_SCHED; PG8_LDA(At, 0, 0); PG8_STAGE(PG8_SA(1, 1), a1 + hstep, voffA);
;             PG8_WAIT_V(8); PG8_WAIT_L(0); PG8_BAR; PG8_MMA(0, 0, At, B0); PG8_MMA(0, 1, At, B1); PG8_BAR; PG8_SCHED;
;             PG8_LDA(At, 0, 1); PG8_STAGE(PG8_SB(0, 0), b2, voffB); PG8_STAGE(PG8_SB(0, 1), b2 + hstep, voffB); PG8_STAGE(PG8_SA(0, 0), a2, voffA);
;             PG8_WAIT_V(8); PG8_WAIT_L(0); PG8_BAR; PG8_MMA(1, 0, At, B0); PG8_MMA(1, 1, At, B1); PG8_BAR; PG8_SCHED;
	s_setprio 1
	s_waitcnt lgkmcnt(0)
	v_mfma_f32_16x16x32_bf16 v[124:127], v[148:151], v[180:183], v[124:127]
	v_mfma_f32_16x16x32_bf16 v[120:123], v[156:159], v[180:183], v[120:123]
	v_mfma_f32_16x16x32_bf16 v[108:111], v[148:151], v[194:197], v[108:111]
	v_mfma_f32_16x16x32_bf16 v[104:107], v[156:159], v[194:197], v[104:107]
	v_mfma_f32_16x16x32_bf16 v[92:95], v[148:151], v[202:205], v[92:95]
	v_mfma_f32_16x16x32_bf16 v[88:91], v[156:159], v[202:205], v[88:91]
	v_mfma_f32_16x16x32_bf16 v[76:79], v[148:151], v[222:225], v[76:79]
	v_mfma_f32_16x16x32_bf16 v[72:75], v[156:159], v[222:225], v[72:75]
	v_mfma_f32_16x16x32_bf16 v[124:127], v[152:155], v[184:187], v[124:127]
	v_mfma_f32_16x16x32_bf16 v[120:123], v[160:163], v[184:187], v[120:123]
	v_mfma_f32_16x16x32_bf16 v[108:111], v[152:155], v[198:201], v[108:111]
	v_mfma_f32_16x16x32_bf16 v[104:107], v[160:163], v[198:201], v[104:107]
	v_mfma_f32_16x16x32_bf16 v[92:95], v[152:155], v[218:221], v[92:95]
	v_mfma_f32_16x16x32_bf16 v[88:91], v[160:163], v[218:221], v[88:91]
	v_mfma_f32_16x16x32_bf16 v[76:79], v[152:155], v[226:229], v[76:79]
	v_mfma_f32_16x16x32_bf16 v[72:75], v[160:163], v[226:229], v[72:75]
	v_mfma_f32_16x16x32_bf16 v[116:119], v[164:167], v[180:183], v[116:119]
	v_mfma_f32_16x16x32_bf16 v[112:115], v[172:175], v[180:183], v[112:115]
	v_mfma_f32_16x16x32_bf16 v[100:103], v[164:167], v[194:197], v[100:103]
	v_mfma_f32_16x16x32_bf16 v[96:99], v[172:175], v[194:197], v[96:99]
	v_mfma_f32_16x16x32_bf16 v[84:87], v[164:167], v[202:205], v[84:87]
	v_mfma_f32_16x16x32_bf16 v[80:83], v[172:175], v[202:205], v[80:83]
	v_mfma_f32_16x16x32_bf16 v[68:71], v[164:167], v[222:225], v[68:71]
	v_mfma_f32_16x16x32_bf16 v[64:67], v[172:175], v[222:225], v[64:67]
	v_mfma_f32_16x16x32_bf16 v[116:119], v[168:171], v[184:187], v[116:119]
	v_mfma_f32_16x16x32_bf16 v[112:115], v[176:179], v[184:187], v[112:115]
	v_mfma_f32_16x16x32_bf16 v[100:103], v[168:171], v[198:201], v[100:103]
	v_mfma_f32_16x16x32_bf16 v[96:99], v[176:179], v[198:201], v[96:99]
	v_mfma_f32_16x16x32_bf16 v[84:87], v[168:171], v[218:221], v[84:87]
	v_mfma_f32_16x16x32_bf16 v[80:83], v[176:179], v[218:221], v[80:83]
	v_mfma_f32_16x16x32_bf16 v[68:71], v[168:171], v[226:229], v[68:71]
	v_mfma_f32_16x16x32_bf16 v[64:67], v[176:179], v[226:229], v[64:67]
	s_setprio 0
	s_barrier
	s_add_i32 s24, s77, s54
	v_lshl_add_u64 v[130:131], s[28:29], 0, v[128:129]
	s_mov_b32 m0, s24
	ds_read_b128 v[180:183], v193 offset:16384
	ds_read_b128 v[184:187], v193 offset:17408
	ds_read_b128 v[194:197], v193 offset:18432
	ds_read_b128 v[198:201], v193 offset:19456
	ds_read_b128 v[202:205], v193 offset:20480
	ds_read_b128 v[218:221], v193 offset:21504
	ds_read_b128 v[222:225], v193 offset:22528
	ds_read_b128 v[226:229], v193 offset:23552
	global_load_lds_dwordx4 v[130:131], off
	s_add_i32 m0, s24, 0x2000
	s_add_u32 s24, s28, 0x160000
	v_lshl_add_u64 v[132:133], s[28:29], 0, v[142:143]
	s_addc_u32 s25, s29, 0
	s_add_i32 s77, vcc_lo, s54
	global_load_lds_dwordx4 v[132:133], off
	v_lshl_add_u64 v[188:189], s[24:25], 0, v[128:129]
	s_mov_b32 m0, s77
	v_lshl_add_u64 v[206:207], s[30:31], 0, v[142:143]
	global_load_lds_dwordx4 v[188:189], off
	v_lshl_add_u64 v[188:189], s[24:25], 0, v[142:143]
	s_add_i32 m0, s77, 0x2000
	s_nop 0
	global_load_lds_dwordx4 v[188:189], off
	v_lshl_add_u64 v[188:189], s[30:31], 0, v[128:129]
	s_mov_b32 m0, s55
	s_nop 0
	global_load_lds_dwordx4 v[188:189], off
	s_mov_b32 m0, s56
	s_nop 0
	global_load_lds_dwordx4 v[206:207], off
	s_waitcnt vmcnt(8)
	s_waitcnt lgkmcnt(0)
	s_barrier
	s_setprio 1
	s_waitcnt lgkmcnt(0)
	v_mfma_f32_16x16x32_bf16 v[60:63], v[148:151], v[180:183], v[60:63]
	v_mfma_f32_16x16x32_bf16 v[56:59], v[156:159], v[180:183], v[56:59]
	v_mfma_f32_16x16x32_bf16 v[44:47], v[148:151], v[194:197], v[44:47]
	v_mfma_f32_16x16x32_bf16 v[40:43], v[156:159], v[194:197], v[40:43]
	v_mfma_f32_16x16x32_bf16 v[28:31], v[148:151], v[202:205], v[28:31]
	v_mfma_f32_16x16x32_bf16 v[24:27], v[156:159], v[202:205], v[24:27]
	v_mfma_f32_16x16x32_bf16 v[12:15], v[148:151], v[222:225], v[12:15]
	v_mfma_f32_16x16x32_bf16 v[8:11], v[156:159], v[222:225], v[8:11]
	v_mfma_f32_16x16x32_bf16 v[60:63], v[152:155], v[184:187], v[60:63]
	v_mfma_f32_16x16x32_bf16 v[56:59], v[160:163], v[184:187], v[56:59]
	v_mfma_f32_16x16x32_bf16 v[44:47], v[152:155], v[198:201], v[44:47]
	v_mfma_f32_16x16x32_bf16 v[40:43], v[160:163], v[198:201], v[40:43]
	v_mfma_f32_16x16x32_bf16 v[28:31], v[152:155], v[218:221], v[28:31]
	v_mfma_f32_16x16x32_bf16 v[24:27], v[160:163], v[218:221], v[24:27]
	v_mfma_f32_16x16x32_bf16 v[12:15], v[152:155], v[226:229], v[12:15]
	v_mfma_f32_16x16x32_bf16 v[8:11], v[160:163], v[226:229], v[8:11]
	v_mfma_f32_16x16x32_bf16 v[52:55], v[164:167], v[180:183], v[52:55]
	v_mfma_f32_16x16x32_bf16 v[48:51], v[172:175], v[180:183], v[48:51]
	v_mfma_f32_16x16x32_bf16 v[36:39], v[164:167], v[194:197], v[36:39]
	v_mfma_f32_16x16x32_bf16 v[32:35], v[172:175], v[194:197], v[32:35]
	v_mfma_f32_16x16x32_bf16 v[20:23], v[164:167], v[202:205], v[20:23]
	v_mfma_f32_16x16x32_bf16 v[16:19], v[172:175], v[202:205], v[16:19]
	v_mfma_f32_16x16x32_bf16 v[4:7], v[164:167], v[222:225], v[4:7]
	v_mfma_f32_16x16x32_bf16 v[0:3], v[172:175], v[222:225], v[0:3]
	v_mfma_f32_16x16x32_bf16 v[52:55], v[168:171], v[184:187], v[52:55]
	v_mfma_f32_16x16x32_bf16 v[48:51], v[176:179], v[184:187], v[48:51]
	v_mfma_f32_16x16x32_bf16 v[36:39], v[168:171], v[198:201], v[36:39]
	v_mfma_f32_16x16x32_bf16 v[32:35], v[176:179], v[198:201], v[32:35]
	v_mfma_f32_16x16x32_bf16 v[20:23], v[168:171], v[218:221], v[20:23]
	v_mfma_f32_16x16x32_bf16 v[16:19], v[176:179], v[218:221], v[16:19]
	v_mfma_f32_16x16x32_bf16 v[4:7], v[168:171], v[226:229], v[4:7]
	v_mfma_f32_16x16x32_bf16 v[0:3], v[176:179], v[226:229], v[0:3]
	s_setprio 0
	s_barrier
; #define PG8_STAGE(bufoff, gbase, voff) do { _Pragma("unroll") for (int _i = 0; _i < 2; ++_i) \
;         __builtin_amdgcn_global_load_lds((const unsigned*)((const char*)(gbase) + (voff)[_i]), (PG8_LAS unsigned*)(lds + (bufoff) + ldsw + _i * 8192), 16, 0, 0); } while (0)
; #define PG8_LDA(dst, b, h) do { _Pragma("unroll") for (int m = 0; m < 4; ++m) _Pragma("unroll") for (int k = 0; k < 2; ++k) dst[m][k] = *(const PG8_LAS bf16x8*)(lds + PG8_SA(b, h) + aoff + m * 2048 + k * 1024); } while (0)
; #define PG8_LDB(dst, b, h) do { _Pragma("unroll") for (int n = 0; n < 2; ++n) _Pragma("unroll") for (int k = 0; k < 2; ++k) dst[n][k] = *(const PG8_LAS bf16x8*)(lds + PG8_SB(b, h) + boff + n * 2048 + k * 1024); } while (0)
; #define PG8_MMA(ai, bj, At, Bt) do { __builtin_amdgcn_s_setprio(1); _Pragma("unroll") for (int m = 0; m < 4; ++m) _Pragma("unroll") for (int n = 0; n < 2; ++n) _Pragma("unroll") for (int k = 0; k < 2; ++k) \
;         acc[ai][bj][m][n] = __builtin_amdgcn_mfma_f32_16x16x32_bf16(Bt[n][k], At[m][k], acc[ai][bj][m][n], 0, 0, 0); __builtin_amdgcn_s_setprio(0); } while (0)
; #define PG8_WAIT_V(n) asm volatile("s_waitcnt vmcnt(" #n ")" ::: "memory")
; #define PG8_WAIT_L(n) asm volatile("s_waitcnt lgkmcnt(" #n ")" ::: "memory")
; #define PG8_BAR __builtin_amdgcn_s_barrier()
; #define PG8_SCHED __builtin_amdgcn_sched_barrier(0)
; template <class Epi, class Sched, bool ALIGN_EPI = false, bool SP2 = false>
; __device__ __forceinline__ void gemm_phase(PG8_LAS unsigned char* lds, const Gemm g, const Sched& S, const Epi& E) {
;     ...
;             PG8_LDB(B0, 1, 0); PG8_LDB(B1, 1, 1); PG8_SCHED; PG8_LDA(At, 1, 0); PG8_STAGE(PG8_SA(0, 1), a2 + hstep, voffA);
;             PG8_WAIT_V(8); PG8_WAIT_L(0); PG8_BAR; PG8_MMA(0, 0, At, B0); PG8_MMA(0, 1, At, B1); PG8_BAR; PG8_SCHED;
	s_add_i32 s77, 0, 0x18000
	v_add_u32_e32 v134, s77, v191
	s_add_i32 vcc_lo, 0, 0x1c000
	ds_read_b128 v[148:151], v134
	ds_read_b128 v[152:155], v134 offset:1024
	ds_read_b128 v[156:159], v134 offset:2048
	ds_read_b128 v[160:163], v134 offset:3072
	v_add_u32_e32 v134, vcc_lo, v191
	ds_read_b128 v[164:167], v134
	ds_read_b128 v[168:171], v134 offset:1024
	ds_read_b128 v[172:175], v134 offset:2048
	ds_read_b128 v[176:179], v134 offset:3072
	s_add_u32 s24, s30, 0x160000
	s_addc_u32 s25, s31, 0
	s_mov_b32 m0, s57
	v_lshl_add_u64 v[230:231], s[24:25], 0, v[128:129]
	ds_read_b128 v[180:183], v193 offset:32768
	ds_read_b128 v[184:187], v193 offset:33792
	ds_read_b128 v[194:197], v193 offset:34816
	ds_read_b128 v[198:201], v193 offset:35840
	ds_read_b128 v[202:205], v193 offset:36864
	ds_read_b128 v[218:221], v193 offset:37888
	ds_read_b128 v[222:225], v193 offset:38912
	ds_read_b128 v[226:229], v193 offset:39936
	global_load_lds_dwordx4 v[230:231], off
	v_lshl_add_u64 v[230:231], s[24:25], 0, v[142:143]
	s_mov_b32 m0, s58
	s_nop 0
	global_load_lds_dwordx4 v[230:231], off
	s_waitcnt vmcnt(8)
	s_waitcnt lgkmcnt(0)
	s_barrier
	s_setprio 1
	s_waitcnt lgkmcnt(0)
	v_mfma_f32_16x16x32_bf16 v[124:127], v[148:151], v[180:183], v[124:127]
	v_mfma_f32_16x16x32_bf16 v[120:123], v[156:159], v[180:183], v[120:123]
	v_mfma_f32_16x16x32_bf16 v[108:111], v[148:151], v[194:197], v[108:111]
	v_mfma_f32_16x16x32_bf16 v[104:107], v[156:159], v[194:197], v[104:107]
	v_mfma_f32_16x16x32_bf16 v[92:95], v[148:151], v[202:205], v[92:95]
	v_mfma_f32_16x16x32_bf16 v[88:91], v[156:159], v[202:205], v[88:91]
	v_mfma_f32_16x16x32_bf16 v[76:79], v[148:151], v[222:225], v[76:79]
	v_mfma_f32_16x16x32_bf16 v[72:75], v[156:159], v[222:225], v[72:75]
	v_mfma_f32_16x16x32_bf16 v[124:127], v[152:155], v[184:187], v[124:127]
	v_mfma_f32_16x16x32_bf16 v[120:123], v[160:163], v[184:187], v[120:123]
	v_mfma_f32_16x16x32_bf16 v[108:111], v[152:155], v[198:201], v[108:111]
	v_mfma_f32_16x16x32_bf16 v[104:107], v[160:163], v[198:201], v[104:107]
	v_mfma_f32_16x16x32_bf16 v[92:95], v[152:155], v[218:221], v[92:95]
	v_mfma_f32_16x16x32_bf16 v[88:91], v[160:163], v[218:221], v[88:91]
	v_mfma_f32_16x16x32_bf16 v[76:79], v[152:155], v[226:229], v[76:79]
	v_mfma_f32_16x16x32_bf16 v[72:75], v[160:163], v[226:229], v[72:75]
	v_mfma_f32_16x16x32_bf16 v[116:119], v[164:167], v[180:183], v[116:119]
	v_mfma_f32_16x16x32_bf16 v[112:115], v[172:175], v[180:183], v[112:115]
	v_mfma_f32_16x16x32_bf16 v[100:103], v[164:167], v[194:197], v[100:103]
	v_mfma_f32_16x16x32_bf16 v[96:99], v[172:175], v[194:197], v[96:99]
	v_mfma_f32_16x16x32_bf16 v[84:87], v[164:167], v[202:205], v[84:87]
	v_mfma_f32_16x16x32_bf16 v[80:83], v[172:175], v[202:205], v[80:83]
	v_mfma_f32_16x16x32_bf16 v[68:71], v[164:167], v[222:225], v[68:71]
	v_mfma_f32_16x16x32_bf16 v[64:67], v[172:175], v[222:225], v[64:67]
	v_mfma_f32_16x16x32_bf16 v[116:119], v[168:171], v[184:187], v[116:119]
	v_mfma_f32_16x16x32_bf16 v[112:115], v[176:179], v[184:187], v[112:115]
	v_mfma_f32_16x16x32_bf16 v[100:103], v[168:171], v[198:201], v[100:103]
	v_mfma_f32_16x16x32_bf16 v[96:99], v[176:179], v[198:201], v[96:99]
	v_mfma_f32_16x16x32_bf16 v[84:87], v[168:171], v[218:221], v[84:87]
	v_mfma_f32_16x16x32_bf16 v[80:83], v[176:179], v[218:221], v[80:83]
	v_mfma_f32_16x16x32_bf16 v[68:71], v[168:171], v[226:229], v[68:71]
	v_mfma_f32_16x16x32_bf16 v[64:67], v[176:179], v[226:229], v[64:67]
	s_setprio 0
	s_barrier
; #define PG8_STAGE(bufoff, gbase, voff) do { _Pragma("unroll") for (int _i = 0; _i < 2; ++_i) \
;         __builtin_amdgcn_global_load_lds((const unsigned*)((const char*)(gbase) + (voff)[_i]), (PG8_LAS unsigned*)(lds + (bufoff) + ldsw + _i * 8192), 16, 0, 0); } while (0)
; #define PG8_LDA(dst, b, h) do { _Pragma("unroll") for (int m = 0; m < 4; ++m) _Pragma("unroll") for (int k = 0; k < 2; ++k) dst[m][k] = *(const PG8_LAS bf16x8*)(lds + PG8_SA(b, h) + aoff + m * 2048 + k * 1024); } while (0)
; #define PG8_MMA(ai, bj, At, Bt) do { __builtin_amdgcn_s_setprio(1); _Pragma("unroll") for (int m = 0; m < 4; ++m) _Pragma("unroll") for (int n = 0; n < 2; ++n) _Pragma("unroll") for (int k = 0; k < 2; ++k) \
;         acc[ai][bj][m][n] = __builtin_amdgcn_mfma_f32_16x16x32_bf16(Bt[n][k], At[m][k], acc[ai][bj][m][n], 0, 0, 0); __builtin_amdgcn_s_setprio(0); } while (0)
; #define PG8_WAIT_V(n) asm volatile("s_waitcnt vmcnt(" #n ")" ::: "memory")
; #define PG8_WAIT_L(n) asm volatile("s_waitcnt lgkmcnt(" #n ")" ::: "memory")
; #define PG8_BAR __builtin_amdgcn_s_barrier()
; #define PG8_SCHED __builtin_amdgcn_sched_barrier(0)
; template <class Epi, class Sched, bool ALIGN_EPI = false, bool SP2 = false>
; __device__ __forceinline__ void gemm_phase(PG8_LAS unsigned char* lds, const Gemm g, const Sched& S, const Epi& E) {
;     ...
;             PG8_LDA(At, 1, 1); PG8_STAGE(PG8_SB(1, 0), b3, voffB); PG8_STAGE(PG8_SB(1, 1), b3 + hstep, voffB); PG8_STAGE(PG8_SA(1, 0), a3, voffA);
;             PG8_WAIT_V(8); PG8_WAIT_L(0); PG8_BAR; PG8_MMA(1, 0, At, B0); PG8_MMA(1, 1, At, B1); PG8_BAR; PG8_SCHED;
;     ...
;         if constexpr (ALIGN_EPI) { if (wr == 0) PG8_BAR; }
	s_add_i32 s24, s77, s54
	v_lshl_add_u64 v[130:131], v[130:131], 0, s[78:79]
	s_mov_b32 m0, s24
	ds_read_b128 v[180:183], v193 offset:49152
	ds_read_b128 v[184:187], v193 offset:50176
	ds_read_b128 v[194:197], v193 offset:51200
	ds_read_b128 v[198:201], v193 offset:52224
	ds_read_b128 v[202:205], v193 offset:53248
	ds_read_b128 v[218:221], v193 offset:54272
	ds_read_b128 v[222:225], v193 offset:55296
	ds_read_b128 v[226:229], v193 offset:56320
	global_load_lds_dwordx4 v[130:131], off
	s_add_i32 m0, s24, 0x2000
	s_add_u32 s24, s28, 0x160080
	v_lshl_add_u64 v[130:131], v[132:133], 0, s[78:79]
	s_addc_u32 s25, s29, 0
	s_add_i32 s28, vcc_lo, s54
	global_load_lds_dwordx4 v[130:131], off
	v_lshl_add_u64 v[130:131], s[24:25], 0, v[128:129]
	s_mov_b32 m0, s28
	s_nop 0
	global_load_lds_dwordx4 v[130:131], off
	v_lshl_add_u64 v[130:131], s[24:25], 0, v[142:143]
	s_add_i32 m0, s28, 0x2000
	s_nop 0
	global_load_lds_dwordx4 v[130:131], off
	v_lshl_add_u64 v[130:131], v[188:189], 0, s[78:79]
	s_mov_b32 m0, s60
	s_nop 0
	global_load_lds_dwordx4 v[130:131], off
	v_lshl_add_u64 v[130:131], v[206:207], 0, s[78:79]
	s_mov_b32 m0, s61
	s_nop 0
	global_load_lds_dwordx4 v[130:131], off
	s_waitcnt vmcnt(8)
	s_waitcnt lgkmcnt(0)
	s_barrier
	s_setprio 1
	s_waitcnt lgkmcnt(0)
	v_mfma_f32_16x16x32_bf16 v[60:63], v[148:151], v[180:183], v[60:63]
	v_mfma_f32_16x16x32_bf16 v[56:59], v[156:159], v[180:183], v[56:59]
	v_mfma_f32_16x16x32_bf16 v[44:47], v[148:151], v[194:197], v[44:47]
	v_mfma_f32_16x16x32_bf16 v[40:43], v[156:159], v[194:197], v[40:43]
	v_mfma_f32_16x16x32_bf16 v[28:31], v[148:151], v[202:205], v[28:31]
	v_mfma_f32_16x16x32_bf16 v[24:27], v[156:159], v[202:205], v[24:27]
	v_mfma_f32_16x16x32_bf16 v[12:15], v[148:151], v[222:225], v[12:15]
	v_mfma_f32_16x16x32_bf16 v[8:11], v[156:159], v[222:225], v[8:11]
	v_mfma_f32_16x16x32_bf16 v[60:63], v[152:155], v[184:187], v[60:63]
	v_mfma_f32_16x16x32_bf16 v[56:59], v[160:163], v[184:187], v[56:59]
	v_mfma_f32_16x16x32_bf16 v[44:47], v[152:155], v[198:201], v[44:47]
	v_mfma_f32_16x16x32_bf16 v[40:43], v[160:163], v[198:201], v[40:43]
	v_mfma_f32_16x16x32_bf16 v[28:31], v[152:155], v[218:221], v[28:31]
	v_mfma_f32_16x16x32_bf16 v[24:27], v[160:163], v[218:221], v[24:27]
	v_mfma_f32_16x16x32_bf16 v[12:15], v[152:155], v[226:229], v[12:15]
	v_mfma_f32_16x16x32_bf16 v[8:11], v[160:163], v[226:229], v[8:11]
	v_mfma_f32_16x16x32_bf16 v[52:55], v[164:167], v[180:183], v[52:55]
	v_mfma_f32_16x16x32_bf16 v[48:51], v[172:175], v[180:183], v[48:51]
	v_mfma_f32_16x16x32_bf16 v[36:39], v[164:167], v[194:197], v[36:39]
	v_mfma_f32_16x16x32_bf16 v[32:35], v[172:175], v[194:197], v[32:35]
	v_mfma_f32_16x16x32_bf16 v[20:23], v[164:167], v[202:205], v[20:23]
	v_mfma_f32_16x16x32_bf16 v[16:19], v[172:175], v[202:205], v[16:19]
	v_mfma_f32_16x16x32_bf16 v[4:7], v[164:167], v[222:225], v[4:7]
	v_mfma_f32_16x16x32_bf16 v[0:3], v[172:175], v[222:225], v[0:3]
	v_mfma_f32_16x16x32_bf16 v[52:55], v[168:171], v[184:187], v[52:55]
	v_mfma_f32_16x16x32_bf16 v[48:51], v[176:179], v[184:187], v[48:51]
	v_mfma_f32_16x16x32_bf16 v[36:39], v[168:171], v[198:201], v[36:39]
	v_mfma_f32_16x16x32_bf16 v[32:35], v[176:179], v[198:201], v[32:35]
	v_mfma_f32_16x16x32_bf16 v[20:23], v[168:171], v[218:221], v[20:23]
	v_mfma_f32_16x16x32_bf16 v[16:19], v[176:179], v[218:221], v[16:19]
	v_mfma_f32_16x16x32_bf16 v[4:7], v[168:171], v[226:229], v[4:7]
	v_mfma_f32_16x16x32_bf16 v[0:3], v[176:179], v[226:229], v[0:3]
	s_setprio 0
	s_barrier
	s_add_i32 s74, s74, 2
	s_add_u32 s44, s44, 0x100
	s_addc_u32 s45, s45, 0
	s_cmpk_gt_u32 s74, 0x55
	s_mov_b64 s[24:25], s[26:27]
	s_cbranch_scc0 .LBB0_1027
	s_and_b64 vcc, exec, s[18:19]
	s_cbranch_vccz .LBB0_1030
	s_barrier

; template <class Epi, class Sched, bool ALIGN_EPI = false, bool SP2 = false>
; __device__ __forceinline__ void gemm_phase(PG8_LAS unsigned char* lds, const Gemm g, const Sched& S, const Epi& E) {
;     ...
;     const char* cA = (const char*)g.A + (size_t)cur.pm * tstep; const char* cB = (const char*)g.Bt + (size_t)cur.pn * tstep;
;     ...
;         const bool has_next = S.next(ui + 1, nxt);
;         const char* nA = has_next ? (const char*)g.A + (size_t)nxt.pm * tstep : cA; const char* nB = has_next ? (const char*)g.Bt + (size_t)nxt.pn * tstep : cB;
.LBB0_1121:
	s_ashr_i32 s23, s22, 31
	s_lshl_b64 s[24:25], s[22:23], 20
	s_add_u32 s24, s38, s24
	s_addc_u32 s25, s39, s25
	s_and_b64 s[26:27], s[40:41], exec
	s_cselect_b32 s23, s25, s31
	s_cselect_b32 s61, s24, s30
	s_ashr_i32 s21, s20, 31
	s_lshl_b64 s[26:27], s[20:21], 20
	s_add_u32 s26, s44, s26
	s_addc_u32 s27, s45, s27
	s_and_b64 s[42:43], s[40:41], exec
	s_cselect_b32 s21, s27, s35
	s_cselect_b32 s62, s26, s34
	s_add_u32 s30, s30, 0x80080
	s_addc_u32 s31, s31, 0
	s_add_u32 s68, s34, 0x100

; template <class Epi, class Sched, bool ALIGN_EPI = false, bool SP2 = false>
; __device__ __forceinline__ void gemm_phase(PG8_LAS unsigned char* lds, const Gemm g, const Sched& S, const Epi& E) {
;     ...
;         for (int t = 0; t < nt; t += 2) {
;             const bool last = (t == nt - 2);
	s_addc_u32 s69, s35, 0
	s_mov_b32 s74, -2


; #define PG8_STAGE(bufoff, gbase, voff) do { _Pragma("unroll") for (int _i = 0; _i < 2; ++_i) \
;         __builtin_amdgcn_global_load_lds((const unsigned*)((const char*)(gbase) + (voff)[_i]), (PG8_LAS unsigned*)(lds + (bufoff) + ldsw + _i * 8192), 16, 0, 0); } while (0)
; #define PG8_LDA(dst, b, h) do { _Pragma("unroll") for (int m = 0; m < 4; ++m) _Pragma("unroll") for (int k = 0; k < 2; ++k) dst[m][k] = *(const PG8_LAS bf16x8*)(lds + PG8_SA(b, h) + aoff + m * 2048 + k * 1024); } while (0)
; #define PG8_LDB(dst, b, h) do { _Pragma("unroll") for (int n = 0; n < 2; ++n) _Pragma("unroll") for (int k = 0; k < 2; ++k) dst[n][k] = *(const PG8_LAS bf16x8*)(lds + PG8_SB(b, h) + boff + n * 2048 + k * 1024); } while (0)
; #define PG8_WAIT_V(n) asm volatile("s_waitcnt vmcnt(" #n ")" ::: "memory")
; #define PG8_WAIT_L(n) asm volatile("s_waitcnt lgkmcnt(" #n ")" ::: "memory")
; #define PG8_BAR __builtin_amdgcn_s_barrier()
; #define PG8_SCHED __builtin_amdgcn_sched_barrier(0)
; template <class Epi, class Sched, bool ALIGN_EPI = false, bool SP2 = false>
; __device__ __forceinline__ void gemm_phase(PG8_LAS unsigned char* lds, const Gemm g, const Sched& S, const Epi& E) {
;     ...
;         const bool has_next = S.next(ui + 1, nxt);
;         const char* nA = has_next ? (const char*)g.A + (size_t)nxt.pm * tstep : cA; const char* nB = has_next ? (const char*)g.Bt + (size_t)nxt.pn * tstep : cB;
;         for (int t = 0; t < nt; t += 2) {
;             const bool last = (t == nt - 2);
;             const char* a1 = cA + (size_t)(t + 1) * kstep;
;             const char* a2 = last ? nA : cA + (size_t)(t + 2) * kstep; const char* b2 = last ? nB : cB + (size_t)(t + 2) * kstep;
;             const char* a3 = a2 + kstep; const char* b3 = b2 + kstep;
;             if (last && has_next) S.a_ready(nxt);
;             if constexpr (SP2) {
;             PG8_LDB(B0, 0, 0); PG8_LDB(B1, 0, 1); PG8_SCHED; PG8_LDA(At, 0, 0); PG8_STAGE(PG8_SA(1, 1), a1 + hstep, voffA);
;             PG8_WAIT_V(8); PG8_WAIT_L(0); PG8_BAR; PG8_MMA(0, 0, At, B0); PG8_MMA(0, 1, At, B1); PG8_BAR; PG8_SCHED;
;             PG8_LDA(At, 0, 1); PG8_STAGE(PG8_SB(0, 0), b2, voffB); PG8_STAGE(PG8_SB(0, 1), b2 + hstep, voffB); PG8_STAGE(PG8_SA(0, 0), a2, voffA);
;             PG8_WAIT_V(8); PG8_WAIT_L(0); PG8_BAR; PG8_MMA(1, 0, At, B0); PG8_MMA(1, 1, At, B1); PG8_BAR; PG8_SCHED;
	s_add_u32 s34, s30, 0xfff80080
	s_addc_u32 s35, s31, -1
	s_add_i32 s76, 0, 0x10000
	s_cmp_eq_u32 s74, 28
	s_cselect_b32 s43, s23, s35
	s_cselect_b32 s42, s61, s34
	v_add_u32_e32 v130, s76, v157
	s_cselect_b32 s35, s21, s69
	s_cselect_b32 s34, s62, s68
	s_add_i32 s80, 0, 0x14000
	ds_read_b128 v[162:165], v130
	ds_read_b128 v[166:169], v130 offset:1024
	ds_read_b128 v[170:173], v130 offset:2048
	ds_read_b128 v[174:177], v130 offset:3072
	v_add_u32_e32 v130, s80, v157
	ds_read_b128 v[178:181], v130
	ds_read_b128 v[182:185], v130 offset:1024
	ds_read_b128 v[186:189], v130 offset:2048
	ds_read_b128 v[190:193], v130 offset:3072
	v_lshl_add_u64 v[130:131], s[30:31], 0, v[148:149]
	s_add_i32 m0, s54, 0xc000
	ds_read_b128 v[194:197], v161
	ds_read_b128 v[198:201], v161 offset:1024
	ds_read_b128 v[202:205], v161 offset:2048
	ds_read_b128 v[218:221], v161 offset:3072
	ds_read_b128 v[222:225], v161 offset:4096
	ds_read_b128 v[226:229], v161 offset:5120
	ds_read_b128 v[230:233], v161 offset:6144
	ds_read_b128 v[234:237], v161 offset:7168
	global_load_lds_dwordx4 v[130:131], off
	v_lshl_add_u64 v[130:131], s[30:31], 0, v[150:151]
	s_add_i32 m0, s54, 0xe000
	s_nop 0
	global_load_lds_dwordx4 v[130:131], off
	s_waitcnt vmcnt(8)
	s_waitcnt lgkmcnt(0)
	s_barrier
	s_setprio 1
	s_waitcnt lgkmcnt(0)
	v_mfma_f32_16x16x32_bf16 v[124:127], v[162:165], v[194:197], 0
	v_mfma_f32_16x16x32_bf16 v[120:123], v[170:173], v[194:197], 0
	v_mfma_f32_16x16x32_bf16 v[108:111], v[162:165], v[202:205], 0
	v_mfma_f32_16x16x32_bf16 v[104:107], v[170:173], v[202:205], 0
	v_mfma_f32_16x16x32_bf16 v[92:95], v[162:165], v[222:225], 0
	v_mfma_f32_16x16x32_bf16 v[88:91], v[170:173], v[222:225], 0
	v_mfma_f32_16x16x32_bf16 v[76:79], v[162:165], v[230:233], 0
	v_mfma_f32_16x16x32_bf16 v[72:75], v[170:173], v[230:233], 0
	v_mfma_f32_16x16x32_bf16 v[124:127], v[166:169], v[198:201], v[124:127]
	v_mfma_f32_16x16x32_bf16 v[120:123], v[174:177], v[198:201], v[120:123]
	v_mfma_f32_16x16x32_bf16 v[108:111], v[166:169], v[218:221], v[108:111]
	v_mfma_f32_16x16x32_bf16 v[104:107], v[174:177], v[218:221], v[104:107]
	v_mfma_f32_16x16x32_bf16 v[92:95], v[166:169], v[226:229], v[92:95]
	v_mfma_f32_16x16x32_bf16 v[88:91], v[174:177], v[226:229], v[88:91]
	v_mfma_f32_16x16x32_bf16 v[76:79], v[166:169], v[234:237], v[76:79]
	v_mfma_f32_16x16x32_bf16 v[72:75], v[174:177], v[234:237], v[72:75]
	v_mfma_f32_16x16x32_bf16 v[116:119], v[178:181], v[194:197], 0
	v_mfma_f32_16x16x32_bf16 v[112:115], v[186:189], v[194:197], 0
	v_mfma_f32_16x16x32_bf16 v[100:103], v[178:181], v[202:205], 0
	v_mfma_f32_16x16x32_bf16 v[96:99], v[186:189], v[202:205], 0
	v_mfma_f32_16x16x32_bf16 v[84:87], v[178:181], v[222:225], 0
	v_mfma_f32_16x16x32_bf16 v[80:83], v[186:189], v[222:225], 0
	v_mfma_f32_16x16x32_bf16 v[68:71], v[178:181], v[230:233], 0
	v_mfma_f32_16x16x32_bf16 v[64:67], v[186:189], v[230:233], 0
	v_mfma_f32_16x16x32_bf16 v[116:119], v[182:185], v[198:201], v[116:119]
	v_mfma_f32_16x16x32_bf16 v[112:115], v[190:193], v[198:201], v[112:115]
	v_mfma_f32_16x16x32_bf16 v[100:103], v[182:185], v[218:221], v[100:103]
	v_mfma_f32_16x16x32_bf16 v[96:99], v[190:193], v[218:221], v[96:99]
	v_mfma_f32_16x16x32_bf16 v[84:87], v[182:185], v[226:229], v[84:87]
	v_mfma_f32_16x16x32_bf16 v[80:83], v[190:193], v[226:229], v[80:83]
	v_mfma_f32_16x16x32_bf16 v[68:71], v[182:185], v[234:237], v[68:71]
	v_mfma_f32_16x16x32_bf16 v[64:67], v[190:193], v[234:237], v[64:67]
	s_setprio 0
	s_barrier
	s_add_i32 s76, s76, s48
	v_lshl_add_u64 v[130:131], s[34:35], 0, v[128:129]
	s_mov_b32 m0, s76
	ds_read_b128 v[194:197], v161 offset:16384
	ds_read_b128 v[198:201], v161 offset:17408
	ds_read_b128 v[202:205], v161 offset:18432
	ds_read_b128 v[218:221], v161 offset:19456
	ds_read_b128 v[222:225], v161 offset:20480
	ds_read_b128 v[226:229], v161 offset:21504
	ds_read_b128 v[230:233], v161 offset:22528
	ds_read_b128 v[234:237], v161 offset:23552
	global_load_lds_dwordx4 v[130:131], off
	s_add_i32 m0, s76, 0x2000
	s_add_u32 s76, s34, 0x80000
	v_lshl_add_u64 v[132:133], s[34:35], 0, v[142:143]
	s_addc_u32 s77, s35, 0
	s_add_i32 s80, s80, s48
	global_load_lds_dwordx4 v[132:133], off
	v_lshl_add_u64 v[154:155], s[76:77], 0, v[128:129]
	s_mov_b32 m0, s80
	v_lshl_add_u64 v[206:207], s[42:43], 0, v[144:145]
	global_load_lds_dwordx4 v[154:155], off
	v_lshl_add_u64 v[154:155], s[76:77], 0, v[142:143]
	s_add_i32 m0, s80, 0x2000
	s_nop 0
	global_load_lds_dwordx4 v[154:155], off
	v_lshl_add_u64 v[154:155], s[42:43], 0, v[146:147]
	s_mov_b32 m0, s54
	s_nop 0
	global_load_lds_dwordx4 v[154:155], off
	s_mov_b32 m0, s55
	s_nop 0
	global_load_lds_dwordx4 v[206:207], off
	s_waitcnt vmcnt(8)
	s_waitcnt lgkmcnt(0)
	s_barrier
; #define PG8_STAGE(bufoff, gbase, voff) do { _Pragma("unroll") for (int _i = 0; _i < 2; ++_i) \
;         __builtin_amdgcn_global_load_lds((const unsigned*)((const char*)(gbase) + (voff)[_i]), (PG8_LAS unsigned*)(lds + (bufoff) + ldsw + _i * 8192), 16, 0, 0); } while (0)
; #define PG8_LDA(dst, b, h) do { _Pragma("unroll") for (int m = 0; m < 4; ++m) _Pragma("unroll") for (int k = 0; k < 2; ++k) dst[m][k] = *(const PG8_LAS bf16x8*)(lds + PG8_SA(b, h) + aoff + m * 2048 + k * 1024); } while (0)
; #define PG8_LDB(dst, b, h) do { _Pragma("unroll") for (int n = 0; n < 2; ++n) _Pragma("unroll") for (int k = 0; k < 2; ++k) dst[n][k] = *(const PG8_LAS bf16x8*)(lds + PG8_SB(b, h) + boff + n * 2048 + k * 1024); } while (0)
; #define PG8_MMA(ai, bj, At, Bt) do { __builtin_amdgcn_s_setprio(1); _Pragma("unroll") for (int m = 0; m < 4; ++m) _Pragma("unroll") for (int n = 0; n < 2; ++n) _Pragma("unroll") for (int k = 0; k < 2; ++k) \
;         acc[ai][bj][m][n] = __builtin_amdgcn_mfma_f32_16x16x32_bf16(Bt[n][k], At[m][k], acc[ai][bj][m][n], 0, 0, 0); __builtin_amdgcn_s_setprio(0); } while (0)
; #define PG8_WAIT_V(n) asm volatile("s_waitcnt vmcnt(" #n ")" ::: "memory")
; #define PG8_WAIT_L(n) asm volatile("s_waitcnt lgkmcnt(" #n ")" ::: "memory")
; #define PG8_BAR __builtin_amdgcn_s_barrier()
; #define PG8_SCHED __builtin_amdgcn_sched_barrier(0)
; template <class Epi, class Sched, bool ALIGN_EPI = false, bool SP2 = false>
; __device__ __forceinline__ void gemm_phase(PG8_LAS unsigned char* lds, const Gemm g, const Sched& S, const Epi& E) {
;     ...
;             PG8_WAIT_V(8); PG8_WAIT_L(0); PG8_BAR; PG8_MMA(1, 0, At, B0); PG8_MMA(1, 1, At, B1); PG8_BAR; PG8_SCHED;
;             PG8_LDB(B0, 1, 0); PG8_LDB(B1, 1, 1); PG8_SCHED; PG8_LDA(At, 1, 0); PG8_STAGE(PG8_SA(0, 1), a2 + hstep, voffA);
;             PG8_WAIT_V(8); PG8_WAIT_L(0); PG8_BAR; PG8_MMA(0, 0, At, B0); PG8_MMA(0, 1, At, B1); PG8_BAR; PG8_SCHED;
	s_setprio 1
	s_waitcnt lgkmcnt(0)
	v_mfma_f32_16x16x32_bf16 v[60:63], v[162:165], v[194:197], 0
	v_mfma_f32_16x16x32_bf16 v[56:59], v[170:173], v[194:197], 0
	v_mfma_f32_16x16x32_bf16 v[44:47], v[162:165], v[202:205], 0
	v_mfma_f32_16x16x32_bf16 v[40:43], v[170:173], v[202:205], 0
	v_mfma_f32_16x16x32_bf16 v[28:31], v[162:165], v[222:225], 0
	v_mfma_f32_16x16x32_bf16 v[24:27], v[170:173], v[222:225], 0
	v_mfma_f32_16x16x32_bf16 v[12:15], v[162:165], v[230:233], 0
	v_mfma_f32_16x16x32_bf16 v[8:11], v[170:173], v[230:233], 0
	v_mfma_f32_16x16x32_bf16 v[60:63], v[166:169], v[198:201], v[60:63]
	v_mfma_f32_16x16x32_bf16 v[56:59], v[174:177], v[198:201], v[56:59]
	v_mfma_f32_16x16x32_bf16 v[44:47], v[166:169], v[218:221], v[44:47]
	v_mfma_f32_16x16x32_bf16 v[40:43], v[174:177], v[218:221], v[40:43]
	v_mfma_f32_16x16x32_bf16 v[28:31], v[166:169], v[226:229], v[28:31]
	v_mfma_f32_16x16x32_bf16 v[24:27], v[174:177], v[226:229], v[24:27]
	v_mfma_f32_16x16x32_bf16 v[12:15], v[166:169], v[234:237], v[12:15]
	v_mfma_f32_16x16x32_bf16 v[8:11], v[174:177], v[234:237], v[8:11]
	v_mfma_f32_16x16x32_bf16 v[52:55], v[178:181], v[194:197], 0
	v_mfma_f32_16x16x32_bf16 v[48:51], v[186:189], v[194:197], 0
	v_mfma_f32_16x16x32_bf16 v[36:39], v[178:181], v[202:205], 0
	v_mfma_f32_16x16x32_bf16 v[32:35], v[186:189], v[202:205], 0
	v_mfma_f32_16x16x32_bf16 v[20:23], v[178:181], v[222:225], 0
	v_mfma_f32_16x16x32_bf16 v[16:19], v[186:189], v[222:225], 0
	v_mfma_f32_16x16x32_bf16 v[4:7], v[178:181], v[230:233], 0
	v_mfma_f32_16x16x32_bf16 v[0:3], v[186:189], v[230:233], 0
	v_mfma_f32_16x16x32_bf16 v[52:55], v[182:185], v[198:201], v[52:55]
	v_mfma_f32_16x16x32_bf16 v[48:51], v[190:193], v[198:201], v[48:51]
	v_mfma_f32_16x16x32_bf16 v[36:39], v[182:185], v[218:221], v[36:39]
	v_mfma_f32_16x16x32_bf16 v[32:35], v[190:193], v[218:221], v[32:35]
	v_mfma_f32_16x16x32_bf16 v[20:23], v[182:185], v[226:229], v[20:23]
	v_mfma_f32_16x16x32_bf16 v[16:19], v[190:193], v[226:229], v[16:19]
	v_mfma_f32_16x16x32_bf16 v[4:7], v[182:185], v[234:237], v[4:7]
	v_mfma_f32_16x16x32_bf16 v[0:3], v[190:193], v[234:237], v[0:3]
	s_setprio 0
	s_barrier
	s_add_i32 s76, 0, 0x18000
	v_add_u32_e32 v134, s76, v157
	s_add_i32 s77, 0, 0x1c000
	ds_read_b128 v[162:165], v134
	ds_read_b128 v[166:169], v134 offset:1024
	ds_read_b128 v[170:173], v134 offset:2048
	ds_read_b128 v[174:177], v134 offset:3072
	v_add_u32_e32 v134, s77, v157
	ds_read_b128 v[178:181], v134
	ds_read_b128 v[182:185], v134 offset:1024
	ds_read_b128 v[186:189], v134 offset:2048
	ds_read_b128 v[190:193], v134 offset:3072
	s_add_u32 s42, s42, 0x80000
	s_addc_u32 s43, s43, 0
	s_mov_b32 m0, s56
	v_lshl_add_u64 v[238:239], s[42:43], 0, v[146:147]
	ds_read_b128 v[194:197], v161 offset:32768
	ds_read_b128 v[198:201], v161 offset:33792
	ds_read_b128 v[202:205], v161 offset:34816
	ds_read_b128 v[218:221], v161 offset:35840
	ds_read_b128 v[222:225], v161 offset:36864
	ds_read_b128 v[226:229], v161 offset:37888
	ds_read_b128 v[230:233], v161 offset:38912
	ds_read_b128 v[234:237], v161 offset:39936
	global_load_lds_dwordx4 v[238:239], off
	v_lshl_add_u64 v[238:239], s[42:43], 0, v[144:145]
	s_mov_b32 m0, s57
	s_nop 0
	global_load_lds_dwordx4 v[238:239], off
	s_waitcnt vmcnt(8)
	s_waitcnt lgkmcnt(0)
	s_barrier
	s_setprio 1
	s_waitcnt lgkmcnt(0)
	v_mfma_f32_16x16x32_bf16 v[124:127], v[162:165], v[194:197], v[124:127]
	v_mfma_f32_16x16x32_bf16 v[120:123], v[170:173], v[194:197], v[120:123]
	v_mfma_f32_16x16x32_bf16 v[108:111], v[162:165], v[202:205], v[108:111]
	v_mfma_f32_16x16x32_bf16 v[104:107], v[170:173], v[202:205], v[104:107]
	v_mfma_f32_16x16x32_bf16 v[92:95], v[162:165], v[222:225], v[92:95]
	v_mfma_f32_16x16x32_bf16 v[88:91], v[170:173], v[222:225], v[88:91]
	v_mfma_f32_16x16x32_bf16 v[76:79], v[162:165], v[230:233], v[76:79]
	v_mfma_f32_16x16x32_bf16 v[72:75], v[170:173], v[230:233], v[72:75]
	v_mfma_f32_16x16x32_bf16 v[124:127], v[166:169], v[198:201], v[124:127]
	v_mfma_f32_16x16x32_bf16 v[120:123], v[174:177], v[198:201], v[120:123]
	v_mfma_f32_16x16x32_bf16 v[108:111], v[166:169], v[218:221], v[108:111]
	v_mfma_f32_16x16x32_bf16 v[104:107], v[174:177], v[218:221], v[104:107]
	v_mfma_f32_16x16x32_bf16 v[92:95], v[166:169], v[226:229], v[92:95]
	v_mfma_f32_16x16x32_bf16 v[88:91], v[174:177], v[226:229], v[88:91]
	v_mfma_f32_16x16x32_bf16 v[76:79], v[166:169], v[234:237], v[76:79]
	v_mfma_f32_16x16x32_bf16 v[72:75], v[174:177], v[234:237], v[72:75]
	v_mfma_f32_16x16x32_bf16 v[116:119], v[178:181], v[194:197], v[116:119]
	v_mfma_f32_16x16x32_bf16 v[112:115], v[186:189], v[194:197], v[112:115]
	v_mfma_f32_16x16x32_bf16 v[100:103], v[178:181], v[202:205], v[100:103]
	v_mfma_f32_16x16x32_bf16 v[96:99], v[186:189], v[202:205], v[96:99]
	v_mfma_f32_16x16x32_bf16 v[84:87], v[178:181], v[222:225], v[84:87]
	v_mfma_f32_16x16x32_bf16 v[80:83], v[186:189], v[222:225], v[80:83]
	v_mfma_f32_16x16x32_bf16 v[68:71], v[178:181], v[230:233], v[68:71]
	v_mfma_f32_16x16x32_bf16 v[64:67], v[186:189], v[230:233], v[64:67]
	v_mfma_f32_16x16x32_bf16 v[116:119], v[182:185], v[198:201], v[116:119]
	v_mfma_f32_16x16x32_bf16 v[112:115], v[190:193], v[198:201], v[112:115]
	v_mfma_f32_16x16x32_bf16 v[100:103], v[182:185], v[218:221], v[100:103]
	v_mfma_f32_16x16x32_bf16 v[96:99], v[190:193], v[218:221], v[96:99]
	v_mfma_f32_16x16x32_bf16 v[84:87], v[182:185], v[226:229], v[84:87]
	v_mfma_f32_16x16x32_bf16 v[80:83], v[190:193], v[226:229], v[80:83]
	v_mfma_f32_16x16x32_bf16 v[68:71], v[182:185], v[234:237], v[68:71]
	v_mfma_f32_16x16x32_bf16 v[64:67], v[190:193], v[234:237], v[64:67]
	s_setprio 0
	s_barrier
; #define PG8_STAGE(bufoff, gbase, voff) do { _Pragma("unroll") for (int _i = 0; _i < 2; ++_i) \
;         __builtin_amdgcn_global_load_lds((const unsigned*)((const char*)(gbase) + (voff)[_i]), (PG8_LAS unsigned*)(lds + (bufoff) + ldsw + _i * 8192), 16, 0, 0); } while (0)
; #define PG8_LDA(dst, b, h) do { _Pragma("unroll") for (int m = 0; m < 4; ++m) _Pragma("unroll") for (int k = 0; k < 2; ++k) dst[m][k] = *(const PG8_LAS bf16x8*)(lds + PG8_SA(b, h) + aoff + m * 2048 + k * 1024); } while (0)
; template <class Epi, class Sched, bool ALIGN_EPI = false, bool SP2 = false>
; __device__ __forceinline__ void gemm_phase(PG8_LAS unsigned char* lds, const Gemm g, const Sched& S, const Epi& E) {
;     ...
;         const bool has_next = S.next(ui + 1, nxt);
;         const char* nA = has_next ? (const char*)g.A + (size_t)nxt.pm * tstep : cA; const char* nB = has_next ? (const char*)g.Bt + (size_t)nxt.pn * tstep : cB;
;         for (int t = 0; t < nt; t += 2) {
;             const bool last = (t == nt - 2);
;             const char* a1 = cA + (size_t)(t + 1) * kstep;
;             const char* a2 = last ? nA : cA + (size_t)(t + 2) * kstep; const char* b2 = last ? nB : cB + (size_t)(t + 2) * kstep;
;             const char* a3 = a2 + kstep; const char* b3 = b2 + kstep;
;             if (last && has_next) S.a_ready(nxt);
;             if constexpr (SP2) {
;             PG8_LDB(B0, 0, 0); PG8_LDB(B1, 0, 1); PG8_SCHED; PG8_LDA(At, 0, 0); PG8_STAGE(PG8_SA(1, 1), a1 + hstep, voffA);
;             PG8_WAIT_V(8); PG8_WAIT_L(0); PG8_BAR; PG8_MMA(0, 0, At, B0); PG8_MMA(0, 1, At, B1); PG8_BAR; PG8_SCHED;
;             PG8_LDA(At, 0, 1); PG8_STAGE(PG8_SB(0, 0), b2, voffB); PG8_STAGE(PG8_SB(0, 1), b2 + hstep, voffB); PG8_STAGE(PG8_SA(0, 0), a2, voffA);
;             PG8_WAIT_V(8); PG8_WAIT_L(0); PG8_BAR; PG8_MMA(1, 0, At, B0); PG8_MMA(1, 1, At, B1); PG8_BAR; PG8_SCHED;
;             PG8_LDB(B0, 1, 0); PG8_LDB(B1, 1, 1); PG8_SCHED; PG8_LDA(At, 1, 0); PG8_STAGE(PG8_SA(0, 1), a2 + hstep, voffA);
;             PG8_WAIT_V(8); PG8_WAIT_L(0); PG8_BAR; PG8_MMA(0, 0, At, B0); PG8_MMA(0, 1, At, B1); PG8_BAR; PG8_SCHED;
;             PG8_LDA(At, 1, 1); PG8_STAGE(PG8_SB(1, 0), b3, voffB); PG8_STAGE(PG8_SB(1, 1), b3 + hstep, voffB); PG8_STAGE(PG8_SA(1, 0), a3, voffA);
;             PG8_WAIT_V(8); PG8_WAIT_L(0); PG8_BAR; PG8_MMA(1, 0, At, B0); PG8_MMA(1, 1, At, B1); PG8_BAR; PG8_SCHED;
	s_add_i32 s42, s76, s48
	v_lshl_add_u64 v[130:131], v[130:131], 0, s[78:79]
	s_mov_b32 m0, s42
	ds_read_b128 v[194:197], v161 offset:49152
	ds_read_b128 v[198:201], v161 offset:50176
	ds_read_b128 v[202:205], v161 offset:51200
	ds_read_b128 v[218:221], v161 offset:52224
	ds_read_b128 v[222:225], v161 offset:53248
	ds_read_b128 v[226:229], v161 offset:54272
	ds_read_b128 v[230:233], v161 offset:55296
	ds_read_b128 v[234:237], v161 offset:56320
	global_load_lds_dwordx4 v[130:131], off
	s_add_i32 m0, s42, 0x2000
	s_add_u32 s34, s34, 0x80080
	v_lshl_add_u64 v[130:131], v[132:133], 0, s[78:79]
	s_addc_u32 s35, s35, 0
	s_add_i32 s42, s77, s48
	global_load_lds_dwordx4 v[130:131], off
	v_lshl_add_u64 v[130:131], s[34:35], 0, v[128:129]
	s_mov_b32 m0, s42
	s_nop 0
	global_load_lds_dwordx4 v[130:131], off
	v_lshl_add_u64 v[130:131], s[34:35], 0, v[142:143]
	s_add_i32 m0, s42, 0x2000
	s_nop 0
	global_load_lds_dwordx4 v[130:131], off
	v_lshl_add_u64 v[130:131], v[154:155], 0, s[78:79]
	s_mov_b32 m0, s58
	s_nop 0
	global_load_lds_dwordx4 v[130:131], off
	v_lshl_add_u64 v[130:131], v[206:207], 0, s[78:79]
	s_mov_b32 m0, s59
	s_nop 0
	global_load_lds_dwordx4 v[130:131], off
	s_waitcnt vmcnt(8)
	s_waitcnt lgkmcnt(0)
	s_barrier
	s_setprio 1
	s_waitcnt lgkmcnt(0)
	v_mfma_f32_16x16x32_bf16 v[60:63], v[162:165], v[194:197], v[60:63]
	v_mfma_f32_16x16x32_bf16 v[56:59], v[170:173], v[194:197], v[56:59]
	v_mfma_f32_16x16x32_bf16 v[44:47], v[162:165], v[202:205], v[44:47]
	v_mfma_f32_16x16x32_bf16 v[40:43], v[170:173], v[202:205], v[40:43]
	v_mfma_f32_16x16x32_bf16 v[28:31], v[162:165], v[222:225], v[28:31]
	v_mfma_f32_16x16x32_bf16 v[24:27], v[170:173], v[222:225], v[24:27]
	v_mfma_f32_16x16x32_bf16 v[12:15], v[162:165], v[230:233], v[12:15]
	v_mfma_f32_16x16x32_bf16 v[8:11], v[170:173], v[230:233], v[8:11]
	v_mfma_f32_16x16x32_bf16 v[60:63], v[166:169], v[198:201], v[60:63]
	v_mfma_f32_16x16x32_bf16 v[56:59], v[174:177], v[198:201], v[56:59]
	v_mfma_f32_16x16x32_bf16 v[44:47], v[166:169], v[218:221], v[44:47]
	v_mfma_f32_16x16x32_bf16 v[40:43], v[174:177], v[218:221], v[40:43]
	v_mfma_f32_16x16x32_bf16 v[28:31], v[166:169], v[226:229], v[28:31]
	v_mfma_f32_16x16x32_bf16 v[24:27], v[174:177], v[226:229], v[24:27]
	v_mfma_f32_16x16x32_bf16 v[12:15], v[166:169], v[234:237], v[12:15]
	v_mfma_f32_16x16x32_bf16 v[8:11], v[174:177], v[234:237], v[8:11]
	v_mfma_f32_16x16x32_bf16 v[52:55], v[178:181], v[194:197], v[52:55]
	v_mfma_f32_16x16x32_bf16 v[48:51], v[186:189], v[194:197], v[48:51]
	v_mfma_f32_16x16x32_bf16 v[36:39], v[178:181], v[202:205], v[36:39]
	v_mfma_f32_16x16x32_bf16 v[32:35], v[186:189], v[202:205], v[32:35]
	v_mfma_f32_16x16x32_bf16 v[20:23], v[178:181], v[222:225], v[20:23]
	v_mfma_f32_16x16x32_bf16 v[16:19], v[186:189], v[222:225], v[16:19]
	v_mfma_f32_16x16x32_bf16 v[4:7], v[178:181], v[230:233], v[4:7]
	v_mfma_f32_16x16x32_bf16 v[0:3], v[186:189], v[230:233], v[0:3]
	v_mfma_f32_16x16x32_bf16 v[52:55], v[182:185], v[198:201], v[52:55]
	v_mfma_f32_16x16x32_bf16 v[48:51], v[190:193], v[198:201], v[48:51]
	v_mfma_f32_16x16x32_bf16 v[36:39], v[182:185], v[218:221], v[36:39]
	v_mfma_f32_16x16x32_bf16 v[32:35], v[190:193], v[218:221], v[32:35]
	v_mfma_f32_16x16x32_bf16 v[20:23], v[182:185], v[226:229], v[20:23]
	v_mfma_f32_16x16x32_bf16 v[16:19], v[190:193], v[226:229], v[16:19]
	v_mfma_f32_16x16x32_bf16 v[4:7], v[182:185], v[234:237], v[4:7]
	v_mfma_f32_16x16x32_bf16 v[0:3], v[190:193], v[234:237], v[0:3]
	s_setprio 0
	s_barrier
	s_add_i32 s74, s74, 2
	s_add_u32 s30, s30, 0x100
	s_addc_u32 s31, s31, 0
	s_add_u32 s68, s68, 0x100
	s_addc_u32 s69, s69, 0
	s_cmp_gt_u32 s74, 29
.LBB0_1122:
	s_add_u32 s34, s30, 0xfff80080
	s_addc_u32 s35, s31, -1
	s_add_i32 s76, 0, 0x10000
	s_cmp_eq_u32 s74, 28
	s_cselect_b32 s43, s23, s35
	s_cselect_b32 s42, s61, s34
	v_add_u32_e32 v130, s76, v157
	s_cselect_b32 s35, s21, s69
	s_cselect_b32 s34, s62, s68
	s_add_i32 s80, 0, 0x14000
	ds_read_b128 v[162:165], v130
	ds_read_b128 v[166:169], v130 offset:1024
	ds_read_b128 v[170:173], v130 offset:2048
	ds_read_b128 v[174:177], v130 offset:3072
	v_add_u32_e32 v130, s80, v157
	ds_read_b128 v[178:181], v130
	ds_read_b128 v[182:185], v130 offset:1024
	ds_read_b128 v[186:189], v130 offset:2048
	ds_read_b128 v[190:193], v130 offset:3072
	v_lshl_add_u64 v[130:131], s[30:31], 0, v[148:149]
	s_add_i32 m0, s54, 0xc000
	ds_read_b128 v[194:197], v161
	ds_read_b128 v[198:201], v161 offset:1024
	ds_read_b128 v[202:205], v161 offset:2048
	ds_read_b128 v[218:221], v161 offset:3072
	ds_read_b128 v[222:225], v161 offset:4096
	ds_read_b128 v[226:229], v161 offset:5120
	ds_read_b128 v[230:233], v161 offset:6144
	ds_read_b128 v[234:237], v161 offset:7168
	global_load_lds_dwordx4 v[130:131], off
	v_lshl_add_u64 v[130:131], s[30:31], 0, v[150:151]
	s_add_i32 m0, s54, 0xe000
	s_nop 0
	global_load_lds_dwordx4 v[130:131], off
	s_waitcnt vmcnt(8)
	s_waitcnt lgkmcnt(0)
	s_barrier
; #define PG8_STAGE(bufoff, gbase, voff) do { _Pragma("unroll") for (int _i = 0; _i < 2; ++_i) \
;         __builtin_amdgcn_global_load_lds((const unsigned*)((const char*)(gbase) + (voff)[_i]), (PG8_LAS unsigned*)(lds + (bufoff) + ldsw + _i * 8192), 16, 0, 0); } while (0)
; #define PG8_LDA(dst, b, h) do { _Pragma("unroll") for (int m = 0; m < 4; ++m) _Pragma("unroll") for (int k = 0; k < 2; ++k) dst[m][k] = *(const PG8_LAS bf16x8*)(lds + PG8_SA(b, h) + aoff + m * 2048 + k * 1024); } while (0)
; #define PG8_LDB(dst, b, h) do { _Pragma("unroll") for (int n = 0; n < 2; ++n) _Pragma("unroll") for (int k = 0; k < 2; ++k) dst[n][k] = *(const PG8_LAS bf16x8*)(lds + PG8_SB(b, h) + boff + n * 2048 + k * 1024); } while (0)
; #define PG8_MMA(ai, bj, At, Bt) do { __builtin_amdgcn_s_setprio(1); _Pragma("unroll") for (int m = 0; m < 4; ++m) _Pragma("unroll") for (int n = 0; n < 2; ++n) _Pragma("unroll") for (int k = 0; k < 2; ++k) \
;         acc[ai][bj][m][n] = __builtin_amdgcn_mfma_f32_16x16x32_bf16(Bt[n][k], At[m][k], acc[ai][bj][m][n], 0, 0, 0); __builtin_amdgcn_s_setprio(0); } while (0)
; #define PG8_WAIT_V(n) asm volatile("s_waitcnt vmcnt(" #n ")" ::: "memory")
; #define PG8_WAIT_L(n) asm volatile("s_waitcnt lgkmcnt(" #n ")" ::: "memory")
; #define PG8_BAR __builtin_amdgcn_s_barrier()
; #define PG8_SCHED __builtin_amdgcn_sched_barrier(0)
; template <class Epi, class Sched, bool ALIGN_EPI = false, bool SP2 = false>
; __device__ __forceinline__ void gemm_phase(PG8_LAS unsigned char* lds, const Gemm g, const Sched& S, const Epi& E) {
;     ...
;             PG8_LDB(B0, 0, 0); PG8_LDB(B1, 0, 1); PG8_SCHED; PG8_LDA(At, 0, 0); PG8_STAGE(PG8_SA(1, 1), a1 + hstep, voffA);
;             PG8_WAIT_V(8); PG8_WAIT_L(0); PG8_BAR; PG8_MMA(0, 0, At, B0); PG8_MMA(0, 1, At, B1); PG8_BAR; PG8_SCHED;
;             PG8_LDA(At, 0, 1); PG8_STAGE(PG8_SB(0, 0), b2, voffB); PG8_STAGE(PG8_SB(0, 1), b2 + hstep, voffB); PG8_STAGE(PG8_SA(0, 0), a2, voffA);
;             PG8_WAIT_V(8); PG8_WAIT_L(0); PG8_BAR; PG8_MMA(1, 0, At, B0); PG8_MMA(1, 1, At, B1); PG8_BAR; PG8_SCHED;
	s_setprio 1
	s_waitcnt lgkmcnt(0)
	v_mfma_f32_16x16x32_bf16 v[124:127], v[162:165], v[194:197], v[124:127]
	v_mfma_f32_16x16x32_bf16 v[120:123], v[170:173], v[194:197], v[120:123]
	v_mfma_f32_16x16x32_bf16 v[108:111], v[162:165], v[202:205], v[108:111]
	v_mfma_f32_16x16x32_bf16 v[104:107], v[170:173], v[202:205], v[104:107]
	v_mfma_f32_16x16x32_bf16 v[92:95], v[162:165], v[222:225], v[92:95]
	v_mfma_f32_16x16x32_bf16 v[88:91], v[170:173], v[222:225], v[88:91]
	v_mfma_f32_16x16x32_bf16 v[76:79], v[162:165], v[230:233], v[76:79]
	v_mfma_f32_16x16x32_bf16 v[72:75], v[170:173], v[230:233], v[72:75]
	v_mfma_f32_16x16x32_bf16 v[124:127], v[166:169], v[198:201], v[124:127]
	v_mfma_f32_16x16x32_bf16 v[120:123], v[174:177], v[198:201], v[120:123]
	v_mfma_f32_16x16x32_bf16 v[108:111], v[166:169], v[218:221], v[108:111]
	v_mfma_f32_16x16x32_bf16 v[104:107], v[174:177], v[218:221], v[104:107]
	v_mfma_f32_16x16x32_bf16 v[92:95], v[166:169], v[226:229], v[92:95]
	v_mfma_f32_16x16x32_bf16 v[88:91], v[174:177], v[226:229], v[88:91]
	v_mfma_f32_16x16x32_bf16 v[76:79], v[166:169], v[234:237], v[76:79]
	v_mfma_f32_16x16x32_bf16 v[72:75], v[174:177], v[234:237], v[72:75]
	v_mfma_f32_16x16x32_bf16 v[116:119], v[178:181], v[194:197], v[116:119]
	v_mfma_f32_16x16x32_bf16 v[112:115], v[186:189], v[194:197], v[112:115]
	v_mfma_f32_16x16x32_bf16 v[100:103], v[178:181], v[202:205], v[100:103]
	v_mfma_f32_16x16x32_bf16 v[96:99], v[186:189], v[202:205], v[96:99]
	v_mfma_f32_16x16x32_bf16 v[84:87], v[178:181], v[222:225], v[84:87]
	v_mfma_f32_16x16x32_bf16 v[80:83], v[186:189], v[222:225], v[80:83]
	v_mfma_f32_16x16x32_bf16 v[68:71], v[178:181], v[230:233], v[68:71]
	v_mfma_f32_16x16x32_bf16 v[64:67], v[186:189], v[230:233], v[64:67]
	v_mfma_f32_16x16x32_bf16 v[116:119], v[182:185], v[198:201], v[116:119]
	v_mfma_f32_16x16x32_bf16 v[112:115], v[190:193], v[198:201], v[112:115]
	v_mfma_f32_16x16x32_bf16 v[100:103], v[182:185], v[218:221], v[100:103]
	v_mfma_f32_16x16x32_bf16 v[96:99], v[190:193], v[218:221], v[96:99]
	v_mfma_f32_16x16x32_bf16 v[84:87], v[182:185], v[226:229], v[84:87]
	v_mfma_f32_16x16x32_bf16 v[80:83], v[190:193], v[226:229], v[80:83]
	v_mfma_f32_16x16x32_bf16 v[68:71], v[182:185], v[234:237], v[68:71]
	v_mfma_f32_16x16x32_bf16 v[64:67], v[190:193], v[234:237], v[64:67]
	s_setprio 0
	s_barrier
	s_add_i32 s76, s76, s48
	v_lshl_add_u64 v[130:131], s[34:35], 0, v[128:129]
	s_mov_b32 m0, s76
	ds_read_b128 v[194:197], v161 offset:16384
	ds_read_b128 v[198:201], v161 offset:17408
	ds_read_b128 v[202:205], v161 offset:18432
	ds_read_b128 v[218:221], v161 offset:19456
	ds_read_b128 v[222:225], v161 offset:20480
	ds_read_b128 v[226:229], v161 offset:21504
	ds_read_b128 v[230:233], v161 offset:22528
	ds_read_b128 v[234:237], v161 offset:23552
	global_load_lds_dwordx4 v[130:131], off
	s_add_i32 m0, s76, 0x2000
	s_add_u32 s76, s34, 0x80000
	v_lshl_add_u64 v[132:133], s[34:35], 0, v[142:143]
	s_addc_u32 s77, s35, 0
	s_add_i32 s80, s80, s48
	global_load_lds_dwordx4 v[132:133], off
	v_lshl_add_u64 v[154:155], s[76:77], 0, v[128:129]
	s_mov_b32 m0, s80
	v_lshl_add_u64 v[206:207], s[42:43], 0, v[144:145]
	global_load_lds_dwordx4 v[154:155], off
	v_lshl_add_u64 v[154:155], s[76:77], 0, v[142:143]
	s_add_i32 m0, s80, 0x2000
	s_nop 0
	global_load_lds_dwordx4 v[154:155], off
	v_lshl_add_u64 v[154:155], s[42:43], 0, v[146:147]
	s_mov_b32 m0, s54
	s_nop 0
	global_load_lds_dwordx4 v[154:155], off
	s_mov_b32 m0, s55
	s_nop 0
	global_load_lds_dwordx4 v[206:207], off
	s_waitcnt vmcnt(8)
	s_waitcnt lgkmcnt(0)
	s_barrier
	s_setprio 1
	s_waitcnt lgkmcnt(0)
	v_mfma_f32_16x16x32_bf16 v[60:63], v[162:165], v[194:197], v[60:63]
	v_mfma_f32_16x16x32_bf16 v[56:59], v[170:173], v[194:197], v[56:59]
	v_mfma_f32_16x16x32_bf16 v[44:47], v[162:165], v[202:205], v[44:47]
	v_mfma_f32_16x16x32_bf16 v[40:43], v[170:173], v[202:205], v[40:43]
	v_mfma_f32_16x16x32_bf16 v[28:31], v[162:165], v[222:225], v[28:31]
	v_mfma_f32_16x16x32_bf16 v[24:27], v[170:173], v[222:225], v[24:27]
	v_mfma_f32_16x16x32_bf16 v[12:15], v[162:165], v[230:233], v[12:15]
	v_mfma_f32_16x16x32_bf16 v[8:11], v[170:173], v[230:233], v[8:11]
	v_mfma_f32_16x16x32_bf16 v[60:63], v[166:169], v[198:201], v[60:63]
	v_mfma_f32_16x16x32_bf16 v[56:59], v[174:177], v[198:201], v[56:59]
	v_mfma_f32_16x16x32_bf16 v[44:47], v[166:169], v[218:221], v[44:47]
	v_mfma_f32_16x16x32_bf16 v[40:43], v[174:177], v[218:221], v[40:43]
	v_mfma_f32_16x16x32_bf16 v[28:31], v[166:169], v[226:229], v[28:31]
	v_mfma_f32_16x16x32_bf16 v[24:27], v[174:177], v[226:229], v[24:27]
	v_mfma_f32_16x16x32_bf16 v[12:15], v[166:169], v[234:237], v[12:15]
	v_mfma_f32_16x16x32_bf16 v[8:11], v[174:177], v[234:237], v[8:11]
	v_mfma_f32_16x16x32_bf16 v[52:55], v[178:181], v[194:197], v[52:55]
	v_mfma_f32_16x16x32_bf16 v[48:51], v[186:189], v[194:197], v[48:51]
	v_mfma_f32_16x16x32_bf16 v[36:39], v[178:181], v[202:205], v[36:39]
	v_mfma_f32_16x16x32_bf16 v[32:35], v[186:189], v[202:205], v[32:35]
	v_mfma_f32_16x16x32_bf16 v[20:23], v[178:181], v[222:225], v[20:23]
	v_mfma_f32_16x16x32_bf16 v[16:19], v[186:189], v[222:225], v[16:19]
	v_mfma_f32_16x16x32_bf16 v[4:7], v[178:181], v[230:233], v[4:7]
	v_mfma_f32_16x16x32_bf16 v[0:3], v[186:189], v[230:233], v[0:3]
	v_mfma_f32_16x16x32_bf16 v[52:55], v[182:185], v[198:201], v[52:55]
	v_mfma_f32_16x16x32_bf16 v[48:51], v[190:193], v[198:201], v[48:51]
	v_mfma_f32_16x16x32_bf16 v[36:39], v[182:185], v[218:221], v[36:39]
	v_mfma_f32_16x16x32_bf16 v[32:35], v[190:193], v[218:221], v[32:35]
	v_mfma_f32_16x16x32_bf16 v[20:23], v[182:185], v[226:229], v[20:23]
	v_mfma_f32_16x16x32_bf16 v[16:19], v[190:193], v[226:229], v[16:19]
	v_mfma_f32_16x16x32_bf16 v[4:7], v[182:185], v[234:237], v[4:7]
	v_mfma_f32_16x16x32_bf16 v[0:3], v[190:193], v[234:237], v[0:3]
	s_setprio 0
	s_barrier
; #define PG8_STAGE(bufoff, gbase, voff) do { _Pragma("unroll") for (int _i = 0; _i < 2; ++_i) \
;         __builtin_amdgcn_global_load_lds((const unsigned*)((const char*)(gbase) + (voff)[_i]), (PG8_LAS unsigned*)(lds + (bufoff) + ldsw + _i * 8192), 16, 0, 0); } while (0)
; #define PG8_LDA(dst, b, h) do { _Pragma("unroll") for (int m = 0; m < 4; ++m) _Pragma("unroll") for (int k = 0; k < 2; ++k) dst[m][k] = *(const PG8_LAS bf16x8*)(lds + PG8_SA(b, h) + aoff + m * 2048 + k * 1024); } while (0)
; #define PG8_LDB(dst, b, h) do { _Pragma("unroll") for (int n = 0; n < 2; ++n) _Pragma("unroll") for (int k = 0; k < 2; ++k) dst[n][k] = *(const PG8_LAS bf16x8*)(lds + PG8_SB(b, h) + boff + n * 2048 + k * 1024); } while (0)
; #define PG8_MMA(ai, bj, At, Bt) do { __builtin_amdgcn_s_setprio(1); _Pragma("unroll") for (int m = 0; m < 4; ++m) _Pragma("unroll") for (int n = 0; n < 2; ++n) _Pragma("unroll") for (int k = 0; k < 2; ++k) \
;         acc[ai][bj][m][n] = __builtin_amdgcn_mfma_f32_16x16x32_bf16(Bt[n][k], At[m][k], acc[ai][bj][m][n], 0, 0, 0); __builtin_amdgcn_s_setprio(0); } while (0)
; #define PG8_WAIT_V(n) asm volatile("s_waitcnt vmcnt(" #n ")" ::: "memory")
; #define PG8_WAIT_L(n) asm volatile("s_waitcnt lgkmcnt(" #n ")" ::: "memory")
; #define PG8_BAR __builtin_amdgcn_s_barrier()
; #define PG8_SCHED __builtin_amdgcn_sched_barrier(0)
; template <class Epi, class Sched, bool ALIGN_EPI = false, bool SP2 = false>
; __device__ __forceinline__ void gemm_phase(PG8_LAS unsigned char* lds, const Gemm g, const Sched& S, const Epi& E) {
;     ...
;             PG8_LDB(B0, 1, 0); PG8_LDB(B1, 1, 1); PG8_SCHED; PG8_LDA(At, 1, 0); PG8_STAGE(PG8_SA(0, 1), a2 + hstep, voffA);
;             PG8_WAIT_V(8); PG8_WAIT_L(0); PG8_BAR; PG8_MMA(0, 0, At, B0); PG8_MMA(0, 1, At, B1); PG8_BAR; PG8_SCHED;
	s_add_i32 s76, 0, 0x18000
	v_add_u32_e32 v134, s76, v157
	s_add_i32 s77, 0, 0x1c000
	ds_read_b128 v[162:165], v134
	ds_read_b128 v[166:169], v134 offset:1024
	ds_read_b128 v[170:173], v134 offset:2048
	ds_read_b128 v[174:177], v134 offset:3072
	v_add_u32_e32 v134, s77, v157
	ds_read_b128 v[178:181], v134
	ds_read_b128 v[182:185], v134 offset:1024
	ds_read_b128 v[186:189], v134 offset:2048
	ds_read_b128 v[190:193], v134 offset:3072
	s_add_u32 s42, s42, 0x80000
	s_addc_u32 s43, s43, 0
	s_mov_b32 m0, s56
	v_lshl_add_u64 v[238:239], s[42:43], 0, v[146:147]
	ds_read_b128 v[194:197], v161 offset:32768
	ds_read_b128 v[198:201], v161 offset:33792
	ds_read_b128 v[202:205], v161 offset:34816
	ds_read_b128 v[218:221], v161 offset:35840
	ds_read_b128 v[222:225], v161 offset:36864
	ds_read_b128 v[226:229], v161 offset:37888
	ds_read_b128 v[230:233], v161 offset:38912
	ds_read_b128 v[234:237], v161 offset:39936
	global_load_lds_dwordx4 v[238:239], off
	v_lshl_add_u64 v[238:239], s[42:43], 0, v[144:145]
	s_mov_b32 m0, s57
	s_nop 0
	global_load_lds_dwordx4 v[238:239], off
	s_waitcnt vmcnt(8)
	s_waitcnt lgkmcnt(0)
	s_barrier
	s_setprio 1
	s_waitcnt lgkmcnt(0)
	v_mfma_f32_16x16x32_bf16 v[124:127], v[162:165], v[194:197], v[124:127]
	v_mfma_f32_16x16x32_bf16 v[120:123], v[170:173], v[194:197], v[120:123]
	v_mfma_f32_16x16x32_bf16 v[108:111], v[162:165], v[202:205], v[108:111]
	v_mfma_f32_16x16x32_bf16 v[104:107], v[170:173], v[202:205], v[104:107]
	v_mfma_f32_16x16x32_bf16 v[92:95], v[162:165], v[222:225], v[92:95]
	v_mfma_f32_16x16x32_bf16 v[88:91], v[170:173], v[222:225], v[88:91]
	v_mfma_f32_16x16x32_bf16 v[76:79], v[162:165], v[230:233], v[76:79]
	v_mfma_f32_16x16x32_bf16 v[72:75], v[170:173], v[230:233], v[72:75]
	v_mfma_f32_16x16x32_bf16 v[124:127], v[166:169], v[198:201], v[124:127]
	v_mfma_f32_16x16x32_bf16 v[120:123], v[174:177], v[198:201], v[120:123]
	v_mfma_f32_16x16x32_bf16 v[108:111], v[166:169], v[218:221], v[108:111]
	v_mfma_f32_16x16x32_bf16 v[104:107], v[174:177], v[218:221], v[104:107]
	v_mfma_f32_16x16x32_bf16 v[92:95], v[166:169], v[226:229], v[92:95]
	v_mfma_f32_16x16x32_bf16 v[88:91], v[174:177], v[226:229], v[88:91]
	v_mfma_f32_16x16x32_bf16 v[76:79], v[166:169], v[234:237], v[76:79]
	v_mfma_f32_16x16x32_bf16 v[72:75], v[174:177], v[234:237], v[72:75]
	v_mfma_f32_16x16x32_bf16 v[116:119], v[178:181], v[194:197], v[116:119]
	v_mfma_f32_16x16x32_bf16 v[112:115], v[186:189], v[194:197], v[112:115]
	v_mfma_f32_16x16x32_bf16 v[100:103], v[178:181], v[202:205], v[100:103]
	v_mfma_f32_16x16x32_bf16 v[96:99], v[186:189], v[202:205], v[96:99]
	v_mfma_f32_16x16x32_bf16 v[84:87], v[178:181], v[222:225], v[84:87]
	v_mfma_f32_16x16x32_bf16 v[80:83], v[186:189], v[222:225], v[80:83]
	v_mfma_f32_16x16x32_bf16 v[68:71], v[178:181], v[230:233], v[68:71]
	v_mfma_f32_16x16x32_bf16 v[64:67], v[186:189], v[230:233], v[64:67]
	v_mfma_f32_16x16x32_bf16 v[116:119], v[182:185], v[198:201], v[116:119]
	v_mfma_f32_16x16x32_bf16 v[112:115], v[190:193], v[198:201], v[112:115]
	v_mfma_f32_16x16x32_bf16 v[100:103], v[182:185], v[218:221], v[100:103]
	v_mfma_f32_16x16x32_bf16 v[96:99], v[190:193], v[218:221], v[96:99]
	v_mfma_f32_16x16x32_bf16 v[84:87], v[182:185], v[226:229], v[84:87]
	v_mfma_f32_16x16x32_bf16 v[80:83], v[190:193], v[226:229], v[80:83]
	v_mfma_f32_16x16x32_bf16 v[68:71], v[182:185], v[234:237], v[68:71]
	v_mfma_f32_16x16x32_bf16 v[64:67], v[190:193], v[234:237], v[64:67]
	s_setprio 0
	s_barrier
; #define PG8_STAGE(bufoff, gbase, voff) do { _Pragma("unroll") for (int _i = 0; _i < 2; ++_i) \
;         __builtin_amdgcn_global_load_lds((const unsigned*)((const char*)(gbase) + (voff)[_i]), (PG8_LAS unsigned*)(lds + (bufoff) + ldsw + _i * 8192), 16, 0, 0); } while (0)
; #define PG8_LDA(dst, b, h) do { _Pragma("unroll") for (int m = 0; m < 4; ++m) _Pragma("unroll") for (int k = 0; k < 2; ++k) dst[m][k] = *(const PG8_LAS bf16x8*)(lds + PG8_SA(b, h) + aoff + m * 2048 + k * 1024); } while (0)
; #define PG8_MMA(ai, bj, At, Bt) do { __builtin_amdgcn_s_setprio(1); _Pragma("unroll") for (int m = 0; m < 4; ++m) _Pragma("unroll") for (int n = 0; n < 2; ++n) _Pragma("unroll") for (int k = 0; k < 2; ++k) \
;         acc[ai][bj][m][n] = __builtin_amdgcn_mfma_f32_16x16x32_bf16(Bt[n][k], At[m][k], acc[ai][bj][m][n], 0, 0, 0); __builtin_amdgcn_s_setprio(0); } while (0)
; #define PG8_WAIT_V(n) asm volatile("s_waitcnt vmcnt(" #n ")" ::: "memory")
; #define PG8_WAIT_L(n) asm volatile("s_waitcnt lgkmcnt(" #n ")" ::: "memory")
; #define PG8_BAR __builtin_amdgcn_s_barrier()
; #define PG8_SCHED __builtin_amdgcn_sched_barrier(0)
; template <class Epi, class Sched, bool ALIGN_EPI = false, bool SP2 = false>
; __device__ __forceinline__ void gemm_phase(PG8_LAS unsigned char* lds, const Gemm g, const Sched& S, const Epi& E) {
;     ...
;             PG8_LDA(At, 1, 1); PG8_STAGE(PG8_SB(1, 0), b3, voffB); PG8_STAGE(PG8_SB(1, 1), b3 + hstep, voffB); PG8_STAGE(PG8_SA(1, 0), a3, voffA);
;             PG8_WAIT_V(8); PG8_WAIT_L(0); PG8_BAR; PG8_MMA(1, 0, At, B0); PG8_MMA(1, 1, At, B1); PG8_BAR; PG8_SCHED;
;     ...
;         if constexpr (ALIGN_EPI) { if (wr == 0) PG8_BAR; }
	s_add_i32 s42, s76, s48
	v_lshl_add_u64 v[130:131], v[130:131], 0, s[78:79]
	s_mov_b32 m0, s42
	ds_read_b128 v[194:197], v161 offset:49152
	ds_read_b128 v[198:201], v161 offset:50176
	ds_read_b128 v[202:205], v161 offset:51200
	ds_read_b128 v[218:221], v161 offset:52224
	ds_read_b128 v[222:225], v161 offset:53248
	ds_read_b128 v[226:229], v161 offset:54272
	ds_read_b128 v[230:233], v161 offset:55296
	ds_read_b128 v[234:237], v161 offset:56320
	global_load_lds_dwordx4 v[130:131], off
	s_add_i32 m0, s42, 0x2000
	s_add_u32 s34, s34, 0x80080
	v_lshl_add_u64 v[130:131], v[132:133], 0, s[78:79]
	s_addc_u32 s35, s35, 0
	s_add_i32 s42, s77, s48
	global_load_lds_dwordx4 v[130:131], off
	v_lshl_add_u64 v[130:131], s[34:35], 0, v[128:129]
	s_mov_b32 m0, s42
	s_nop 0
	global_load_lds_dwordx4 v[130:131], off
	v_lshl_add_u64 v[130:131], s[34:35], 0, v[142:143]
	s_add_i32 m0, s42, 0x2000
	s_nop 0
	global_load_lds_dwordx4 v[130:131], off
	v_lshl_add_u64 v[130:131], v[154:155], 0, s[78:79]
	s_mov_b32 m0, s58
	s_nop 0
	global_load_lds_dwordx4 v[130:131], off
	v_lshl_add_u64 v[130:131], v[206:207], 0, s[78:79]
	s_mov_b32 m0, s59
	s_nop 0
	global_load_lds_dwordx4 v[130:131], off
	s_waitcnt vmcnt(8)
	s_waitcnt lgkmcnt(0)
	s_barrier
	s_setprio 1
	s_waitcnt lgkmcnt(0)
	v_mfma_f32_16x16x32_bf16 v[60:63], v[162:165], v[194:197], v[60:63]
	v_mfma_f32_16x16x32_bf16 v[56:59], v[170:173], v[194:197], v[56:59]
	v_mfma_f32_16x16x32_bf16 v[44:47], v[162:165], v[202:205], v[44:47]
	v_mfma_f32_16x16x32_bf16 v[40:43], v[170:173], v[202:205], v[40:43]
	v_mfma_f32_16x16x32_bf16 v[28:31], v[162:165], v[222:225], v[28:31]
	v_mfma_f32_16x16x32_bf16 v[24:27], v[170:173], v[222:225], v[24:27]
	v_mfma_f32_16x16x32_bf16 v[12:15], v[162:165], v[230:233], v[12:15]
	v_mfma_f32_16x16x32_bf16 v[8:11], v[170:173], v[230:233], v[8:11]
	v_mfma_f32_16x16x32_bf16 v[60:63], v[166:169], v[198:201], v[60:63]
	v_mfma_f32_16x16x32_bf16 v[56:59], v[174:177], v[198:201], v[56:59]
	v_mfma_f32_16x16x32_bf16 v[44:47], v[166:169], v[218:221], v[44:47]
	v_mfma_f32_16x16x32_bf16 v[40:43], v[174:177], v[218:221], v[40:43]
	v_mfma_f32_16x16x32_bf16 v[28:31], v[166:169], v[226:229], v[28:31]
	v_mfma_f32_16x16x32_bf16 v[24:27], v[174:177], v[226:229], v[24:27]
	v_mfma_f32_16x16x32_bf16 v[12:15], v[166:169], v[234:237], v[12:15]
	v_mfma_f32_16x16x32_bf16 v[8:11], v[174:177], v[234:237], v[8:11]
	v_mfma_f32_16x16x32_bf16 v[52:55], v[178:181], v[194:197], v[52:55]
	v_mfma_f32_16x16x32_bf16 v[48:51], v[186:189], v[194:197], v[48:51]
	v_mfma_f32_16x16x32_bf16 v[36:39], v[178:181], v[202:205], v[36:39]
	v_mfma_f32_16x16x32_bf16 v[32:35], v[186:189], v[202:205], v[32:35]
	v_mfma_f32_16x16x32_bf16 v[20:23], v[178:181], v[222:225], v[20:23]
	v_mfma_f32_16x16x32_bf16 v[16:19], v[186:189], v[222:225], v[16:19]
	v_mfma_f32_16x16x32_bf16 v[4:7], v[178:181], v[230:233], v[4:7]
	v_mfma_f32_16x16x32_bf16 v[0:3], v[186:189], v[230:233], v[0:3]
	v_mfma_f32_16x16x32_bf16 v[52:55], v[182:185], v[198:201], v[52:55]
	v_mfma_f32_16x16x32_bf16 v[48:51], v[190:193], v[198:201], v[48:51]
	v_mfma_f32_16x16x32_bf16 v[36:39], v[182:185], v[218:221], v[36:39]
	v_mfma_f32_16x16x32_bf16 v[32:35], v[190:193], v[218:221], v[32:35]
	v_mfma_f32_16x16x32_bf16 v[20:23], v[182:185], v[226:229], v[20:23]
	v_mfma_f32_16x16x32_bf16 v[16:19], v[190:193], v[226:229], v[16:19]
	v_mfma_f32_16x16x32_bf16 v[4:7], v[182:185], v[234:237], v[4:7]
	v_mfma_f32_16x16x32_bf16 v[0:3], v[190:193], v[234:237], v[0:3]
	s_setprio 0
	s_barrier
	s_add_i32 s74, s74, 2
	s_add_u32 s30, s30, 0x100
	s_addc_u32 s31, s31, 0
	s_add_u32 s68, s68, 0x100
	s_addc_u32 s69, s69, 0
	s_cmp_gt_u32 s74, 29
	s_cbranch_scc0 .LBB0_1122
	s_and_b64 vcc, exec, s[18:19]
	s_cbranch_vccz .LBB0_1125
	s_barrier

; #define PG8_STAGE(bufoff, gbase, voff) do { _Pragma("unroll") for (int _i = 0; _i < 2; ++_i) \
;         __builtin_amdgcn_global_load_lds((const unsigned*)((const char*)(gbase) + (voff)[_i]), (PG8_LAS unsigned*)(lds + (bufoff) + ldsw + _i * 8192), 16, 0, 0); } while (0)
; #define PG8_LDA(dst, b, h) do { _Pragma("unroll") for (int m = 0; m < 4; ++m) _Pragma("unroll") for (int k = 0; k < 2; ++k) dst[m][k] = *(const PG8_LAS bf16x8*)(lds + PG8_SA(b, h) + aoff + m * 2048 + k * 1024); } while (0)
; #define PG8_LDB(dst, b, h) do { _Pragma("unroll") for (int n = 0; n < 2; ++n) _Pragma("unroll") for (int k = 0; k < 2; ++k) dst[n][k] = *(const PG8_LAS bf16x8*)(lds + PG8_SB(b, h) + boff + n * 2048 + k * 1024); } while (0)
; #define PG8_WAIT_V(n) asm volatile("s_waitcnt vmcnt(" #n ")" ::: "memory")
; #define PG8_WAIT_L(n) asm volatile("s_waitcnt lgkmcnt(" #n ")" ::: "memory")
; #define PG8_BAR __builtin_amdgcn_s_barrier()
; #define PG8_SCHED __builtin_amdgcn_sched_barrier(0)
; template <class Epi, class Sched, bool ALIGN_EPI = false, bool SP2 = false>
; __device__ __forceinline__ void gemm_phase(PG8_LAS unsigned char* lds, const Gemm g, const Sched& S, const Epi& E) {
;     ...
;         const bool has_next = S.next(ui + 1, nxt);
;         const char* nA = has_next ? (const char*)g.A + (size_t)nxt.pm * tstep : cA; const char* nB = has_next ? (const char*)g.Bt + (size_t)nxt.pn * tstep : cB;
;         for (int t = 0; t < nt; t += 2) {
;             const bool last = (t == nt - 2);
;             const char* a1 = cA + (size_t)(t + 1) * kstep;
;             const char* a2 = last ? nA : cA + (size_t)(t + 2) * kstep; const char* b2 = last ? nB : cB + (size_t)(t + 2) * kstep;
;             const char* a3 = a2 + kstep; const char* b3 = b2 + kstep;
;             if (last && has_next) S.a_ready(nxt);
;             if constexpr (SP2) {
;             PG8_LDB(B0, 0, 0); PG8_LDB(B1, 0, 1); PG8_SCHED; PG8_LDA(At, 0, 0); PG8_STAGE(PG8_SA(1, 1), a1 + hstep, voffA);
;             PG8_WAIT_V(8); PG8_WAIT_L(0); PG8_BAR; PG8_MMA(0, 0, At, B0); PG8_MMA(0, 1, At, B1); PG8_BAR; PG8_SCHED;
;             PG8_LDA(At, 0, 1); PG8_STAGE(PG8_SB(0, 0), b2, voffB); PG8_STAGE(PG8_SB(0, 1), b2 + hstep, voffB); PG8_STAGE(PG8_SA(0, 0), a2, voffA);
;             PG8_WAIT_V(8); PG8_WAIT_L(0); PG8_BAR; PG8_MMA(1, 0, At, B0); PG8_MMA(1, 1, At, B1); PG8_BAR; PG8_SCHED;
.LBB0_1189:
	s_ashr_i32 s23, s22, 31
	s_lshl_b64 s[24:25], s[22:23], 17
	s_add_u32 s24, s38, s24
	s_addc_u32 s25, s39, s25
	s_and_b64 s[26:27], s[42:43], exec
	s_cselect_b32 s81, s25, s35
	s_cselect_b32 s80, s24, s34
	s_ashr_i32 s21, s20, 31
	s_lshl_b64 s[26:27], s[20:21], 17
	s_add_u32 s26, s48, s26
	s_addc_u32 s27, s54, s27
	s_and_b64 s[68:69], s[42:43], exec
	s_cselect_b32 vcc_hi, s27, s45
	s_cselect_b32 vcc_lo, s26, s44
	s_add_i32 s23, 0, 0x10000
	s_add_i32 s29, 0, 0x14000
	v_add_u32_e32 v134, s23, v218
	v_add_u32_e32 v135, s29, v218
	s_waitcnt lgkmcnt(0)
	ds_read_b128 v[0:3], v134
	ds_read_b128 v[4:7], v134 offset:1024
	ds_read_b128 v[8:11], v134 offset:2048
	ds_read_b128 v[12:15], v134 offset:3072
	ds_read_b128 v[16:19], v135
	ds_read_b128 v[20:23], v135 offset:1024
	ds_read_b128 v[24:27], v135 offset:2048
	ds_read_b128 v[28:31], v135 offset:3072
	s_add_u32 s68, s34, 0x10080
	s_addc_u32 s69, s35, 0
	s_add_i32 s76, s31, 0xc000
	v_lshl_add_u64 v[64:65], s[68:69], 0, v[128:129]
	s_mov_b32 m0, s76
	s_add_i32 s21, s31, 0xe000
	ds_read_b128 v[32:35], v220
	ds_read_b128 v[36:39], v220 offset:1024
	ds_read_b128 v[40:43], v220 offset:2048
	ds_read_b128 v[44:47], v220 offset:3072
	ds_read_b128 v[48:51], v220 offset:4096
	ds_read_b128 v[52:55], v220 offset:5120
	ds_read_b128 v[56:59], v220 offset:6144
	ds_read_b128 v[60:63], v220 offset:7168
	global_load_lds_dwordx4 v[64:65], off
	v_lshl_add_u64 v[64:65], s[68:69], 0, v[142:143]
	s_mov_b32 m0, s21
	s_nop 0
	global_load_lds_dwordx4 v[64:65], off
	s_waitcnt vmcnt(8)
	s_waitcnt lgkmcnt(0)
	s_barrier
	s_setprio 1
	s_waitcnt lgkmcnt(0)
	v_mfma_f32_16x16x32_bf16 v[64:67], v[0:3], v[32:35], 0
	v_mfma_f32_16x16x32_bf16 v[68:71], v[8:11], v[32:35], 0
	v_mfma_f32_16x16x32_bf16 v[72:75], v[0:3], v[40:43], 0
	v_mfma_f32_16x16x32_bf16 v[76:79], v[8:11], v[40:43], 0
	v_mfma_f32_16x16x32_bf16 v[80:83], v[0:3], v[48:51], 0
	v_mfma_f32_16x16x32_bf16 v[84:87], v[8:11], v[48:51], 0
	v_mfma_f32_16x16x32_bf16 v[88:91], v[0:3], v[56:59], 0
	v_mfma_f32_16x16x32_bf16 v[92:95], v[8:11], v[56:59], 0
	v_mfma_f32_16x16x32_bf16 v[64:67], v[4:7], v[36:39], v[64:67]
	v_mfma_f32_16x16x32_bf16 v[68:71], v[12:15], v[36:39], v[68:71]
	v_mfma_f32_16x16x32_bf16 v[72:75], v[4:7], v[44:47], v[72:75]
	v_mfma_f32_16x16x32_bf16 v[76:79], v[12:15], v[44:47], v[76:79]
	v_mfma_f32_16x16x32_bf16 v[80:83], v[4:7], v[52:55], v[80:83]
	v_mfma_f32_16x16x32_bf16 v[84:87], v[12:15], v[52:55], v[84:87]
	v_mfma_f32_16x16x32_bf16 v[88:91], v[4:7], v[60:63], v[88:91]
	v_mfma_f32_16x16x32_bf16 v[92:95], v[12:15], v[60:63], v[92:95]
	v_mfma_f32_16x16x32_bf16 v[96:99], v[16:19], v[32:35], 0
	v_mfma_f32_16x16x32_bf16 v[32:35], v[24:27], v[32:35], 0
	v_mfma_f32_16x16x32_bf16 v[96:99], v[20:23], v[36:39], v[96:99]
	v_mfma_f32_16x16x32_bf16 v[32:35], v[28:31], v[36:39], v[32:35]
	v_mfma_f32_16x16x32_bf16 v[36:39], v[16:19], v[40:43], 0
	v_mfma_f32_16x16x32_bf16 v[40:43], v[24:27], v[40:43], 0
	v_mfma_f32_16x16x32_bf16 v[36:39], v[20:23], v[44:47], v[36:39]
	v_mfma_f32_16x16x32_bf16 v[40:43], v[28:31], v[44:47], v[40:43]
	v_mfma_f32_16x16x32_bf16 v[44:47], v[16:19], v[48:51], 0
	v_mfma_f32_16x16x32_bf16 v[48:51], v[24:27], v[48:51], 0
	v_mfma_f32_16x16x32_bf16 v[44:47], v[20:23], v[52:55], v[44:47]
	v_mfma_f32_16x16x32_bf16 v[48:51], v[28:31], v[52:55], v[48:51]
	v_mfma_f32_16x16x32_bf16 v[52:55], v[16:19], v[56:59], 0
	v_mfma_f32_16x16x32_bf16 v[56:59], v[24:27], v[56:59], 0
	v_mfma_f32_16x16x32_bf16 v[52:55], v[20:23], v[60:63], v[52:55]
	v_mfma_f32_16x16x32_bf16 v[56:59], v[28:31], v[60:63], v[56:59]
	s_setprio 0
	s_barrier
	v_lshl_add_u64 v[130:131], s[44:45], 0, v[128:129]
	s_add_i32 s69, s23, s55
	v_lshl_add_u64 v[132:133], v[130:131], 0, s[82:83]
	s_mov_b32 m0, s69
	s_add_i32 s23, s69, 0x2000
	ds_read_b128 v[60:63], v220 offset:16384
	ds_read_b128 v[100:103], v220 offset:17408
	ds_read_b128 v[104:107], v220 offset:18432
	ds_read_b128 v[108:111], v220 offset:19456
	ds_read_b128 v[112:115], v220 offset:20480
	ds_read_b128 v[116:119], v220 offset:21504
	ds_read_b128 v[120:123], v220 offset:22528
	ds_read_b128 v[124:127], v220 offset:23552
	global_load_lds_dwordx4 v[132:133], off
	v_lshl_add_u64 v[132:133], s[44:45], 0, v[142:143]
	s_add_u32 s96, s44, 0x10100
	v_lshl_add_u64 v[144:145], v[132:133], 0, s[82:83]
	s_mov_b32 m0, s23
	s_addc_u32 s97, s45, 0
	s_add_i32 s29, s29, s55
	global_load_lds_dwordx4 v[144:145], off
	v_lshl_add_u64 v[144:145], s[96:97], 0, v[128:129]
	s_mov_b32 m0, s29
	s_add_i32 s68, s29, 0x2000
	global_load_lds_dwordx4 v[144:145], off
	v_lshl_add_u64 v[144:145], s[96:97], 0, v[142:143]
	s_mov_b32 m0, s68
	v_lshl_add_u64 v[222:223], s[34:35], 0, v[128:129]
	global_load_lds_dwordx4 v[144:145], off
	v_lshl_add_u64 v[144:145], v[222:223], 0, s[82:83]
	s_mov_b32 m0, s31
	v_lshl_add_u64 v[224:225], s[34:35], 0, v[142:143]
	global_load_lds_dwordx4 v[144:145], off
	v_lshl_add_u64 v[144:145], v[224:225], 0, s[82:83]
	s_mov_b32 m0, s56
	s_nop 0
	global_load_lds_dwordx4 v[144:145], off
	s_waitcnt vmcnt(8)
	s_waitcnt lgkmcnt(0)
	s_barrier
; #define PG8_STAGE(bufoff, gbase, voff) do { _Pragma("unroll") for (int _i = 0; _i < 2; ++_i) \
;         __builtin_amdgcn_global_load_lds((const unsigned*)((const char*)(gbase) + (voff)[_i]), (PG8_LAS unsigned*)(lds + (bufoff) + ldsw + _i * 8192), 16, 0, 0); } while (0)
; #define PG8_LDA(dst, b, h) do { _Pragma("unroll") for (int m = 0; m < 4; ++m) _Pragma("unroll") for (int k = 0; k < 2; ++k) dst[m][k] = *(const PG8_LAS bf16x8*)(lds + PG8_SA(b, h) + aoff + m * 2048 + k * 1024); } while (0)
; #define PG8_LDB(dst, b, h) do { _Pragma("unroll") for (int n = 0; n < 2; ++n) _Pragma("unroll") for (int k = 0; k < 2; ++k) dst[n][k] = *(const PG8_LAS bf16x8*)(lds + PG8_SB(b, h) + boff + n * 2048 + k * 1024); } while (0)
; #define PG8_MMA(ai, bj, At, Bt) do { __builtin_amdgcn_s_setprio(1); _Pragma("unroll") for (int m = 0; m < 4; ++m) _Pragma("unroll") for (int n = 0; n < 2; ++n) _Pragma("unroll") for (int k = 0; k < 2; ++k) \
;         acc[ai][bj][m][n] = __builtin_amdgcn_mfma_f32_16x16x32_bf16(Bt[n][k], At[m][k], acc[ai][bj][m][n], 0, 0, 0); __builtin_amdgcn_s_setprio(0); } while (0)
; #define PG8_WAIT_V(n) asm volatile("s_waitcnt vmcnt(" #n ")" ::: "memory")
; #define PG8_WAIT_L(n) asm volatile("s_waitcnt lgkmcnt(" #n ")" ::: "memory")
; #define PG8_BAR __builtin_amdgcn_s_barrier()
; #define PG8_SCHED __builtin_amdgcn_sched_barrier(0)
; template <class Epi, class Sched, bool ALIGN_EPI = false, bool SP2 = false>
; __device__ __forceinline__ void gemm_phase(PG8_LAS unsigned char* lds, const Gemm g, const Sched& S, const Epi& E) {
;     ...
;             PG8_WAIT_V(8); PG8_WAIT_L(0); PG8_BAR; PG8_MMA(1, 0, At, B0); PG8_MMA(1, 1, At, B1); PG8_BAR; PG8_SCHED;
;             PG8_LDB(B0, 1, 0); PG8_LDB(B1, 1, 1); PG8_SCHED; PG8_LDA(At, 1, 0); PG8_STAGE(PG8_SA(0, 1), a2 + hstep, voffA);
;             PG8_WAIT_V(8); PG8_WAIT_L(0); PG8_BAR; PG8_MMA(0, 0, At, B0); PG8_MMA(0, 1, At, B1); PG8_BAR; PG8_SCHED;
	s_setprio 1
	s_waitcnt lgkmcnt(0)
	v_mfma_f32_16x16x32_bf16 v[144:147], v[0:3], v[60:63], 0
	v_mfma_f32_16x16x32_bf16 v[152:155], v[0:3], v[104:107], 0
	v_mfma_f32_16x16x32_bf16 v[160:163], v[0:3], v[112:115], 0
	v_mfma_f32_16x16x32_bf16 v[0:3], v[0:3], v[120:123], 0
	v_mfma_f32_16x16x32_bf16 v[144:147], v[4:7], v[100:103], v[144:147]
	v_mfma_f32_16x16x32_bf16 v[152:155], v[4:7], v[108:111], v[152:155]
	v_mfma_f32_16x16x32_bf16 v[160:163], v[4:7], v[116:119], v[160:163]
	v_mfma_f32_16x16x32_bf16 v[0:3], v[4:7], v[124:127], v[0:3]
	v_mfma_f32_16x16x32_bf16 v[4:7], v[8:11], v[120:123], 0
	v_mfma_f32_16x16x32_bf16 v[148:151], v[8:11], v[60:63], 0
	v_mfma_f32_16x16x32_bf16 v[156:159], v[8:11], v[104:107], 0
	v_mfma_f32_16x16x32_bf16 v[164:167], v[8:11], v[112:115], 0
	v_mfma_f32_16x16x32_bf16 v[4:7], v[12:15], v[124:127], v[4:7]
	v_mfma_f32_16x16x32_bf16 v[148:151], v[12:15], v[100:103], v[148:151]
	v_mfma_f32_16x16x32_bf16 v[156:159], v[12:15], v[108:111], v[156:159]
	v_mfma_f32_16x16x32_bf16 v[164:167], v[12:15], v[116:119], v[164:167]
	v_mfma_f32_16x16x32_bf16 v[8:11], v[16:19], v[60:63], 0
	v_mfma_f32_16x16x32_bf16 v[12:15], v[24:27], v[60:63], 0
	v_mfma_f32_16x16x32_bf16 v[8:11], v[20:23], v[100:103], v[8:11]
	v_mfma_f32_16x16x32_bf16 v[12:15], v[28:31], v[100:103], v[12:15]
	v_mfma_f32_16x16x32_bf16 v[60:63], v[16:19], v[104:107], 0
	v_mfma_f32_16x16x32_bf16 v[100:103], v[24:27], v[104:107], 0
	v_mfma_f32_16x16x32_bf16 v[104:107], v[16:19], v[112:115], 0
	v_mfma_f32_16x16x32_bf16 v[16:19], v[16:19], v[120:123], 0
	v_mfma_f32_16x16x32_bf16 v[60:63], v[20:23], v[108:111], v[60:63]
	v_mfma_f32_16x16x32_bf16 v[100:103], v[28:31], v[108:111], v[100:103]
	v_mfma_f32_16x16x32_bf16 v[104:107], v[20:23], v[116:119], v[104:107]
	v_mfma_f32_16x16x32_bf16 v[108:111], v[24:27], v[112:115], 0
	v_mfma_f32_16x16x32_bf16 v[16:19], v[20:23], v[124:127], v[16:19]
	v_mfma_f32_16x16x32_bf16 v[20:23], v[24:27], v[120:123], 0
	v_mfma_f32_16x16x32_bf16 v[108:111], v[28:31], v[116:119], v[108:111]
	v_mfma_f32_16x16x32_bf16 v[20:23], v[28:31], v[124:127], v[20:23]
	s_setprio 0
	s_barrier
	s_add_i32 s77, 0, 0x18000
	s_add_i32 s93, 0, 0x1c000
	v_add_u32_e32 v221, s77, v218
	v_add_u32_e32 v234, s93, v218
	ds_read_b128 v[24:27], v221
	ds_read_b128 v[28:31], v221 offset:1024
	ds_read_b128 v[112:115], v221 offset:2048
	ds_read_b128 v[116:119], v221 offset:3072
	ds_read_b128 v[120:123], v234
	ds_read_b128 v[124:127], v234 offset:1024
	ds_read_b128 v[168:171], v234 offset:2048
	ds_read_b128 v[172:175], v234 offset:3072
	s_add_u32 s96, s34, 0x10100
	s_addc_u32 s97, s35, 0
	s_mov_b32 m0, s57
	v_lshl_add_u64 v[226:227], s[96:97], 0, v[128:129]
	ds_read_b128 v[176:179], v220 offset:32768
	ds_read_b128 v[180:183], v220 offset:33792
	ds_read_b128 v[184:187], v220 offset:34816
	ds_read_b128 v[188:191], v220 offset:35840
	ds_read_b128 v[192:195], v220 offset:36864
	ds_read_b128 v[196:199], v220 offset:37888
	ds_read_b128 v[200:203], v220 offset:38912
	ds_read_b128 v[204:207], v220 offset:39936
	global_load_lds_dwordx4 v[226:227], off
	v_lshl_add_u64 v[226:227], s[96:97], 0, v[142:143]
	s_mov_b32 m0, s58
	s_nop 0
	global_load_lds_dwordx4 v[226:227], off
	s_waitcnt vmcnt(8)
	s_waitcnt lgkmcnt(0)
	s_barrier
	s_setprio 1
	s_waitcnt lgkmcnt(0)
	v_mfma_f32_16x16x32_bf16 v[64:67], v[24:27], v[176:179], v[64:67]
	v_mfma_f32_16x16x32_bf16 v[68:71], v[112:115], v[176:179], v[68:71]
	v_mfma_f32_16x16x32_bf16 v[72:75], v[24:27], v[184:187], v[72:75]
	v_mfma_f32_16x16x32_bf16 v[76:79], v[112:115], v[184:187], v[76:79]
	v_mfma_f32_16x16x32_bf16 v[80:83], v[24:27], v[192:195], v[80:83]
	v_mfma_f32_16x16x32_bf16 v[84:87], v[112:115], v[192:195], v[84:87]
	v_mfma_f32_16x16x32_bf16 v[88:91], v[24:27], v[200:203], v[88:91]
	v_mfma_f32_16x16x32_bf16 v[92:95], v[112:115], v[200:203], v[92:95]
	v_mfma_f32_16x16x32_bf16 v[64:67], v[28:31], v[180:183], v[64:67]
	v_mfma_f32_16x16x32_bf16 v[68:71], v[116:119], v[180:183], v[68:71]
	v_mfma_f32_16x16x32_bf16 v[72:75], v[28:31], v[188:191], v[72:75]
	v_mfma_f32_16x16x32_bf16 v[76:79], v[116:119], v[188:191], v[76:79]
	v_mfma_f32_16x16x32_bf16 v[80:83], v[28:31], v[196:199], v[80:83]
	v_mfma_f32_16x16x32_bf16 v[84:87], v[116:119], v[196:199], v[84:87]
	v_mfma_f32_16x16x32_bf16 v[88:91], v[28:31], v[204:207], v[88:91]
	v_mfma_f32_16x16x32_bf16 v[92:95], v[116:119], v[204:207], v[92:95]
	v_mfma_f32_16x16x32_bf16 v[96:99], v[120:123], v[176:179], v[96:99]
	v_mfma_f32_16x16x32_bf16 v[32:35], v[168:171], v[176:179], v[32:35]
	v_mfma_f32_16x16x32_bf16 v[36:39], v[120:123], v[184:187], v[36:39]
	v_mfma_f32_16x16x32_bf16 v[40:43], v[168:171], v[184:187], v[40:43]
	v_mfma_f32_16x16x32_bf16 v[44:47], v[120:123], v[192:195], v[44:47]
	v_mfma_f32_16x16x32_bf16 v[48:51], v[168:171], v[192:195], v[48:51]
	v_mfma_f32_16x16x32_bf16 v[52:55], v[120:123], v[200:203], v[52:55]
	v_mfma_f32_16x16x32_bf16 v[56:59], v[168:171], v[200:203], v[56:59]
	v_mfma_f32_16x16x32_bf16 v[96:99], v[124:127], v[180:183], v[96:99]
	v_mfma_f32_16x16x32_bf16 v[32:35], v[172:175], v[180:183], v[32:35]
	v_mfma_f32_16x16x32_bf16 v[36:39], v[124:127], v[188:191], v[36:39]
	v_mfma_f32_16x16x32_bf16 v[40:43], v[172:175], v[188:191], v[40:43]
	v_mfma_f32_16x16x32_bf16 v[44:47], v[124:127], v[196:199], v[44:47]
	v_mfma_f32_16x16x32_bf16 v[48:51], v[172:175], v[196:199], v[48:51]
	v_mfma_f32_16x16x32_bf16 v[52:55], v[124:127], v[204:207], v[52:55]
	v_mfma_f32_16x16x32_bf16 v[56:59], v[172:175], v[204:207], v[56:59]
	s_setprio 0
	s_barrier
; #define PG8_STAGE(bufoff, gbase, voff) do { _Pragma("unroll") for (int _i = 0; _i < 2; ++_i) \
;         __builtin_amdgcn_global_load_lds((const unsigned*)((const char*)(gbase) + (voff)[_i]), (PG8_LAS unsigned*)(lds + (bufoff) + ldsw + _i * 8192), 16, 0, 0); } while (0)
; #define PG8_LDA(dst, b, h) do { _Pragma("unroll") for (int m = 0; m < 4; ++m) _Pragma("unroll") for (int k = 0; k < 2; ++k) dst[m][k] = *(const PG8_LAS bf16x8*)(lds + PG8_SA(b, h) + aoff + m * 2048 + k * 1024); } while (0)
; #define PG8_LDB(dst, b, h) do { _Pragma("unroll") for (int n = 0; n < 2; ++n) _Pragma("unroll") for (int k = 0; k < 2; ++k) dst[n][k] = *(const PG8_LAS bf16x8*)(lds + PG8_SB(b, h) + boff + n * 2048 + k * 1024); } while (0)
; #define PG8_MMA(ai, bj, At, Bt) do { __builtin_amdgcn_s_setprio(1); _Pragma("unroll") for (int m = 0; m < 4; ++m) _Pragma("unroll") for (int n = 0; n < 2; ++n) _Pragma("unroll") for (int k = 0; k < 2; ++k) \
;         acc[ai][bj][m][n] = __builtin_amdgcn_mfma_f32_16x16x32_bf16(Bt[n][k], At[m][k], acc[ai][bj][m][n], 0, 0, 0); __builtin_amdgcn_s_setprio(0); } while (0)
; #define PG8_WAIT_V(n) asm volatile("s_waitcnt vmcnt(" #n ")" ::: "memory")
; #define PG8_WAIT_L(n) asm volatile("s_waitcnt lgkmcnt(" #n ")" ::: "memory")
; #define PG8_BAR __builtin_amdgcn_s_barrier()
; #define PG8_SCHED __builtin_amdgcn_sched_barrier(0)
; template <class Epi, class Sched, bool ALIGN_EPI = false, bool SP2 = false>
; __device__ __forceinline__ void gemm_phase(PG8_LAS unsigned char* lds, const Gemm g, const Sched& S, const Epi& E) {
;     ...
;             PG8_LDA(At, 1, 1); PG8_STAGE(PG8_SB(1, 0), b3, voffB); PG8_STAGE(PG8_SB(1, 1), b3 + hstep, voffB); PG8_STAGE(PG8_SA(1, 0), a3, voffA);
;             PG8_WAIT_V(8); PG8_WAIT_L(0); PG8_BAR; PG8_MMA(1, 0, At, B0); PG8_MMA(1, 1, At, B1); PG8_BAR; PG8_SCHED;
;             } else {
;             PG8_LDB(B0, 0, 0); PG8_SCHED; PG8_LDA(At, 0, 0); PG8_STAGE(PG8_SA(1, 1), a1 + hstep, voffA);
	s_add_i32 s77, s77, s55
	s_add_i32 s74, s77, 0x2000
	v_lshl_add_u64 v[130:131], v[130:131], 0, s[46:47]
	s_mov_b32 m0, s77
	s_add_u32 s96, s44, 0x10180
	ds_read_b128 v[176:179], v220 offset:49152
	ds_read_b128 v[180:183], v220 offset:50176
	ds_read_b128 v[184:187], v220 offset:51200
	ds_read_b128 v[188:191], v220 offset:52224
	ds_read_b128 v[192:195], v220 offset:53248
	ds_read_b128 v[196:199], v220 offset:54272
	ds_read_b128 v[200:203], v220 offset:55296
	ds_read_b128 v[204:207], v220 offset:56320
	global_load_lds_dwordx4 v[130:131], off
	v_lshl_add_u64 v[130:131], v[132:133], 0, s[46:47]
	s_mov_b32 m0, s74
	s_addc_u32 s97, s45, 0
	s_add_i32 s44, s93, s55
	global_load_lds_dwordx4 v[130:131], off
	v_lshl_add_u64 v[130:131], s[96:97], 0, v[128:129]
	s_mov_b32 m0, s44
	s_add_i32 s45, s44, 0x2000
	global_load_lds_dwordx4 v[130:131], off
	v_lshl_add_u64 v[130:131], s[96:97], 0, v[142:143]
	s_mov_b32 m0, s45
	s_nop 0
	global_load_lds_dwordx4 v[130:131], off
	v_lshl_add_u64 v[130:131], v[222:223], 0, s[46:47]
	s_mov_b32 m0, s60
	s_nop 0
	global_load_lds_dwordx4 v[130:131], off
	v_lshl_add_u64 v[130:131], v[224:225], 0, s[46:47]
	s_mov_b32 m0, s61
	s_nop 0
	global_load_lds_dwordx4 v[130:131], off
	s_waitcnt vmcnt(8)
	s_waitcnt lgkmcnt(0)
	s_barrier
	s_setprio 1
	s_waitcnt lgkmcnt(0)
	v_mfma_f32_16x16x32_bf16 v[0:3], v[24:27], v[200:203], v[0:3]
	v_mfma_f32_16x16x32_bf16 v[4:7], v[112:115], v[200:203], v[4:7]
	v_mfma_f32_16x16x32_bf16 v[144:147], v[24:27], v[176:179], v[144:147]
	v_mfma_f32_16x16x32_bf16 v[148:151], v[112:115], v[176:179], v[148:151]
	v_mfma_f32_16x16x32_bf16 v[152:155], v[24:27], v[184:187], v[152:155]
	v_mfma_f32_16x16x32_bf16 v[156:159], v[112:115], v[184:187], v[156:159]
	v_mfma_f32_16x16x32_bf16 v[160:163], v[24:27], v[192:195], v[160:163]
	v_mfma_f32_16x16x32_bf16 v[164:167], v[112:115], v[192:195], v[164:167]
	v_mfma_f32_16x16x32_bf16 v[0:3], v[28:31], v[204:207], v[0:3]
	v_mfma_f32_16x16x32_bf16 v[4:7], v[116:119], v[204:207], v[4:7]
	v_mfma_f32_16x16x32_bf16 v[144:147], v[28:31], v[180:183], v[144:147]
	v_mfma_f32_16x16x32_bf16 v[148:151], v[116:119], v[180:183], v[148:151]
	v_mfma_f32_16x16x32_bf16 v[152:155], v[28:31], v[188:191], v[152:155]
	v_mfma_f32_16x16x32_bf16 v[156:159], v[116:119], v[188:191], v[156:159]
	v_mfma_f32_16x16x32_bf16 v[160:163], v[28:31], v[196:199], v[160:163]
	v_mfma_f32_16x16x32_bf16 v[164:167], v[116:119], v[196:199], v[164:167]
	v_mfma_f32_16x16x32_bf16 v[8:11], v[120:123], v[176:179], v[8:11]
	v_mfma_f32_16x16x32_bf16 v[12:15], v[168:171], v[176:179], v[12:15]
	v_mfma_f32_16x16x32_bf16 v[24:27], v[120:123], v[184:187], v[60:63]
	v_mfma_f32_16x16x32_bf16 v[28:31], v[168:171], v[184:187], v[100:103]
	v_mfma_f32_16x16x32_bf16 v[60:63], v[120:123], v[192:195], v[104:107]
	v_mfma_f32_16x16x32_bf16 v[100:103], v[168:171], v[192:195], v[108:111]
	v_mfma_f32_16x16x32_bf16 v[16:19], v[120:123], v[200:203], v[16:19]
	v_mfma_f32_16x16x32_bf16 v[20:23], v[168:171], v[200:203], v[20:23]
	v_mfma_f32_16x16x32_bf16 v[8:11], v[124:127], v[180:183], v[8:11]
	v_mfma_f32_16x16x32_bf16 v[12:15], v[172:175], v[180:183], v[12:15]
	v_mfma_f32_16x16x32_bf16 v[24:27], v[124:127], v[188:191], v[24:27]
	v_mfma_f32_16x16x32_bf16 v[28:31], v[172:175], v[188:191], v[28:31]
	v_mfma_f32_16x16x32_bf16 v[60:63], v[124:127], v[196:199], v[60:63]
	v_mfma_f32_16x16x32_bf16 v[100:103], v[172:175], v[196:199], v[100:103]
	v_mfma_f32_16x16x32_bf16 v[16:19], v[124:127], v[204:207], v[16:19]
	v_mfma_f32_16x16x32_bf16 v[20:23], v[172:175], v[204:207], v[20:23]
	s_setprio 0
	s_barrier
	ds_read_b128 v[104:107], v134
	ds_read_b128 v[108:111], v134 offset:1024
	ds_read_b128 v[112:115], v134 offset:2048
	ds_read_b128 v[116:119], v134 offset:3072
	ds_read_b128 v[120:123], v135
	ds_read_b128 v[124:127], v135 offset:1024
	ds_read_b128 v[168:171], v135 offset:2048
	ds_read_b128 v[172:175], v135 offset:3072
	s_add_u32 s34, s34, 0x10180
	s_addc_u32 s35, s35, 0
	s_mov_b32 m0, s76
	v_lshl_add_u64 v[130:131], s[34:35], 0, v[128:129]
	ds_read_b128 v[176:179], v220
	ds_read_b128 v[180:183], v220 offset:1024
	ds_read_b128 v[184:187], v220 offset:2048
	ds_read_b128 v[188:191], v220 offset:3072
	ds_read_b128 v[192:195], v220 offset:4096
	ds_read_b128 v[196:199], v220 offset:5120
	ds_read_b128 v[200:203], v220 offset:6144
	ds_read_b128 v[204:207], v220 offset:7168
	global_load_lds_dwordx4 v[130:131], off
	v_lshl_add_u64 v[130:131], s[34:35], 0, v[142:143]
	s_mov_b32 m0, s21
	s_nop 0
	global_load_lds_dwordx4 v[130:131], off
	s_waitcnt vmcnt(8)
	s_waitcnt lgkmcnt(0)
	s_barrier
; #define PG8_STAGE(bufoff, gbase, voff) do { _Pragma("unroll") for (int _i = 0; _i < 2; ++_i) \
;         __builtin_amdgcn_global_load_lds((const unsigned*)((const char*)(gbase) + (voff)[_i]), (PG8_LAS unsigned*)(lds + (bufoff) + ldsw + _i * 8192), 16, 0, 0); } while (0)
; #define PG8_LDA(dst, b, h) do { _Pragma("unroll") for (int m = 0; m < 4; ++m) _Pragma("unroll") for (int k = 0; k < 2; ++k) dst[m][k] = *(const PG8_LAS bf16x8*)(lds + PG8_SA(b, h) + aoff + m * 2048 + k * 1024); } while (0)
; #define PG8_LDB(dst, b, h) do { _Pragma("unroll") for (int n = 0; n < 2; ++n) _Pragma("unroll") for (int k = 0; k < 2; ++k) dst[n][k] = *(const PG8_LAS bf16x8*)(lds + PG8_SB(b, h) + boff + n * 2048 + k * 1024); } while (0)
; #define PG8_MMA(ai, bj, At, Bt) do { __builtin_amdgcn_s_setprio(1); _Pragma("unroll") for (int m = 0; m < 4; ++m) _Pragma("unroll") for (int n = 0; n < 2; ++n) _Pragma("unroll") for (int k = 0; k < 2; ++k) \
;         acc[ai][bj][m][n] = __builtin_amdgcn_mfma_f32_16x16x32_bf16(Bt[n][k], At[m][k], acc[ai][bj][m][n], 0, 0, 0); __builtin_amdgcn_s_setprio(0); } while (0)
; #define PG8_WAIT_V(n) asm volatile("s_waitcnt vmcnt(" #n ")" ::: "memory")
; #define PG8_WAIT_L(n) asm volatile("s_waitcnt lgkmcnt(" #n ")" ::: "memory")
; #define PG8_BAR __builtin_amdgcn_s_barrier()
; #define PG8_SCHED __builtin_amdgcn_sched_barrier(0)
; template <class Epi, class Sched, bool ALIGN_EPI = false, bool SP2 = false>
; __device__ __forceinline__ void gemm_phase(PG8_LAS unsigned char* lds, const Gemm g, const Sched& S, const Epi& E) {
;     ...
;             PG8_LDB(B0, 0, 0); PG8_LDB(B1, 0, 1); PG8_SCHED; PG8_LDA(At, 0, 0); PG8_STAGE(PG8_SA(1, 1), a1 + hstep, voffA);
;             PG8_WAIT_V(8); PG8_WAIT_L(0); PG8_BAR; PG8_MMA(0, 0, At, B0); PG8_MMA(0, 1, At, B1); PG8_BAR; PG8_SCHED;
;             PG8_LDA(At, 0, 1); PG8_STAGE(PG8_SB(0, 0), b2, voffB); PG8_STAGE(PG8_SB(0, 1), b2 + hstep, voffB); PG8_STAGE(PG8_SA(0, 0), a2, voffA);
;             PG8_WAIT_V(8); PG8_WAIT_L(0); PG8_BAR; PG8_MMA(1, 0, At, B0); PG8_MMA(1, 1, At, B1); PG8_BAR; PG8_SCHED;
	s_setprio 1
	s_waitcnt lgkmcnt(0)
	v_mfma_f32_16x16x32_bf16 v[64:67], v[104:107], v[176:179], v[64:67]
	v_mfma_f32_16x16x32_bf16 v[68:71], v[112:115], v[176:179], v[68:71]
	v_mfma_f32_16x16x32_bf16 v[72:75], v[104:107], v[184:187], v[72:75]
	v_mfma_f32_16x16x32_bf16 v[76:79], v[112:115], v[184:187], v[76:79]
	v_mfma_f32_16x16x32_bf16 v[80:83], v[104:107], v[192:195], v[80:83]
	v_mfma_f32_16x16x32_bf16 v[84:87], v[112:115], v[192:195], v[84:87]
	v_mfma_f32_16x16x32_bf16 v[88:91], v[104:107], v[200:203], v[88:91]
	v_mfma_f32_16x16x32_bf16 v[64:67], v[108:111], v[180:183], v[64:67]
	v_mfma_f32_16x16x32_bf16 v[68:71], v[116:119], v[180:183], v[68:71]
	v_mfma_f32_16x16x32_bf16 v[72:75], v[108:111], v[188:191], v[72:75]
	v_mfma_f32_16x16x32_bf16 v[76:79], v[116:119], v[188:191], v[76:79]
	v_mfma_f32_16x16x32_bf16 v[80:83], v[108:111], v[196:199], v[80:83]
	v_mfma_f32_16x16x32_bf16 v[84:87], v[116:119], v[196:199], v[84:87]
	v_mfma_f32_16x16x32_bf16 v[222:225], v[108:111], v[204:207], v[88:91]
	v_mfma_f32_16x16x32_bf16 v[88:91], v[112:115], v[200:203], v[92:95]
	v_mfma_f32_16x16x32_bf16 v[226:229], v[116:119], v[204:207], v[88:91]
	v_mfma_f32_16x16x32_bf16 v[88:91], v[120:123], v[176:179], v[96:99]
	v_mfma_f32_16x16x32_bf16 v[32:35], v[168:171], v[176:179], v[32:35]
	v_mfma_f32_16x16x32_bf16 v[36:39], v[120:123], v[184:187], v[36:39]
	v_mfma_f32_16x16x32_bf16 v[40:43], v[168:171], v[184:187], v[40:43]
	v_mfma_f32_16x16x32_bf16 v[44:47], v[120:123], v[192:195], v[44:47]
	v_mfma_f32_16x16x32_bf16 v[48:51], v[168:171], v[192:195], v[48:51]
	v_mfma_f32_16x16x32_bf16 v[52:55], v[120:123], v[200:203], v[52:55]
	v_mfma_f32_16x16x32_bf16 v[56:59], v[168:171], v[200:203], v[56:59]
	v_mfma_f32_16x16x32_bf16 v[96:99], v[124:127], v[180:183], v[88:91]
	v_mfma_f32_16x16x32_bf16 v[32:35], v[172:175], v[180:183], v[32:35]
	v_mfma_f32_16x16x32_bf16 v[36:39], v[124:127], v[188:191], v[36:39]
	v_mfma_f32_16x16x32_bf16 v[40:43], v[172:175], v[188:191], v[40:43]
	v_mfma_f32_16x16x32_bf16 v[44:47], v[124:127], v[196:199], v[44:47]
	v_mfma_f32_16x16x32_bf16 v[48:51], v[172:175], v[196:199], v[48:51]
	v_mfma_f32_16x16x32_bf16 v[52:55], v[124:127], v[204:207], v[52:55]
	v_mfma_f32_16x16x32_bf16 v[56:59], v[172:175], v[204:207], v[56:59]
	s_setprio 0
	s_barrier
	s_mov_b32 m0, s69
	v_lshl_add_u64 v[140:141], vcc, 0, v[128:129]
	s_add_u32 s34, vcc_lo, 0x10000
	ds_read_b128 v[88:91], v220 offset:16384
	ds_read_b128 v[92:95], v220 offset:17408
	ds_read_b128 v[176:179], v220 offset:18432
	ds_read_b128 v[180:183], v220 offset:19456
	ds_read_b128 v[184:187], v220 offset:20480
	ds_read_b128 v[188:191], v220 offset:21504
	ds_read_b128 v[192:195], v220 offset:22528
	ds_read_b128 v[196:199], v220 offset:23552
	global_load_lds_dwordx4 v[140:141], off
	v_lshl_add_u64 v[210:211], vcc, 0, v[142:143]
	s_mov_b32 m0, s23
	s_addc_u32 s35, vcc_hi, 0
	global_load_lds_dwordx4 v[210:211], off
	v_lshl_add_u64 v[130:131], s[34:35], 0, v[128:129]
	s_mov_b32 m0, s29
	v_lshl_add_u64 v[138:139], s[80:81], 0, v[128:129]
	global_load_lds_dwordx4 v[130:131], off
	v_lshl_add_u64 v[130:131], s[34:35], 0, v[142:143]
	s_mov_b32 m0, s68
	v_lshl_add_u64 v[134:135], s[80:81], 0, v[142:143]
	global_load_lds_dwordx4 v[130:131], off
	s_mov_b32 m0, s31
	s_nop 0
	global_load_lds_dwordx4 v[138:139], off
	s_mov_b32 m0, s56
	s_nop 0
	global_load_lds_dwordx4 v[134:135], off
	s_waitcnt vmcnt(8)
	s_waitcnt lgkmcnt(0)
	s_barrier
	s_setprio 1
	s_waitcnt lgkmcnt(0)
	v_mfma_f32_16x16x32_bf16 v[0:3], v[104:107], v[192:195], v[0:3]
	v_mfma_f32_16x16x32_bf16 v[4:7], v[112:115], v[192:195], v[4:7]
	v_mfma_f32_16x16x32_bf16 v[144:147], v[104:107], v[88:91], v[144:147]
	v_mfma_f32_16x16x32_bf16 v[148:151], v[112:115], v[88:91], v[148:151]
	v_mfma_f32_16x16x32_bf16 v[152:155], v[104:107], v[176:179], v[152:155]
	v_mfma_f32_16x16x32_bf16 v[156:159], v[112:115], v[176:179], v[156:159]
	v_mfma_f32_16x16x32_bf16 v[160:163], v[104:107], v[184:187], v[160:163]
	v_mfma_f32_16x16x32_bf16 v[164:167], v[112:115], v[184:187], v[164:167]
	v_mfma_f32_16x16x32_bf16 v[0:3], v[108:111], v[196:199], v[0:3]
	v_mfma_f32_16x16x32_bf16 v[4:7], v[116:119], v[196:199], v[4:7]
	v_mfma_f32_16x16x32_bf16 v[144:147], v[108:111], v[92:95], v[144:147]
	v_mfma_f32_16x16x32_bf16 v[148:151], v[116:119], v[92:95], v[148:151]
	v_mfma_f32_16x16x32_bf16 v[152:155], v[108:111], v[180:183], v[152:155]
	v_mfma_f32_16x16x32_bf16 v[156:159], v[116:119], v[180:183], v[156:159]
	v_mfma_f32_16x16x32_bf16 v[160:163], v[108:111], v[188:191], v[160:163]
	v_mfma_f32_16x16x32_bf16 v[164:167], v[116:119], v[188:191], v[164:167]
	v_mfma_f32_16x16x32_bf16 v[8:11], v[120:123], v[88:91], v[8:11]
	v_mfma_f32_16x16x32_bf16 v[200:203], v[124:127], v[92:95], v[8:11]
	v_mfma_f32_16x16x32_bf16 v[8:11], v[168:171], v[88:91], v[12:15]
	v_mfma_f32_16x16x32_bf16 v[204:207], v[172:175], v[92:95], v[8:11]
	v_mfma_f32_16x16x32_bf16 v[8:11], v[120:123], v[176:179], v[24:27]
	v_mfma_f32_16x16x32_bf16 v[230:233], v[124:127], v[180:183], v[8:11]
	v_mfma_f32_16x16x32_bf16 v[8:11], v[168:171], v[176:179], v[28:31]
	v_mfma_f32_16x16x32_bf16 v[176:179], v[172:175], v[180:183], v[8:11]
	v_mfma_f32_16x16x32_bf16 v[8:11], v[120:123], v[184:187], v[60:63]
	v_mfma_f32_16x16x32_bf16 v[180:183], v[124:127], v[188:191], v[8:11]
	v_mfma_f32_16x16x32_bf16 v[8:11], v[168:171], v[184:187], v[100:103]
	v_mfma_f32_16x16x32_bf16 v[184:187], v[172:175], v[188:191], v[8:11]
	v_mfma_f32_16x16x32_bf16 v[8:11], v[120:123], v[192:195], v[16:19]
	v_mfma_f32_16x16x32_bf16 v[188:191], v[124:127], v[196:199], v[8:11]
	v_mfma_f32_16x16x32_bf16 v[8:11], v[168:171], v[192:195], v[20:23]
	v_mfma_f32_16x16x32_bf16 v[168:171], v[172:175], v[196:199], v[8:11]
	s_setprio 0
	s_barrier
; #define PG8_STAGE(bufoff, gbase, voff) do { _Pragma("unroll") for (int _i = 0; _i < 2; ++_i) \
;         __builtin_amdgcn_global_load_lds((const unsigned*)((const char*)(gbase) + (voff)[_i]), (PG8_LAS unsigned*)(lds + (bufoff) + ldsw + _i * 8192), 16, 0, 0); } while (0)
; #define PG8_LDA(dst, b, h) do { _Pragma("unroll") for (int m = 0; m < 4; ++m) _Pragma("unroll") for (int k = 0; k < 2; ++k) dst[m][k] = *(const PG8_LAS bf16x8*)(lds + PG8_SA(b, h) + aoff + m * 2048 + k * 1024); } while (0)
; #define PG8_LDB(dst, b, h) do { _Pragma("unroll") for (int n = 0; n < 2; ++n) _Pragma("unroll") for (int k = 0; k < 2; ++k) dst[n][k] = *(const PG8_LAS bf16x8*)(lds + PG8_SB(b, h) + boff + n * 2048 + k * 1024); } while (0)
; #define PG8_MMA(ai, bj, At, Bt) do { __builtin_amdgcn_s_setprio(1); _Pragma("unroll") for (int m = 0; m < 4; ++m) _Pragma("unroll") for (int n = 0; n < 2; ++n) _Pragma("unroll") for (int k = 0; k < 2; ++k) \
;         acc[ai][bj][m][n] = __builtin_amdgcn_mfma_f32_16x16x32_bf16(Bt[n][k], At[m][k], acc[ai][bj][m][n], 0, 0, 0); __builtin_amdgcn_s_setprio(0); } while (0)
; #define PG8_WAIT_V(n) asm volatile("s_waitcnt vmcnt(" #n ")" ::: "memory")
; #define PG8_WAIT_L(n) asm volatile("s_waitcnt lgkmcnt(" #n ")" ::: "memory")
; #define PG8_BAR __builtin_amdgcn_s_barrier()
; #define PG8_SCHED __builtin_amdgcn_sched_barrier(0)
; template <class Epi, class Sched, bool ALIGN_EPI = false, bool SP2 = false>
; __device__ __forceinline__ void gemm_phase(PG8_LAS unsigned char* lds, const Gemm g, const Sched& S, const Epi& E) {
;     ...
;             PG8_LDB(B0, 1, 0); PG8_LDB(B1, 1, 1); PG8_SCHED; PG8_LDA(At, 1, 0); PG8_STAGE(PG8_SA(0, 1), a2 + hstep, voffA);
;             PG8_WAIT_V(8); PG8_WAIT_L(0); PG8_BAR; PG8_MMA(0, 0, At, B0); PG8_MMA(0, 1, At, B1); PG8_BAR; PG8_SCHED;
;             PG8_LDA(At, 1, 1); PG8_STAGE(PG8_SB(1, 0), b3, voffB); PG8_STAGE(PG8_SB(1, 1), b3 + hstep, voffB); PG8_STAGE(PG8_SA(1, 0), a3, voffA);
;             PG8_WAIT_V(8); PG8_WAIT_L(0); PG8_BAR; PG8_MMA(1, 0, At, B0); PG8_MMA(1, 1, At, B1); PG8_BAR; PG8_SCHED;
;     ...
;         if constexpr (ALIGN_EPI) { if (wr == 0) PG8_BAR; }
	s_nop 4
	ds_read_b128 v[8:11], v221
	ds_read_b128 v[12:15], v221 offset:1024
	ds_read_b128 v[16:19], v221 offset:2048
	ds_read_b128 v[20:23], v221 offset:3072
	ds_read_b128 v[172:175], v234
	ds_read_b128 v[192:195], v234 offset:1024
	ds_read_b128 v[196:199], v234 offset:2048
	ds_read_b128 v[234:237], v234 offset:3072
	s_add_u32 s34, s80, 0x10000
	s_addc_u32 s35, s81, 0
	s_mov_b32 m0, s57
	v_lshl_add_u64 v[88:89], s[34:35], 0, v[128:129]
	ds_read_b128 v[24:27], v220 offset:32768
	ds_read_b128 v[28:31], v220 offset:33792
	ds_read_b128 v[60:63], v220 offset:34816
	ds_read_b128 v[238:241], v220 offset:35840
	ds_read_b128 v[242:245], v220 offset:36864
	ds_read_b128 v[246:249], v220 offset:37888
	ds_read_b128 v[250:253], v220 offset:38912
	ds_read_b128 v[130:133], v220 offset:39936
	global_load_lds_dwordx4 v[88:89], off
	v_lshl_add_u64 v[88:89], s[34:35], 0, v[142:143]
	s_mov_b32 m0, s58
	s_nop 0
	global_load_lds_dwordx4 v[88:89], off
	s_waitcnt vmcnt(8)
	s_waitcnt lgkmcnt(0)
	s_barrier
	s_setprio 1
	s_waitcnt lgkmcnt(0)
	v_mfma_f32_16x16x32_bf16 v[64:67], v[8:11], v[24:27], v[64:67]
	v_mfma_f32_16x16x32_bf16 v[124:127], v[12:15], v[28:31], v[64:67]
	v_mfma_f32_16x16x32_bf16 v[64:67], v[16:19], v[24:27], v[68:71]
	v_mfma_f32_16x16x32_bf16 v[120:123], v[20:23], v[28:31], v[64:67]
	v_mfma_f32_16x16x32_bf16 v[64:67], v[8:11], v[60:63], v[72:75]
	v_mfma_f32_16x16x32_bf16 v[108:111], v[12:15], v[238:241], v[64:67]
	v_mfma_f32_16x16x32_bf16 v[64:67], v[16:19], v[60:63], v[76:79]
	v_mfma_f32_16x16x32_bf16 v[104:107], v[20:23], v[238:241], v[64:67]
	v_mfma_f32_16x16x32_bf16 v[64:67], v[8:11], v[242:245], v[80:83]
	v_mfma_f32_16x16x32_bf16 v[92:95], v[12:15], v[246:249], v[64:67]
	v_mfma_f32_16x16x32_bf16 v[64:67], v[16:19], v[242:245], v[84:87]
	v_mfma_f32_16x16x32_bf16 v[88:91], v[20:23], v[246:249], v[64:67]
	v_mfma_f32_16x16x32_bf16 v[64:67], v[8:11], v[250:253], v[222:225]
	v_mfma_f32_16x16x32_bf16 v[76:79], v[12:15], v[130:133], v[64:67]
	v_mfma_f32_16x16x32_bf16 v[64:67], v[16:19], v[250:253], v[226:229]
	v_mfma_f32_16x16x32_bf16 v[72:75], v[20:23], v[130:133], v[64:67]
	v_mfma_f32_16x16x32_bf16 v[64:67], v[172:175], v[24:27], v[96:99]
	v_mfma_f32_16x16x32_bf16 v[24:27], v[196:199], v[24:27], v[32:35]
	v_mfma_f32_16x16x32_bf16 v[112:115], v[234:237], v[28:31], v[24:27]
	v_mfma_f32_16x16x32_bf16 v[24:27], v[172:175], v[60:63], v[36:39]
	v_mfma_f32_16x16x32_bf16 v[100:103], v[192:195], v[238:241], v[24:27]
	v_mfma_f32_16x16x32_bf16 v[24:27], v[196:199], v[60:63], v[40:43]
	v_mfma_f32_16x16x32_bf16 v[96:99], v[234:237], v[238:241], v[24:27]
	v_mfma_f32_16x16x32_bf16 v[24:27], v[172:175], v[242:245], v[44:47]
	v_mfma_f32_16x16x32_bf16 v[84:87], v[192:195], v[246:249], v[24:27]
	v_mfma_f32_16x16x32_bf16 v[24:27], v[196:199], v[242:245], v[48:51]
	v_mfma_f32_16x16x32_bf16 v[80:83], v[234:237], v[246:249], v[24:27]
	v_mfma_f32_16x16x32_bf16 v[24:27], v[172:175], v[250:253], v[52:55]
	v_mfma_f32_16x16x32_bf16 v[68:71], v[192:195], v[130:133], v[24:27]
	v_mfma_f32_16x16x32_bf16 v[24:27], v[196:199], v[250:253], v[56:59]
	v_mfma_f32_16x16x32_bf16 v[116:119], v[192:195], v[28:31], v[64:67]
	v_mfma_f32_16x16x32_bf16 v[64:67], v[234:237], v[130:133], v[24:27]
	s_setprio 0
	s_barrier
	s_mov_b32 m0, s77
	s_nop 2
	v_lshl_add_u64 v[24:25], v[140:141], 0, s[78:79]
	s_add_u32 s34, vcc_lo, 0x10080
	ds_read_b128 v[32:35], v220 offset:49152
	ds_read_b128 v[36:39], v220 offset:50176
	ds_read_b128 v[130:133], v220 offset:51200
	ds_read_b128 v[222:225], v220 offset:52224
	ds_read_b128 v[226:229], v220 offset:53248
	ds_read_b128 v[238:241], v220 offset:54272
	ds_read_b128 v[242:245], v220 offset:55296
	ds_read_b128 v[246:249], v220 offset:56320
	global_load_lds_dwordx4 v[24:25], off
	v_lshl_add_u64 v[24:25], v[210:211], 0, s[78:79]
	s_mov_b32 m0, s74
	s_addc_u32 s35, vcc_hi, 0
	global_load_lds_dwordx4 v[24:25], off
	v_lshl_add_u64 v[24:25], s[34:35], 0, v[128:129]
	s_mov_b32 m0, s44
	s_nop 0
	global_load_lds_dwordx4 v[24:25], off
	v_lshl_add_u64 v[24:25], s[34:35], 0, v[142:143]
	s_mov_b32 m0, s45
	s_nop 0
	global_load_lds_dwordx4 v[24:25], off
	v_lshl_add_u64 v[24:25], v[138:139], 0, s[78:79]
	s_mov_b32 m0, s60
	s_nop 0
	global_load_lds_dwordx4 v[24:25], off
	v_lshl_add_u64 v[24:25], v[134:135], 0, s[78:79]
	s_mov_b32 m0, s61
	s_nop 0
	global_load_lds_dwordx4 v[24:25], off
	s_waitcnt vmcnt(8)
	s_waitcnt lgkmcnt(0)
	s_barrier
	s_setprio 1
	s_waitcnt lgkmcnt(0)
	v_mfma_f32_16x16x32_bf16 v[24:27], v[8:11], v[32:35], v[144:147]
	v_mfma_f32_16x16x32_bf16 v[60:63], v[12:15], v[36:39], v[24:27]
	v_mfma_f32_16x16x32_bf16 v[24:27], v[16:19], v[32:35], v[148:151]
	v_mfma_f32_16x16x32_bf16 v[56:59], v[20:23], v[36:39], v[24:27]
	v_mfma_f32_16x16x32_bf16 v[24:27], v[8:11], v[130:133], v[152:155]
	v_mfma_f32_16x16x32_bf16 v[44:47], v[12:15], v[222:225], v[24:27]
	v_mfma_f32_16x16x32_bf16 v[24:27], v[16:19], v[130:133], v[156:159]
	v_mfma_f32_16x16x32_bf16 v[40:43], v[20:23], v[222:225], v[24:27]
	v_mfma_f32_16x16x32_bf16 v[24:27], v[8:11], v[226:229], v[160:163]
	v_mfma_f32_16x16x32_bf16 v[0:3], v[8:11], v[242:245], v[0:3]
	v_mfma_f32_16x16x32_bf16 v[28:31], v[12:15], v[238:241], v[24:27]
	v_mfma_f32_16x16x32_bf16 v[24:27], v[16:19], v[226:229], v[164:167]
	v_mfma_f32_16x16x32_bf16 v[12:15], v[12:15], v[246:249], v[0:3]
	v_mfma_f32_16x16x32_bf16 v[0:3], v[16:19], v[242:245], v[4:7]
	v_mfma_f32_16x16x32_bf16 v[24:27], v[20:23], v[238:241], v[24:27]
	v_mfma_f32_16x16x32_bf16 v[8:11], v[20:23], v[246:249], v[0:3]
	v_mfma_f32_16x16x32_bf16 v[0:3], v[172:175], v[32:35], v[200:203]
	v_mfma_f32_16x16x32_bf16 v[52:55], v[192:195], v[36:39], v[0:3]
	v_mfma_f32_16x16x32_bf16 v[0:3], v[196:199], v[32:35], v[204:207]
	v_mfma_f32_16x16x32_bf16 v[48:51], v[234:237], v[36:39], v[0:3]
	v_mfma_f32_16x16x32_bf16 v[0:3], v[172:175], v[130:133], v[230:233]
	v_mfma_f32_16x16x32_bf16 v[36:39], v[192:195], v[222:225], v[0:3]
	v_mfma_f32_16x16x32_bf16 v[0:3], v[196:199], v[130:133], v[176:179]
	v_mfma_f32_16x16x32_bf16 v[32:35], v[234:237], v[222:225], v[0:3]
	v_mfma_f32_16x16x32_bf16 v[0:3], v[172:175], v[226:229], v[180:183]
	v_mfma_f32_16x16x32_bf16 v[20:23], v[192:195], v[238:241], v[0:3]
	v_mfma_f32_16x16x32_bf16 v[0:3], v[196:199], v[226:229], v[184:187]
	v_mfma_f32_16x16x32_bf16 v[16:19], v[234:237], v[238:241], v[0:3]
	v_mfma_f32_16x16x32_bf16 v[0:3], v[172:175], v[242:245], v[188:191]
	v_mfma_f32_16x16x32_bf16 v[4:7], v[192:195], v[246:249], v[0:3]
	v_mfma_f32_16x16x32_bf16 v[0:3], v[196:199], v[242:245], v[168:171]
	v_mfma_f32_16x16x32_bf16 v[0:3], v[234:237], v[246:249], v[0:3]
	s_setprio 0
	s_barrier
	s_andn2_b64 vcc, exec, s[16:17]
	s_cbranch_vccnz .LBB0_1191
	s_barrier
